# epilogues un-aligned: the leading half's align barrier moved to the end of its epilogue (its epilogue overlaps the lagging half's last MFMA segment, the lagging half's epilogue overlaps the leading ha
# baseline (speedup 1.0000x reference)
; #define PG8_STAGE(bufoff, gbase, voff) do { _Pragma("unroll") for (int _i = 0; _i < 2; ++_i) \
;         __builtin_amdgcn_global_load_lds((const unsigned*)((const char*)(gbase) + (voff)[_i]), (LAS unsigned*)(lds + (bufoff) + ldsw + _i * 8192), 16, 0, 0); } while (0)
; #define PG8_LDA(dst, b, h) do { _Pragma("unroll") for (int m = 0; m < 4; ++m) _Pragma("unroll") for (int k = 0; k < 2; ++k) dst[m][k] = *(const LAS bf16x8*)(lds + PG8_SA(b, h) + aoff + m * 2048 + k * 1024); } while (0)
; #define PG8_LDB(dst, b, h) do { _Pragma("unroll") for (int n = 0; n < 2; ++n) _Pragma("unroll") for (int k = 0; k < 2; ++k) dst[n][k] = *(const LAS bf16x8*)(lds + PG8_SB(b, h) + boff + n * 2048 + k * 1024); } while (0)
; #define PG8_MMA(ai, bj, At, Bt) do { __builtin_amdgcn_s_setprio(1); _Pragma("unroll") for (int m = 0; m < 4; ++m) _Pragma("unroll") for (int n = 0; n < 2; ++n) _Pragma("unroll") for (int k = 0; k < 2; ++k) \
;         acc[ai][bj][m][n] = __builtin_amdgcn_mfma_f32_16x16x32_bf16(Bt[n][k], At[m][k], acc[ai][bj][m][n], 0, 0, 0); __builtin_amdgcn_s_setprio(0); } while (0)
; #define PG8_WAIT_V(n) asm volatile("s_waitcnt vmcnt(" #n ")" ::: "memory")
; template <class Epi, class Sched, bool ABLK = false, bool ALIGN_EPI = true, bool SP2 = true, bool BBLK = true>
; __device__ __forceinline__ void gemm_phase(LAS unsigned char* lds, const Gemm g, const Sched& S, const Epi& E) {
;     ...
;         for (int t = 0; t < nt; t += 2) {
;             const bool last = (t == nt - 2);
;             const char* a1 = a_tile(uA, tbA + t + 1);
;             const char* a2 = last ? a_tile(nuA, ntbA) : a_tile(uA, tbA + t + 2); const char* b2 = last ? nB : cB + (size_t)(t + 2) * kstepB;
;             const char* a3 = last ? a_tile(nuA, ntbA + 1) : a_tile(uA, tbA + t + 3); const char* b3 = b2 + kstepB;
;             if (last && has_next) S.a_ready(nxt);
;             if constexpr (SP2) {
;             PG8_LDB(B0, 0, 0); PG8_LDB(B1, 0, 1); PG8_SCHED; PG8_LDA(At, 0, 0); PG8_STAGE(PG8_SA(1, 1), a1 + hstepA, voffA);
;             PG8_WAIT_V(8); PG8_WAIT_L(0); PG8_BAR; PG8_MMA(0, 0, At, B0); PG8_MMA(0, 1, At, B1); PG8_BAR; PG8_SCHED;
;             PG8_LDA(At, 0, 1); PG8_STAGE(PG8_SB(0, 0), b2, voffB); PG8_STAGE(PG8_SB(0, 1), b2 + hstepB, voffB); PG8_STAGE(PG8_SA(0, 0), a2, voffA);
;             PG8_WAIT_V(8); PG8_WAIT_L(0); PG8_BAR; PG8_MMA(1, 0, At, B0); PG8_MMA(1, 1, At, B1); PG8_BAR; PG8_SCHED;
.LBB0_350:
	ds_read_b128 v[152:155], v148
	ds_read_b128 v[156:159], v148 offset:1024
	ds_read_b128 v[160:163], v148 offset:2048
	ds_read_b128 v[164:167], v148 offset:3072
	ds_read_b128 v[168:171], v149
	ds_read_b128 v[172:175], v149 offset:1024
	ds_read_b128 v[176:179], v149 offset:2048
	ds_read_b128 v[180:183], v149 offset:3072
	s_add_u32 s28, s24, s26
	s_addc_u32 s29, s25, s27
	s_add_u32 s34, s28, 0x100
	s_addc_u32 s35, s29, 0
	s_add_u32 s28, s28, 0x180
	s_addc_u32 s29, s29, 0
	s_cmpk_eq_i32 s26, 0xf00
	s_cselect_b32 s29, s51, s29
	s_cselect_b32 s28, s50, s28
	s_cselect_b32 s31, s9, s53
	s_cselect_b32 s30, s11, s52
	s_cselect_b32 s35, s4, s35
	s_cselect_b32 s34, s5, s34
	s_mov_b32 m0, s49
	v_lshl_add_u64 v[216:217], v[142:143], 0, s[26:27]
	ds_read_b128 v[184:187], v150
	ds_read_b128 v[188:191], v150 offset:1024
	ds_read_b128 v[192:195], v150 offset:2048
	ds_read_b128 v[196:199], v150 offset:3072
	ds_read_b128 v[200:203], v150 offset:4096
	ds_read_b128 v[204:207], v150 offset:5120
	ds_read_b128 v[208:211], v150 offset:6144
	ds_read_b128 v[212:215], v150 offset:7168
	global_load_lds_dwordx4 v[216:217], off
	v_lshl_add_u64 v[216:217], v[144:145], 0, s[26:27]
	s_add_i32 m0, s21, 0xe000
	s_nop 0
	global_load_lds_dwordx4 v[216:217], off
	s_waitcnt vmcnt(8) lgkmcnt(0)
	s_barrier
	v_mfma_f32_16x16x32_bf16 v[122:125], v[152:155], v[184:187], v[122:125]
	v_mfma_f32_16x16x32_bf16 v[118:121], v[160:163], v[184:187], v[118:121]
	v_mfma_f32_16x16x32_bf16 v[106:109], v[152:155], v[192:195], v[106:109]
	v_mfma_f32_16x16x32_bf16 v[102:105], v[160:163], v[192:195], v[102:105]
	v_mfma_f32_16x16x32_bf16 v[90:93], v[152:155], v[200:203], v[90:93]
	v_mfma_f32_16x16x32_bf16 v[86:89], v[160:163], v[200:203], v[86:89]
	v_mfma_f32_16x16x32_bf16 v[74:77], v[152:155], v[208:211], v[74:77]
	v_mfma_f32_16x16x32_bf16 v[70:73], v[160:163], v[208:211], v[70:73]
	v_mfma_f32_16x16x32_bf16 v[122:125], v[156:159], v[188:191], v[122:125]
	v_mfma_f32_16x16x32_bf16 v[118:121], v[164:167], v[188:191], v[118:121]
	v_mfma_f32_16x16x32_bf16 v[106:109], v[156:159], v[196:199], v[106:109]
	v_mfma_f32_16x16x32_bf16 v[102:105], v[164:167], v[196:199], v[102:105]
	v_mfma_f32_16x16x32_bf16 v[90:93], v[156:159], v[204:207], v[90:93]
	v_mfma_f32_16x16x32_bf16 v[86:89], v[164:167], v[204:207], v[86:89]
	v_mfma_f32_16x16x32_bf16 v[74:77], v[156:159], v[212:215], v[74:77]
	v_mfma_f32_16x16x32_bf16 v[70:73], v[164:167], v[212:215], v[70:73]
	v_mfma_f32_16x16x32_bf16 v[126:129], v[168:171], v[184:187], v[126:129]
	v_mfma_f32_16x16x32_bf16 v[114:117], v[176:179], v[184:187], v[114:117]
	v_mfma_f32_16x16x32_bf16 v[110:113], v[168:171], v[192:195], v[110:113]
	v_mfma_f32_16x16x32_bf16 v[98:101], v[176:179], v[192:195], v[98:101]
	v_mfma_f32_16x16x32_bf16 v[94:97], v[168:171], v[200:203], v[94:97]
	v_mfma_f32_16x16x32_bf16 v[82:85], v[176:179], v[200:203], v[82:85]
	v_mfma_f32_16x16x32_bf16 v[78:81], v[168:171], v[208:211], v[78:81]
	v_mfma_f32_16x16x32_bf16 v[66:69], v[176:179], v[208:211], v[66:69]
	v_mfma_f32_16x16x32_bf16 v[126:129], v[172:175], v[188:191], v[126:129]
	v_mfma_f32_16x16x32_bf16 v[114:117], v[180:183], v[188:191], v[114:117]
	v_mfma_f32_16x16x32_bf16 v[110:113], v[172:175], v[196:199], v[110:113]
	v_mfma_f32_16x16x32_bf16 v[98:101], v[180:183], v[196:199], v[98:101]
	v_mfma_f32_16x16x32_bf16 v[94:97], v[172:175], v[204:207], v[94:97]
	v_mfma_f32_16x16x32_bf16 v[82:85], v[180:183], v[204:207], v[82:85]
	v_mfma_f32_16x16x32_bf16 v[78:81], v[172:175], v[212:215], v[78:81]
	v_mfma_f32_16x16x32_bf16 v[66:69], v[180:183], v[212:215], v[66:69]
	s_barrier
	s_add_i32 s55, s44, s33
	s_mov_b32 m0, s55
	ds_read_b128 v[184:187], v150 offset:16384
	ds_read_b128 v[188:191], v150 offset:17408
	ds_read_b128 v[192:195], v150 offset:18432
	ds_read_b128 v[196:199], v150 offset:19456
	ds_read_b128 v[200:203], v150 offset:20480
	ds_read_b128 v[204:207], v150 offset:21504
	ds_read_b128 v[208:211], v150 offset:22528
	ds_read_b128 v[212:215], v150 offset:23552
	global_load_lds_dwordx4 v134, s[30:31]
	s_add_i32 m0, s55, 0x2000
	s_add_u32 s56, s30, 0x4000
	s_addc_u32 s57, s31, 0
	s_add_i32 s55, s45, s33
	global_load_lds_dwordx4 v130, s[30:31]
	s_mov_b32 m0, s55
	s_nop 0
	global_load_lds_dwordx4 v134, s[56:57]
	s_add_i32 m0, s55, 0x2000
	s_nop 0
	global_load_lds_dwordx4 v130, s[56:57]
	s_mov_b32 m0, s21
	s_nop 0
	global_load_lds_dwordx4 v136, s[34:35]
	s_mov_b32 m0, s23
	s_nop 0
	global_load_lds_dwordx4 v132, s[34:35]
	s_waitcnt vmcnt(8) lgkmcnt(0)
	s_barrier
	v_mfma_f32_16x16x32_bf16 v[58:61], v[152:155], v[184:187], v[58:61]
	v_mfma_f32_16x16x32_bf16 v[54:57], v[160:163], v[184:187], v[54:57]
	v_mfma_f32_16x16x32_bf16 v[42:45], v[152:155], v[192:195], v[42:45]
	v_mfma_f32_16x16x32_bf16 v[38:41], v[160:163], v[192:195], v[38:41]
	v_mfma_f32_16x16x32_bf16 v[26:29], v[152:155], v[200:203], v[26:29]
	v_mfma_f32_16x16x32_bf16 v[22:25], v[160:163], v[200:203], v[22:25]
	v_mfma_f32_16x16x32_bf16 v[10:13], v[152:155], v[208:211], v[10:13]
	v_mfma_f32_16x16x32_bf16 v[6:9], v[160:163], v[208:211], v[6:9]
	v_mfma_f32_16x16x32_bf16 v[58:61], v[156:159], v[188:191], v[58:61]
	v_mfma_f32_16x16x32_bf16 v[54:57], v[164:167], v[188:191], v[54:57]
	v_mfma_f32_16x16x32_bf16 v[42:45], v[156:159], v[196:199], v[42:45]
	v_mfma_f32_16x16x32_bf16 v[38:41], v[164:167], v[196:199], v[38:41]
	v_mfma_f32_16x16x32_bf16 v[26:29], v[156:159], v[204:207], v[26:29]
	v_mfma_f32_16x16x32_bf16 v[22:25], v[164:167], v[204:207], v[22:25]
	v_mfma_f32_16x16x32_bf16 v[10:13], v[156:159], v[212:215], v[10:13]
	v_mfma_f32_16x16x32_bf16 v[6:9], v[164:167], v[212:215], v[6:9]
	v_mfma_f32_16x16x32_bf16 v[62:65], v[168:171], v[184:187], v[62:65]
	v_mfma_f32_16x16x32_bf16 v[50:53], v[176:179], v[184:187], v[50:53]
	v_mfma_f32_16x16x32_bf16 v[46:49], v[168:171], v[192:195], v[46:49]
	v_mfma_f32_16x16x32_bf16 v[34:37], v[176:179], v[192:195], v[34:37]
	v_mfma_f32_16x16x32_bf16 v[30:33], v[168:171], v[200:203], v[30:33]
	v_mfma_f32_16x16x32_bf16 v[18:21], v[176:179], v[200:203], v[18:21]
	v_mfma_f32_16x16x32_bf16 v[14:17], v[168:171], v[208:211], v[14:17]
	v_mfma_f32_16x16x32_bf16 v[2:5], v[176:179], v[208:211], v[2:5]
	v_mfma_f32_16x16x32_bf16 v[62:65], v[172:175], v[188:191], v[62:65]
	v_mfma_f32_16x16x32_bf16 v[50:53], v[180:183], v[188:191], v[50:53]
	v_mfma_f32_16x16x32_bf16 v[46:49], v[172:175], v[196:199], v[46:49]
	v_mfma_f32_16x16x32_bf16 v[34:37], v[180:183], v[196:199], v[34:37]
	v_mfma_f32_16x16x32_bf16 v[30:33], v[172:175], v[204:207], v[30:33]
	v_mfma_f32_16x16x32_bf16 v[18:21], v[180:183], v[204:207], v[18:21]
	v_mfma_f32_16x16x32_bf16 v[14:17], v[172:175], v[212:215], v[14:17]
	v_mfma_f32_16x16x32_bf16 v[2:5], v[180:183], v[212:215], v[2:5]
	s_barrier
; #define PG8_STAGE(bufoff, gbase, voff) do { _Pragma("unroll") for (int _i = 0; _i < 2; ++_i) \
;         __builtin_amdgcn_global_load_lds((const unsigned*)((const char*)(gbase) + (voff)[_i]), (LAS unsigned*)(lds + (bufoff) + ldsw + _i * 8192), 16, 0, 0); } while (0)
; #define PG8_LDA(dst, b, h) do { _Pragma("unroll") for (int m = 0; m < 4; ++m) _Pragma("unroll") for (int k = 0; k < 2; ++k) dst[m][k] = *(const LAS bf16x8*)(lds + PG8_SA(b, h) + aoff + m * 2048 + k * 1024); } while (0)
; #define PG8_LDB(dst, b, h) do { _Pragma("unroll") for (int n = 0; n < 2; ++n) _Pragma("unroll") for (int k = 0; k < 2; ++k) dst[n][k] = *(const LAS bf16x8*)(lds + PG8_SB(b, h) + boff + n * 2048 + k * 1024); } while (0)
; #define PG8_MMA(ai, bj, At, Bt) do { __builtin_amdgcn_s_setprio(1); _Pragma("unroll") for (int m = 0; m < 4; ++m) _Pragma("unroll") for (int n = 0; n < 2; ++n) _Pragma("unroll") for (int k = 0; k < 2; ++k) \
;         acc[ai][bj][m][n] = __builtin_amdgcn_mfma_f32_16x16x32_bf16(Bt[n][k], At[m][k], acc[ai][bj][m][n], 0, 0, 0); __builtin_amdgcn_s_setprio(0); } while (0)
; #define PG8_WAIT_V(n) asm volatile("s_waitcnt vmcnt(" #n ")" ::: "memory")
; #define PG8_WAIT_L(n) asm volatile("s_waitcnt lgkmcnt(" #n ")" ::: "memory")
; #define PG8_BAR __builtin_amdgcn_s_barrier()
; #define PG8_SCHED __builtin_amdgcn_sched_barrier(0)
; template <class Epi, class Sched, bool ABLK = false, bool ALIGN_EPI = true, bool SP2 = true, bool BBLK = true>
; __device__ __forceinline__ void gemm_phase(LAS unsigned char* lds, const Gemm g, const Sched& S, const Epi& E) {
;     ...
;             PG8_WAIT_V(8); PG8_WAIT_L(0); PG8_BAR; PG8_MMA(1, 0, At, B0); PG8_MMA(1, 1, At, B1); PG8_BAR; PG8_SCHED;
;             PG8_LDB(B0, 1, 0); PG8_LDB(B1, 1, 1); PG8_SCHED; PG8_LDA(At, 1, 0); PG8_STAGE(PG8_SA(0, 1), a2 + hstepA, voffA);
;             PG8_WAIT_V(8); PG8_WAIT_L(0); PG8_BAR; PG8_MMA(0, 0, At, B0); PG8_MMA(0, 1, At, B1); PG8_BAR; PG8_SCHED;
;             PG8_LDA(At, 1, 1); PG8_STAGE(PG8_SB(1, 0), b3, voffB); PG8_STAGE(PG8_SB(1, 1), b3 + hstepB, voffB); PG8_STAGE(PG8_SA(1, 0), a3, voffA);
	s_add_i32 s55, 0, 0x18000
	v_add_u32_e32 v151, s55, v146
	s_add_i32 s56, 0, 0x1c000
	ds_read_b128 v[152:155], v151
	ds_read_b128 v[156:159], v151 offset:1024
	ds_read_b128 v[160:163], v151 offset:2048
	ds_read_b128 v[164:167], v151 offset:3072
	v_add_u32_e32 v151, s56, v146
	ds_read_b128 v[168:171], v151
	ds_read_b128 v[172:175], v151 offset:1024
	ds_read_b128 v[176:179], v151 offset:2048
	ds_read_b128 v[180:183], v151 offset:3072
	s_add_u32 s34, s34, 0x80000
	s_addc_u32 s35, s35, 0
	s_mov_b32 m0, s39
	ds_read_b128 v[184:187], v150 offset:32768
	ds_read_b128 v[188:191], v150 offset:33792
	ds_read_b128 v[192:195], v150 offset:34816
	ds_read_b128 v[196:199], v150 offset:35840
	ds_read_b128 v[200:203], v150 offset:36864
	ds_read_b128 v[204:207], v150 offset:37888
	ds_read_b128 v[208:211], v150 offset:38912
	ds_read_b128 v[212:215], v150 offset:39936
	global_load_lds_dwordx4 v136, s[34:35]
	s_mov_b32 m0, s40
	s_nop 0
	global_load_lds_dwordx4 v132, s[34:35]
	s_waitcnt vmcnt(8) lgkmcnt(0)
	s_barrier
	v_mfma_f32_16x16x32_bf16 v[122:125], v[152:155], v[184:187], v[122:125]
	v_mfma_f32_16x16x32_bf16 v[118:121], v[160:163], v[184:187], v[118:121]
	v_mfma_f32_16x16x32_bf16 v[106:109], v[152:155], v[192:195], v[106:109]
	v_mfma_f32_16x16x32_bf16 v[102:105], v[160:163], v[192:195], v[102:105]
	v_mfma_f32_16x16x32_bf16 v[90:93], v[152:155], v[200:203], v[90:93]
	v_mfma_f32_16x16x32_bf16 v[86:89], v[160:163], v[200:203], v[86:89]
	v_mfma_f32_16x16x32_bf16 v[74:77], v[152:155], v[208:211], v[74:77]
	v_mfma_f32_16x16x32_bf16 v[70:73], v[160:163], v[208:211], v[70:73]
	v_mfma_f32_16x16x32_bf16 v[122:125], v[156:159], v[188:191], v[122:125]
	v_mfma_f32_16x16x32_bf16 v[118:121], v[164:167], v[188:191], v[118:121]
	v_mfma_f32_16x16x32_bf16 v[106:109], v[156:159], v[196:199], v[106:109]
	v_mfma_f32_16x16x32_bf16 v[102:105], v[164:167], v[196:199], v[102:105]
	v_mfma_f32_16x16x32_bf16 v[90:93], v[156:159], v[204:207], v[90:93]
	v_mfma_f32_16x16x32_bf16 v[86:89], v[164:167], v[204:207], v[86:89]
	v_mfma_f32_16x16x32_bf16 v[74:77], v[156:159], v[212:215], v[74:77]
	v_mfma_f32_16x16x32_bf16 v[70:73], v[164:167], v[212:215], v[70:73]
	v_mfma_f32_16x16x32_bf16 v[126:129], v[168:171], v[184:187], v[126:129]
	v_mfma_f32_16x16x32_bf16 v[114:117], v[176:179], v[184:187], v[114:117]
	v_mfma_f32_16x16x32_bf16 v[110:113], v[168:171], v[192:195], v[110:113]
	v_mfma_f32_16x16x32_bf16 v[98:101], v[176:179], v[192:195], v[98:101]
	v_mfma_f32_16x16x32_bf16 v[94:97], v[168:171], v[200:203], v[94:97]
	v_mfma_f32_16x16x32_bf16 v[82:85], v[176:179], v[200:203], v[82:85]
	v_mfma_f32_16x16x32_bf16 v[78:81], v[168:171], v[208:211], v[78:81]
	v_mfma_f32_16x16x32_bf16 v[66:69], v[176:179], v[208:211], v[66:69]
	v_mfma_f32_16x16x32_bf16 v[126:129], v[172:175], v[188:191], v[126:129]
	v_mfma_f32_16x16x32_bf16 v[114:117], v[180:183], v[188:191], v[114:117]
	v_mfma_f32_16x16x32_bf16 v[110:113], v[172:175], v[196:199], v[110:113]
	v_mfma_f32_16x16x32_bf16 v[98:101], v[180:183], v[196:199], v[98:101]
	v_mfma_f32_16x16x32_bf16 v[94:97], v[172:175], v[204:207], v[94:97]
	v_mfma_f32_16x16x32_bf16 v[82:85], v[180:183], v[204:207], v[82:85]
	v_mfma_f32_16x16x32_bf16 v[78:81], v[172:175], v[212:215], v[78:81]
	v_mfma_f32_16x16x32_bf16 v[66:69], v[180:183], v[212:215], v[66:69]
	s_barrier
	s_add_u32 s34, s30, 0x8000
	s_addc_u32 s35, s31, 0
	s_add_i32 s55, s55, s33
	s_mov_b32 m0, s55
	ds_read_b128 v[184:187], v150 offset:49152
	ds_read_b128 v[188:191], v150 offset:50176
	ds_read_b128 v[192:195], v150 offset:51200
	ds_read_b128 v[196:199], v150 offset:52224
	ds_read_b128 v[200:203], v150 offset:53248
	ds_read_b128 v[204:207], v150 offset:54272
	ds_read_b128 v[208:211], v150 offset:55296
	ds_read_b128 v[212:215], v150 offset:56320
	global_load_lds_dwordx4 v134, s[34:35]
	s_add_i32 m0, s55, 0x2000
	s_add_u32 s30, s30, 0xc000
	v_lshl_add_u64 v[216:217], s[34:35], 0, v[130:131]
	s_addc_u32 s31, s31, 0
	s_add_i32 s34, s56, s33
	global_load_lds_dwordx4 v[216:217], off
	s_mov_b32 m0, s34
	s_nop 0
	global_load_lds_dwordx4 v134, s[30:31]
	s_add_i32 m0, s34, 0x2000
	s_nop 0
	global_load_lds_dwordx4 v130, s[30:31]
	s_mov_b32 m0, s42
	s_nop 0
	global_load_lds_dwordx4 v136, s[28:29]
	s_mov_b32 m0, s43
	s_nop 0
	global_load_lds_dwordx4 v132, s[28:29]
	s_waitcnt vmcnt(8) lgkmcnt(0)
	s_barrier
	v_mfma_f32_16x16x32_bf16 v[58:61], v[152:155], v[184:187], v[58:61]
	v_mfma_f32_16x16x32_bf16 v[54:57], v[160:163], v[184:187], v[54:57]
	v_mfma_f32_16x16x32_bf16 v[42:45], v[152:155], v[192:195], v[42:45]
	v_mfma_f32_16x16x32_bf16 v[38:41], v[160:163], v[192:195], v[38:41]
	v_mfma_f32_16x16x32_bf16 v[26:29], v[152:155], v[200:203], v[26:29]
	v_mfma_f32_16x16x32_bf16 v[22:25], v[160:163], v[200:203], v[22:25]
	v_mfma_f32_16x16x32_bf16 v[10:13], v[152:155], v[208:211], v[10:13]
	v_mfma_f32_16x16x32_bf16 v[6:9], v[160:163], v[208:211], v[6:9]
	v_mfma_f32_16x16x32_bf16 v[58:61], v[156:159], v[188:191], v[58:61]
	v_mfma_f32_16x16x32_bf16 v[54:57], v[164:167], v[188:191], v[54:57]
	v_mfma_f32_16x16x32_bf16 v[42:45], v[156:159], v[196:199], v[42:45]
	v_mfma_f32_16x16x32_bf16 v[38:41], v[164:167], v[196:199], v[38:41]
	v_mfma_f32_16x16x32_bf16 v[26:29], v[156:159], v[204:207], v[26:29]
	v_mfma_f32_16x16x32_bf16 v[22:25], v[164:167], v[204:207], v[22:25]
	v_mfma_f32_16x16x32_bf16 v[10:13], v[156:159], v[212:215], v[10:13]
	v_mfma_f32_16x16x32_bf16 v[6:9], v[164:167], v[212:215], v[6:9]
	v_mfma_f32_16x16x32_bf16 v[62:65], v[168:171], v[184:187], v[62:65]
	v_mfma_f32_16x16x32_bf16 v[50:53], v[176:179], v[184:187], v[50:53]
	v_mfma_f32_16x16x32_bf16 v[46:49], v[168:171], v[192:195], v[46:49]
	v_mfma_f32_16x16x32_bf16 v[34:37], v[176:179], v[192:195], v[34:37]
	v_mfma_f32_16x16x32_bf16 v[30:33], v[168:171], v[200:203], v[30:33]
	v_mfma_f32_16x16x32_bf16 v[18:21], v[176:179], v[200:203], v[18:21]
	v_mfma_f32_16x16x32_bf16 v[14:17], v[168:171], v[208:211], v[14:17]
	v_mfma_f32_16x16x32_bf16 v[2:5], v[176:179], v[208:211], v[2:5]
	v_mfma_f32_16x16x32_bf16 v[62:65], v[172:175], v[188:191], v[62:65]
	v_mfma_f32_16x16x32_bf16 v[50:53], v[180:183], v[188:191], v[50:53]
	v_mfma_f32_16x16x32_bf16 v[46:49], v[172:175], v[196:199], v[46:49]
	v_mfma_f32_16x16x32_bf16 v[34:37], v[180:183], v[196:199], v[34:37]
	v_mfma_f32_16x16x32_bf16 v[30:33], v[172:175], v[204:207], v[30:33]
	v_mfma_f32_16x16x32_bf16 v[18:21], v[180:183], v[204:207], v[18:21]
	v_mfma_f32_16x16x32_bf16 v[14:17], v[172:175], v[212:215], v[14:17]
	v_mfma_f32_16x16x32_bf16 v[2:5], v[180:183], v[212:215], v[2:5]
	s_barrier
; __device__ __forceinline__ unsigned pk2(float lo, float hi) { const f32x2 v = {lo, hi}; return __builtin_bit_cast(unsigned, __builtin_convertvector(v, bf16x2_t)); }
; __device__ __forceinline__ float sigmoidf_(float x) { return __builtin_amdgcn_rcpf(1.0f + __expf(-x)); }
;     __device__ __forceinline__ void operator()(const f32x4 (&acc)[2][2][4][2], const Unit& u, int wr, int wc, int fr, int fq) const {
;         const int row0 = u.pm * 256 + wr * 64 + fr, ch0 = u.pn * 128 + wc * 32 + 8 * fq;
; #pragma unroll
;         for (int ai = 0; ai < 2; ++ai)
; #pragma unroll
;             for (int m = 0; m < 4; ++m) { f32x4 z[2];
; #pragma unroll
;                 for (int n = 0; n < 2; ++n) { const f32x4 o = acc[ai][0][m][n], gt = acc[ai][1][m][n];
; #pragma unroll
;                     for (int j = 0; j < 4; ++j) z[n][j] = o[j] * sigmoidf_(gt[j]); }
;                 u32x4 w; w.x = pk2(z[0][0], z[0][1]); w.y = pk2(z[0][2], z[0][3]); w.z = pk2(z[1][0], z[1][1]); w.w = pk2(z[1][2], z[1][3]);
;                 *(u32x4*)(Z + (size_t)(row0 + ai * 128 + m * 16) * D + ch0) = w; }
	s_add_i32 s54, s54, 2
	s_add_u32 s26, s26, 0x100
	s_addc_u32 s27, s27, 0
	s_add_u32 s52, s52, 0x10000
	s_addc_u32 s53, s53, 0
	s_cmp_gt_u32 s54, 29
	s_cbranch_scc0 .LBB0_350
	v_mul_f32_e32 v114, 0xbfb8aa3b, v114
	v_mul_f32_e32 v115, 0xbfb8aa3b, v115
	v_exp_f32_e32 v114, v114
	v_exp_f32_e32 v115, v115
	v_mul_f32_e32 v116, 0xbfb8aa3b, v116
	v_mul_f32_e32 v117, 0xbfb8aa3b, v117
	v_exp_f32_e32 v116, v116
	v_exp_f32_e32 v117, v117
	v_mul_f32_e32 v50, 0xbfb8aa3b, v50
	v_mul_f32_e32 v51, 0xbfb8aa3b, v51
	v_exp_f32_e32 v50, v50
	v_exp_f32_e32 v51, v51
	v_mul_f32_e32 v52, 0xbfb8aa3b, v52
	v_mul_f32_e32 v53, 0xbfb8aa3b, v53
	v_add_f32_e32 v114, 1.0, v114
	v_add_f32_e32 v115, 1.0, v115
	v_exp_f32_e32 v52, v52
	v_exp_f32_e32 v53, v53
	v_mul_f32_e32 v34, 0xbfb8aa3b, v34
	v_mul_f32_e32 v35, 0xbfb8aa3b, v35
	v_rcp_f32_e32 v114, v114
	v_rcp_f32_e32 v115, v115
	v_add_f32_e32 v116, 1.0, v116
	v_add_f32_e32 v117, 1.0, v117
	v_exp_f32_e32 v34, v34
	v_exp_f32_e32 v35, v35
	v_mul_f32_e32 v36, 0xbfb8aa3b, v36
	v_mul_f32_e32 v37, 0xbfb8aa3b, v37
	v_rcp_f32_e32 v116, v116
	v_rcp_f32_e32 v117, v117
	v_mul_f32_e32 v98, 0xbfb8aa3b, v98
	v_mul_f32_e32 v99, 0xbfb8aa3b, v99
	v_mul_f32_e32 v82, 0xbfb8aa3b, v82
	v_mul_f32_e32 v83, 0xbfb8aa3b, v83
	v_mul_f32_e32 v66, 0xbfb8aa3b, v66
	v_mul_f32_e32 v67, 0xbfb8aa3b, v67
	v_exp_f32_e32 v36, v36
	v_exp_f32_e32 v37, v37
	v_mul_f32_e32 v18, 0xbfb8aa3b, v18
	v_mul_f32_e32 v19, 0xbfb8aa3b, v19
	v_exp_f32_e32 v98, v98
	v_exp_f32_e32 v99, v99
	v_mul_f32_e32 v100, 0xbfb8aa3b, v100
	v_mul_f32_e32 v101, 0xbfb8aa3b, v101
	v_exp_f32_e32 v82, v82
	v_exp_f32_e32 v83, v83
	v_mul_f32_e32 v84, 0xbfb8aa3b, v84
	v_mul_f32_e32 v85, 0xbfb8aa3b, v85
	v_exp_f32_e32 v66, v66
	v_exp_f32_e32 v67, v67
	v_mul_f32_e32 v68, 0xbfb8aa3b, v68
	v_mul_f32_e32 v69, 0xbfb8aa3b, v69
	v_add_f32_e32 v50, 1.0, v50
	v_add_f32_e32 v51, 1.0, v51
	v_exp_f32_e32 v18, v18
	v_exp_f32_e32 v19, v19
	v_mul_f32_e32 v20, 0xbfb8aa3b, v20
	v_mul_f32_e32 v21, 0xbfb8aa3b, v21
	v_lshl_add_u32 v142, s20, 8, v1
	v_exp_f32_e32 v100, v100
	v_exp_f32_e32 v101, v101
	v_exp_f32_e32 v84, v84
	v_exp_f32_e32 v85, v85
	v_exp_f32_e32 v68, v68
	v_exp_f32_e32 v69, v69
	v_rcp_f32_e32 v50, v50
	v_rcp_f32_e32 v51, v51
	v_add_f32_e32 v52, 1.0, v52
	v_add_f32_e32 v53, 1.0, v53
	v_exp_f32_e32 v20, v20
	v_exp_f32_e32 v21, v21
	v_mul_f32_e32 v2, 0xbfb8aa3b, v2
	v_mul_f32_e32 v3, 0xbfb8aa3b, v3
	v_lshl_or_b32 v144, s22, 7, v147
	v_pk_mul_f32 v[114:115], v[118:119], v[114:115]
	v_ashrrev_i32_e32 v143, 31, v142
	v_rcp_f32_e32 v52, v52
	v_rcp_f32_e32 v53, v53
	v_add_f32_e32 v34, 1.0, v34
	v_add_f32_e32 v35, 1.0, v35
	v_exp_f32_e32 v2, v2
	v_exp_f32_e32 v3, v3
	v_mul_f32_e32 v4, 0xbfb8aa3b, v4
	v_mul_f32_e32 v5, 0xbfb8aa3b, v5
	v_mul_f32_e32 v126, 0xbfb8aa3b, v126
	v_mul_f32_e32 v127, 0xbfb8aa3b, v127
	v_ashrrev_i32_e32 v145, 31, v144
	v_mul_f32_e32 v128, 0xbfb8aa3b, v128
	v_mul_f32_e32 v129, 0xbfb8aa3b, v129
	v_pk_mul_f32 v[120:121], v[120:121], v[116:117]
	v_cvt_pk_bf16_f32 v118, v114, v115
	v_lshlrev_b64 v[114:115], 12, v[142:143]
	v_mul_f32_e32 v110, 0xbfb8aa3b, v110
	v_mul_f32_e32 v111, 0xbfb8aa3b, v111
	v_mul_f32_e32 v112, 0xbfb8aa3b, v112
	v_mul_f32_e32 v113, 0xbfb8aa3b, v113
	v_mul_f32_e32 v94, 0xbfb8aa3b, v94
	v_mul_f32_e32 v95, 0xbfb8aa3b, v95
	v_mul_f32_e32 v96, 0xbfb8aa3b, v96
	v_mul_f32_e32 v97, 0xbfb8aa3b, v97
	v_mul_f32_e32 v78, 0xbfb8aa3b, v78
	v_mul_f32_e32 v79, 0xbfb8aa3b, v79
	v_mul_f32_e32 v80, 0xbfb8aa3b, v80
	v_mul_f32_e32 v81, 0xbfb8aa3b, v81
	v_mul_f32_e32 v62, 0xbfb8aa3b, v62
	v_mul_f32_e32 v63, 0xbfb8aa3b, v63
	v_mul_f32_e32 v64, 0xbfb8aa3b, v64
	v_mul_f32_e32 v65, 0xbfb8aa3b, v65
	v_mul_f32_e32 v46, 0xbfb8aa3b, v46
	v_mul_f32_e32 v47, 0xbfb8aa3b, v47
	v_mul_f32_e32 v48, 0xbfb8aa3b, v48
	v_mul_f32_e32 v49, 0xbfb8aa3b, v49
	v_rcp_f32_e32 v34, v34
	v_rcp_f32_e32 v35, v35
	v_add_f32_e32 v36, 1.0, v36
	v_add_f32_e32 v37, 1.0, v37
	v_mul_f32_e32 v30, 0xbfb8aa3b, v30
	v_mul_f32_e32 v31, 0xbfb8aa3b, v31
	v_mul_f32_e32 v32, 0xbfb8aa3b, v32
	v_mul_f32_e32 v33, 0xbfb8aa3b, v33
	v_mul_f32_e32 v14, 0xbfb8aa3b, v14
	v_mul_f32_e32 v15, 0xbfb8aa3b, v15
	v_mul_f32_e32 v16, 0xbfb8aa3b, v16
	v_mul_f32_e32 v17, 0xbfb8aa3b, v17
	v_exp_f32_e32 v4, v4
	v_exp_f32_e32 v5, v5
	v_exp_f32_e32 v126, v126
	v_exp_f32_e32 v127, v127
	v_exp_f32_e32 v128, v128
	v_exp_f32_e32 v129, v129
	v_cvt_pk_bf16_f32 v119, v120, v121
	v_lshl_add_u64 v[114:115], s[16:17], 0, v[114:115]
	v_lshlrev_b64 v[120:121], 1, v[144:145]
	v_exp_f32_e32 v110, v110
	v_exp_f32_e32 v111, v111
	v_exp_f32_e32 v112, v112
	v_exp_f32_e32 v113, v113
	v_add_f32_e32 v98, 1.0, v98
	v_add_f32_e32 v99, 1.0, v99
	v_exp_f32_e32 v94, v94
	v_exp_f32_e32 v95, v95
	v_exp_f32_e32 v96, v96
	v_exp_f32_e32 v97, v97
	v_add_f32_e32 v82, 1.0, v82
	v_add_f32_e32 v83, 1.0, v83
	v_exp_f32_e32 v78, v78
	v_exp_f32_e32 v79, v79
	v_exp_f32_e32 v80, v80
	v_exp_f32_e32 v81, v81
	v_add_f32_e32 v66, 1.0, v66
	v_add_f32_e32 v67, 1.0, v67
	v_exp_f32_e32 v62, v62
	v_exp_f32_e32 v63, v63
	v_exp_f32_e32 v64, v64
	v_exp_f32_e32 v65, v65
	v_exp_f32_e32 v46, v46
	v_exp_f32_e32 v47, v47
	v_exp_f32_e32 v48, v48
	v_exp_f32_e32 v49, v49
	v_rcp_f32_e32 v36, v36
	v_rcp_f32_e32 v37, v37
	v_exp_f32_e32 v30, v30
	v_exp_f32_e32 v31, v31
	v_exp_f32_e32 v32, v32
	v_exp_f32_e32 v33, v33
	v_add_f32_e32 v18, 1.0, v18
	v_add_f32_e32 v19, 1.0, v19
	v_exp_f32_e32 v14, v14
	v_exp_f32_e32 v15, v15
	v_exp_f32_e32 v16, v16
	v_exp_f32_e32 v17, v17
	v_lshl_add_u64 v[114:115], v[114:115], 0, v[120:121]
	v_rcp_f32_e32 v98, v98
	v_rcp_f32_e32 v99, v99
	v_add_f32_e32 v100, 1.0, v100
	v_add_f32_e32 v101, 1.0, v101
	v_rcp_f32_e32 v82, v82
	v_rcp_f32_e32 v83, v83
	v_add_f32_e32 v84, 1.0, v84
	v_add_f32_e32 v85, 1.0, v85
; __device__ __forceinline__ unsigned pk2(float lo, float hi) { const f32x2 v = {lo, hi}; return __builtin_bit_cast(unsigned, __builtin_convertvector(v, bf16x2_t)); }
; __device__ __forceinline__ float sigmoidf_(float x) { return __builtin_amdgcn_rcpf(1.0f + __expf(-x)); }
; #define PG8_BAR __builtin_amdgcn_s_barrier()
; template <class Epi, class Sched, bool ABLK = false, bool ALIGN_EPI = true, bool SP2 = true, bool BBLK = true>
; __device__ __forceinline__ void gemm_phase(LAS unsigned char* lds, const Gemm g, const Sched& S, const Epi& E) {
;     ...
;         if constexpr (ALIGN_EPI) { if (wr == 0) PG8_BAR; }
;         E(acc, cur, wr, wc, fr, fq); S.done(cur);
;         if (!has_next) break;
;     __device__ __forceinline__ void operator()(const f32x4 (&acc)[2][2][4][2], const Unit& u, int wr, int wc, int fr, int fq) const {
;         const int row0 = u.pm * 256 + wr * 64 + fr, ch0 = u.pn * 128 + wc * 32 + 8 * fq;
; #pragma unroll
;         for (int ai = 0; ai < 2; ++ai)
; #pragma unroll
;             for (int m = 0; m < 4; ++m) { f32x4 z[2];
; #pragma unroll
;                 for (int n = 0; n < 2; ++n) { const f32x4 o = acc[ai][0][m][n], gt = acc[ai][1][m][n];
; #pragma unroll
;                     for (int j = 0; j < 4; ++j) z[n][j] = o[j] * sigmoidf_(gt[j]); }
;                 u32x4 w; w.x = pk2(z[0][0], z[0][1]); w.y = pk2(z[0][2], z[0][3]); w.z = pk2(z[1][0], z[1][1]); w.w = pk2(z[1][2], z[1][3]);
;                 *(u32x4*)(Z + (size_t)(row0 + ai * 128 + m * 16) * D + ch0) = w; }
	v_rcp_f32_e32 v66, v66
	v_rcp_f32_e32 v67, v67
	v_add_f32_e32 v68, 1.0, v68
	v_add_f32_e32 v69, 1.0, v69
	v_pk_mul_f32 v[54:55], v[54:55], v[50:51]
	v_rcp_f32_e32 v18, v18
	v_rcp_f32_e32 v19, v19
	v_add_f32_e32 v20, 1.0, v20
	v_add_f32_e32 v21, 1.0, v21
	v_rcp_f32_e32 v100, v100
	v_rcp_f32_e32 v101, v101
	v_rcp_f32_e32 v84, v84
	v_rcp_f32_e32 v85, v85
	v_rcp_f32_e32 v68, v68
	v_rcp_f32_e32 v69, v69
	v_pk_mul_f32 v[56:57], v[56:57], v[52:53]
	v_cvt_pk_bf16_f32 v52, v54, v55
	v_add_co_u32_e32 v54, vcc, s46, v114
	v_rcp_f32_e32 v20, v20
	v_rcp_f32_e32 v21, v21
	v_add_f32_e32 v2, 1.0, v2
	v_add_f32_e32 v3, 1.0, v3
	v_addc_co_u32_e32 v55, vcc, 0, v115, vcc
	v_pk_mul_f32 v[38:39], v[38:39], v[34:35]
	v_rcp_f32_e32 v2, v2
	v_rcp_f32_e32 v3, v3
	v_add_f32_e32 v4, 1.0, v4
	v_add_f32_e32 v5, 1.0, v5
	v_add_f32_e32 v126, 1.0, v126
	v_add_f32_e32 v127, 1.0, v127
	v_add_f32_e32 v128, 1.0, v128
	v_add_f32_e32 v129, 1.0, v129
	v_add_f32_e32 v110, 1.0, v110
	v_add_f32_e32 v111, 1.0, v111
	v_add_f32_e32 v112, 1.0, v112
	v_add_f32_e32 v113, 1.0, v113
	v_add_f32_e32 v94, 1.0, v94
	v_add_f32_e32 v95, 1.0, v95
	v_add_f32_e32 v96, 1.0, v96
	v_add_f32_e32 v97, 1.0, v97
	v_add_f32_e32 v78, 1.0, v78
	v_add_f32_e32 v79, 1.0, v79
	v_add_f32_e32 v80, 1.0, v80
	v_add_f32_e32 v81, 1.0, v81
	v_add_f32_e32 v62, 1.0, v62
	v_add_f32_e32 v63, 1.0, v63
	v_add_f32_e32 v64, 1.0, v64
	v_add_f32_e32 v65, 1.0, v65
	v_add_f32_e32 v46, 1.0, v46
	v_add_f32_e32 v47, 1.0, v47
	v_add_f32_e32 v48, 1.0, v48
	v_add_f32_e32 v49, 1.0, v49
	v_pk_mul_f32 v[40:41], v[40:41], v[36:37]
	v_cvt_pk_bf16_f32 v36, v38, v39
	v_add_co_u32_e32 v38, vcc, s47, v114
	v_add_f32_e32 v30, 1.0, v30
	v_add_f32_e32 v31, 1.0, v31
	v_add_f32_e32 v32, 1.0, v32
	v_add_f32_e32 v33, 1.0, v33
	v_add_f32_e32 v14, 1.0, v14
	v_add_f32_e32 v15, 1.0, v15
	v_add_f32_e32 v16, 1.0, v16
	v_add_f32_e32 v17, 1.0, v17
	v_rcp_f32_e32 v4, v4
	v_rcp_f32_e32 v5, v5
	v_rcp_f32_e32 v126, v126
	v_rcp_f32_e32 v127, v127
	v_rcp_f32_e32 v128, v128
	v_rcp_f32_e32 v129, v129
	v_rcp_f32_e32 v110, v110
	v_rcp_f32_e32 v111, v111
	v_rcp_f32_e32 v112, v112
	v_rcp_f32_e32 v113, v113
	v_pk_mul_f32 v[102:103], v[102:103], v[98:99]
	v_rcp_f32_e32 v94, v94
	v_rcp_f32_e32 v95, v95
	v_rcp_f32_e32 v96, v96
	v_rcp_f32_e32 v97, v97
	v_pk_mul_f32 v[86:87], v[86:87], v[82:83]
	v_rcp_f32_e32 v78, v78
	v_rcp_f32_e32 v79, v79
	v_rcp_f32_e32 v80, v80
	v_rcp_f32_e32 v81, v81
	v_pk_mul_f32 v[70:71], v[70:71], v[66:67]
	v_rcp_f32_e32 v62, v62
	v_rcp_f32_e32 v63, v63
	v_rcp_f32_e32 v64, v64
	v_rcp_f32_e32 v65, v65
	v_rcp_f32_e32 v46, v46
	v_rcp_f32_e32 v47, v47
	v_rcp_f32_e32 v48, v48
	v_rcp_f32_e32 v49, v49
	v_addc_co_u32_e32 v39, vcc, 0, v115, vcc
	v_rcp_f32_e32 v30, v30
	v_rcp_f32_e32 v31, v31
	v_rcp_f32_e32 v32, v32
	v_rcp_f32_e32 v33, v33
	v_pk_mul_f32 v[22:23], v[22:23], v[18:19]
	v_rcp_f32_e32 v14, v14
	v_rcp_f32_e32 v15, v15
	v_rcp_f32_e32 v16, v16
	v_rcp_f32_e32 v17, v17
	v_pk_mul_f32 v[104:105], v[104:105], v[100:101]
	v_cvt_pk_bf16_f32 v100, v102, v103
	v_or_b32_e32 v102, 16, v142
	v_pk_mul_f32 v[88:89], v[88:89], v[84:85]
	v_cvt_pk_bf16_f32 v84, v86, v87
	v_or_b32_e32 v86, 32, v142
	v_pk_mul_f32 v[72:73], v[72:73], v[68:69]
	v_cvt_pk_bf16_f32 v68, v70, v71
	v_or_b32_e32 v70, 48, v142
	v_pk_mul_f32 v[24:25], v[24:25], v[20:21]
	v_cvt_pk_bf16_f32 v20, v22, v23
	v_add_co_u32_e32 v22, vcc, s48, v114
	v_ashrrev_i32_e32 v103, 31, v102
	v_ashrrev_i32_e32 v87, 31, v86
	v_ashrrev_i32_e32 v71, 31, v70
	v_addc_co_u32_e32 v23, vcc, 0, v115, vcc
	v_pk_mul_f32 v[6:7], v[6:7], v[2:3]
	v_lshlrev_b64 v[102:103], 12, v[102:103]
	v_lshlrev_b64 v[86:87], 12, v[86:87]
	v_lshlrev_b64 v[70:71], 12, v[70:71]
	v_pk_mul_f32 v[8:9], v[8:9], v[4:5]
	v_cvt_pk_bf16_f32 v4, v6, v7
	v_add_co_u32_e32 v6, vcc, 0xb0000, v114
	v_pk_mul_f32 v[122:123], v[122:123], v[126:127]
	v_pk_mul_f32 v[124:125], v[124:125], v[128:129]
	v_pk_mul_f32 v[106:107], v[106:107], v[110:111]
	v_pk_mul_f32 v[108:109], v[108:109], v[112:113]
	v_lshl_add_u64 v[102:103], s[16:17], 0, v[102:103]
	v_pk_mul_f32 v[90:91], v[90:91], v[94:95]
	v_pk_mul_f32 v[92:93], v[92:93], v[96:97]
	v_lshl_add_u64 v[86:87], s[16:17], 0, v[86:87]
	v_pk_mul_f32 v[74:75], v[74:75], v[78:79]
	v_pk_mul_f32 v[76:77], v[76:77], v[80:81]
	v_lshl_add_u64 v[70:71], s[16:17], 0, v[70:71]
	v_pk_mul_f32 v[58:59], v[58:59], v[62:63]
	v_pk_mul_f32 v[60:61], v[60:61], v[64:65]
	v_pk_mul_f32 v[42:43], v[42:43], v[46:47]
	v_pk_mul_f32 v[44:45], v[44:45], v[48:49]
	v_pk_mul_f32 v[26:27], v[26:27], v[30:31]
	v_pk_mul_f32 v[28:29], v[28:29], v[32:33]
	v_pk_mul_f32 v[10:11], v[10:11], v[14:15]
	v_pk_mul_f32 v[12:13], v[12:13], v[16:17]
	v_addc_co_u32_e32 v7, vcc, 0, v115, vcc
	v_cvt_pk_bf16_f32 v116, v122, v123
	v_cvt_pk_bf16_f32 v117, v124, v125
	v_cvt_pk_bf16_f32 v98, v106, v107
	v_cvt_pk_bf16_f32 v99, v108, v109
	v_cvt_pk_bf16_f32 v101, v104, v105
	v_lshl_add_u64 v[102:103], v[102:103], 0, v[120:121]
	v_cvt_pk_bf16_f32 v82, v90, v91
	v_cvt_pk_bf16_f32 v83, v92, v93
	v_cvt_pk_bf16_f32 v85, v88, v89
	v_lshl_add_u64 v[86:87], v[86:87], 0, v[120:121]
	v_cvt_pk_bf16_f32 v66, v74, v75
	v_cvt_pk_bf16_f32 v67, v76, v77
	v_cvt_pk_bf16_f32 v69, v72, v73
	v_lshl_add_u64 v[70:71], v[70:71], 0, v[120:121]
	v_cvt_pk_bf16_f32 v50, v58, v59
	v_cvt_pk_bf16_f32 v51, v60, v61
	v_cvt_pk_bf16_f32 v53, v56, v57
	v_cvt_pk_bf16_f32 v34, v42, v43
	v_cvt_pk_bf16_f32 v35, v44, v45
	v_cvt_pk_bf16_f32 v37, v40, v41
	v_cvt_pk_bf16_f32 v18, v26, v27
	v_cvt_pk_bf16_f32 v19, v28, v29
	v_cvt_pk_bf16_f32 v21, v24, v25
	v_cvt_pk_bf16_f32 v2, v10, v11
	v_cvt_pk_bf16_f32 v3, v12, v13
	v_cvt_pk_bf16_f32 v5, v8, v9
	s_and_b64 vcc, exec, s[6:7]
	s_cbranch_vccz .LBB0_353
	s_barrier
.LBB0_353:
	s_andn2_b64 vcc, exec, s[14:15]
	s_mov_b64 s[4:5], -1
	global_store_dwordx4 v[114:115], v[116:119], off
	global_store_dwordx4 v[102:103], v[98:101], off
	global_store_dwordx4 v[86:87], v[82:85], off
	global_store_dwordx4 v[70:71], v[66:69], off
	global_store_dwordx4 v[54:55], v[50:53], off
	global_store_dwordx4 v[38:39], v[34:37], off
	global_store_dwordx4 v[22:23], v[18:21], off
	global_store_dwordx4 v[6:7], v[2:5], off
	s_cbranch_vccnz .LBB0_346
	s_andn2_b64 vcc, exec, s[2:3]
	s_cbranch_vccnz .LBB0_345
	s_barrier
	s_branch .LBB0_345

; #define PG8_STAGE(bufoff, gbase, voff) do { _Pragma("unroll") for (int _i = 0; _i < 2; ++_i) \
;         __builtin_amdgcn_global_load_lds((const unsigned*)((const char*)(gbase) + (voff)[_i]), (LAS unsigned*)(lds + (bufoff) + ldsw + _i * 8192), 16, 0, 0); } while (0)
; #define PG8_LDA(dst, b, h) do { _Pragma("unroll") for (int m = 0; m < 4; ++m) _Pragma("unroll") for (int k = 0; k < 2; ++k) dst[m][k] = *(const LAS bf16x8*)(lds + PG8_SA(b, h) + aoff + m * 2048 + k * 1024); } while (0)
; #define PG8_LDB(dst, b, h) do { _Pragma("unroll") for (int n = 0; n < 2; ++n) _Pragma("unroll") for (int k = 0; k < 2; ++k) dst[n][k] = *(const LAS bf16x8*)(lds + PG8_SB(b, h) + boff + n * 2048 + k * 1024); } while (0)
; #define PG8_MMA(ai, bj, At, Bt) do { __builtin_amdgcn_s_setprio(1); _Pragma("unroll") for (int m = 0; m < 4; ++m) _Pragma("unroll") for (int n = 0; n < 2; ++n) _Pragma("unroll") for (int k = 0; k < 2; ++k) \
;         acc[ai][bj][m][n] = __builtin_amdgcn_mfma_f32_16x16x32_bf16(Bt[n][k], At[m][k], acc[ai][bj][m][n], 0, 0, 0); __builtin_amdgcn_s_setprio(0); } while (0)
; #define PG8_WAIT_V(n) asm volatile("s_waitcnt vmcnt(" #n ")" ::: "memory")
; template <class Epi, class Sched, bool ABLK = false, bool ALIGN_EPI = true, bool SP2 = true, bool BBLK = true>
; __device__ __forceinline__ void gemm_phase(LAS unsigned char* lds, const Gemm g, const Sched& S, const Epi& E) {
;     ...
;         for (int t = 0; t < nt; t += 2) {
;             const bool last = (t == nt - 2);
;             const char* a1 = a_tile(uA, tbA + t + 1);
;             const char* a2 = last ? a_tile(nuA, ntbA) : a_tile(uA, tbA + t + 2); const char* b2 = last ? nB : cB + (size_t)(t + 2) * kstepB;
;             const char* a3 = last ? a_tile(nuA, ntbA + 1) : a_tile(uA, tbA + t + 3); const char* b3 = b2 + kstepB;
;             if (last && has_next) S.a_ready(nxt);
;             if constexpr (SP2) {
;             PG8_LDB(B0, 0, 0); PG8_LDB(B1, 0, 1); PG8_SCHED; PG8_LDA(At, 0, 0); PG8_STAGE(PG8_SA(1, 1), a1 + hstepA, voffA);
;             PG8_WAIT_V(8); PG8_WAIT_L(0); PG8_BAR; PG8_MMA(0, 0, At, B0); PG8_MMA(0, 1, At, B1); PG8_BAR; PG8_SCHED;
;             PG8_LDA(At, 0, 1); PG8_STAGE(PG8_SB(0, 0), b2, voffB); PG8_STAGE(PG8_SB(0, 1), b2 + hstepB, voffB); PG8_STAGE(PG8_SA(0, 0), a2, voffA);
;             PG8_WAIT_V(8); PG8_WAIT_L(0); PG8_BAR; PG8_MMA(1, 0, At, B0); PG8_MMA(1, 1, At, B1); PG8_BAR; PG8_SCHED;
.LBB0_475:
	ds_read_b128 v[172:175], v168
	ds_read_b128 v[176:179], v168 offset:1024
	ds_read_b128 v[180:183], v168 offset:2048
	ds_read_b128 v[184:187], v168 offset:3072
	ds_read_b128 v[188:191], v169
	ds_read_b128 v[192:195], v169 offset:1024
	ds_read_b128 v[196:199], v169 offset:2048
	ds_read_b128 v[200:203], v169 offset:3072
	s_add_u32 s30, s26, s28
	s_addc_u32 s31, s27, s29
	s_add_u32 s36, s30, 0x100
	s_addc_u32 s37, s31, 0
	s_add_u32 s30, s30, 0x180
	s_addc_u32 s31, s31, 0
	s_cmpk_eq_i32 s28, 0xf00
	s_cselect_b32 s31, s57, s31
	s_cselect_b32 s30, s23, s30
	s_cselect_b32 s35, s11, s59
	s_cselect_b32 s34, s13, s58
	s_cselect_b32 s37, s4, s37
	s_cselect_b32 s36, s5, s36
	s_mov_b32 m0, s53
	v_lshl_add_u64 v[236:237], v[164:165], 0, s[28:29]
	ds_read_b128 v[204:207], v170
	ds_read_b128 v[208:211], v170 offset:1024
	ds_read_b128 v[212:215], v170 offset:2048
	ds_read_b128 v[216:219], v170 offset:3072
	ds_read_b128 v[220:223], v170 offset:4096
	ds_read_b128 v[224:227], v170 offset:5120
	ds_read_b128 v[228:231], v170 offset:6144
	ds_read_b128 v[232:235], v170 offset:7168
	global_load_lds_dwordx4 v[236:237], off
	v_lshl_add_u64 v[236:237], v[166:167], 0, s[28:29]
	s_mov_b32 m0, s54
	s_nop 0
	global_load_lds_dwordx4 v[236:237], off
	s_waitcnt vmcnt(8) lgkmcnt(0)
	s_barrier
	v_mfma_f32_16x16x32_bf16 v[126:129], v[172:175], v[204:207], v[126:129]
	v_mfma_f32_16x16x32_bf16 v[122:125], v[180:183], v[204:207], v[122:125]
	v_mfma_f32_16x16x32_bf16 v[110:113], v[172:175], v[212:215], v[110:113]
	v_mfma_f32_16x16x32_bf16 v[106:109], v[180:183], v[212:215], v[106:109]
	v_mfma_f32_16x16x32_bf16 v[94:97], v[172:175], v[220:223], v[94:97]
	v_mfma_f32_16x16x32_bf16 v[90:93], v[180:183], v[220:223], v[90:93]
	v_mfma_f32_16x16x32_bf16 v[78:81], v[172:175], v[228:231], v[78:81]
	v_mfma_f32_16x16x32_bf16 v[74:77], v[180:183], v[228:231], v[74:77]
	v_mfma_f32_16x16x32_bf16 v[126:129], v[176:179], v[208:211], v[126:129]
	v_mfma_f32_16x16x32_bf16 v[122:125], v[184:187], v[208:211], v[122:125]
	v_mfma_f32_16x16x32_bf16 v[110:113], v[176:179], v[216:219], v[110:113]
	v_mfma_f32_16x16x32_bf16 v[106:109], v[184:187], v[216:219], v[106:109]
	v_mfma_f32_16x16x32_bf16 v[94:97], v[176:179], v[224:227], v[94:97]
	v_mfma_f32_16x16x32_bf16 v[90:93], v[184:187], v[224:227], v[90:93]
	v_mfma_f32_16x16x32_bf16 v[78:81], v[176:179], v[232:235], v[78:81]
	v_mfma_f32_16x16x32_bf16 v[74:77], v[184:187], v[232:235], v[74:77]
	v_mfma_f32_16x16x32_bf16 v[118:121], v[188:191], v[204:207], v[118:121]
	v_mfma_f32_16x16x32_bf16 v[114:117], v[196:199], v[204:207], v[114:117]
	v_mfma_f32_16x16x32_bf16 v[102:105], v[188:191], v[212:215], v[102:105]
	v_mfma_f32_16x16x32_bf16 v[98:101], v[196:199], v[212:215], v[98:101]
	v_mfma_f32_16x16x32_bf16 v[86:89], v[188:191], v[220:223], v[86:89]
	v_mfma_f32_16x16x32_bf16 v[82:85], v[196:199], v[220:223], v[82:85]
	v_mfma_f32_16x16x32_bf16 v[70:73], v[188:191], v[228:231], v[70:73]
	v_mfma_f32_16x16x32_bf16 v[66:69], v[196:199], v[228:231], v[66:69]
	v_mfma_f32_16x16x32_bf16 v[118:121], v[192:195], v[208:211], v[118:121]
	v_mfma_f32_16x16x32_bf16 v[114:117], v[200:203], v[208:211], v[114:117]
	v_mfma_f32_16x16x32_bf16 v[102:105], v[192:195], v[216:219], v[102:105]
	v_mfma_f32_16x16x32_bf16 v[98:101], v[200:203], v[216:219], v[98:101]
	v_mfma_f32_16x16x32_bf16 v[86:89], v[192:195], v[224:227], v[86:89]
	v_mfma_f32_16x16x32_bf16 v[82:85], v[200:203], v[224:227], v[82:85]
	v_mfma_f32_16x16x32_bf16 v[70:73], v[192:195], v[232:235], v[70:73]
	v_mfma_f32_16x16x32_bf16 v[66:69], v[200:203], v[232:235], v[66:69]
	s_barrier
	s_mov_b32 m0, s55
	s_add_u32 s62, s34, 0x4000
	ds_read_b128 v[204:207], v170 offset:16384
	ds_read_b128 v[208:211], v170 offset:17408
	ds_read_b128 v[212:215], v170 offset:18432
	ds_read_b128 v[216:219], v170 offset:19456
	ds_read_b128 v[220:223], v170 offset:20480
	ds_read_b128 v[224:227], v170 offset:21504
	ds_read_b128 v[228:231], v170 offset:22528
	ds_read_b128 v[232:235], v170 offset:23552
	global_load_lds_dwordx4 v134, s[34:35]
	s_mov_b32 m0, s56
	s_addc_u32 s63, s35, 0
	s_add_i32 s61, s52, s40
	global_load_lds_dwordx4 v130, s[34:35]
	s_mov_b32 m0, s61
	s_nop 0
	global_load_lds_dwordx4 v134, s[62:63]
	s_add_i32 m0, s61, 0x2000
	s_nop 0
	global_load_lds_dwordx4 v130, s[62:63]
	s_mov_b32 m0, s25
	s_nop 0
	global_load_lds_dwordx4 v136, s[36:37]
	s_mov_b32 m0, s43
	s_nop 0
	global_load_lds_dwordx4 v132, s[36:37]
	s_waitcnt vmcnt(8) lgkmcnt(0)
	s_barrier
	v_mfma_f32_16x16x32_bf16 v[62:65], v[172:175], v[204:207], v[62:65]
	v_mfma_f32_16x16x32_bf16 v[58:61], v[180:183], v[204:207], v[58:61]
	v_mfma_f32_16x16x32_bf16 v[46:49], v[172:175], v[212:215], v[46:49]
	v_mfma_f32_16x16x32_bf16 v[42:45], v[180:183], v[212:215], v[42:45]
	v_mfma_f32_16x16x32_bf16 v[30:33], v[172:175], v[220:223], v[30:33]
	v_mfma_f32_16x16x32_bf16 v[26:29], v[180:183], v[220:223], v[26:29]
	v_mfma_f32_16x16x32_bf16 v[14:17], v[172:175], v[228:231], v[14:17]
	v_mfma_f32_16x16x32_bf16 v[10:13], v[180:183], v[228:231], v[10:13]
	v_mfma_f32_16x16x32_bf16 v[62:65], v[176:179], v[208:211], v[62:65]
	v_mfma_f32_16x16x32_bf16 v[58:61], v[184:187], v[208:211], v[58:61]
	v_mfma_f32_16x16x32_bf16 v[46:49], v[176:179], v[216:219], v[46:49]
	v_mfma_f32_16x16x32_bf16 v[42:45], v[184:187], v[216:219], v[42:45]
	v_mfma_f32_16x16x32_bf16 v[30:33], v[176:179], v[224:227], v[30:33]
	v_mfma_f32_16x16x32_bf16 v[26:29], v[184:187], v[224:227], v[26:29]
	v_mfma_f32_16x16x32_bf16 v[14:17], v[176:179], v[232:235], v[14:17]
	v_mfma_f32_16x16x32_bf16 v[10:13], v[184:187], v[232:235], v[10:13]
	v_mfma_f32_16x16x32_bf16 v[54:57], v[188:191], v[204:207], v[54:57]
	v_mfma_f32_16x16x32_bf16 v[50:53], v[196:199], v[204:207], v[50:53]
	v_mfma_f32_16x16x32_bf16 v[38:41], v[188:191], v[212:215], v[38:41]
	v_mfma_f32_16x16x32_bf16 v[34:37], v[196:199], v[212:215], v[34:37]
	v_mfma_f32_16x16x32_bf16 v[22:25], v[188:191], v[220:223], v[22:25]
	v_mfma_f32_16x16x32_bf16 v[18:21], v[196:199], v[220:223], v[18:21]
	v_mfma_f32_16x16x32_bf16 v[6:9], v[188:191], v[228:231], v[6:9]
	v_mfma_f32_16x16x32_bf16 v[2:5], v[196:199], v[228:231], v[2:5]
	v_mfma_f32_16x16x32_bf16 v[54:57], v[192:195], v[208:211], v[54:57]
	v_mfma_f32_16x16x32_bf16 v[50:53], v[200:203], v[208:211], v[50:53]
	v_mfma_f32_16x16x32_bf16 v[38:41], v[192:195], v[216:219], v[38:41]
	v_mfma_f32_16x16x32_bf16 v[34:37], v[200:203], v[216:219], v[34:37]
	v_mfma_f32_16x16x32_bf16 v[22:25], v[192:195], v[224:227], v[22:25]
	v_mfma_f32_16x16x32_bf16 v[18:21], v[200:203], v[224:227], v[18:21]
	v_mfma_f32_16x16x32_bf16 v[6:9], v[192:195], v[232:235], v[6:9]
	v_mfma_f32_16x16x32_bf16 v[2:5], v[200:203], v[232:235], v[2:5]
	s_barrier
; #define PG8_STAGE(bufoff, gbase, voff) do { _Pragma("unroll") for (int _i = 0; _i < 2; ++_i) \
;         __builtin_amdgcn_global_load_lds((const unsigned*)((const char*)(gbase) + (voff)[_i]), (LAS unsigned*)(lds + (bufoff) + ldsw + _i * 8192), 16, 0, 0); } while (0)
; #define PG8_LDA(dst, b, h) do { _Pragma("unroll") for (int m = 0; m < 4; ++m) _Pragma("unroll") for (int k = 0; k < 2; ++k) dst[m][k] = *(const LAS bf16x8*)(lds + PG8_SA(b, h) + aoff + m * 2048 + k * 1024); } while (0)
; #define PG8_LDB(dst, b, h) do { _Pragma("unroll") for (int n = 0; n < 2; ++n) _Pragma("unroll") for (int k = 0; k < 2; ++k) dst[n][k] = *(const LAS bf16x8*)(lds + PG8_SB(b, h) + boff + n * 2048 + k * 1024); } while (0)
; #define PG8_MMA(ai, bj, At, Bt) do { __builtin_amdgcn_s_setprio(1); _Pragma("unroll") for (int m = 0; m < 4; ++m) _Pragma("unroll") for (int n = 0; n < 2; ++n) _Pragma("unroll") for (int k = 0; k < 2; ++k) \
;         acc[ai][bj][m][n] = __builtin_amdgcn_mfma_f32_16x16x32_bf16(Bt[n][k], At[m][k], acc[ai][bj][m][n], 0, 0, 0); __builtin_amdgcn_s_setprio(0); } while (0)
; #define PG8_WAIT_V(n) asm volatile("s_waitcnt vmcnt(" #n ")" ::: "memory")
; #define PG8_WAIT_L(n) asm volatile("s_waitcnt lgkmcnt(" #n ")" ::: "memory")
; #define PG8_BAR __builtin_amdgcn_s_barrier()
; #define PG8_SCHED __builtin_amdgcn_sched_barrier(0)
; template <class Epi, class Sched, bool ABLK = false, bool ALIGN_EPI = true, bool SP2 = true, bool BBLK = true>
; __device__ __forceinline__ void gemm_phase(LAS unsigned char* lds, const Gemm g, const Sched& S, const Epi& E) {
;     ...
;             PG8_WAIT_V(8); PG8_WAIT_L(0); PG8_BAR; PG8_MMA(1, 0, At, B0); PG8_MMA(1, 1, At, B1); PG8_BAR; PG8_SCHED;
;             PG8_LDB(B0, 1, 0); PG8_LDB(B1, 1, 1); PG8_SCHED; PG8_LDA(At, 1, 0); PG8_STAGE(PG8_SA(0, 1), a2 + hstepA, voffA);
;             PG8_WAIT_V(8); PG8_WAIT_L(0); PG8_BAR; PG8_MMA(0, 0, At, B0); PG8_MMA(0, 1, At, B1); PG8_BAR; PG8_SCHED;
;             PG8_LDA(At, 1, 1); PG8_STAGE(PG8_SB(1, 0), b3, voffB); PG8_STAGE(PG8_SB(1, 1), b3 + hstepB, voffB); PG8_STAGE(PG8_SA(1, 0), a3, voffA);
	s_add_i32 s61, 0, 0x18000
	v_add_u32_e32 v171, s61, v1
	s_add_i32 s62, 0, 0x1c000
	ds_read_b128 v[172:175], v171
	ds_read_b128 v[176:179], v171 offset:1024
	ds_read_b128 v[180:183], v171 offset:2048
	ds_read_b128 v[184:187], v171 offset:3072
	v_add_u32_e32 v171, s62, v1
	ds_read_b128 v[188:191], v171
	ds_read_b128 v[192:195], v171 offset:1024
	ds_read_b128 v[196:199], v171 offset:2048
	ds_read_b128 v[200:203], v171 offset:3072
	s_add_u32 s36, s36, 0x80000
	s_addc_u32 s37, s37, 0
	s_mov_b32 m0, s46
	ds_read_b128 v[204:207], v170 offset:32768
	ds_read_b128 v[208:211], v170 offset:33792
	ds_read_b128 v[212:215], v170 offset:34816
	ds_read_b128 v[216:219], v170 offset:35840
	ds_read_b128 v[220:223], v170 offset:36864
	ds_read_b128 v[224:227], v170 offset:37888
	ds_read_b128 v[228:231], v170 offset:38912
	ds_read_b128 v[232:235], v170 offset:39936
	global_load_lds_dwordx4 v136, s[36:37]
	s_mov_b32 m0, s47
	s_nop 0
	global_load_lds_dwordx4 v132, s[36:37]
	s_waitcnt vmcnt(8) lgkmcnt(0)
	s_barrier
	v_mfma_f32_16x16x32_bf16 v[126:129], v[172:175], v[204:207], v[126:129]
	v_mfma_f32_16x16x32_bf16 v[122:125], v[180:183], v[204:207], v[122:125]
	v_mfma_f32_16x16x32_bf16 v[110:113], v[172:175], v[212:215], v[110:113]
	v_mfma_f32_16x16x32_bf16 v[106:109], v[180:183], v[212:215], v[106:109]
	v_mfma_f32_16x16x32_bf16 v[94:97], v[172:175], v[220:223], v[94:97]
	v_mfma_f32_16x16x32_bf16 v[90:93], v[180:183], v[220:223], v[90:93]
	v_mfma_f32_16x16x32_bf16 v[78:81], v[172:175], v[228:231], v[78:81]
	v_mfma_f32_16x16x32_bf16 v[74:77], v[180:183], v[228:231], v[74:77]
	v_mfma_f32_16x16x32_bf16 v[126:129], v[176:179], v[208:211], v[126:129]
	v_mfma_f32_16x16x32_bf16 v[122:125], v[184:187], v[208:211], v[122:125]
	v_mfma_f32_16x16x32_bf16 v[110:113], v[176:179], v[216:219], v[110:113]
	v_mfma_f32_16x16x32_bf16 v[106:109], v[184:187], v[216:219], v[106:109]
	v_mfma_f32_16x16x32_bf16 v[94:97], v[176:179], v[224:227], v[94:97]
	v_mfma_f32_16x16x32_bf16 v[90:93], v[184:187], v[224:227], v[90:93]
	v_mfma_f32_16x16x32_bf16 v[78:81], v[176:179], v[232:235], v[78:81]
	v_mfma_f32_16x16x32_bf16 v[74:77], v[184:187], v[232:235], v[74:77]
	v_mfma_f32_16x16x32_bf16 v[118:121], v[188:191], v[204:207], v[118:121]
	v_mfma_f32_16x16x32_bf16 v[114:117], v[196:199], v[204:207], v[114:117]
	v_mfma_f32_16x16x32_bf16 v[102:105], v[188:191], v[212:215], v[102:105]
	v_mfma_f32_16x16x32_bf16 v[98:101], v[196:199], v[212:215], v[98:101]
	v_mfma_f32_16x16x32_bf16 v[86:89], v[188:191], v[220:223], v[86:89]
	v_mfma_f32_16x16x32_bf16 v[82:85], v[196:199], v[220:223], v[82:85]
	v_mfma_f32_16x16x32_bf16 v[70:73], v[188:191], v[228:231], v[70:73]
	v_mfma_f32_16x16x32_bf16 v[66:69], v[196:199], v[228:231], v[66:69]
	v_mfma_f32_16x16x32_bf16 v[118:121], v[192:195], v[208:211], v[118:121]
	v_mfma_f32_16x16x32_bf16 v[114:117], v[200:203], v[208:211], v[114:117]
	v_mfma_f32_16x16x32_bf16 v[102:105], v[192:195], v[216:219], v[102:105]
	v_mfma_f32_16x16x32_bf16 v[98:101], v[200:203], v[216:219], v[98:101]
	v_mfma_f32_16x16x32_bf16 v[86:89], v[192:195], v[224:227], v[86:89]
	v_mfma_f32_16x16x32_bf16 v[82:85], v[200:203], v[224:227], v[82:85]
	v_mfma_f32_16x16x32_bf16 v[70:73], v[192:195], v[232:235], v[70:73]
	v_mfma_f32_16x16x32_bf16 v[66:69], v[200:203], v[232:235], v[66:69]
	s_barrier
	s_add_u32 s36, s34, 0x8000
	s_addc_u32 s37, s35, 0
	s_add_i32 s61, s61, s40
	s_mov_b32 m0, s61
	ds_read_b128 v[204:207], v170 offset:49152
	ds_read_b128 v[208:211], v170 offset:50176
	ds_read_b128 v[212:215], v170 offset:51200
	ds_read_b128 v[216:219], v170 offset:52224
	ds_read_b128 v[220:223], v170 offset:53248
	ds_read_b128 v[224:227], v170 offset:54272
	ds_read_b128 v[228:231], v170 offset:55296
	ds_read_b128 v[232:235], v170 offset:56320
	global_load_lds_dwordx4 v134, s[36:37]
	s_add_i32 m0, s61, 0x2000
	s_add_u32 s34, s34, 0xc000
	v_lshl_add_u64 v[236:237], s[36:37], 0, v[130:131]
	s_addc_u32 s35, s35, 0
	s_add_i32 s36, s62, s40
	global_load_lds_dwordx4 v[236:237], off
	s_mov_b32 m0, s36
	s_nop 0
	global_load_lds_dwordx4 v134, s[34:35]
	s_add_i32 m0, s36, 0x2000
	s_nop 0
	global_load_lds_dwordx4 v130, s[34:35]
	s_mov_b32 m0, s50
	s_nop 0
	global_load_lds_dwordx4 v136, s[30:31]
	s_mov_b32 m0, s51
	s_nop 0
	global_load_lds_dwordx4 v132, s[30:31]
	s_waitcnt vmcnt(8) lgkmcnt(0)
	s_barrier
	v_mfma_f32_16x16x32_bf16 v[62:65], v[172:175], v[204:207], v[62:65]
	v_mfma_f32_16x16x32_bf16 v[58:61], v[180:183], v[204:207], v[58:61]
	v_mfma_f32_16x16x32_bf16 v[46:49], v[172:175], v[212:215], v[46:49]
	v_mfma_f32_16x16x32_bf16 v[42:45], v[180:183], v[212:215], v[42:45]
	v_mfma_f32_16x16x32_bf16 v[30:33], v[172:175], v[220:223], v[30:33]
	v_mfma_f32_16x16x32_bf16 v[26:29], v[180:183], v[220:223], v[26:29]
	v_mfma_f32_16x16x32_bf16 v[14:17], v[172:175], v[228:231], v[14:17]
	v_mfma_f32_16x16x32_bf16 v[10:13], v[180:183], v[228:231], v[10:13]
	v_mfma_f32_16x16x32_bf16 v[62:65], v[176:179], v[208:211], v[62:65]
	v_mfma_f32_16x16x32_bf16 v[58:61], v[184:187], v[208:211], v[58:61]
	v_mfma_f32_16x16x32_bf16 v[46:49], v[176:179], v[216:219], v[46:49]
	v_mfma_f32_16x16x32_bf16 v[42:45], v[184:187], v[216:219], v[42:45]
	v_mfma_f32_16x16x32_bf16 v[30:33], v[176:179], v[224:227], v[30:33]
	v_mfma_f32_16x16x32_bf16 v[26:29], v[184:187], v[224:227], v[26:29]
	v_mfma_f32_16x16x32_bf16 v[14:17], v[176:179], v[232:235], v[14:17]
	v_mfma_f32_16x16x32_bf16 v[10:13], v[184:187], v[232:235], v[10:13]
	v_mfma_f32_16x16x32_bf16 v[54:57], v[188:191], v[204:207], v[54:57]
	v_mfma_f32_16x16x32_bf16 v[50:53], v[196:199], v[204:207], v[50:53]
	v_mfma_f32_16x16x32_bf16 v[38:41], v[188:191], v[212:215], v[38:41]
	v_mfma_f32_16x16x32_bf16 v[34:37], v[196:199], v[212:215], v[34:37]
	v_mfma_f32_16x16x32_bf16 v[22:25], v[188:191], v[220:223], v[22:25]
	v_mfma_f32_16x16x32_bf16 v[18:21], v[196:199], v[220:223], v[18:21]
	v_mfma_f32_16x16x32_bf16 v[6:9], v[188:191], v[228:231], v[6:9]
	v_mfma_f32_16x16x32_bf16 v[2:5], v[196:199], v[228:231], v[2:5]
	v_mfma_f32_16x16x32_bf16 v[54:57], v[192:195], v[208:211], v[54:57]
	v_mfma_f32_16x16x32_bf16 v[50:53], v[200:203], v[208:211], v[50:53]
	v_mfma_f32_16x16x32_bf16 v[38:41], v[192:195], v[216:219], v[38:41]
	v_mfma_f32_16x16x32_bf16 v[34:37], v[200:203], v[216:219], v[34:37]
	v_mfma_f32_16x16x32_bf16 v[22:25], v[192:195], v[224:227], v[22:25]
	v_mfma_f32_16x16x32_bf16 v[18:21], v[200:203], v[224:227], v[18:21]
	v_mfma_f32_16x16x32_bf16 v[6:9], v[192:195], v[232:235], v[6:9]
	v_mfma_f32_16x16x32_bf16 v[2:5], v[200:203], v[232:235], v[2:5]
	s_barrier
; __device__ __forceinline__ unsigned pk2(float lo, float hi) { const f32x2 v = {lo, hi}; return __builtin_bit_cast(unsigned, __builtin_convertvector(v, bf16x2_t)); }
; __device__ __forceinline__ u32x4 ror8(u32x4 v) { u32x4 r;
; #pragma unroll
;     for (int i = 0; i < 4; ++i) r[i] = (unsigned)__builtin_amdgcn_mov_dpp((int)v[i], 0x128, 0xf, 0xf, true);
;     return r; }
; __device__ __forceinline__ void store_pair(unsigned char* own, size_t stride8, int hi_off, u32x4 lo, u32x4 hi, bool upper) {
;     const u32x4 tlo = ror8(lo), thi = ror8(hi);
;     const u32x4 A = upper ? thi : lo, B = upper ? hi : tlo;
;     unsigned char* pa = upper ? own - stride8 + hi_off : own;
;     unsigned char* pb = upper ? own + hi_off : own + stride8;
;     *(u32x4*)pa = A; *(u32x4*)pb = B;
;     __device__ __forceinline__ void operator()(const f32x4 (&acc)[2][2][4][2], const Unit& u, int wr, int wc, int fr, int fq) const {
; #pragma unroll
;         for (int ai = 0; ai < 2; ++ai)
; #pragma unroll
;             for (int m = 0; m < 4; ++m) { unsigned char* rowp = (unsigned char*)(H + ((size_t)(u.pm * (FF / 64) + u.pn * 4 + wc) * 256 + (wr * 64 + fr + ai * 128 + m * 16)) * 64 + 8 * fq); u32x4 w[2];
; #pragma unroll
;                 for (int bj = 0; bj < 2; ++bj) { f32x4 v0 = acc[ai][bj][m][0], v1 = acc[ai][bj][m][1];
; #pragma unroll
;                     for (int j = 0; j < 4; ++j) { const float a = fmaxf(v0[j], 0.f), b = fmaxf(v1[j], 0.f); v0[j] = a * a; v1[j] = b * b; }
;                     w[bj].x = pk2(v0[0], v0[1]); w[bj].y = pk2(v0[2], v0[3]); w[bj].z = pk2(v1[0], v1[1]); w[bj].w = pk2(v1[2], v1[3]); }
;                 store_pair(rowp, (size_t)8 * 64 * 2, 64, w[0], w[1], fr >= 8); }
	s_add_i32 s60, s60, 2
	s_add_u32 s28, s28, 0x100
	s_addc_u32 s29, s29, 0
	s_add_u32 s58, s58, 0x10000
	s_addc_u32 s59, s59, 0
	s_cmp_gt_u32 s60, 29
	s_cbranch_scc0 .LBB0_475
	s_lshl_b32 s4, s22, 7
	s_lshl_b32 s5, s24, 2
	s_add_i32 s5, s5, s4
	s_or_b32 s4, s5, s49
	s_ashr_i32 s5, s4, 31
	s_lshl_b64 s[4:5], s[4:5], 15
	s_add_u32 s22, s1, s4
	v_max_f32_e32 v126, 0, v126
	v_max_f32_e32 v122, 0, v122
	v_max_f32_e32 v127, 0, v127
	v_max_f32_e32 v123, 0, v123
	v_max_f32_e32 v128, 0, v128
	v_max_f32_e32 v124, 0, v124
	v_max_f32_e32 v129, 0, v129
	v_max_f32_e32 v125, 0, v125
	v_max_f32_e32 v118, 0, v118
	v_max_f32_e32 v114, 0, v114
	v_max_f32_e32 v119, 0, v119
	v_max_f32_e32 v115, 0, v115
	v_max_f32_e32 v120, 0, v120
	v_max_f32_e32 v116, 0, v116
	v_max_f32_e32 v121, 0, v121
	v_max_f32_e32 v117, 0, v117
	s_addc_u32 s23, s33, s5
	v_pk_mul_f32 v[126:127], v[126:127], v[126:127]
	v_pk_mul_f32 v[122:123], v[122:123], v[122:123]
	v_pk_mul_f32 v[128:129], v[128:129], v[128:129]
	v_pk_mul_f32 v[124:125], v[124:125], v[124:125]
	v_pk_mul_f32 v[118:119], v[118:119], v[118:119]
	v_pk_mul_f32 v[114:115], v[114:115], v[114:115]
	v_pk_mul_f32 v[120:121], v[120:121], v[120:121]
	v_pk_mul_f32 v[116:117], v[116:117], v[116:117]
	v_lshl_add_u64 v[164:165], s[22:23], 0, v[144:145]
	v_cvt_pk_bf16_f32 v126, v126, v127
	v_cvt_pk_bf16_f32 v127, v128, v129
	v_cvt_pk_bf16_f32 v128, v122, v123
	v_cvt_pk_bf16_f32 v129, v124, v125
	v_cvt_pk_bf16_f32 v118, v118, v119
	v_cvt_pk_bf16_f32 v119, v120, v121
	v_cvt_pk_bf16_f32 v114, v114, v115
	v_cvt_pk_bf16_f32 v115, v116, v117
	v_lshl_add_u64 v[122:123], v[164:165], 0, v[138:139]
	v_mov_b32_dpp v120, v126 row_ror:8 row_mask:0xf bank_mask:0xf bound_ctrl:1
	v_mov_b32_dpp v121, v127 row_ror:8 row_mask:0xf bank_mask:0xf bound_ctrl:1
	v_mov_b32_dpp v116, v128 row_ror:8 row_mask:0xf bank_mask:0xf bound_ctrl:1
	v_mov_b32_dpp v117, v129 row_ror:8 row_mask:0xf bank_mask:0xf bound_ctrl:1
	v_mov_b32_dpp v164, v118 row_ror:8 row_mask:0xf bank_mask:0xf bound_ctrl:1
	v_mov_b32_dpp v165, v119 row_ror:8 row_mask:0xf bank_mask:0xf bound_ctrl:1
	v_mov_b32_dpp v166, v114 row_ror:8 row_mask:0xf bank_mask:0xf bound_ctrl:1
	v_mov_b32_dpp v167, v115 row_ror:8 row_mask:0xf bank_mask:0xf bound_ctrl:1
	v_max_f32_e32 v110, 0, v110
	v_max_f32_e32 v106, 0, v106
	v_max_f32_e32 v111, 0, v111
	v_max_f32_e32 v107, 0, v107
	v_max_f32_e32 v112, 0, v112
	v_max_f32_e32 v108, 0, v108
	v_max_f32_e32 v113, 0, v113
	v_max_f32_e32 v109, 0, v109
	v_max_f32_e32 v102, 0, v102
	v_max_f32_e32 v98, 0, v98
	v_max_f32_e32 v103, 0, v103
	v_max_f32_e32 v99, 0, v99
	v_max_f32_e32 v104, 0, v104
	v_max_f32_e32 v100, 0, v100
	v_max_f32_e32 v105, 0, v105
	v_max_f32_e32 v101, 0, v101
	v_lshl_add_u64 v[124:125], v[122:123], 0, v[140:141]
	v_cndmask_b32_e64 v117, v117, v115, s[6:7]
	v_cndmask_b32_e64 v116, v116, v114, s[6:7]
	v_cndmask_b32_e64 v115, v121, v119, s[6:7]
	v_cndmask_b32_e64 v114, v120, v118, s[6:7]
	v_cndmask_b32_e64 v121, v129, v167, s[6:7]
	v_cndmask_b32_e64 v120, v128, v166, s[6:7]
	v_cndmask_b32_e64 v119, v127, v165, s[6:7]
	v_cndmask_b32_e64 v118, v126, v164, s[6:7]
	v_pk_mul_f32 v[110:111], v[110:111], v[110:111]
	v_pk_mul_f32 v[106:107], v[106:107], v[106:107]
	v_pk_mul_f32 v[112:113], v[112:113], v[112:113]
	v_pk_mul_f32 v[108:109], v[108:109], v[108:109]
	v_pk_mul_f32 v[102:103], v[102:103], v[102:103]
	v_pk_mul_f32 v[98:99], v[98:99], v[98:99]
	v_pk_mul_f32 v[104:105], v[104:105], v[104:105]
	v_pk_mul_f32 v[100:101], v[100:101], v[100:101]
	v_lshl_add_u64 v[122:123], v[122:123], 0, v[142:143]
	global_store_dwordx4 v[124:125], v[118:121], off
	global_store_dwordx4 v[122:123], v[114:117], off
	v_cvt_pk_bf16_f32 v110, v110, v111
	v_cvt_pk_bf16_f32 v111, v112, v113
	v_lshl_add_u64 v[114:115], s[22:23], 0, v[146:147]
	v_cvt_pk_bf16_f32 v112, v106, v107
	v_cvt_pk_bf16_f32 v113, v108, v109
	v_cvt_pk_bf16_f32 v102, v102, v103
	v_cvt_pk_bf16_f32 v103, v104, v105
	v_cvt_pk_bf16_f32 v98, v98, v99
	v_cvt_pk_bf16_f32 v99, v100, v101
	v_lshl_add_u64 v[106:107], v[114:115], 0, v[138:139]
	v_mov_b32_dpp v104, v110 row_ror:8 row_mask:0xf bank_mask:0xf bound_ctrl:1
	v_mov_b32_dpp v105, v111 row_ror:8 row_mask:0xf bank_mask:0xf bound_ctrl:1
	v_mov_b32_dpp v100, v112 row_ror:8 row_mask:0xf bank_mask:0xf bound_ctrl:1
	v_mov_b32_dpp v101, v113 row_ror:8 row_mask:0xf bank_mask:0xf bound_ctrl:1
	v_mov_b32_dpp v114, v102 row_ror:8 row_mask:0xf bank_mask:0xf bound_ctrl:1
	v_mov_b32_dpp v115, v103 row_ror:8 row_mask:0xf bank_mask:0xf bound_ctrl:1
	v_mov_b32_dpp v116, v98 row_ror:8 row_mask:0xf bank_mask:0xf bound_ctrl:1
	v_mov_b32_dpp v117, v99 row_ror:8 row_mask:0xf bank_mask:0xf bound_ctrl:1
	v_max_f32_e32 v94, 0, v94
	v_max_f32_e32 v90, 0, v90
	v_max_f32_e32 v95, 0, v95
	v_max_f32_e32 v91, 0, v91
	v_max_f32_e32 v96, 0, v96
	v_max_f32_e32 v92, 0, v92
	v_max_f32_e32 v97, 0, v97
	v_max_f32_e32 v93, 0, v93
	v_max_f32_e32 v86, 0, v86
	v_max_f32_e32 v82, 0, v82
	v_max_f32_e32 v87, 0, v87
	v_max_f32_e32 v83, 0, v83
	v_max_f32_e32 v88, 0, v88
	v_max_f32_e32 v84, 0, v84
	v_max_f32_e32 v89, 0, v89
	v_max_f32_e32 v85, 0, v85
	v_lshl_add_u64 v[108:109], v[106:107], 0, v[140:141]
	v_cndmask_b32_e64 v101, v101, v99, s[6:7]
	v_cndmask_b32_e64 v100, v100, v98, s[6:7]
	v_cndmask_b32_e64 v99, v105, v103, s[6:7]
	v_cndmask_b32_e64 v98, v104, v102, s[6:7]
	v_cndmask_b32_e64 v105, v113, v117, s[6:7]
	v_cndmask_b32_e64 v104, v112, v116, s[6:7]
	v_cndmask_b32_e64 v103, v111, v115, s[6:7]
	v_cndmask_b32_e64 v102, v110, v114, s[6:7]
	v_pk_mul_f32 v[94:95], v[94:95], v[94:95]
	v_pk_mul_f32 v[90:91], v[90:91], v[90:91]
	v_pk_mul_f32 v[96:97], v[96:97], v[96:97]
	v_pk_mul_f32 v[92:93], v[92:93], v[92:93]
; __device__ __forceinline__ unsigned pk2(float lo, float hi) { const f32x2 v = {lo, hi}; return __builtin_bit_cast(unsigned, __builtin_convertvector(v, bf16x2_t)); }
; __device__ __forceinline__ u32x4 ror8(u32x4 v) { u32x4 r;
; #pragma unroll
;     for (int i = 0; i < 4; ++i) r[i] = (unsigned)__builtin_amdgcn_mov_dpp((int)v[i], 0x128, 0xf, 0xf, true);
;     return r; }
; __device__ __forceinline__ void store_pair(unsigned char* own, size_t stride8, int hi_off, u32x4 lo, u32x4 hi, bool upper) {
;     const u32x4 tlo = ror8(lo), thi = ror8(hi);
;     const u32x4 A = upper ? thi : lo, B = upper ? hi : tlo;
;     unsigned char* pa = upper ? own - stride8 + hi_off : own;
;     unsigned char* pb = upper ? own + hi_off : own + stride8;
;     *(u32x4*)pa = A; *(u32x4*)pb = B;
;     __device__ __forceinline__ void operator()(const f32x4 (&acc)[2][2][4][2], const Unit& u, int wr, int wc, int fr, int fq) const {
;     ...
;             for (int m = 0; m < 4; ++m) { unsigned char* rowp = (unsigned char*)(H + ((size_t)(u.pm * (FF / 64) + u.pn * 4 + wc) * 256 + (wr * 64 + fr + ai * 128 + m * 16)) * 64 + 8 * fq); u32x4 w[2];
; #pragma unroll
;                 for (int bj = 0; bj < 2; ++bj) { f32x4 v0 = acc[ai][bj][m][0], v1 = acc[ai][bj][m][1];
; #pragma unroll
;                     for (int j = 0; j < 4; ++j) { const float a = fmaxf(v0[j], 0.f), b = fmaxf(v1[j], 0.f); v0[j] = a * a; v1[j] = b * b; }
;                     w[bj].x = pk2(v0[0], v0[1]); w[bj].y = pk2(v0[2], v0[3]); w[bj].z = pk2(v1[0], v1[1]); w[bj].w = pk2(v1[2], v1[3]); }
;                 store_pair(rowp, (size_t)8 * 64 * 2, 64, w[0], w[1], fr >= 8); }
	v_pk_mul_f32 v[86:87], v[86:87], v[86:87]
	v_pk_mul_f32 v[82:83], v[82:83], v[82:83]
	v_pk_mul_f32 v[88:89], v[88:89], v[88:89]
	v_pk_mul_f32 v[84:85], v[84:85], v[84:85]
	v_lshl_add_u64 v[106:107], v[106:107], 0, v[142:143]
	global_store_dwordx4 v[108:109], v[102:105], off
	global_store_dwordx4 v[106:107], v[98:101], off
	v_cvt_pk_bf16_f32 v94, v94, v95
	v_cvt_pk_bf16_f32 v95, v96, v97
	v_lshl_add_u64 v[98:99], s[22:23], 0, v[148:149]
	v_cvt_pk_bf16_f32 v96, v90, v91
	v_cvt_pk_bf16_f32 v97, v92, v93
	v_cvt_pk_bf16_f32 v86, v86, v87
	v_cvt_pk_bf16_f32 v87, v88, v89
	v_cvt_pk_bf16_f32 v82, v82, v83
	v_cvt_pk_bf16_f32 v83, v84, v85
	v_lshl_add_u64 v[90:91], v[98:99], 0, v[138:139]
	v_mov_b32_dpp v88, v94 row_ror:8 row_mask:0xf bank_mask:0xf bound_ctrl:1
	v_mov_b32_dpp v89, v95 row_ror:8 row_mask:0xf bank_mask:0xf bound_ctrl:1
	v_mov_b32_dpp v84, v96 row_ror:8 row_mask:0xf bank_mask:0xf bound_ctrl:1
	v_mov_b32_dpp v85, v97 row_ror:8 row_mask:0xf bank_mask:0xf bound_ctrl:1
	v_mov_b32_dpp v98, v86 row_ror:8 row_mask:0xf bank_mask:0xf bound_ctrl:1
	v_mov_b32_dpp v99, v87 row_ror:8 row_mask:0xf bank_mask:0xf bound_ctrl:1
	v_mov_b32_dpp v100, v82 row_ror:8 row_mask:0xf bank_mask:0xf bound_ctrl:1
	v_mov_b32_dpp v101, v83 row_ror:8 row_mask:0xf bank_mask:0xf bound_ctrl:1
	v_max_f32_e32 v78, 0, v78
	v_max_f32_e32 v74, 0, v74
	v_max_f32_e32 v79, 0, v79
	v_max_f32_e32 v75, 0, v75
	v_max_f32_e32 v80, 0, v80
	v_max_f32_e32 v76, 0, v76
	v_max_f32_e32 v81, 0, v81
	v_max_f32_e32 v77, 0, v77
	v_max_f32_e32 v70, 0, v70
	v_max_f32_e32 v66, 0, v66
	v_max_f32_e32 v71, 0, v71
	v_max_f32_e32 v67, 0, v67
	v_max_f32_e32 v72, 0, v72
	v_max_f32_e32 v68, 0, v68
	v_max_f32_e32 v73, 0, v73
	v_max_f32_e32 v69, 0, v69
	v_lshl_add_u64 v[92:93], v[90:91], 0, v[140:141]
	v_cndmask_b32_e64 v85, v85, v83, s[6:7]
	v_cndmask_b32_e64 v84, v84, v82, s[6:7]
	v_cndmask_b32_e64 v83, v89, v87, s[6:7]
	v_cndmask_b32_e64 v82, v88, v86, s[6:7]
	v_cndmask_b32_e64 v89, v97, v101, s[6:7]
	v_cndmask_b32_e64 v88, v96, v100, s[6:7]
	v_cndmask_b32_e64 v87, v95, v99, s[6:7]
	v_cndmask_b32_e64 v86, v94, v98, s[6:7]
	v_pk_mul_f32 v[78:79], v[78:79], v[78:79]
	v_pk_mul_f32 v[74:75], v[74:75], v[74:75]
	v_pk_mul_f32 v[80:81], v[80:81], v[80:81]
	v_pk_mul_f32 v[76:77], v[76:77], v[76:77]
	v_pk_mul_f32 v[70:71], v[70:71], v[70:71]
	v_pk_mul_f32 v[66:67], v[66:67], v[66:67]
	v_pk_mul_f32 v[72:73], v[72:73], v[72:73]
	v_pk_mul_f32 v[68:69], v[68:69], v[68:69]
	v_lshl_add_u64 v[90:91], v[90:91], 0, v[142:143]
	global_store_dwordx4 v[92:93], v[86:89], off
	global_store_dwordx4 v[90:91], v[82:85], off
	v_cvt_pk_bf16_f32 v78, v78, v79
	v_cvt_pk_bf16_f32 v79, v80, v81
	v_lshl_add_u64 v[82:83], s[22:23], 0, v[150:151]
	v_cvt_pk_bf16_f32 v80, v74, v75
	v_cvt_pk_bf16_f32 v81, v76, v77
	v_cvt_pk_bf16_f32 v70, v70, v71
	v_cvt_pk_bf16_f32 v71, v72, v73
	v_cvt_pk_bf16_f32 v66, v66, v67
	v_cvt_pk_bf16_f32 v67, v68, v69
	v_lshl_add_u64 v[74:75], v[82:83], 0, v[138:139]
	v_mov_b32_dpp v72, v78 row_ror:8 row_mask:0xf bank_mask:0xf bound_ctrl:1
	v_mov_b32_dpp v73, v79 row_ror:8 row_mask:0xf bank_mask:0xf bound_ctrl:1
	v_mov_b32_dpp v68, v80 row_ror:8 row_mask:0xf bank_mask:0xf bound_ctrl:1
	v_mov_b32_dpp v69, v81 row_ror:8 row_mask:0xf bank_mask:0xf bound_ctrl:1
	v_mov_b32_dpp v82, v70 row_ror:8 row_mask:0xf bank_mask:0xf bound_ctrl:1
	v_mov_b32_dpp v83, v71 row_ror:8 row_mask:0xf bank_mask:0xf bound_ctrl:1
	v_mov_b32_dpp v84, v66 row_ror:8 row_mask:0xf bank_mask:0xf bound_ctrl:1
	v_mov_b32_dpp v85, v67 row_ror:8 row_mask:0xf bank_mask:0xf bound_ctrl:1
	v_max_f32_e32 v62, 0, v62
	v_max_f32_e32 v58, 0, v58
	v_max_f32_e32 v63, 0, v63
	v_max_f32_e32 v59, 0, v59
	v_max_f32_e32 v64, 0, v64
	v_max_f32_e32 v60, 0, v60
	v_max_f32_e32 v65, 0, v65
	v_max_f32_e32 v61, 0, v61
	v_max_f32_e32 v54, 0, v54
	v_max_f32_e32 v50, 0, v50
	v_max_f32_e32 v55, 0, v55
	v_max_f32_e32 v51, 0, v51
	v_max_f32_e32 v56, 0, v56
	v_max_f32_e32 v52, 0, v52
	v_max_f32_e32 v57, 0, v57
	v_max_f32_e32 v53, 0, v53
	v_lshl_add_u64 v[76:77], v[74:75], 0, v[140:141]
	v_cndmask_b32_e64 v69, v69, v67, s[6:7]
	v_cndmask_b32_e64 v68, v68, v66, s[6:7]
	v_cndmask_b32_e64 v67, v73, v71, s[6:7]
	v_cndmask_b32_e64 v66, v72, v70, s[6:7]
	v_cndmask_b32_e64 v73, v81, v85, s[6:7]
	v_cndmask_b32_e64 v72, v80, v84, s[6:7]
	v_cndmask_b32_e64 v71, v79, v83, s[6:7]
	v_cndmask_b32_e64 v70, v78, v82, s[6:7]
	v_pk_mul_f32 v[62:63], v[62:63], v[62:63]
	v_pk_mul_f32 v[58:59], v[58:59], v[58:59]
	v_pk_mul_f32 v[64:65], v[64:65], v[64:65]
	v_pk_mul_f32 v[60:61], v[60:61], v[60:61]
	v_pk_mul_f32 v[54:55], v[54:55], v[54:55]
	v_pk_mul_f32 v[50:51], v[50:51], v[50:51]
	v_pk_mul_f32 v[56:57], v[56:57], v[56:57]
	v_pk_mul_f32 v[52:53], v[52:53], v[52:53]
	v_lshl_add_u64 v[74:75], v[74:75], 0, v[142:143]
	global_store_dwordx4 v[76:77], v[70:73], off
	global_store_dwordx4 v[74:75], v[66:69], off
	v_cvt_pk_bf16_f32 v62, v62, v63
	v_cvt_pk_bf16_f32 v63, v64, v65
	v_lshl_add_u64 v[66:67], s[22:23], 0, v[152:153]
	v_cvt_pk_bf16_f32 v64, v58, v59
	v_cvt_pk_bf16_f32 v65, v60, v61
	v_cvt_pk_bf16_f32 v54, v54, v55
	v_cvt_pk_bf16_f32 v55, v56, v57
	v_cvt_pk_bf16_f32 v50, v50, v51
	v_cvt_pk_bf16_f32 v51, v52, v53
	v_lshl_add_u64 v[58:59], v[66:67], 0, v[138:139]
	v_mov_b32_dpp v56, v62 row_ror:8 row_mask:0xf bank_mask:0xf bound_ctrl:1
	v_mov_b32_dpp v57, v63 row_ror:8 row_mask:0xf bank_mask:0xf bound_ctrl:1
	v_mov_b32_dpp v52, v64 row_ror:8 row_mask:0xf bank_mask:0xf bound_ctrl:1
	v_mov_b32_dpp v53, v65 row_ror:8 row_mask:0xf bank_mask:0xf bound_ctrl:1
	v_mov_b32_dpp v66, v54 row_ror:8 row_mask:0xf bank_mask:0xf bound_ctrl:1
	v_mov_b32_dpp v67, v55 row_ror:8 row_mask:0xf bank_mask:0xf bound_ctrl:1
; __device__ __forceinline__ unsigned pk2(float lo, float hi) { const f32x2 v = {lo, hi}; return __builtin_bit_cast(unsigned, __builtin_convertvector(v, bf16x2_t)); }
; __device__ __forceinline__ u32x4 ror8(u32x4 v) { u32x4 r;
; #pragma unroll
;     for (int i = 0; i < 4; ++i) r[i] = (unsigned)__builtin_amdgcn_mov_dpp((int)v[i], 0x128, 0xf, 0xf, true);
;     return r; }
; __device__ __forceinline__ void store_pair(unsigned char* own, size_t stride8, int hi_off, u32x4 lo, u32x4 hi, bool upper) {
;     const u32x4 tlo = ror8(lo), thi = ror8(hi);
;     const u32x4 A = upper ? thi : lo, B = upper ? hi : tlo;
;     unsigned char* pa = upper ? own - stride8 + hi_off : own;
;     unsigned char* pb = upper ? own + hi_off : own + stride8;
;     *(u32x4*)pa = A; *(u32x4*)pb = B;
;     __device__ __forceinline__ void operator()(const f32x4 (&acc)[2][2][4][2], const Unit& u, int wr, int wc, int fr, int fq) const {
;     ...
;             for (int m = 0; m < 4; ++m) { unsigned char* rowp = (unsigned char*)(H + ((size_t)(u.pm * (FF / 64) + u.pn * 4 + wc) * 256 + (wr * 64 + fr + ai * 128 + m * 16)) * 64 + 8 * fq); u32x4 w[2];
; #pragma unroll
;                 for (int bj = 0; bj < 2; ++bj) { f32x4 v0 = acc[ai][bj][m][0], v1 = acc[ai][bj][m][1];
; #pragma unroll
;                     for (int j = 0; j < 4; ++j) { const float a = fmaxf(v0[j], 0.f), b = fmaxf(v1[j], 0.f); v0[j] = a * a; v1[j] = b * b; }
;                     w[bj].x = pk2(v0[0], v0[1]); w[bj].y = pk2(v0[2], v0[3]); w[bj].z = pk2(v1[0], v1[1]); w[bj].w = pk2(v1[2], v1[3]); }
;                 store_pair(rowp, (size_t)8 * 64 * 2, 64, w[0], w[1], fr >= 8); }
	v_mov_b32_dpp v68, v50 row_ror:8 row_mask:0xf bank_mask:0xf bound_ctrl:1
	v_mov_b32_dpp v69, v51 row_ror:8 row_mask:0xf bank_mask:0xf bound_ctrl:1
	v_max_f32_e32 v46, 0, v46
	v_max_f32_e32 v42, 0, v42
	v_max_f32_e32 v47, 0, v47
	v_max_f32_e32 v43, 0, v43
	v_max_f32_e32 v48, 0, v48
	v_max_f32_e32 v44, 0, v44
	v_max_f32_e32 v49, 0, v49
	v_max_f32_e32 v45, 0, v45
	v_max_f32_e32 v38, 0, v38
	v_max_f32_e32 v34, 0, v34
	v_max_f32_e32 v39, 0, v39
	v_max_f32_e32 v35, 0, v35
	v_max_f32_e32 v40, 0, v40
	v_max_f32_e32 v36, 0, v36
	v_max_f32_e32 v41, 0, v41
	v_max_f32_e32 v37, 0, v37
	v_lshl_add_u64 v[60:61], v[58:59], 0, v[140:141]
	v_cndmask_b32_e64 v53, v53, v51, s[6:7]
	v_cndmask_b32_e64 v52, v52, v50, s[6:7]
	v_cndmask_b32_e64 v51, v57, v55, s[6:7]
	v_cndmask_b32_e64 v50, v56, v54, s[6:7]
	v_cndmask_b32_e64 v57, v65, v69, s[6:7]
	v_cndmask_b32_e64 v56, v64, v68, s[6:7]
	v_cndmask_b32_e64 v55, v63, v67, s[6:7]
	v_cndmask_b32_e64 v54, v62, v66, s[6:7]
	v_pk_mul_f32 v[46:47], v[46:47], v[46:47]
	v_pk_mul_f32 v[42:43], v[42:43], v[42:43]
	v_pk_mul_f32 v[48:49], v[48:49], v[48:49]
	v_pk_mul_f32 v[44:45], v[44:45], v[44:45]
	v_pk_mul_f32 v[38:39], v[38:39], v[38:39]
	v_pk_mul_f32 v[34:35], v[34:35], v[34:35]
	v_pk_mul_f32 v[40:41], v[40:41], v[40:41]
	v_pk_mul_f32 v[36:37], v[36:37], v[36:37]
	v_lshl_add_u64 v[58:59], v[58:59], 0, v[142:143]
	global_store_dwordx4 v[60:61], v[54:57], off
	global_store_dwordx4 v[58:59], v[50:53], off
	v_cvt_pk_bf16_f32 v46, v46, v47
	v_cvt_pk_bf16_f32 v47, v48, v49
	v_lshl_add_u64 v[50:51], s[22:23], 0, v[154:155]
	v_cvt_pk_bf16_f32 v48, v42, v43
	v_cvt_pk_bf16_f32 v49, v44, v45
	v_cvt_pk_bf16_f32 v38, v38, v39
	v_cvt_pk_bf16_f32 v39, v40, v41
	v_cvt_pk_bf16_f32 v34, v34, v35
	v_cvt_pk_bf16_f32 v35, v36, v37
	v_lshl_add_u64 v[42:43], v[50:51], 0, v[138:139]
	v_mov_b32_dpp v40, v46 row_ror:8 row_mask:0xf bank_mask:0xf bound_ctrl:1
	v_mov_b32_dpp v41, v47 row_ror:8 row_mask:0xf bank_mask:0xf bound_ctrl:1
	v_mov_b32_dpp v36, v48 row_ror:8 row_mask:0xf bank_mask:0xf bound_ctrl:1
	v_mov_b32_dpp v37, v49 row_ror:8 row_mask:0xf bank_mask:0xf bound_ctrl:1
	v_mov_b32_dpp v50, v38 row_ror:8 row_mask:0xf bank_mask:0xf bound_ctrl:1
	v_mov_b32_dpp v51, v39 row_ror:8 row_mask:0xf bank_mask:0xf bound_ctrl:1
	v_mov_b32_dpp v52, v34 row_ror:8 row_mask:0xf bank_mask:0xf bound_ctrl:1
	v_mov_b32_dpp v53, v35 row_ror:8 row_mask:0xf bank_mask:0xf bound_ctrl:1
	v_max_f32_e32 v30, 0, v30
	v_max_f32_e32 v26, 0, v26
	v_max_f32_e32 v31, 0, v31
	v_max_f32_e32 v27, 0, v27
	v_max_f32_e32 v32, 0, v32
	v_max_f32_e32 v28, 0, v28
	v_max_f32_e32 v33, 0, v33
	v_max_f32_e32 v29, 0, v29
	v_max_f32_e32 v22, 0, v22
	v_max_f32_e32 v18, 0, v18
	v_max_f32_e32 v23, 0, v23
	v_max_f32_e32 v19, 0, v19
	v_max_f32_e32 v24, 0, v24
	v_max_f32_e32 v20, 0, v20
	v_max_f32_e32 v25, 0, v25
	v_max_f32_e32 v21, 0, v21
	v_lshl_add_u64 v[44:45], v[42:43], 0, v[140:141]
	v_cndmask_b32_e64 v37, v37, v35, s[6:7]
	v_cndmask_b32_e64 v36, v36, v34, s[6:7]
	v_cndmask_b32_e64 v35, v41, v39, s[6:7]
	v_cndmask_b32_e64 v34, v40, v38, s[6:7]
	v_cndmask_b32_e64 v41, v49, v53, s[6:7]
	v_cndmask_b32_e64 v40, v48, v52, s[6:7]
	v_cndmask_b32_e64 v39, v47, v51, s[6:7]
	v_cndmask_b32_e64 v38, v46, v50, s[6:7]
	v_pk_mul_f32 v[30:31], v[30:31], v[30:31]
	v_pk_mul_f32 v[26:27], v[26:27], v[26:27]
	v_pk_mul_f32 v[32:33], v[32:33], v[32:33]
	v_pk_mul_f32 v[28:29], v[28:29], v[28:29]
	v_pk_mul_f32 v[22:23], v[22:23], v[22:23]
	v_pk_mul_f32 v[18:19], v[18:19], v[18:19]
	v_pk_mul_f32 v[24:25], v[24:25], v[24:25]
	v_pk_mul_f32 v[20:21], v[20:21], v[20:21]
	v_lshl_add_u64 v[42:43], v[42:43], 0, v[142:143]
	global_store_dwordx4 v[44:45], v[38:41], off
	global_store_dwordx4 v[42:43], v[34:37], off
	v_cvt_pk_bf16_f32 v30, v30, v31
	v_cvt_pk_bf16_f32 v31, v32, v33
	v_lshl_add_u64 v[34:35], s[22:23], 0, v[156:157]
; __device__ __forceinline__ unsigned pk2(float lo, float hi) { const f32x2 v = {lo, hi}; return __builtin_bit_cast(unsigned, __builtin_convertvector(v, bf16x2_t)); }
; #define PG8_BAR __builtin_amdgcn_s_barrier()
; template <class Epi, class Sched, bool ABLK = false, bool ALIGN_EPI = true, bool SP2 = true, bool BBLK = true>
; __device__ __forceinline__ void gemm_phase(LAS unsigned char* lds, const Gemm g, const Sched& S, const Epi& E) {
;     ...
;         if constexpr (ALIGN_EPI) { if (wr == 0) PG8_BAR; }
;         E(acc, cur, wr, wc, fr, fq); S.done(cur);
;         if (!has_next) break;
;     __device__ __forceinline__ void operator()(const f32x4 (&acc)[2][2][4][2], const Unit& u, int wr, int wc, int fr, int fq) const {
; #pragma unroll
;         for (int ai = 0; ai < 2; ++ai)
; #pragma unroll
;             for (int m = 0; m < 4; ++m) { unsigned char* rowp = (unsigned char*)(H + ((size_t)(u.pm * (FF / 64) + u.pn * 4 + wc) * 256 + (wr * 64 + fr + ai * 128 + m * 16)) * 64 + 8 * fq); u32x4 w[2];
; #pragma unroll
;                 for (int bj = 0; bj < 2; ++bj) { f32x4 v0 = acc[ai][bj][m][0], v1 = acc[ai][bj][m][1];
; #pragma unroll
;                     for (int j = 0; j < 4; ++j) { const float a = fmaxf(v0[j], 0.f), b = fmaxf(v1[j], 0.f); v0[j] = a * a; v1[j] = b * b; }
;                     w[bj].x = pk2(v0[0], v0[1]); w[bj].y = pk2(v0[2], v0[3]); w[bj].z = pk2(v1[0], v1[1]); w[bj].w = pk2(v1[2], v1[3]); }
;                 store_pair(rowp, (size_t)8 * 64 * 2, 64, w[0], w[1], fr >= 8); }
;     }
	v_cvt_pk_bf16_f32 v32, v26, v27
	v_cvt_pk_bf16_f32 v33, v28, v29
	v_cvt_pk_bf16_f32 v22, v22, v23
	v_cvt_pk_bf16_f32 v23, v24, v25
	v_cvt_pk_bf16_f32 v18, v18, v19
	v_cvt_pk_bf16_f32 v19, v20, v21
	v_lshl_add_u64 v[26:27], v[34:35], 0, v[138:139]
	v_mov_b32_dpp v24, v30 row_ror:8 row_mask:0xf bank_mask:0xf bound_ctrl:1
	v_mov_b32_dpp v25, v31 row_ror:8 row_mask:0xf bank_mask:0xf bound_ctrl:1
	v_mov_b32_dpp v20, v32 row_ror:8 row_mask:0xf bank_mask:0xf bound_ctrl:1
	v_mov_b32_dpp v21, v33 row_ror:8 row_mask:0xf bank_mask:0xf bound_ctrl:1
	v_mov_b32_dpp v34, v22 row_ror:8 row_mask:0xf bank_mask:0xf bound_ctrl:1
	v_mov_b32_dpp v35, v23 row_ror:8 row_mask:0xf bank_mask:0xf bound_ctrl:1
	v_mov_b32_dpp v36, v18 row_ror:8 row_mask:0xf bank_mask:0xf bound_ctrl:1
	v_mov_b32_dpp v37, v19 row_ror:8 row_mask:0xf bank_mask:0xf bound_ctrl:1
	v_max_f32_e32 v14, 0, v14
	v_max_f32_e32 v10, 0, v10
	v_max_f32_e32 v15, 0, v15
	v_max_f32_e32 v11, 0, v11
	v_max_f32_e32 v16, 0, v16
	v_max_f32_e32 v12, 0, v12
	v_max_f32_e32 v17, 0, v17
	v_max_f32_e32 v13, 0, v13
	v_max_f32_e32 v6, 0, v6
	v_max_f32_e32 v2, 0, v2
	v_max_f32_e32 v7, 0, v7
	v_max_f32_e32 v3, 0, v3
	v_max_f32_e32 v8, 0, v8
	v_max_f32_e32 v4, 0, v4
	v_max_f32_e32 v9, 0, v9
	v_max_f32_e32 v5, 0, v5
	v_lshl_add_u64 v[28:29], v[26:27], 0, v[140:141]
	v_cndmask_b32_e64 v21, v21, v19, s[6:7]
	v_cndmask_b32_e64 v20, v20, v18, s[6:7]
	v_cndmask_b32_e64 v19, v25, v23, s[6:7]
	v_cndmask_b32_e64 v18, v24, v22, s[6:7]
	v_cndmask_b32_e64 v25, v33, v37, s[6:7]
	v_cndmask_b32_e64 v24, v32, v36, s[6:7]
	v_cndmask_b32_e64 v23, v31, v35, s[6:7]
	v_cndmask_b32_e64 v22, v30, v34, s[6:7]
	v_pk_mul_f32 v[14:15], v[14:15], v[14:15]
	v_pk_mul_f32 v[10:11], v[10:11], v[10:11]
	v_pk_mul_f32 v[16:17], v[16:17], v[16:17]
	v_pk_mul_f32 v[12:13], v[12:13], v[12:13]
	v_pk_mul_f32 v[6:7], v[6:7], v[6:7]
	v_pk_mul_f32 v[2:3], v[2:3], v[2:3]
	v_pk_mul_f32 v[8:9], v[8:9], v[8:9]
	v_pk_mul_f32 v[4:5], v[4:5], v[4:5]
	v_lshl_add_u64 v[26:27], v[26:27], 0, v[142:143]
	global_store_dwordx4 v[28:29], v[22:25], off
	global_store_dwordx4 v[26:27], v[18:21], off
	v_cvt_pk_bf16_f32 v14, v14, v15
	v_cvt_pk_bf16_f32 v15, v16, v17
	v_lshl_add_u64 v[18:19], s[22:23], 0, v[158:159]
	v_cvt_pk_bf16_f32 v16, v10, v11
	v_cvt_pk_bf16_f32 v17, v12, v13
	v_cvt_pk_bf16_f32 v6, v6, v7
	v_cvt_pk_bf16_f32 v7, v8, v9
	v_cvt_pk_bf16_f32 v2, v2, v3
	v_cvt_pk_bf16_f32 v3, v4, v5
	v_lshl_add_u64 v[10:11], v[18:19], 0, v[138:139]
	v_mov_b32_dpp v8, v14 row_ror:8 row_mask:0xf bank_mask:0xf bound_ctrl:1
	v_mov_b32_dpp v9, v15 row_ror:8 row_mask:0xf bank_mask:0xf bound_ctrl:1
	v_mov_b32_dpp v4, v16 row_ror:8 row_mask:0xf bank_mask:0xf bound_ctrl:1
	v_mov_b32_dpp v5, v17 row_ror:8 row_mask:0xf bank_mask:0xf bound_ctrl:1
	v_mov_b32_dpp v18, v6 row_ror:8 row_mask:0xf bank_mask:0xf bound_ctrl:1
	v_mov_b32_dpp v19, v7 row_ror:8 row_mask:0xf bank_mask:0xf bound_ctrl:1
	v_mov_b32_dpp v20, v2 row_ror:8 row_mask:0xf bank_mask:0xf bound_ctrl:1
	v_mov_b32_dpp v21, v3 row_ror:8 row_mask:0xf bank_mask:0xf bound_ctrl:1
	v_lshl_add_u64 v[12:13], v[10:11], 0, v[140:141]
	v_cndmask_b32_e64 v5, v5, v3, s[6:7]
	v_cndmask_b32_e64 v4, v4, v2, s[6:7]
	v_cndmask_b32_e64 v3, v9, v7, s[6:7]
	v_cndmask_b32_e64 v2, v8, v6, s[6:7]
	v_cndmask_b32_e64 v9, v17, v21, s[6:7]
	v_cndmask_b32_e64 v8, v16, v20, s[6:7]
	v_cndmask_b32_e64 v7, v15, v19, s[6:7]
	v_cndmask_b32_e64 v6, v14, v18, s[6:7]
	s_and_b64 vcc, exec, s[8:9]
	s_cbranch_vccz .LBB0_478
	s_barrier
.LBB0_478:
	s_andn2_b64 vcc, exec, s[18:19]
	s_mov_b64 s[4:5], -1
	v_lshl_add_u64 v[10:11], v[10:11], 0, v[142:143]
	global_store_dwordx4 v[12:13], v[6:9], off
	global_store_dwordx4 v[10:11], v[2:5], off
	s_cbranch_vccnz .LBB0_471
	s_andn2_b64 vcc, exec, s[2:3]
	s_cbranch_vccnz .LBB0_470
	s_barrier
	s_branch .LBB0_470

; #define PG8_STAGE(bufoff, gbase, voff) do { _Pragma("unroll") for (int _i = 0; _i < 2; ++_i) \
;         __builtin_amdgcn_global_load_lds((const unsigned*)((const char*)(gbase) + (voff)[_i]), (LAS unsigned*)(lds + (bufoff) + ldsw + _i * 8192), 16, 0, 0); } while (0)
; #define PG8_LDA(dst, b, h) do { _Pragma("unroll") for (int m = 0; m < 4; ++m) _Pragma("unroll") for (int k = 0; k < 2; ++k) dst[m][k] = *(const LAS bf16x8*)(lds + PG8_SA(b, h) + aoff + m * 2048 + k * 1024); } while (0)
; #define PG8_LDB(dst, b, h) do { _Pragma("unroll") for (int n = 0; n < 2; ++n) _Pragma("unroll") for (int k = 0; k < 2; ++k) dst[n][k] = *(const LAS bf16x8*)(lds + PG8_SB(b, h) + boff + n * 2048 + k * 1024); } while (0)
; #define PG8_MMA(ai, bj, At, Bt) do { __builtin_amdgcn_s_setprio(1); _Pragma("unroll") for (int m = 0; m < 4; ++m) _Pragma("unroll") for (int n = 0; n < 2; ++n) _Pragma("unroll") for (int k = 0; k < 2; ++k) \
;         acc[ai][bj][m][n] = __builtin_amdgcn_mfma_f32_16x16x32_bf16(Bt[n][k], At[m][k], acc[ai][bj][m][n], 0, 0, 0); __builtin_amdgcn_s_setprio(0); } while (0)
; #define PG8_WAIT_V(n) asm volatile("s_waitcnt vmcnt(" #n ")" ::: "memory")
; template <class Epi, class Sched, bool ABLK = false, bool ALIGN_EPI = true, bool SP2 = true, bool BBLK = true>
; __device__ __forceinline__ void gemm_phase(LAS unsigned char* lds, const Gemm g, const Sched& S, const Epi& E) {
;     ...
;         for (int t = 0; t < nt; t += 2) {
;             const bool last = (t == nt - 2);
;             const char* a1 = a_tile(uA, tbA + t + 1);
;             const char* a2 = last ? a_tile(nuA, ntbA) : a_tile(uA, tbA + t + 2); const char* b2 = last ? nB : cB + (size_t)(t + 2) * kstepB;
;             const char* a3 = last ? a_tile(nuA, ntbA + 1) : a_tile(uA, tbA + t + 3); const char* b3 = b2 + kstepB;
;             if (last && has_next) S.a_ready(nxt);
;             if constexpr (SP2) {
;             PG8_LDB(B0, 0, 0); PG8_LDB(B1, 0, 1); PG8_SCHED; PG8_LDA(At, 0, 0); PG8_STAGE(PG8_SA(1, 1), a1 + hstepA, voffA);
;             PG8_WAIT_V(8); PG8_WAIT_L(0); PG8_BAR; PG8_MMA(0, 0, At, B0); PG8_MMA(0, 1, At, B1); PG8_BAR; PG8_SCHED;
;             PG8_LDA(At, 0, 1); PG8_STAGE(PG8_SB(0, 0), b2, voffB); PG8_STAGE(PG8_SB(0, 1), b2 + hstepB, voffB); PG8_STAGE(PG8_SA(0, 0), a2, voffA);
;             PG8_WAIT_V(8); PG8_WAIT_L(0); PG8_BAR; PG8_MMA(1, 0, At, B0); PG8_MMA(1, 1, At, B1); PG8_BAR; PG8_SCHED;
.LBB0_540:
	ds_read_b128 v[152:155], v148
	ds_read_b128 v[156:159], v148 offset:1024
	ds_read_b128 v[160:163], v148 offset:2048
	ds_read_b128 v[164:167], v148 offset:3072
	ds_read_b128 v[168:171], v149
	ds_read_b128 v[172:175], v149 offset:1024
	ds_read_b128 v[176:179], v149 offset:2048
	ds_read_b128 v[180:183], v149 offset:3072
	s_add_u32 s42, s75, s40
	s_addc_u32 s43, s76, s41
	s_add_u32 s48, s42, 0x10000
	s_addc_u32 s49, s43, 0
	s_add_i32 s79, s79, 2
	s_add_u32 s46, s66, s40
	s_addc_u32 s47, s67, s41
	s_add_u32 s42, s42, 0x18000
	s_addc_u32 s43, s43, 0
	s_cmp_eq_u32 s77, s40
	s_cselect_b32 s43, s65, s43
	s_cselect_b32 s42, s64, s42
	s_cselect_b32 s47, s4, s47
	s_cselect_b32 s46, s5, s46
	s_cselect_b32 s49, s63, s49
	s_cselect_b32 s48, s35, s48
	v_lshl_add_u64 v[216:217], v[142:143], 0, s[40:41]
	s_add_i32 m0, s52, 0xc000
	ds_read_b128 v[184:187], v150
	ds_read_b128 v[188:191], v150 offset:1024
	ds_read_b128 v[192:195], v150 offset:2048
	ds_read_b128 v[196:199], v150 offset:3072
	ds_read_b128 v[200:203], v150 offset:4096
	ds_read_b128 v[204:207], v150 offset:5120
	ds_read_b128 v[208:211], v150 offset:6144
	ds_read_b128 v[212:215], v150 offset:7168
	global_load_lds_dwordx4 v[216:217], off
	v_lshl_add_u64 v[216:217], v[144:145], 0, s[40:41]
	s_add_i32 m0, s52, 0xe000
	s_nop 0
	global_load_lds_dwordx4 v[216:217], off
	s_waitcnt vmcnt(8) lgkmcnt(0)
	s_barrier
	v_mfma_f32_16x16x32_bf16 v[126:129], v[152:155], v[184:187], v[126:129]
	v_mfma_f32_16x16x32_bf16 v[122:125], v[160:163], v[184:187], v[122:125]
	v_mfma_f32_16x16x32_bf16 v[110:113], v[152:155], v[192:195], v[110:113]
	v_mfma_f32_16x16x32_bf16 v[106:109], v[160:163], v[192:195], v[106:109]
	v_mfma_f32_16x16x32_bf16 v[94:97], v[152:155], v[200:203], v[94:97]
	v_mfma_f32_16x16x32_bf16 v[90:93], v[160:163], v[200:203], v[90:93]
	v_mfma_f32_16x16x32_bf16 v[78:81], v[152:155], v[208:211], v[78:81]
	v_mfma_f32_16x16x32_bf16 v[74:77], v[160:163], v[208:211], v[74:77]
	v_mfma_f32_16x16x32_bf16 v[126:129], v[156:159], v[188:191], v[126:129]
	v_mfma_f32_16x16x32_bf16 v[122:125], v[164:167], v[188:191], v[122:125]
	v_mfma_f32_16x16x32_bf16 v[110:113], v[156:159], v[196:199], v[110:113]
	v_mfma_f32_16x16x32_bf16 v[106:109], v[164:167], v[196:199], v[106:109]
	v_mfma_f32_16x16x32_bf16 v[94:97], v[156:159], v[204:207], v[94:97]
	v_mfma_f32_16x16x32_bf16 v[90:93], v[164:167], v[204:207], v[90:93]
	v_mfma_f32_16x16x32_bf16 v[78:81], v[156:159], v[212:215], v[78:81]
	v_mfma_f32_16x16x32_bf16 v[74:77], v[164:167], v[212:215], v[74:77]
	v_mfma_f32_16x16x32_bf16 v[118:121], v[168:171], v[184:187], v[118:121]
	v_mfma_f32_16x16x32_bf16 v[114:117], v[176:179], v[184:187], v[114:117]
	v_mfma_f32_16x16x32_bf16 v[102:105], v[168:171], v[192:195], v[102:105]
	v_mfma_f32_16x16x32_bf16 v[98:101], v[176:179], v[192:195], v[98:101]
	v_mfma_f32_16x16x32_bf16 v[86:89], v[168:171], v[200:203], v[86:89]
	v_mfma_f32_16x16x32_bf16 v[82:85], v[176:179], v[200:203], v[82:85]
	v_mfma_f32_16x16x32_bf16 v[70:73], v[168:171], v[208:211], v[70:73]
	v_mfma_f32_16x16x32_bf16 v[66:69], v[176:179], v[208:211], v[66:69]
	v_mfma_f32_16x16x32_bf16 v[118:121], v[172:175], v[188:191], v[118:121]
	v_mfma_f32_16x16x32_bf16 v[114:117], v[180:183], v[188:191], v[114:117]
	v_mfma_f32_16x16x32_bf16 v[102:105], v[172:175], v[196:199], v[102:105]
	v_mfma_f32_16x16x32_bf16 v[98:101], v[180:183], v[196:199], v[98:101]
	v_mfma_f32_16x16x32_bf16 v[86:89], v[172:175], v[204:207], v[86:89]
	v_mfma_f32_16x16x32_bf16 v[82:85], v[180:183], v[204:207], v[82:85]
	v_mfma_f32_16x16x32_bf16 v[70:73], v[172:175], v[212:215], v[70:73]
	v_mfma_f32_16x16x32_bf16 v[66:69], v[180:183], v[212:215], v[66:69]
	s_barrier
	s_add_i32 s60, s72, s51
	s_mov_b32 m0, s60
	ds_read_b128 v[184:187], v150 offset:16384
	ds_read_b128 v[188:191], v150 offset:17408
	ds_read_b128 v[192:195], v150 offset:18432
	ds_read_b128 v[196:199], v150 offset:19456
	ds_read_b128 v[200:203], v150 offset:20480
	ds_read_b128 v[204:207], v150 offset:21504
	ds_read_b128 v[208:211], v150 offset:22528
	ds_read_b128 v[212:215], v150 offset:23552
	global_load_lds_dwordx4 v130, s[46:47]
	s_add_i32 m0, s60, 0x2000
	s_add_u32 s60, s46, 0x4000
	s_addc_u32 s61, s47, 0
	s_add_i32 s81, s73, s51
	global_load_lds_dwordx4 v132, s[46:47]
	s_mov_b32 m0, s81
	s_nop 0
	global_load_lds_dwordx4 v130, s[60:61]
	s_add_i32 m0, s81, 0x2000
	s_nop 0
	global_load_lds_dwordx4 v132, s[60:61]
	s_mov_b32 m0, s52
	s_nop 0
	global_load_lds_dwordx4 v130, s[48:49]
	s_mov_b32 m0, s53
	s_nop 0
	global_load_lds_dwordx4 v132, s[48:49]
	s_waitcnt vmcnt(8) lgkmcnt(0)
	s_barrier
; #define PG8_STAGE(bufoff, gbase, voff) do { _Pragma("unroll") for (int _i = 0; _i < 2; ++_i) \
;         __builtin_amdgcn_global_load_lds((const unsigned*)((const char*)(gbase) + (voff)[_i]), (LAS unsigned*)(lds + (bufoff) + ldsw + _i * 8192), 16, 0, 0); } while (0)
; #define PG8_LDA(dst, b, h) do { _Pragma("unroll") for (int m = 0; m < 4; ++m) _Pragma("unroll") for (int k = 0; k < 2; ++k) dst[m][k] = *(const LAS bf16x8*)(lds + PG8_SA(b, h) + aoff + m * 2048 + k * 1024); } while (0)
; #define PG8_LDB(dst, b, h) do { _Pragma("unroll") for (int n = 0; n < 2; ++n) _Pragma("unroll") for (int k = 0; k < 2; ++k) dst[n][k] = *(const LAS bf16x8*)(lds + PG8_SB(b, h) + boff + n * 2048 + k * 1024); } while (0)
; #define PG8_MMA(ai, bj, At, Bt) do { __builtin_amdgcn_s_setprio(1); _Pragma("unroll") for (int m = 0; m < 4; ++m) _Pragma("unroll") for (int n = 0; n < 2; ++n) _Pragma("unroll") for (int k = 0; k < 2; ++k) \
;         acc[ai][bj][m][n] = __builtin_amdgcn_mfma_f32_16x16x32_bf16(Bt[n][k], At[m][k], acc[ai][bj][m][n], 0, 0, 0); __builtin_amdgcn_s_setprio(0); } while (0)
; #define PG8_WAIT_V(n) asm volatile("s_waitcnt vmcnt(" #n ")" ::: "memory")
; #define PG8_WAIT_L(n) asm volatile("s_waitcnt lgkmcnt(" #n ")" ::: "memory")
; #define PG8_BAR __builtin_amdgcn_s_barrier()
; #define PG8_SCHED __builtin_amdgcn_sched_barrier(0)
; template <class Epi, class Sched, bool ABLK = false, bool ALIGN_EPI = true, bool SP2 = true, bool BBLK = true>
; __device__ __forceinline__ void gemm_phase(LAS unsigned char* lds, const Gemm g, const Sched& S, const Epi& E) {
;     ...
;             PG8_WAIT_V(8); PG8_WAIT_L(0); PG8_BAR; PG8_MMA(1, 0, At, B0); PG8_MMA(1, 1, At, B1); PG8_BAR; PG8_SCHED;
;             PG8_LDB(B0, 1, 0); PG8_LDB(B1, 1, 1); PG8_SCHED; PG8_LDA(At, 1, 0); PG8_STAGE(PG8_SA(0, 1), a2 + hstepA, voffA);
;             PG8_WAIT_V(8); PG8_WAIT_L(0); PG8_BAR; PG8_MMA(0, 0, At, B0); PG8_MMA(0, 1, At, B1); PG8_BAR; PG8_SCHED;
;             PG8_LDA(At, 1, 1); PG8_STAGE(PG8_SB(1, 0), b3, voffB); PG8_STAGE(PG8_SB(1, 1), b3 + hstepB, voffB); PG8_STAGE(PG8_SA(1, 0), a3, voffA);
	v_mfma_f32_16x16x32_bf16 v[62:65], v[152:155], v[184:187], v[62:65]
	v_mfma_f32_16x16x32_bf16 v[58:61], v[160:163], v[184:187], v[58:61]
	v_mfma_f32_16x16x32_bf16 v[46:49], v[152:155], v[192:195], v[46:49]
	v_mfma_f32_16x16x32_bf16 v[42:45], v[160:163], v[192:195], v[42:45]
	v_mfma_f32_16x16x32_bf16 v[30:33], v[152:155], v[200:203], v[30:33]
	v_mfma_f32_16x16x32_bf16 v[26:29], v[160:163], v[200:203], v[26:29]
	v_mfma_f32_16x16x32_bf16 v[14:17], v[152:155], v[208:211], v[14:17]
	v_mfma_f32_16x16x32_bf16 v[10:13], v[160:163], v[208:211], v[10:13]
	v_mfma_f32_16x16x32_bf16 v[62:65], v[156:159], v[188:191], v[62:65]
	v_mfma_f32_16x16x32_bf16 v[58:61], v[164:167], v[188:191], v[58:61]
	v_mfma_f32_16x16x32_bf16 v[46:49], v[156:159], v[196:199], v[46:49]
	v_mfma_f32_16x16x32_bf16 v[42:45], v[164:167], v[196:199], v[42:45]
	v_mfma_f32_16x16x32_bf16 v[30:33], v[156:159], v[204:207], v[30:33]
	v_mfma_f32_16x16x32_bf16 v[26:29], v[164:167], v[204:207], v[26:29]
	v_mfma_f32_16x16x32_bf16 v[14:17], v[156:159], v[212:215], v[14:17]
	v_mfma_f32_16x16x32_bf16 v[10:13], v[164:167], v[212:215], v[10:13]
	v_mfma_f32_16x16x32_bf16 v[54:57], v[168:171], v[184:187], v[54:57]
	v_mfma_f32_16x16x32_bf16 v[50:53], v[176:179], v[184:187], v[50:53]
	v_mfma_f32_16x16x32_bf16 v[38:41], v[168:171], v[192:195], v[38:41]
	v_mfma_f32_16x16x32_bf16 v[34:37], v[176:179], v[192:195], v[34:37]
	v_mfma_f32_16x16x32_bf16 v[22:25], v[168:171], v[200:203], v[22:25]
	v_mfma_f32_16x16x32_bf16 v[18:21], v[176:179], v[200:203], v[18:21]
	v_mfma_f32_16x16x32_bf16 v[6:9], v[168:171], v[208:211], v[6:9]
	v_mfma_f32_16x16x32_bf16 v[2:5], v[176:179], v[208:211], v[2:5]
	v_mfma_f32_16x16x32_bf16 v[54:57], v[172:175], v[188:191], v[54:57]
	v_mfma_f32_16x16x32_bf16 v[50:53], v[180:183], v[188:191], v[50:53]
	v_mfma_f32_16x16x32_bf16 v[38:41], v[172:175], v[196:199], v[38:41]
	v_mfma_f32_16x16x32_bf16 v[34:37], v[180:183], v[196:199], v[34:37]
	v_mfma_f32_16x16x32_bf16 v[22:25], v[172:175], v[204:207], v[22:25]
	v_mfma_f32_16x16x32_bf16 v[18:21], v[180:183], v[204:207], v[18:21]
	v_mfma_f32_16x16x32_bf16 v[6:9], v[172:175], v[212:215], v[6:9]
	v_mfma_f32_16x16x32_bf16 v[2:5], v[180:183], v[212:215], v[2:5]
	s_barrier
	s_add_i32 s60, 0, 0x18000
	v_add_u32_e32 v151, s60, v146
	s_add_i32 s61, 0, 0x1c000
	ds_read_b128 v[152:155], v151
	ds_read_b128 v[156:159], v151 offset:1024
	ds_read_b128 v[160:163], v151 offset:2048
	ds_read_b128 v[164:167], v151 offset:3072
	v_add_u32_e32 v151, s61, v146
	ds_read_b128 v[168:171], v151
	ds_read_b128 v[172:175], v151 offset:1024
	ds_read_b128 v[176:179], v151 offset:2048
	ds_read_b128 v[180:183], v151 offset:3072
	s_add_u32 s48, s48, 0x4000
	s_addc_u32 s49, s49, 0
	s_mov_b32 m0, s54
	ds_read_b128 v[184:187], v150 offset:32768
	ds_read_b128 v[188:191], v150 offset:33792
	ds_read_b128 v[192:195], v150 offset:34816
	ds_read_b128 v[196:199], v150 offset:35840
	ds_read_b128 v[200:203], v150 offset:36864
	ds_read_b128 v[204:207], v150 offset:37888
	ds_read_b128 v[208:211], v150 offset:38912
	ds_read_b128 v[212:215], v150 offset:39936
	global_load_lds_dwordx4 v130, s[48:49]
	s_mov_b32 m0, s55
	s_nop 0
	global_load_lds_dwordx4 v132, s[48:49]
	s_waitcnt vmcnt(8) lgkmcnt(0)
	s_barrier
	v_mfma_f32_16x16x32_bf16 v[126:129], v[152:155], v[184:187], v[126:129]
	v_mfma_f32_16x16x32_bf16 v[122:125], v[160:163], v[184:187], v[122:125]
	v_mfma_f32_16x16x32_bf16 v[110:113], v[152:155], v[192:195], v[110:113]
	v_mfma_f32_16x16x32_bf16 v[106:109], v[160:163], v[192:195], v[106:109]
	v_mfma_f32_16x16x32_bf16 v[94:97], v[152:155], v[200:203], v[94:97]
	v_mfma_f32_16x16x32_bf16 v[90:93], v[160:163], v[200:203], v[90:93]
	v_mfma_f32_16x16x32_bf16 v[78:81], v[152:155], v[208:211], v[78:81]
	v_mfma_f32_16x16x32_bf16 v[74:77], v[160:163], v[208:211], v[74:77]
	v_mfma_f32_16x16x32_bf16 v[126:129], v[156:159], v[188:191], v[126:129]
	v_mfma_f32_16x16x32_bf16 v[122:125], v[164:167], v[188:191], v[122:125]
	v_mfma_f32_16x16x32_bf16 v[110:113], v[156:159], v[196:199], v[110:113]
	v_mfma_f32_16x16x32_bf16 v[106:109], v[164:167], v[196:199], v[106:109]
	v_mfma_f32_16x16x32_bf16 v[94:97], v[156:159], v[204:207], v[94:97]
	v_mfma_f32_16x16x32_bf16 v[90:93], v[164:167], v[204:207], v[90:93]
	v_mfma_f32_16x16x32_bf16 v[78:81], v[156:159], v[212:215], v[78:81]
	v_mfma_f32_16x16x32_bf16 v[74:77], v[164:167], v[212:215], v[74:77]
	v_mfma_f32_16x16x32_bf16 v[118:121], v[168:171], v[184:187], v[118:121]
	v_mfma_f32_16x16x32_bf16 v[114:117], v[176:179], v[184:187], v[114:117]
	v_mfma_f32_16x16x32_bf16 v[102:105], v[168:171], v[192:195], v[102:105]
	v_mfma_f32_16x16x32_bf16 v[98:101], v[176:179], v[192:195], v[98:101]
	v_mfma_f32_16x16x32_bf16 v[86:89], v[168:171], v[200:203], v[86:89]
	v_mfma_f32_16x16x32_bf16 v[82:85], v[176:179], v[200:203], v[82:85]
	v_mfma_f32_16x16x32_bf16 v[70:73], v[168:171], v[208:211], v[70:73]
	v_mfma_f32_16x16x32_bf16 v[66:69], v[176:179], v[208:211], v[66:69]
	v_mfma_f32_16x16x32_bf16 v[118:121], v[172:175], v[188:191], v[118:121]
	v_mfma_f32_16x16x32_bf16 v[114:117], v[180:183], v[188:191], v[114:117]
	v_mfma_f32_16x16x32_bf16 v[102:105], v[172:175], v[196:199], v[102:105]
	v_mfma_f32_16x16x32_bf16 v[98:101], v[180:183], v[196:199], v[98:101]
	v_mfma_f32_16x16x32_bf16 v[86:89], v[172:175], v[204:207], v[86:89]
	v_mfma_f32_16x16x32_bf16 v[82:85], v[180:183], v[204:207], v[82:85]
	v_mfma_f32_16x16x32_bf16 v[70:73], v[172:175], v[212:215], v[70:73]
	v_mfma_f32_16x16x32_bf16 v[66:69], v[180:183], v[212:215], v[66:69]
	s_barrier
; __device__ __forceinline__ unsigned pk2(float lo, float hi) { const f32x2 v = {lo, hi}; return __builtin_bit_cast(unsigned, __builtin_convertvector(v, bf16x2_t)); }
; #define PG8_STAGE(bufoff, gbase, voff) do { _Pragma("unroll") for (int _i = 0; _i < 2; ++_i) \
;         __builtin_amdgcn_global_load_lds((const unsigned*)((const char*)(gbase) + (voff)[_i]), (LAS unsigned*)(lds + (bufoff) + ldsw + _i * 8192), 16, 0, 0); } while (0)
; #define PG8_LDA(dst, b, h) do { _Pragma("unroll") for (int m = 0; m < 4; ++m) _Pragma("unroll") for (int k = 0; k < 2; ++k) dst[m][k] = *(const LAS bf16x8*)(lds + PG8_SA(b, h) + aoff + m * 2048 + k * 1024); } while (0)
; #define PG8_MMA(ai, bj, At, Bt) do { __builtin_amdgcn_s_setprio(1); _Pragma("unroll") for (int m = 0; m < 4; ++m) _Pragma("unroll") for (int n = 0; n < 2; ++n) _Pragma("unroll") for (int k = 0; k < 2; ++k) \
;         acc[ai][bj][m][n] = __builtin_amdgcn_mfma_f32_16x16x32_bf16(Bt[n][k], At[m][k], acc[ai][bj][m][n], 0, 0, 0); __builtin_amdgcn_s_setprio(0); } while (0)
; template <class Epi, class Sched, bool ABLK = false, bool ALIGN_EPI = true, bool SP2 = true, bool BBLK = true>
; __device__ __forceinline__ void gemm_phase(LAS unsigned char* lds, const Gemm g, const Sched& S, const Epi& E) {
;     ...
;             PG8_LDA(At, 1, 1); PG8_STAGE(PG8_SB(1, 0), b3, voffB); PG8_STAGE(PG8_SB(1, 1), b3 + hstepB, voffB); PG8_STAGE(PG8_SA(1, 0), a3, voffA);
;             PG8_WAIT_V(8); PG8_WAIT_L(0); PG8_BAR; PG8_MMA(1, 0, At, B0); PG8_MMA(1, 1, At, B1); PG8_BAR; PG8_SCHED;
;     __device__ __forceinline__ void operator()(const f32x4 (&acc)[2][2][4][2], const Unit& u, int wr, int wc, int fr, int fq) const {
;         const int row0 = u.pm * 256 + wr * 64 + fr, col0 = u.pn * 256 + wc * 64 + 8 * fq;
;         bf16_t* base = u.part == 0 ? Z + (size_t)row0 * D + col0 : P + ((size_t)(u.part - 1) * MS + (row0 - MP)) * D + col0;
; #pragma unroll
;         for (int ai = 0; ai < 2; ++ai)
; #pragma unroll
;             for (int m = 0; m < 4; ++m) { u32x4 w[2];
; #pragma unroll
;                 for (int bj = 0; bj < 2; ++bj) { const f32x4 v0 = acc[ai][bj][m][0], v1 = acc[ai][bj][m][1]; w[bj].x = pk2(v0[0], v0[1]); w[bj].y = pk2(v0[2], v0[3]); w[bj].z = pk2(v1[0], v1[1]); w[bj].w = pk2(v1[2], v1[3]); }
;                 store_pair((unsigned char*)(base + (size_t)(ai * 128 + m * 16) * D), (size_t)8 * D * 2, 64, w[0], w[1], fr >= 8); }
	s_add_u32 s48, s46, 0x8000
	s_addc_u32 s49, s47, 0
	s_add_i32 s81, s60, s51
	s_mov_b32 m0, s81
	ds_read_b128 v[184:187], v150 offset:49152
	ds_read_b128 v[188:191], v150 offset:50176
	ds_read_b128 v[192:195], v150 offset:51200
	ds_read_b128 v[196:199], v150 offset:52224
	ds_read_b128 v[200:203], v150 offset:53248
	ds_read_b128 v[204:207], v150 offset:54272
	ds_read_b128 v[208:211], v150 offset:55296
	ds_read_b128 v[212:215], v150 offset:56320
	global_load_lds_dwordx4 v130, s[48:49]
	s_add_i32 m0, s81, 0x2000
	s_add_u32 s46, s46, 0xc000
	v_lshl_add_u64 v[216:217], s[48:49], 0, v[132:133]
	s_addc_u32 s47, s47, 0
	s_add_i32 s48, s61, s51
	global_load_lds_dwordx4 v[216:217], off
	s_mov_b32 m0, s48
	s_nop 0
	global_load_lds_dwordx4 v130, s[46:47]
	s_add_i32 m0, s48, 0x2000
	s_nop 0
	global_load_lds_dwordx4 v132, s[46:47]
	s_mov_b32 m0, s56
	s_nop 0
	global_load_lds_dwordx4 v130, s[42:43]
	s_mov_b32 m0, s57
	s_nop 0
	global_load_lds_dwordx4 v132, s[42:43]
	s_waitcnt vmcnt(8) lgkmcnt(0)
	s_barrier
	v_mfma_f32_16x16x32_bf16 v[62:65], v[152:155], v[184:187], v[62:65]
	v_mfma_f32_16x16x32_bf16 v[58:61], v[160:163], v[184:187], v[58:61]
	v_mfma_f32_16x16x32_bf16 v[46:49], v[152:155], v[192:195], v[46:49]
	v_mfma_f32_16x16x32_bf16 v[42:45], v[160:163], v[192:195], v[42:45]
	v_mfma_f32_16x16x32_bf16 v[30:33], v[152:155], v[200:203], v[30:33]
	v_mfma_f32_16x16x32_bf16 v[26:29], v[160:163], v[200:203], v[26:29]
	v_mfma_f32_16x16x32_bf16 v[14:17], v[152:155], v[208:211], v[14:17]
	v_mfma_f32_16x16x32_bf16 v[10:13], v[160:163], v[208:211], v[10:13]
	v_mfma_f32_16x16x32_bf16 v[62:65], v[156:159], v[188:191], v[62:65]
	v_mfma_f32_16x16x32_bf16 v[58:61], v[164:167], v[188:191], v[58:61]
	v_mfma_f32_16x16x32_bf16 v[46:49], v[156:159], v[196:199], v[46:49]
	v_mfma_f32_16x16x32_bf16 v[42:45], v[164:167], v[196:199], v[42:45]
	v_mfma_f32_16x16x32_bf16 v[30:33], v[156:159], v[204:207], v[30:33]
	v_mfma_f32_16x16x32_bf16 v[26:29], v[164:167], v[204:207], v[26:29]
	v_mfma_f32_16x16x32_bf16 v[14:17], v[156:159], v[212:215], v[14:17]
	v_mfma_f32_16x16x32_bf16 v[10:13], v[164:167], v[212:215], v[10:13]
	v_mfma_f32_16x16x32_bf16 v[54:57], v[168:171], v[184:187], v[54:57]
	v_mfma_f32_16x16x32_bf16 v[50:53], v[176:179], v[184:187], v[50:53]
	v_mfma_f32_16x16x32_bf16 v[38:41], v[168:171], v[192:195], v[38:41]
	v_mfma_f32_16x16x32_bf16 v[34:37], v[176:179], v[192:195], v[34:37]
	v_mfma_f32_16x16x32_bf16 v[22:25], v[168:171], v[200:203], v[22:25]
	v_mfma_f32_16x16x32_bf16 v[18:21], v[176:179], v[200:203], v[18:21]
	v_mfma_f32_16x16x32_bf16 v[6:9], v[168:171], v[208:211], v[6:9]
	v_mfma_f32_16x16x32_bf16 v[2:5], v[176:179], v[208:211], v[2:5]
	v_mfma_f32_16x16x32_bf16 v[54:57], v[172:175], v[188:191], v[54:57]
	v_mfma_f32_16x16x32_bf16 v[50:53], v[180:183], v[188:191], v[50:53]
	v_mfma_f32_16x16x32_bf16 v[38:41], v[172:175], v[196:199], v[38:41]
	v_mfma_f32_16x16x32_bf16 v[34:37], v[180:183], v[196:199], v[34:37]
	v_mfma_f32_16x16x32_bf16 v[22:25], v[172:175], v[204:207], v[22:25]
	v_mfma_f32_16x16x32_bf16 v[18:21], v[180:183], v[204:207], v[18:21]
	v_mfma_f32_16x16x32_bf16 v[6:9], v[172:175], v[212:215], v[6:9]
	v_mfma_f32_16x16x32_bf16 v[2:5], v[180:183], v[212:215], v[2:5]
	s_barrier
	s_add_u32 s40, s40, 0x10000
	s_addc_u32 s41, s41, 0
	s_cmp_ge_u32 s79, s59
	s_cbranch_scc0 .LBB0_540
	v_lshl_add_u32 v143, s62, 8, v1
	v_add_u32_e32 v144, 0xffffe000, v143
	v_sub_co_u32_e64 v142, vcc, s58, 1
	v_mov_b32_e32 v145, s17
	s_nop 0
	v_cndmask_b32_e32 v144, v144, v143, vcc
	v_ashrrev_i32_e32 v143, 31, v142
	v_lshlrev_b64 v[142:143], 23, v[142:143]
	v_lshl_add_u64 v[142:143], s[10:11], 0, v[142:143]
	v_cndmask_b32_e32 v143, v143, v145, vcc
	v_mov_b32_e32 v145, s16
	v_cndmask_b32_e32 v142, v142, v145, vcc
	v_ashrrev_i32_e32 v145, 31, v144
	v_lshl_or_b32 v152, s78, 8, v147
	v_lshlrev_b64 v[144:145], 12, v[144:145]
	v_lshl_add_u64 v[142:143], v[142:143], 0, v[144:145]
	v_ashrrev_i32_e32 v153, 31, v152
	v_cvt_pk_bf16_f32 v126, v126, v127
	v_cvt_pk_bf16_f32 v127, v128, v129
	v_cvt_pk_bf16_f32 v128, v122, v123
	v_cvt_pk_bf16_f32 v124, v124, v125
	v_cvt_pk_bf16_f32 v118, v118, v119
	v_cvt_pk_bf16_f32 v119, v120, v121
	v_cvt_pk_bf16_f32 v114, v114, v115
	v_cvt_pk_bf16_f32 v115, v116, v117
	v_lshl_add_u64 v[142:143], v[152:153], 1, v[142:143]
	v_mov_b32_dpp v120, v126 row_ror:8 row_mask:0xf bank_mask:0xf bound_ctrl:1
	v_mov_b32_dpp v121, v127 row_ror:8 row_mask:0xf bank_mask:0xf bound_ctrl:1
	v_mov_b32_dpp v116, v128 row_ror:8 row_mask:0xf bank_mask:0xf bound_ctrl:1
	v_mov_b32_dpp v117, v124 row_ror:8 row_mask:0xf bank_mask:0xf bound_ctrl:1
	v_mov_b32_dpp v125, v118 row_ror:8 row_mask:0xf bank_mask:0xf bound_ctrl:1
	v_mov_b32_dpp v129, v119 row_ror:8 row_mask:0xf bank_mask:0xf bound_ctrl:1
	v_mov_b32_dpp v144, v114 row_ror:8 row_mask:0xf bank_mask:0xf bound_ctrl:1
	v_mov_b32_dpp v145, v115 row_ror:8 row_mask:0xf bank_mask:0xf bound_ctrl:1
	v_lshl_add_u64 v[122:123], v[142:143], 0, v[134:135]
	v_cndmask_b32_e64 v117, v117, v115, s[6:7]
	v_cndmask_b32_e64 v116, v116, v114, s[6:7]
	v_cndmask_b32_e64 v115, v121, v119, s[6:7]
	v_cndmask_b32_e64 v114, v120, v118, s[6:7]
	v_cndmask_b32_e64 v121, v124, v145, s[6:7]
	v_cndmask_b32_e64 v120, v128, v144, s[6:7]
	v_cndmask_b32_e64 v119, v127, v129, s[6:7]
	v_cndmask_b32_e64 v118, v126, v125, s[6:7]
	v_cvt_pk_bf16_f32 v110, v110, v111
	v_cvt_pk_bf16_f32 v111, v112, v113
	v_cvt_pk_bf16_f32 v112, v106, v107
	v_cvt_pk_bf16_f32 v113, v108, v109
	v_cvt_pk_bf16_f32 v102, v102, v103
	v_cvt_pk_bf16_f32 v103, v104, v105
	v_cvt_pk_bf16_f32 v98, v98, v99
	v_cvt_pk_bf16_f32 v99, v100, v101
	v_lshl_add_u64 v[124:125], v[142:143], 0, v[136:137]
; __device__ __forceinline__ unsigned pk2(float lo, float hi) { const f32x2 v = {lo, hi}; return __builtin_bit_cast(unsigned, __builtin_convertvector(v, bf16x2_t)); }
; __device__ __forceinline__ u32x4 ror8(u32x4 v) { u32x4 r;
; #pragma unroll
;     for (int i = 0; i < 4; ++i) r[i] = (unsigned)__builtin_amdgcn_mov_dpp((int)v[i], 0x128, 0xf, 0xf, true);
;     return r; }
; __device__ __forceinline__ void store_pair(unsigned char* own, size_t stride8, int hi_off, u32x4 lo, u32x4 hi, bool upper) {
;     const u32x4 tlo = ror8(lo), thi = ror8(hi);
;     const u32x4 A = upper ? thi : lo, B = upper ? hi : tlo;
;     unsigned char* pa = upper ? own - stride8 + hi_off : own;
;     unsigned char* pb = upper ? own + hi_off : own + stride8;
;     *(u32x4*)pa = A; *(u32x4*)pb = B;
;     __device__ __forceinline__ void operator()(const f32x4 (&acc)[2][2][4][2], const Unit& u, int wr, int wc, int fr, int fq) const {
;         const int row0 = u.pm * 256 + wr * 64 + fr, col0 = u.pn * 256 + wc * 64 + 8 * fq;
;         bf16_t* base = u.part == 0 ? Z + (size_t)row0 * D + col0 : P + ((size_t)(u.part - 1) * MS + (row0 - MP)) * D + col0;
; #pragma unroll
;         for (int ai = 0; ai < 2; ++ai)
; #pragma unroll
;             for (int m = 0; m < 4; ++m) { u32x4 w[2];
; #pragma unroll
;                 for (int bj = 0; bj < 2; ++bj) { const f32x4 v0 = acc[ai][bj][m][0], v1 = acc[ai][bj][m][1]; w[bj].x = pk2(v0[0], v0[1]); w[bj].y = pk2(v0[2], v0[3]); w[bj].z = pk2(v1[0], v1[1]); w[bj].w = pk2(v1[2], v1[3]); }
;                 store_pair((unsigned char*)(base + (size_t)(ai * 128 + m * 16) * D), (size_t)8 * D * 2, 64, w[0], w[1], fr >= 8); }
	global_store_dwordx4 v[122:123], v[118:121], off
	global_store_dwordx4 v[124:125], v[114:117], off
	v_lshl_add_u64 v[106:107], v[142:143], 0, s[14:15]
	v_mov_b32_dpp v104, v110 row_ror:8 row_mask:0xf bank_mask:0xf bound_ctrl:1
	v_mov_b32_dpp v105, v111 row_ror:8 row_mask:0xf bank_mask:0xf bound_ctrl:1
	v_mov_b32_dpp v100, v112 row_ror:8 row_mask:0xf bank_mask:0xf bound_ctrl:1
	v_mov_b32_dpp v101, v113 row_ror:8 row_mask:0xf bank_mask:0xf bound_ctrl:1
	v_mov_b32_dpp v114, v102 row_ror:8 row_mask:0xf bank_mask:0xf bound_ctrl:1
	v_mov_b32_dpp v115, v103 row_ror:8 row_mask:0xf bank_mask:0xf bound_ctrl:1
	v_mov_b32_dpp v116, v98 row_ror:8 row_mask:0xf bank_mask:0xf bound_ctrl:1
	v_mov_b32_dpp v117, v99 row_ror:8 row_mask:0xf bank_mask:0xf bound_ctrl:1
	v_lshl_add_u64 v[108:109], v[106:107], 0, v[134:135]
	v_cndmask_b32_e64 v101, v101, v99, s[6:7]
	v_cndmask_b32_e64 v100, v100, v98, s[6:7]
	v_cndmask_b32_e64 v99, v105, v103, s[6:7]
	v_cndmask_b32_e64 v98, v104, v102, s[6:7]
	v_cndmask_b32_e64 v105, v113, v117, s[6:7]
	v_cndmask_b32_e64 v104, v112, v116, s[6:7]
	v_cndmask_b32_e64 v103, v111, v115, s[6:7]
	v_cndmask_b32_e64 v102, v110, v114, s[6:7]
	v_cvt_pk_bf16_f32 v94, v94, v95
	v_cvt_pk_bf16_f32 v95, v96, v97
	v_cvt_pk_bf16_f32 v96, v90, v91
	v_cvt_pk_bf16_f32 v97, v92, v93
	v_cvt_pk_bf16_f32 v86, v86, v87
	v_cvt_pk_bf16_f32 v87, v88, v89
	v_cvt_pk_bf16_f32 v82, v82, v83
	v_cvt_pk_bf16_f32 v83, v84, v85
	v_lshl_add_u64 v[106:107], v[106:107], 0, v[136:137]
	global_store_dwordx4 v[108:109], v[102:105], off
	global_store_dwordx4 v[106:107], v[98:101], off
	v_lshl_add_u64 v[90:91], v[142:143], 0, s[18:19]
	v_mov_b32_dpp v88, v94 row_ror:8 row_mask:0xf bank_mask:0xf bound_ctrl:1
	v_mov_b32_dpp v89, v95 row_ror:8 row_mask:0xf bank_mask:0xf bound_ctrl:1
	v_mov_b32_dpp v84, v96 row_ror:8 row_mask:0xf bank_mask:0xf bound_ctrl:1
	v_mov_b32_dpp v85, v97 row_ror:8 row_mask:0xf bank_mask:0xf bound_ctrl:1
	v_mov_b32_dpp v98, v86 row_ror:8 row_mask:0xf bank_mask:0xf bound_ctrl:1
	v_mov_b32_dpp v99, v87 row_ror:8 row_mask:0xf bank_mask:0xf bound_ctrl:1
	v_mov_b32_dpp v100, v82 row_ror:8 row_mask:0xf bank_mask:0xf bound_ctrl:1
	v_mov_b32_dpp v101, v83 row_ror:8 row_mask:0xf bank_mask:0xf bound_ctrl:1
	v_lshl_add_u64 v[92:93], v[90:91], 0, v[134:135]
	v_cndmask_b32_e64 v85, v85, v83, s[6:7]
	v_cndmask_b32_e64 v84, v84, v82, s[6:7]
	v_cndmask_b32_e64 v83, v89, v87, s[6:7]
	v_cndmask_b32_e64 v82, v88, v86, s[6:7]
	v_cndmask_b32_e64 v89, v97, v101, s[6:7]
	v_cndmask_b32_e64 v88, v96, v100, s[6:7]
	v_cndmask_b32_e64 v87, v95, v99, s[6:7]
	v_cndmask_b32_e64 v86, v94, v98, s[6:7]
	v_cvt_pk_bf16_f32 v78, v78, v79
	v_cvt_pk_bf16_f32 v79, v80, v81
	v_cvt_pk_bf16_f32 v80, v74, v75
	v_cvt_pk_bf16_f32 v81, v76, v77
	v_cvt_pk_bf16_f32 v70, v70, v71
	v_cvt_pk_bf16_f32 v71, v72, v73
	v_cvt_pk_bf16_f32 v66, v66, v67
	v_cvt_pk_bf16_f32 v67, v68, v69
	v_lshl_add_u64 v[90:91], v[90:91], 0, v[136:137]
	global_store_dwordx4 v[92:93], v[86:89], off
	global_store_dwordx4 v[90:91], v[82:85], off
	v_lshl_add_u64 v[74:75], v[142:143], 0, s[20:21]
	v_mov_b32_dpp v72, v78 row_ror:8 row_mask:0xf bank_mask:0xf bound_ctrl:1
	v_mov_b32_dpp v73, v79 row_ror:8 row_mask:0xf bank_mask:0xf bound_ctrl:1
	v_mov_b32_dpp v68, v80 row_ror:8 row_mask:0xf bank_mask:0xf bound_ctrl:1
	v_mov_b32_dpp v69, v81 row_ror:8 row_mask:0xf bank_mask:0xf bound_ctrl:1
	v_mov_b32_dpp v82, v70 row_ror:8 row_mask:0xf bank_mask:0xf bound_ctrl:1
	v_mov_b32_dpp v83, v71 row_ror:8 row_mask:0xf bank_mask:0xf bound_ctrl:1
	v_mov_b32_dpp v84, v66 row_ror:8 row_mask:0xf bank_mask:0xf bound_ctrl:1
	v_mov_b32_dpp v85, v67 row_ror:8 row_mask:0xf bank_mask:0xf bound_ctrl:1
	v_lshl_add_u64 v[76:77], v[74:75], 0, v[134:135]
	v_cndmask_b32_e64 v69, v69, v67, s[6:7]
	v_cndmask_b32_e64 v68, v68, v66, s[6:7]
	v_cndmask_b32_e64 v67, v73, v71, s[6:7]
	v_cndmask_b32_e64 v66, v72, v70, s[6:7]
	v_cndmask_b32_e64 v73, v81, v85, s[6:7]
	v_cndmask_b32_e64 v72, v80, v84, s[6:7]
	v_cndmask_b32_e64 v71, v79, v83, s[6:7]
	v_cndmask_b32_e64 v70, v78, v82, s[6:7]
	v_cvt_pk_bf16_f32 v62, v62, v63
	v_cvt_pk_bf16_f32 v63, v64, v65
	v_cvt_pk_bf16_f32 v64, v58, v59
	v_cvt_pk_bf16_f32 v65, v60, v61
	v_cvt_pk_bf16_f32 v54, v54, v55
	v_cvt_pk_bf16_f32 v55, v56, v57
	v_cvt_pk_bf16_f32 v50, v50, v51
	v_cvt_pk_bf16_f32 v51, v52, v53
	v_lshl_add_u64 v[74:75], v[74:75], 0, v[136:137]
	global_store_dwordx4 v[76:77], v[70:73], off
	global_store_dwordx4 v[74:75], v[66:69], off
	v_lshl_add_u64 v[58:59], v[142:143], 0, s[22:23]
	v_mov_b32_dpp v56, v62 row_ror:8 row_mask:0xf bank_mask:0xf bound_ctrl:1
	v_mov_b32_dpp v57, v63 row_ror:8 row_mask:0xf bank_mask:0xf bound_ctrl:1
	v_mov_b32_dpp v52, v64 row_ror:8 row_mask:0xf bank_mask:0xf bound_ctrl:1
	v_mov_b32_dpp v53, v65 row_ror:8 row_mask:0xf bank_mask:0xf bound_ctrl:1
	v_mov_b32_dpp v66, v54 row_ror:8 row_mask:0xf bank_mask:0xf bound_ctrl:1
	v_mov_b32_dpp v67, v55 row_ror:8 row_mask:0xf bank_mask:0xf bound_ctrl:1
	v_mov_b32_dpp v68, v50 row_ror:8 row_mask:0xf bank_mask:0xf bound_ctrl:1
	v_mov_b32_dpp v69, v51 row_ror:8 row_mask:0xf bank_mask:0xf bound_ctrl:1
; __device__ __forceinline__ unsigned pk2(float lo, float hi) { const f32x2 v = {lo, hi}; return __builtin_bit_cast(unsigned, __builtin_convertvector(v, bf16x2_t)); }
; #define PG8_BAR __builtin_amdgcn_s_barrier()
; template <class Epi, class Sched, bool ABLK = false, bool ALIGN_EPI = true, bool SP2 = true, bool BBLK = true>
; __device__ __forceinline__ void gemm_phase(LAS unsigned char* lds, const Gemm g, const Sched& S, const Epi& E) {
;     ...
;         if constexpr (ALIGN_EPI) { if (wr == 0) PG8_BAR; }
;     __device__ __forceinline__ void operator()(const f32x4 (&acc)[2][2][4][2], const Unit& u, int wr, int wc, int fr, int fq) const {
;     ...
;         for (int ai = 0; ai < 2; ++ai)
; #pragma unroll
;             for (int m = 0; m < 4; ++m) { u32x4 w[2];
; #pragma unroll
;                 for (int bj = 0; bj < 2; ++bj) { const f32x4 v0 = acc[ai][bj][m][0], v1 = acc[ai][bj][m][1]; w[bj].x = pk2(v0[0], v0[1]); w[bj].y = pk2(v0[2], v0[3]); w[bj].z = pk2(v1[0], v1[1]); w[bj].w = pk2(v1[2], v1[3]); }
;                 store_pair((unsigned char*)(base + (size_t)(ai * 128 + m * 16) * D), (size_t)8 * D * 2, 64, w[0], w[1], fr >= 8); }
	v_lshl_add_u64 v[60:61], v[58:59], 0, v[134:135]
	v_cndmask_b32_e64 v53, v53, v51, s[6:7]
	v_cndmask_b32_e64 v52, v52, v50, s[6:7]
	v_cndmask_b32_e64 v51, v57, v55, s[6:7]
	v_cndmask_b32_e64 v50, v56, v54, s[6:7]
	v_cndmask_b32_e64 v57, v65, v69, s[6:7]
	v_cndmask_b32_e64 v56, v64, v68, s[6:7]
	v_cndmask_b32_e64 v55, v63, v67, s[6:7]
	v_cndmask_b32_e64 v54, v62, v66, s[6:7]
	v_cvt_pk_bf16_f32 v46, v46, v47
	v_cvt_pk_bf16_f32 v47, v48, v49
	v_cvt_pk_bf16_f32 v48, v42, v43
	v_cvt_pk_bf16_f32 v49, v44, v45
	v_cvt_pk_bf16_f32 v38, v38, v39
	v_cvt_pk_bf16_f32 v39, v40, v41
	v_cvt_pk_bf16_f32 v34, v34, v35
	v_cvt_pk_bf16_f32 v35, v36, v37
	v_lshl_add_u64 v[58:59], v[58:59], 0, v[136:137]
	global_store_dwordx4 v[60:61], v[54:57], off
	global_store_dwordx4 v[58:59], v[50:53], off
	v_lshl_add_u64 v[42:43], v[142:143], 0, s[24:25]
	v_mov_b32_dpp v40, v46 row_ror:8 row_mask:0xf bank_mask:0xf bound_ctrl:1
	v_mov_b32_dpp v41, v47 row_ror:8 row_mask:0xf bank_mask:0xf bound_ctrl:1
	v_mov_b32_dpp v36, v48 row_ror:8 row_mask:0xf bank_mask:0xf bound_ctrl:1
	v_mov_b32_dpp v37, v49 row_ror:8 row_mask:0xf bank_mask:0xf bound_ctrl:1
	v_mov_b32_dpp v50, v38 row_ror:8 row_mask:0xf bank_mask:0xf bound_ctrl:1
	v_mov_b32_dpp v51, v39 row_ror:8 row_mask:0xf bank_mask:0xf bound_ctrl:1
	v_mov_b32_dpp v52, v34 row_ror:8 row_mask:0xf bank_mask:0xf bound_ctrl:1
	v_mov_b32_dpp v53, v35 row_ror:8 row_mask:0xf bank_mask:0xf bound_ctrl:1
	v_lshl_add_u64 v[44:45], v[42:43], 0, v[134:135]
	v_cndmask_b32_e64 v37, v37, v35, s[6:7]
	v_cndmask_b32_e64 v36, v36, v34, s[6:7]
	v_cndmask_b32_e64 v35, v41, v39, s[6:7]
	v_cndmask_b32_e64 v34, v40, v38, s[6:7]
	v_cndmask_b32_e64 v41, v49, v53, s[6:7]
	v_cndmask_b32_e64 v40, v48, v52, s[6:7]
	v_cndmask_b32_e64 v39, v47, v51, s[6:7]
	v_cndmask_b32_e64 v38, v46, v50, s[6:7]
	v_cvt_pk_bf16_f32 v30, v30, v31
	v_cvt_pk_bf16_f32 v31, v32, v33
	v_cvt_pk_bf16_f32 v32, v26, v27
	v_cvt_pk_bf16_f32 v33, v28, v29
	v_cvt_pk_bf16_f32 v22, v22, v23
	v_cvt_pk_bf16_f32 v23, v24, v25
	v_cvt_pk_bf16_f32 v18, v18, v19
	v_cvt_pk_bf16_f32 v19, v20, v21
	v_lshl_add_u64 v[42:43], v[42:43], 0, v[136:137]
	global_store_dwordx4 v[44:45], v[38:41], off
	global_store_dwordx4 v[42:43], v[34:37], off
	v_lshl_add_u64 v[26:27], v[142:143], 0, s[26:27]
	v_mov_b32_dpp v24, v30 row_ror:8 row_mask:0xf bank_mask:0xf bound_ctrl:1
	v_mov_b32_dpp v25, v31 row_ror:8 row_mask:0xf bank_mask:0xf bound_ctrl:1
	v_mov_b32_dpp v20, v32 row_ror:8 row_mask:0xf bank_mask:0xf bound_ctrl:1
	v_mov_b32_dpp v21, v33 row_ror:8 row_mask:0xf bank_mask:0xf bound_ctrl:1
	v_mov_b32_dpp v34, v22 row_ror:8 row_mask:0xf bank_mask:0xf bound_ctrl:1
	v_mov_b32_dpp v35, v23 row_ror:8 row_mask:0xf bank_mask:0xf bound_ctrl:1
	v_mov_b32_dpp v36, v18 row_ror:8 row_mask:0xf bank_mask:0xf bound_ctrl:1
	v_mov_b32_dpp v37, v19 row_ror:8 row_mask:0xf bank_mask:0xf bound_ctrl:1
	v_lshl_add_u64 v[28:29], v[26:27], 0, v[134:135]
	v_cndmask_b32_e64 v21, v21, v19, s[6:7]
	v_cndmask_b32_e64 v20, v20, v18, s[6:7]
	v_cndmask_b32_e64 v19, v25, v23, s[6:7]
	v_cndmask_b32_e64 v18, v24, v22, s[6:7]
	v_cndmask_b32_e64 v25, v33, v37, s[6:7]
	v_cndmask_b32_e64 v24, v32, v36, s[6:7]
	v_cndmask_b32_e64 v23, v31, v35, s[6:7]
	v_cndmask_b32_e64 v22, v30, v34, s[6:7]
	v_cvt_pk_bf16_f32 v14, v14, v15
	v_cvt_pk_bf16_f32 v15, v16, v17
	v_cvt_pk_bf16_f32 v16, v10, v11
	v_cvt_pk_bf16_f32 v17, v12, v13
	v_cvt_pk_bf16_f32 v6, v6, v7
	v_cvt_pk_bf16_f32 v7, v8, v9
	v_cvt_pk_bf16_f32 v2, v2, v3
	v_cvt_pk_bf16_f32 v3, v4, v5
	v_lshl_add_u64 v[26:27], v[26:27], 0, v[136:137]
	global_store_dwordx4 v[28:29], v[22:25], off
	global_store_dwordx4 v[26:27], v[18:21], off
	v_lshl_add_u64 v[10:11], v[142:143], 0, s[28:29]
	v_mov_b32_dpp v8, v14 row_ror:8 row_mask:0xf bank_mask:0xf bound_ctrl:1
	v_mov_b32_dpp v9, v15 row_ror:8 row_mask:0xf bank_mask:0xf bound_ctrl:1
	v_mov_b32_dpp v4, v16 row_ror:8 row_mask:0xf bank_mask:0xf bound_ctrl:1
	v_mov_b32_dpp v5, v17 row_ror:8 row_mask:0xf bank_mask:0xf bound_ctrl:1
	v_mov_b32_dpp v18, v6 row_ror:8 row_mask:0xf bank_mask:0xf bound_ctrl:1
	v_mov_b32_dpp v19, v7 row_ror:8 row_mask:0xf bank_mask:0xf bound_ctrl:1
	v_mov_b32_dpp v20, v2 row_ror:8 row_mask:0xf bank_mask:0xf bound_ctrl:1
	v_mov_b32_dpp v21, v3 row_ror:8 row_mask:0xf bank_mask:0xf bound_ctrl:1
	v_lshl_add_u64 v[12:13], v[10:11], 0, v[134:135]
	v_cndmask_b32_e64 v5, v5, v3, s[6:7]
	v_cndmask_b32_e64 v4, v4, v2, s[6:7]
	v_cndmask_b32_e64 v3, v9, v7, s[6:7]
	v_cndmask_b32_e64 v2, v8, v6, s[6:7]
	v_cndmask_b32_e64 v9, v17, v21, s[6:7]
	v_cndmask_b32_e64 v8, v16, v20, s[6:7]
	v_cndmask_b32_e64 v7, v15, v19, s[6:7]
	v_cndmask_b32_e64 v6, v14, v18, s[6:7]
	s_and_b64 vcc, exec, s[12:13]
	s_cbranch_vccz .LBB0_543
	s_barrier
.LBB0_543:
	s_and_b64 vcc, exec, s[8:9]
	s_mov_b64 s[8:9], -1
	v_lshl_add_u64 v[10:11], v[10:11], 0, v[136:137]
	global_store_dwordx4 v[12:13], v[6:9], off
	global_store_dwordx4 v[10:11], v[2:5], off
	s_cbranch_vccnz .LBB0_538
	s_andn2_b64 vcc, exec, s[2:3]
	s_cbranch_vccnz .LBB0_537
	s_barrier
	s_branch .LBB0_537

; #define PG8_STAGE(bufoff, gbase, voff) do { _Pragma("unroll") for (int _i = 0; _i < 2; ++_i) \
;         __builtin_amdgcn_global_load_lds((const unsigned*)((const char*)(gbase) + (voff)[_i]), (LAS unsigned*)(lds + (bufoff) + ldsw + _i * 8192), 16, 0, 0); } while (0)
; #define PG8_LDA(dst, b, h) do { _Pragma("unroll") for (int m = 0; m < 4; ++m) _Pragma("unroll") for (int k = 0; k < 2; ++k) dst[m][k] = *(const LAS bf16x8*)(lds + PG8_SA(b, h) + aoff + m * 2048 + k * 1024); } while (0)
; #define PG8_LDB(dst, b, h) do { _Pragma("unroll") for (int n = 0; n < 2; ++n) _Pragma("unroll") for (int k = 0; k < 2; ++k) dst[n][k] = *(const LAS bf16x8*)(lds + PG8_SB(b, h) + boff + n * 2048 + k * 1024); } while (0)
; #define PG8_MMA(ai, bj, At, Bt) do { __builtin_amdgcn_s_setprio(1); _Pragma("unroll") for (int m = 0; m < 4; ++m) _Pragma("unroll") for (int n = 0; n < 2; ++n) _Pragma("unroll") for (int k = 0; k < 2; ++k) \
;         acc[ai][bj][m][n] = __builtin_amdgcn_mfma_f32_16x16x32_bf16(Bt[n][k], At[m][k], acc[ai][bj][m][n], 0, 0, 0); __builtin_amdgcn_s_setprio(0); } while (0)
; #define PG8_WAIT_V(n) asm volatile("s_waitcnt vmcnt(" #n ")" ::: "memory")
; #define PG8_WAIT_L(n) asm volatile("s_waitcnt lgkmcnt(" #n ")" ::: "memory")
; #define PG8_BAR __builtin_amdgcn_s_barrier()
; #define PG8_SCHED __builtin_amdgcn_sched_barrier(0)
; template <class Epi, class Sched, bool ABLK = false, bool ALIGN_EPI = true, bool SP2 = true, bool BBLK = true>
; __device__ __forceinline__ void gemm_phase(LAS unsigned char* lds, const Gemm g, const Sched& S, const Epi& E) {
;     ...
;             if constexpr (SP2) {
;             PG8_LDB(B0, 0, 0); PG8_LDB(B1, 0, 1); PG8_SCHED; PG8_LDA(At, 0, 0); PG8_STAGE(PG8_SA(1, 1), a1 + hstepA, voffA);
;             PG8_WAIT_V(8); PG8_WAIT_L(0); PG8_BAR; PG8_MMA(0, 0, At, B0); PG8_MMA(0, 1, At, B1); PG8_BAR; PG8_SCHED;
;             PG8_LDA(At, 0, 1); PG8_STAGE(PG8_SB(0, 0), b2, voffB); PG8_STAGE(PG8_SB(0, 1), b2 + hstepB, voffB); PG8_STAGE(PG8_SA(0, 0), a2, voffA);
;             PG8_WAIT_V(8); PG8_WAIT_L(0); PG8_BAR; PG8_MMA(1, 0, At, B0); PG8_MMA(1, 1, At, B1); PG8_BAR; PG8_SCHED;
.LBB0_1038:
	ds_read_b128 v[156:159], v153
	ds_read_b128 v[160:163], v153 offset:1024
	ds_read_b128 v[164:167], v153 offset:2048
	ds_read_b128 v[168:171], v153 offset:3072
	ds_read_b128 v[172:175], v154
	ds_read_b128 v[176:179], v154 offset:1024
	ds_read_b128 v[180:183], v154 offset:2048
	ds_read_b128 v[184:187], v154 offset:3072
	s_add_u32 s22, s56, s20
	s_addc_u32 s23, s57, s21
	s_add_u32 s26, s22, 0x100
	s_addc_u32 s27, s23, 0
	s_add_i32 s65, s65, 2
	s_add_u32 s22, s22, 0x180
	s_addc_u32 s23, s23, 0
	s_cmp_eq_u32 s64, s20
	s_cselect_b32 s23, s50, s23
	s_cselect_b32 s22, s49, s22
	s_cselect_b32 s25, s4, s55
	s_cselect_b32 s24, s5, s51
	s_cselect_b32 s27, s48, s27
	s_cselect_b32 s26, s17, s26
	v_lshl_add_u64 v[220:221], v[146:147], 0, s[20:21]
	s_add_i32 m0, s35, 0xc000
	ds_read_b128 v[188:191], v155
	ds_read_b128 v[192:195], v155 offset:1024
	ds_read_b128 v[196:199], v155 offset:2048
	ds_read_b128 v[200:203], v155 offset:3072
	ds_read_b128 v[204:207], v155 offset:4096
	ds_read_b128 v[208:211], v155 offset:5120
	ds_read_b128 v[212:215], v155 offset:6144
	ds_read_b128 v[216:219], v155 offset:7168
	global_load_lds_dwordx4 v[220:221], off
	v_lshl_add_u64 v[220:221], v[148:149], 0, s[20:21]
	s_add_i32 m0, s35, 0xe000
	s_nop 0
	global_load_lds_dwordx4 v[220:221], off
	s_waitcnt vmcnt(8) lgkmcnt(0)
	s_barrier
	v_mfma_f32_16x16x32_bf16 v[126:129], v[156:159], v[188:191], v[126:129]
	v_mfma_f32_16x16x32_bf16 v[122:125], v[164:167], v[188:191], v[122:125]
	v_mfma_f32_16x16x32_bf16 v[110:113], v[156:159], v[196:199], v[110:113]
	v_mfma_f32_16x16x32_bf16 v[106:109], v[164:167], v[196:199], v[106:109]
	v_mfma_f32_16x16x32_bf16 v[94:97], v[156:159], v[204:207], v[94:97]
	v_mfma_f32_16x16x32_bf16 v[90:93], v[164:167], v[204:207], v[90:93]
	v_mfma_f32_16x16x32_bf16 v[78:81], v[156:159], v[212:215], v[78:81]
	v_mfma_f32_16x16x32_bf16 v[74:77], v[164:167], v[212:215], v[74:77]
	v_mfma_f32_16x16x32_bf16 v[126:129], v[160:163], v[192:195], v[126:129]
	v_mfma_f32_16x16x32_bf16 v[122:125], v[168:171], v[192:195], v[122:125]
	v_mfma_f32_16x16x32_bf16 v[110:113], v[160:163], v[200:203], v[110:113]
	v_mfma_f32_16x16x32_bf16 v[106:109], v[168:171], v[200:203], v[106:109]
	v_mfma_f32_16x16x32_bf16 v[94:97], v[160:163], v[208:211], v[94:97]
	v_mfma_f32_16x16x32_bf16 v[90:93], v[168:171], v[208:211], v[90:93]
	v_mfma_f32_16x16x32_bf16 v[78:81], v[160:163], v[216:219], v[78:81]
	v_mfma_f32_16x16x32_bf16 v[74:77], v[168:171], v[216:219], v[74:77]
	v_mfma_f32_16x16x32_bf16 v[118:121], v[172:175], v[188:191], v[118:121]
	v_mfma_f32_16x16x32_bf16 v[114:117], v[180:183], v[188:191], v[114:117]
	v_mfma_f32_16x16x32_bf16 v[102:105], v[172:175], v[196:199], v[102:105]
	v_mfma_f32_16x16x32_bf16 v[98:101], v[180:183], v[196:199], v[98:101]
	v_mfma_f32_16x16x32_bf16 v[86:89], v[172:175], v[204:207], v[86:89]
	v_mfma_f32_16x16x32_bf16 v[82:85], v[180:183], v[204:207], v[82:85]
	v_mfma_f32_16x16x32_bf16 v[70:73], v[172:175], v[212:215], v[70:73]
	v_mfma_f32_16x16x32_bf16 v[66:69], v[180:183], v[212:215], v[66:69]
	v_mfma_f32_16x16x32_bf16 v[118:121], v[176:179], v[192:195], v[118:121]
	v_mfma_f32_16x16x32_bf16 v[114:117], v[184:187], v[192:195], v[114:117]
	v_mfma_f32_16x16x32_bf16 v[102:105], v[176:179], v[200:203], v[102:105]
	v_mfma_f32_16x16x32_bf16 v[98:101], v[184:187], v[200:203], v[98:101]
	v_mfma_f32_16x16x32_bf16 v[86:89], v[176:179], v[208:211], v[86:89]
	v_mfma_f32_16x16x32_bf16 v[82:85], v[184:187], v[208:211], v[82:85]
	v_mfma_f32_16x16x32_bf16 v[70:73], v[176:179], v[216:219], v[70:73]
	v_mfma_f32_16x16x32_bf16 v[66:69], v[184:187], v[216:219], v[66:69]
	s_barrier
	s_add_i32 s66, s72, s34
	s_mov_b32 m0, s66
	ds_read_b128 v[188:191], v155 offset:16384
	ds_read_b128 v[192:195], v155 offset:17408
	ds_read_b128 v[196:199], v155 offset:18432
	ds_read_b128 v[200:203], v155 offset:19456
	ds_read_b128 v[204:207], v155 offset:20480
	ds_read_b128 v[208:211], v155 offset:21504
	ds_read_b128 v[212:215], v155 offset:22528
	ds_read_b128 v[216:219], v155 offset:23552
	global_load_lds_dwordx4 v132, s[24:25]
	s_add_i32 m0, s66, 0x2000
	s_add_u32 s66, s24, 0x4000
	s_addc_u32 s67, s25, 0
	s_add_i32 s75, s73, s34
	global_load_lds_dwordx4 v136, s[24:25]
	s_mov_b32 m0, s75
	s_nop 0
	global_load_lds_dwordx4 v132, s[66:67]
	s_add_i32 m0, s75, 0x2000
	s_nop 0
	global_load_lds_dwordx4 v136, s[66:67]
	s_mov_b32 m0, s35
	s_nop 0
	global_load_lds_dwordx4 v130, s[26:27]
	s_mov_b32 m0, s36
	s_nop 0
	global_load_lds_dwordx4 v134, s[26:27]
	s_waitcnt vmcnt(8) lgkmcnt(0)
	s_barrier
	v_mfma_f32_16x16x32_bf16 v[62:65], v[156:159], v[188:191], v[62:65]
	v_mfma_f32_16x16x32_bf16 v[58:61], v[164:167], v[188:191], v[58:61]
	v_mfma_f32_16x16x32_bf16 v[46:49], v[156:159], v[196:199], v[46:49]
	v_mfma_f32_16x16x32_bf16 v[42:45], v[164:167], v[196:199], v[42:45]
	v_mfma_f32_16x16x32_bf16 v[30:33], v[156:159], v[204:207], v[30:33]
	v_mfma_f32_16x16x32_bf16 v[26:29], v[164:167], v[204:207], v[26:29]
	v_mfma_f32_16x16x32_bf16 v[14:17], v[156:159], v[212:215], v[14:17]
	v_mfma_f32_16x16x32_bf16 v[10:13], v[164:167], v[212:215], v[10:13]
	v_mfma_f32_16x16x32_bf16 v[62:65], v[160:163], v[192:195], v[62:65]
	v_mfma_f32_16x16x32_bf16 v[58:61], v[168:171], v[192:195], v[58:61]
	v_mfma_f32_16x16x32_bf16 v[46:49], v[160:163], v[200:203], v[46:49]
	v_mfma_f32_16x16x32_bf16 v[42:45], v[168:171], v[200:203], v[42:45]
	v_mfma_f32_16x16x32_bf16 v[30:33], v[160:163], v[208:211], v[30:33]
	v_mfma_f32_16x16x32_bf16 v[26:29], v[168:171], v[208:211], v[26:29]
	v_mfma_f32_16x16x32_bf16 v[14:17], v[160:163], v[216:219], v[14:17]
	v_mfma_f32_16x16x32_bf16 v[10:13], v[168:171], v[216:219], v[10:13]
	v_mfma_f32_16x16x32_bf16 v[54:57], v[172:175], v[188:191], v[54:57]
	v_mfma_f32_16x16x32_bf16 v[50:53], v[180:183], v[188:191], v[50:53]
	v_mfma_f32_16x16x32_bf16 v[38:41], v[172:175], v[196:199], v[38:41]
	v_mfma_f32_16x16x32_bf16 v[34:37], v[180:183], v[196:199], v[34:37]
	v_mfma_f32_16x16x32_bf16 v[22:25], v[172:175], v[204:207], v[22:25]
	v_mfma_f32_16x16x32_bf16 v[18:21], v[180:183], v[204:207], v[18:21]
	v_mfma_f32_16x16x32_bf16 v[6:9], v[172:175], v[212:215], v[6:9]
	v_mfma_f32_16x16x32_bf16 v[2:5], v[180:183], v[212:215], v[2:5]
	v_mfma_f32_16x16x32_bf16 v[54:57], v[176:179], v[192:195], v[54:57]
	v_mfma_f32_16x16x32_bf16 v[50:53], v[184:187], v[192:195], v[50:53]
	v_mfma_f32_16x16x32_bf16 v[38:41], v[176:179], v[200:203], v[38:41]
	v_mfma_f32_16x16x32_bf16 v[34:37], v[184:187], v[200:203], v[34:37]
	v_mfma_f32_16x16x32_bf16 v[22:25], v[176:179], v[208:211], v[22:25]
	v_mfma_f32_16x16x32_bf16 v[18:21], v[184:187], v[208:211], v[18:21]
	v_mfma_f32_16x16x32_bf16 v[6:9], v[176:179], v[216:219], v[6:9]
	v_mfma_f32_16x16x32_bf16 v[2:5], v[184:187], v[216:219], v[2:5]
	s_barrier
; #define PG8_STAGE(bufoff, gbase, voff) do { _Pragma("unroll") for (int _i = 0; _i < 2; ++_i) \
;         __builtin_amdgcn_global_load_lds((const unsigned*)((const char*)(gbase) + (voff)[_i]), (LAS unsigned*)(lds + (bufoff) + ldsw + _i * 8192), 16, 0, 0); } while (0)
; #define PG8_LDA(dst, b, h) do { _Pragma("unroll") for (int m = 0; m < 4; ++m) _Pragma("unroll") for (int k = 0; k < 2; ++k) dst[m][k] = *(const LAS bf16x8*)(lds + PG8_SA(b, h) + aoff + m * 2048 + k * 1024); } while (0)
; #define PG8_LDB(dst, b, h) do { _Pragma("unroll") for (int n = 0; n < 2; ++n) _Pragma("unroll") for (int k = 0; k < 2; ++k) dst[n][k] = *(const LAS bf16x8*)(lds + PG8_SB(b, h) + boff + n * 2048 + k * 1024); } while (0)
; #define PG8_MMA(ai, bj, At, Bt) do { __builtin_amdgcn_s_setprio(1); _Pragma("unroll") for (int m = 0; m < 4; ++m) _Pragma("unroll") for (int n = 0; n < 2; ++n) _Pragma("unroll") for (int k = 0; k < 2; ++k) \
;         acc[ai][bj][m][n] = __builtin_amdgcn_mfma_f32_16x16x32_bf16(Bt[n][k], At[m][k], acc[ai][bj][m][n], 0, 0, 0); __builtin_amdgcn_s_setprio(0); } while (0)
; #define PG8_WAIT_V(n) asm volatile("s_waitcnt vmcnt(" #n ")" ::: "memory")
; #define PG8_WAIT_L(n) asm volatile("s_waitcnt lgkmcnt(" #n ")" ::: "memory")
; #define PG8_BAR __builtin_amdgcn_s_barrier()
; #define PG8_SCHED __builtin_amdgcn_sched_barrier(0)
; template <class Epi, class Sched, bool ABLK = false, bool ALIGN_EPI = true, bool SP2 = true, bool BBLK = true>
; __device__ __forceinline__ void gemm_phase(LAS unsigned char* lds, const Gemm g, const Sched& S, const Epi& E) {
;     ...
;             PG8_LDB(B0, 1, 0); PG8_LDB(B1, 1, 1); PG8_SCHED; PG8_LDA(At, 1, 0); PG8_STAGE(PG8_SA(0, 1), a2 + hstepA, voffA);
;             PG8_WAIT_V(8); PG8_WAIT_L(0); PG8_BAR; PG8_MMA(0, 0, At, B0); PG8_MMA(0, 1, At, B1); PG8_BAR; PG8_SCHED;
;             PG8_LDA(At, 1, 1); PG8_STAGE(PG8_SB(1, 0), b3, voffB); PG8_STAGE(PG8_SB(1, 1), b3 + hstepB, voffB); PG8_STAGE(PG8_SA(1, 0), a3, voffA);
;             PG8_WAIT_V(8); PG8_WAIT_L(0); PG8_BAR; PG8_MMA(1, 0, At, B0); PG8_MMA(1, 1, At, B1); PG8_BAR; PG8_SCHED;
	v_add_u32_e32 v168, s60, v151
	v_add_u32_e32 v184, s61, v151
	ds_read_b128 v[156:159], v168
	ds_read_b128 v[160:163], v168 offset:1024
	ds_read_b128 v[164:167], v168 offset:2048
	ds_read_b128 v[168:171], v168 offset:3072
	ds_read_b128 v[172:175], v184
	ds_read_b128 v[176:179], v184 offset:1024
	ds_read_b128 v[180:183], v184 offset:2048
	ds_read_b128 v[184:187], v184 offset:3072
	s_add_u32 s26, s26, 0x80000
	s_addc_u32 s27, s27, 0
	s_mov_b32 m0, s37
	ds_read_b128 v[188:191], v155 offset:32768
	ds_read_b128 v[192:195], v155 offset:33792
	ds_read_b128 v[196:199], v155 offset:34816
	ds_read_b128 v[200:203], v155 offset:35840
	ds_read_b128 v[204:207], v155 offset:36864
	ds_read_b128 v[208:211], v155 offset:37888
	ds_read_b128 v[212:215], v155 offset:38912
	ds_read_b128 v[216:219], v155 offset:39936
	global_load_lds_dwordx4 v130, s[26:27]
	s_mov_b32 m0, s40
	s_nop 0
	global_load_lds_dwordx4 v134, s[26:27]
	s_waitcnt vmcnt(8) lgkmcnt(0)
	s_barrier
	v_mfma_f32_16x16x32_bf16 v[126:129], v[156:159], v[188:191], v[126:129]
	v_mfma_f32_16x16x32_bf16 v[122:125], v[164:167], v[188:191], v[122:125]
	v_mfma_f32_16x16x32_bf16 v[110:113], v[156:159], v[196:199], v[110:113]
	v_mfma_f32_16x16x32_bf16 v[106:109], v[164:167], v[196:199], v[106:109]
	v_mfma_f32_16x16x32_bf16 v[94:97], v[156:159], v[204:207], v[94:97]
	v_mfma_f32_16x16x32_bf16 v[90:93], v[164:167], v[204:207], v[90:93]
	v_mfma_f32_16x16x32_bf16 v[78:81], v[156:159], v[212:215], v[78:81]
	v_mfma_f32_16x16x32_bf16 v[74:77], v[164:167], v[212:215], v[74:77]
	v_mfma_f32_16x16x32_bf16 v[126:129], v[160:163], v[192:195], v[126:129]
	v_mfma_f32_16x16x32_bf16 v[122:125], v[168:171], v[192:195], v[122:125]
	v_mfma_f32_16x16x32_bf16 v[110:113], v[160:163], v[200:203], v[110:113]
	v_mfma_f32_16x16x32_bf16 v[106:109], v[168:171], v[200:203], v[106:109]
	v_mfma_f32_16x16x32_bf16 v[94:97], v[160:163], v[208:211], v[94:97]
	v_mfma_f32_16x16x32_bf16 v[90:93], v[168:171], v[208:211], v[90:93]
	v_mfma_f32_16x16x32_bf16 v[78:81], v[160:163], v[216:219], v[78:81]
	v_mfma_f32_16x16x32_bf16 v[74:77], v[168:171], v[216:219], v[74:77]
	v_mfma_f32_16x16x32_bf16 v[118:121], v[172:175], v[188:191], v[118:121]
	v_mfma_f32_16x16x32_bf16 v[114:117], v[180:183], v[188:191], v[114:117]
	v_mfma_f32_16x16x32_bf16 v[102:105], v[172:175], v[196:199], v[102:105]
	v_mfma_f32_16x16x32_bf16 v[98:101], v[180:183], v[196:199], v[98:101]
	v_mfma_f32_16x16x32_bf16 v[86:89], v[172:175], v[204:207], v[86:89]
	v_mfma_f32_16x16x32_bf16 v[82:85], v[180:183], v[204:207], v[82:85]
	v_mfma_f32_16x16x32_bf16 v[70:73], v[172:175], v[212:215], v[70:73]
	v_mfma_f32_16x16x32_bf16 v[66:69], v[180:183], v[212:215], v[66:69]
	v_mfma_f32_16x16x32_bf16 v[118:121], v[176:179], v[192:195], v[118:121]
	v_mfma_f32_16x16x32_bf16 v[114:117], v[184:187], v[192:195], v[114:117]
	v_mfma_f32_16x16x32_bf16 v[102:105], v[176:179], v[200:203], v[102:105]
	v_mfma_f32_16x16x32_bf16 v[98:101], v[184:187], v[200:203], v[98:101]
	v_mfma_f32_16x16x32_bf16 v[86:89], v[176:179], v[208:211], v[86:89]
	v_mfma_f32_16x16x32_bf16 v[82:85], v[184:187], v[208:211], v[82:85]
	v_mfma_f32_16x16x32_bf16 v[70:73], v[176:179], v[216:219], v[70:73]
	v_mfma_f32_16x16x32_bf16 v[66:69], v[184:187], v[216:219], v[66:69]
	s_barrier
	s_add_u32 s26, s24, 0x8000
	s_addc_u32 s27, s25, 0
	s_add_i32 s66, s60, s34
	s_mov_b32 m0, s66
	ds_read_b128 v[188:191], v155 offset:49152
	ds_read_b128 v[192:195], v155 offset:50176
	ds_read_b128 v[196:199], v155 offset:51200
	ds_read_b128 v[200:203], v155 offset:52224
	ds_read_b128 v[204:207], v155 offset:53248
	ds_read_b128 v[208:211], v155 offset:54272
	ds_read_b128 v[212:215], v155 offset:55296
	ds_read_b128 v[216:219], v155 offset:56320
	global_load_lds_dwordx4 v132, s[26:27]
	s_add_i32 m0, s66, 0x2000
	s_add_u32 s24, s24, 0xc000
	v_lshl_add_u64 v[220:221], s[26:27], 0, v[136:137]
	s_addc_u32 s25, s25, 0
	s_add_i32 s26, s61, s34
	global_load_lds_dwordx4 v[220:221], off
	s_mov_b32 m0, s26
	s_nop 0
	global_load_lds_dwordx4 v132, s[24:25]
	s_add_i32 m0, s26, 0x2000
	s_nop 0
	global_load_lds_dwordx4 v136, s[24:25]
	s_mov_b32 m0, s41
	s_nop 0
	global_load_lds_dwordx4 v130, s[22:23]
	s_mov_b32 m0, s42
	s_nop 0
	global_load_lds_dwordx4 v134, s[22:23]
	s_waitcnt vmcnt(8) lgkmcnt(0)
	s_barrier
	v_mfma_f32_16x16x32_bf16 v[62:65], v[156:159], v[188:191], v[62:65]
	v_mfma_f32_16x16x32_bf16 v[58:61], v[164:167], v[188:191], v[58:61]
	v_mfma_f32_16x16x32_bf16 v[46:49], v[156:159], v[196:199], v[46:49]
	v_mfma_f32_16x16x32_bf16 v[42:45], v[164:167], v[196:199], v[42:45]
	v_mfma_f32_16x16x32_bf16 v[30:33], v[156:159], v[204:207], v[30:33]
	v_mfma_f32_16x16x32_bf16 v[26:29], v[164:167], v[204:207], v[26:29]
	v_mfma_f32_16x16x32_bf16 v[14:17], v[156:159], v[212:215], v[14:17]
	v_mfma_f32_16x16x32_bf16 v[10:13], v[164:167], v[212:215], v[10:13]
	v_mfma_f32_16x16x32_bf16 v[62:65], v[160:163], v[192:195], v[62:65]
	v_mfma_f32_16x16x32_bf16 v[58:61], v[168:171], v[192:195], v[58:61]
	v_mfma_f32_16x16x32_bf16 v[46:49], v[160:163], v[200:203], v[46:49]
	v_mfma_f32_16x16x32_bf16 v[42:45], v[168:171], v[200:203], v[42:45]
	v_mfma_f32_16x16x32_bf16 v[30:33], v[160:163], v[208:211], v[30:33]
	v_mfma_f32_16x16x32_bf16 v[26:29], v[168:171], v[208:211], v[26:29]
	v_mfma_f32_16x16x32_bf16 v[14:17], v[160:163], v[216:219], v[14:17]
	v_mfma_f32_16x16x32_bf16 v[10:13], v[168:171], v[216:219], v[10:13]
	v_mfma_f32_16x16x32_bf16 v[54:57], v[172:175], v[188:191], v[54:57]
	v_mfma_f32_16x16x32_bf16 v[50:53], v[180:183], v[188:191], v[50:53]
	v_mfma_f32_16x16x32_bf16 v[38:41], v[172:175], v[196:199], v[38:41]
	v_mfma_f32_16x16x32_bf16 v[34:37], v[180:183], v[196:199], v[34:37]
	v_mfma_f32_16x16x32_bf16 v[22:25], v[172:175], v[204:207], v[22:25]
	v_mfma_f32_16x16x32_bf16 v[18:21], v[180:183], v[204:207], v[18:21]
	v_mfma_f32_16x16x32_bf16 v[6:9], v[172:175], v[212:215], v[6:9]
	v_mfma_f32_16x16x32_bf16 v[2:5], v[180:183], v[212:215], v[2:5]
	v_mfma_f32_16x16x32_bf16 v[54:57], v[176:179], v[192:195], v[54:57]
	v_mfma_f32_16x16x32_bf16 v[50:53], v[184:187], v[192:195], v[50:53]
	v_mfma_f32_16x16x32_bf16 v[38:41], v[176:179], v[200:203], v[38:41]
	v_mfma_f32_16x16x32_bf16 v[34:37], v[184:187], v[200:203], v[34:37]
	v_mfma_f32_16x16x32_bf16 v[22:25], v[176:179], v[208:211], v[22:25]
	v_mfma_f32_16x16x32_bf16 v[18:21], v[184:187], v[208:211], v[18:21]
	v_mfma_f32_16x16x32_bf16 v[6:9], v[176:179], v[216:219], v[6:9]
	v_mfma_f32_16x16x32_bf16 v[2:5], v[184:187], v[216:219], v[2:5]
	s_barrier
; __device__ __forceinline__ unsigned pk2(float lo, float hi) { const f32x2 v = {lo, hi}; return __builtin_bit_cast(unsigned, __builtin_convertvector(v, bf16x2_t)); }
; #define PG8_BAR __builtin_amdgcn_s_barrier()
; template <class Epi, class Sched, bool ABLK = false, bool ALIGN_EPI = true, bool SP2 = true, bool BBLK = true>
; __device__ __forceinline__ void gemm_phase(LAS unsigned char* lds, const Gemm g, const Sched& S, const Epi& E) {
;     ...
;         if constexpr (ALIGN_EPI) { if (wr == 0) PG8_BAR; }
;     __device__ __forceinline__ void operator()(const f32x4 (&acc)[2][2][4][2], const Unit& u, int wr, int wc, int fr, int fq) const {
;         const int row0 = u.pm * 256 + wr * 64 + fr, col0 = u.pn * 256 + wc * 64 + 8 * fq;
;         bf16_t* base = u.part == 0 ? Z + (size_t)row0 * D + col0 : P + ((size_t)(u.part - 1) * MS + (row0 - MP)) * D + col0;
; #pragma unroll
;         for (int ai = 0; ai < 2; ++ai)
; #pragma unroll
;             for (int m = 0; m < 4; ++m) { u32x4 w[2];
; #pragma unroll
;                 for (int bj = 0; bj < 2; ++bj) { const f32x4 v0 = acc[ai][bj][m][0], v1 = acc[ai][bj][m][1]; w[bj].x = pk2(v0[0], v0[1]); w[bj].y = pk2(v0[2], v0[3]); w[bj].z = pk2(v1[0], v1[1]); w[bj].w = pk2(v1[2], v1[3]); }
;                 store_pair((unsigned char*)(base + (size_t)(ai * 128 + m * 16) * D), (size_t)8 * D * 2, 64, w[0], w[1], fr >= 8); }
	s_add_u32 s51, s51, 0x10000
	s_addc_u32 s55, s55, 0
	s_add_u32 s20, s20, 0x100
	s_addc_u32 s21, s21, 0
	s_cmp_ge_u32 s65, s46
	s_cbranch_scc0 .LBB0_1038
	v_lshl_add_u32 v147, s47, 8, v150
	v_add_u32_e32 v148, 0xffffe000, v147
	v_sub_co_u32_e64 v146, vcc, s43, 1
	v_mov_b32_e32 v149, s54
	s_nop 0
	v_cndmask_b32_e32 v148, v148, v147, vcc
	v_ashrrev_i32_e32 v147, 31, v146
	v_lshlrev_b64 v[146:147], 23, v[146:147]
	v_lshl_add_u64 v[146:147], s[12:13], 0, v[146:147]
	v_cndmask_b32_e32 v147, v147, v149, vcc
	v_mov_b32_e32 v149, s52
	v_cndmask_b32_e32 v146, v146, v149, vcc
	v_ashrrev_i32_e32 v149, 31, v148
	v_lshl_or_b32 v156, s78, 8, v152
	v_lshlrev_b64 v[148:149], 12, v[148:149]
	v_lshl_add_u64 v[146:147], v[146:147], 0, v[148:149]
	v_ashrrev_i32_e32 v157, 31, v156
	v_cvt_pk_bf16_f32 v126, v126, v127
	v_cvt_pk_bf16_f32 v127, v128, v129
	v_cvt_pk_bf16_f32 v128, v122, v123
	v_cvt_pk_bf16_f32 v124, v124, v125
	v_cvt_pk_bf16_f32 v118, v118, v119
	v_cvt_pk_bf16_f32 v119, v120, v121
	v_cvt_pk_bf16_f32 v114, v114, v115
	v_cvt_pk_bf16_f32 v115, v116, v117
	v_lshl_add_u64 v[146:147], v[156:157], 1, v[146:147]
	v_mov_b32_dpp v120, v126 row_ror:8 row_mask:0xf bank_mask:0xf bound_ctrl:1
	v_mov_b32_dpp v121, v127 row_ror:8 row_mask:0xf bank_mask:0xf bound_ctrl:1
	v_mov_b32_dpp v116, v128 row_ror:8 row_mask:0xf bank_mask:0xf bound_ctrl:1
	v_mov_b32_dpp v117, v124 row_ror:8 row_mask:0xf bank_mask:0xf bound_ctrl:1
	v_mov_b32_dpp v125, v118 row_ror:8 row_mask:0xf bank_mask:0xf bound_ctrl:1
	v_mov_b32_dpp v129, v119 row_ror:8 row_mask:0xf bank_mask:0xf bound_ctrl:1
	v_mov_b32_dpp v148, v114 row_ror:8 row_mask:0xf bank_mask:0xf bound_ctrl:1
	v_mov_b32_dpp v149, v115 row_ror:8 row_mask:0xf bank_mask:0xf bound_ctrl:1
	v_lshl_add_u64 v[122:123], v[146:147], 0, v[138:139]
	v_cndmask_b32_e64 v117, v117, v115, s[6:7]
	v_cndmask_b32_e64 v116, v116, v114, s[6:7]
	v_cndmask_b32_e64 v115, v121, v119, s[6:7]
	v_cndmask_b32_e64 v114, v120, v118, s[6:7]
	v_cndmask_b32_e64 v121, v124, v149, s[6:7]
	v_cndmask_b32_e64 v120, v128, v148, s[6:7]
	v_cndmask_b32_e64 v119, v127, v129, s[6:7]
	v_cndmask_b32_e64 v118, v126, v125, s[6:7]
	v_cvt_pk_bf16_f32 v110, v110, v111
	v_cvt_pk_bf16_f32 v111, v112, v113
	v_cvt_pk_bf16_f32 v112, v106, v107
	v_cvt_pk_bf16_f32 v113, v108, v109
	v_cvt_pk_bf16_f32 v102, v102, v103
	v_cvt_pk_bf16_f32 v103, v104, v105
	v_cvt_pk_bf16_f32 v98, v98, v99
	v_cvt_pk_bf16_f32 v99, v100, v101
	s_mov_b64 s[4:5], 0x10000
	v_lshl_add_u64 v[124:125], v[146:147], 0, v[140:141]
	global_store_dwordx4 v[122:123], v[118:121], off
	global_store_dwordx4 v[124:125], v[114:117], off
	v_lshl_add_u64 v[106:107], v[146:147], 0, s[4:5]
	v_mov_b32_dpp v104, v110 row_ror:8 row_mask:0xf bank_mask:0xf bound_ctrl:1
	v_mov_b32_dpp v105, v111 row_ror:8 row_mask:0xf bank_mask:0xf bound_ctrl:1
	v_mov_b32_dpp v100, v112 row_ror:8 row_mask:0xf bank_mask:0xf bound_ctrl:1
	v_mov_b32_dpp v101, v113 row_ror:8 row_mask:0xf bank_mask:0xf bound_ctrl:1
	v_mov_b32_dpp v114, v102 row_ror:8 row_mask:0xf bank_mask:0xf bound_ctrl:1
	v_mov_b32_dpp v115, v103 row_ror:8 row_mask:0xf bank_mask:0xf bound_ctrl:1
	v_mov_b32_dpp v116, v98 row_ror:8 row_mask:0xf bank_mask:0xf bound_ctrl:1
	v_mov_b32_dpp v117, v99 row_ror:8 row_mask:0xf bank_mask:0xf bound_ctrl:1
	v_lshl_add_u64 v[108:109], v[106:107], 0, v[138:139]
	v_cndmask_b32_e64 v101, v101, v99, s[6:7]
	v_cndmask_b32_e64 v100, v100, v98, s[6:7]
	v_cndmask_b32_e64 v99, v105, v103, s[6:7]
	v_cndmask_b32_e64 v98, v104, v102, s[6:7]
	v_cndmask_b32_e64 v105, v113, v117, s[6:7]
	v_cndmask_b32_e64 v104, v112, v116, s[6:7]
	v_cndmask_b32_e64 v103, v111, v115, s[6:7]
	v_cndmask_b32_e64 v102, v110, v114, s[6:7]
	v_cvt_pk_bf16_f32 v94, v94, v95
	v_cvt_pk_bf16_f32 v95, v96, v97
	v_cvt_pk_bf16_f32 v96, v90, v91
	v_cvt_pk_bf16_f32 v97, v92, v93
	v_cvt_pk_bf16_f32 v86, v86, v87
	v_cvt_pk_bf16_f32 v87, v88, v89
	v_cvt_pk_bf16_f32 v82, v82, v83
	v_cvt_pk_bf16_f32 v83, v84, v85
	s_mov_b64 s[4:5], 0x20000
	v_lshl_add_u64 v[106:107], v[106:107], 0, v[140:141]
	global_store_dwordx4 v[108:109], v[102:105], off
	global_store_dwordx4 v[106:107], v[98:101], off
	v_lshl_add_u64 v[90:91], v[146:147], 0, s[4:5]
	v_mov_b32_dpp v88, v94 row_ror:8 row_mask:0xf bank_mask:0xf bound_ctrl:1
	v_mov_b32_dpp v89, v95 row_ror:8 row_mask:0xf bank_mask:0xf bound_ctrl:1
	v_mov_b32_dpp v84, v96 row_ror:8 row_mask:0xf bank_mask:0xf bound_ctrl:1
	v_mov_b32_dpp v85, v97 row_ror:8 row_mask:0xf bank_mask:0xf bound_ctrl:1
	v_mov_b32_dpp v98, v86 row_ror:8 row_mask:0xf bank_mask:0xf bound_ctrl:1
	v_mov_b32_dpp v99, v87 row_ror:8 row_mask:0xf bank_mask:0xf bound_ctrl:1
	v_mov_b32_dpp v100, v82 row_ror:8 row_mask:0xf bank_mask:0xf bound_ctrl:1
	v_mov_b32_dpp v101, v83 row_ror:8 row_mask:0xf bank_mask:0xf bound_ctrl:1
	v_lshl_add_u64 v[92:93], v[90:91], 0, v[138:139]
	v_cndmask_b32_e64 v85, v85, v83, s[6:7]
	v_cndmask_b32_e64 v84, v84, v82, s[6:7]
	v_cndmask_b32_e64 v83, v89, v87, s[6:7]
	v_cndmask_b32_e64 v82, v88, v86, s[6:7]
	v_cndmask_b32_e64 v89, v97, v101, s[6:7]
	v_cndmask_b32_e64 v88, v96, v100, s[6:7]
	v_cndmask_b32_e64 v87, v95, v99, s[6:7]
	v_cndmask_b32_e64 v86, v94, v98, s[6:7]
	v_cvt_pk_bf16_f32 v78, v78, v79
	v_cvt_pk_bf16_f32 v79, v80, v81
	v_cvt_pk_bf16_f32 v80, v74, v75
	v_cvt_pk_bf16_f32 v81, v76, v77
	v_cvt_pk_bf16_f32 v70, v70, v71
	v_cvt_pk_bf16_f32 v71, v72, v73
	v_cvt_pk_bf16_f32 v66, v66, v67
	v_cvt_pk_bf16_f32 v67, v68, v69
	s_mov_b64 s[4:5], 0x30000
	v_lshl_add_u64 v[90:91], v[90:91], 0, v[140:141]
	global_store_dwordx4 v[92:93], v[86:89], off
	global_store_dwordx4 v[90:91], v[82:85], off
	v_lshl_add_u64 v[74:75], v[146:147], 0, s[4:5]
	v_mov_b32_dpp v72, v78 row_ror:8 row_mask:0xf bank_mask:0xf bound_ctrl:1
; __device__ __forceinline__ unsigned pk2(float lo, float hi) { const f32x2 v = {lo, hi}; return __builtin_bit_cast(unsigned, __builtin_convertvector(v, bf16x2_t)); }
; __device__ __forceinline__ void store_pair(unsigned char* own, size_t stride8, int hi_off, u32x4 lo, u32x4 hi, bool upper) {
;     const u32x4 tlo = ror8(lo), thi = ror8(hi);
;     const u32x4 A = upper ? thi : lo, B = upper ? hi : tlo;
;     unsigned char* pa = upper ? own - stride8 + hi_off : own;
;     unsigned char* pb = upper ? own + hi_off : own + stride8;
;     *(u32x4*)pa = A; *(u32x4*)pb = B;
; }
;     __device__ __forceinline__ void operator()(const f32x4 (&acc)[2][2][4][2], const Unit& u, int wr, int wc, int fr, int fq) const {
;     ...
;         for (int ai = 0; ai < 2; ++ai)
; #pragma unroll
;             for (int m = 0; m < 4; ++m) { u32x4 w[2];
; #pragma unroll
;                 for (int bj = 0; bj < 2; ++bj) { const f32x4 v0 = acc[ai][bj][m][0], v1 = acc[ai][bj][m][1]; w[bj].x = pk2(v0[0], v0[1]); w[bj].y = pk2(v0[2], v0[3]); w[bj].z = pk2(v1[0], v1[1]); w[bj].w = pk2(v1[2], v1[3]); }
;                 store_pair((unsigned char*)(base + (size_t)(ai * 128 + m * 16) * D), (size_t)8 * D * 2, 64, w[0], w[1], fr >= 8); }
	v_mov_b32_dpp v73, v79 row_ror:8 row_mask:0xf bank_mask:0xf bound_ctrl:1
	v_mov_b32_dpp v68, v80 row_ror:8 row_mask:0xf bank_mask:0xf bound_ctrl:1
	v_mov_b32_dpp v69, v81 row_ror:8 row_mask:0xf bank_mask:0xf bound_ctrl:1
	v_mov_b32_dpp v82, v70 row_ror:8 row_mask:0xf bank_mask:0xf bound_ctrl:1
	v_mov_b32_dpp v83, v71 row_ror:8 row_mask:0xf bank_mask:0xf bound_ctrl:1
	v_mov_b32_dpp v84, v66 row_ror:8 row_mask:0xf bank_mask:0xf bound_ctrl:1
	v_mov_b32_dpp v85, v67 row_ror:8 row_mask:0xf bank_mask:0xf bound_ctrl:1
	v_lshl_add_u64 v[76:77], v[74:75], 0, v[138:139]
	v_cndmask_b32_e64 v69, v69, v67, s[6:7]
	v_cndmask_b32_e64 v68, v68, v66, s[6:7]
	v_cndmask_b32_e64 v67, v73, v71, s[6:7]
	v_cndmask_b32_e64 v66, v72, v70, s[6:7]
	v_cndmask_b32_e64 v73, v81, v85, s[6:7]
	v_cndmask_b32_e64 v72, v80, v84, s[6:7]
	v_cndmask_b32_e64 v71, v79, v83, s[6:7]
	v_cndmask_b32_e64 v70, v78, v82, s[6:7]
	v_cvt_pk_bf16_f32 v62, v62, v63
	v_cvt_pk_bf16_f32 v63, v64, v65
	v_cvt_pk_bf16_f32 v64, v58, v59
	v_cvt_pk_bf16_f32 v65, v60, v61
	v_cvt_pk_bf16_f32 v54, v54, v55
	v_cvt_pk_bf16_f32 v55, v56, v57
	v_cvt_pk_bf16_f32 v50, v50, v51
	v_cvt_pk_bf16_f32 v51, v52, v53
	s_mov_b64 s[4:5], 0x80000
	v_lshl_add_u64 v[74:75], v[74:75], 0, v[140:141]
	global_store_dwordx4 v[76:77], v[70:73], off
	global_store_dwordx4 v[74:75], v[66:69], off
	v_lshl_add_u64 v[58:59], v[146:147], 0, s[4:5]
	v_mov_b32_dpp v56, v62 row_ror:8 row_mask:0xf bank_mask:0xf bound_ctrl:1
	v_mov_b32_dpp v57, v63 row_ror:8 row_mask:0xf bank_mask:0xf bound_ctrl:1
	v_mov_b32_dpp v52, v64 row_ror:8 row_mask:0xf bank_mask:0xf bound_ctrl:1
	v_mov_b32_dpp v53, v65 row_ror:8 row_mask:0xf bank_mask:0xf bound_ctrl:1
	v_mov_b32_dpp v66, v54 row_ror:8 row_mask:0xf bank_mask:0xf bound_ctrl:1
	v_mov_b32_dpp v67, v55 row_ror:8 row_mask:0xf bank_mask:0xf bound_ctrl:1
	v_mov_b32_dpp v68, v50 row_ror:8 row_mask:0xf bank_mask:0xf bound_ctrl:1
	v_mov_b32_dpp v69, v51 row_ror:8 row_mask:0xf bank_mask:0xf bound_ctrl:1
	v_lshl_add_u64 v[60:61], v[58:59], 0, v[138:139]
	v_cndmask_b32_e64 v53, v53, v51, s[6:7]
	v_cndmask_b32_e64 v52, v52, v50, s[6:7]
	v_cndmask_b32_e64 v51, v57, v55, s[6:7]
	v_cndmask_b32_e64 v50, v56, v54, s[6:7]
	v_cndmask_b32_e64 v57, v65, v69, s[6:7]
	v_cndmask_b32_e64 v56, v64, v68, s[6:7]
	v_cndmask_b32_e64 v55, v63, v67, s[6:7]
	v_cndmask_b32_e64 v54, v62, v66, s[6:7]
	v_cvt_pk_bf16_f32 v46, v46, v47
	v_cvt_pk_bf16_f32 v47, v48, v49
	v_cvt_pk_bf16_f32 v48, v42, v43
	v_cvt_pk_bf16_f32 v49, v44, v45
	v_cvt_pk_bf16_f32 v38, v38, v39
	v_cvt_pk_bf16_f32 v39, v40, v41
	v_cvt_pk_bf16_f32 v34, v34, v35
	v_cvt_pk_bf16_f32 v35, v36, v37
	s_mov_b64 s[4:5], 0x90000
	v_lshl_add_u64 v[58:59], v[58:59], 0, v[140:141]
	global_store_dwordx4 v[60:61], v[54:57], off
	global_store_dwordx4 v[58:59], v[50:53], off
	v_lshl_add_u64 v[42:43], v[146:147], 0, s[4:5]
	v_mov_b32_dpp v40, v46 row_ror:8 row_mask:0xf bank_mask:0xf bound_ctrl:1
	v_mov_b32_dpp v41, v47 row_ror:8 row_mask:0xf bank_mask:0xf bound_ctrl:1
	v_mov_b32_dpp v36, v48 row_ror:8 row_mask:0xf bank_mask:0xf bound_ctrl:1
	v_mov_b32_dpp v37, v49 row_ror:8 row_mask:0xf bank_mask:0xf bound_ctrl:1
	v_mov_b32_dpp v50, v38 row_ror:8 row_mask:0xf bank_mask:0xf bound_ctrl:1
	v_mov_b32_dpp v51, v39 row_ror:8 row_mask:0xf bank_mask:0xf bound_ctrl:1
	v_mov_b32_dpp v52, v34 row_ror:8 row_mask:0xf bank_mask:0xf bound_ctrl:1
	v_mov_b32_dpp v53, v35 row_ror:8 row_mask:0xf bank_mask:0xf bound_ctrl:1
	v_lshl_add_u64 v[44:45], v[42:43], 0, v[138:139]
	v_cndmask_b32_e64 v37, v37, v35, s[6:7]
	v_cndmask_b32_e64 v36, v36, v34, s[6:7]
	v_cndmask_b32_e64 v35, v41, v39, s[6:7]
	v_cndmask_b32_e64 v34, v40, v38, s[6:7]
	v_cndmask_b32_e64 v41, v49, v53, s[6:7]
	v_cndmask_b32_e64 v40, v48, v52, s[6:7]
	v_cndmask_b32_e64 v39, v47, v51, s[6:7]
	v_cndmask_b32_e64 v38, v46, v50, s[6:7]
	v_cvt_pk_bf16_f32 v30, v30, v31
	v_cvt_pk_bf16_f32 v31, v32, v33
	v_cvt_pk_bf16_f32 v32, v26, v27
	v_cvt_pk_bf16_f32 v33, v28, v29
	v_cvt_pk_bf16_f32 v22, v22, v23
	v_cvt_pk_bf16_f32 v23, v24, v25
	v_cvt_pk_bf16_f32 v18, v18, v19
	v_cvt_pk_bf16_f32 v19, v20, v21
	s_mov_b64 s[4:5], 0xa0000
	v_lshl_add_u64 v[42:43], v[42:43], 0, v[140:141]
	global_store_dwordx4 v[44:45], v[38:41], off
	global_store_dwordx4 v[42:43], v[34:37], off
	v_lshl_add_u64 v[26:27], v[146:147], 0, s[4:5]
	v_mov_b32_dpp v24, v30 row_ror:8 row_mask:0xf bank_mask:0xf bound_ctrl:1
	v_mov_b32_dpp v25, v31 row_ror:8 row_mask:0xf bank_mask:0xf bound_ctrl:1
	v_mov_b32_dpp v20, v32 row_ror:8 row_mask:0xf bank_mask:0xf bound_ctrl:1
	v_mov_b32_dpp v21, v33 row_ror:8 row_mask:0xf bank_mask:0xf bound_ctrl:1
	v_mov_b32_dpp v34, v22 row_ror:8 row_mask:0xf bank_mask:0xf bound_ctrl:1
	v_mov_b32_dpp v35, v23 row_ror:8 row_mask:0xf bank_mask:0xf bound_ctrl:1
	v_mov_b32_dpp v36, v18 row_ror:8 row_mask:0xf bank_mask:0xf bound_ctrl:1
	v_mov_b32_dpp v37, v19 row_ror:8 row_mask:0xf bank_mask:0xf bound_ctrl:1
	v_lshl_add_u64 v[28:29], v[26:27], 0, v[138:139]
	v_cndmask_b32_e64 v21, v21, v19, s[6:7]
	v_cndmask_b32_e64 v20, v20, v18, s[6:7]
	v_cndmask_b32_e64 v19, v25, v23, s[6:7]
	v_cndmask_b32_e64 v18, v24, v22, s[6:7]
	v_cndmask_b32_e64 v25, v33, v37, s[6:7]
	v_cndmask_b32_e64 v24, v32, v36, s[6:7]
	v_cndmask_b32_e64 v23, v31, v35, s[6:7]
	v_cndmask_b32_e64 v22, v30, v34, s[6:7]
	v_cvt_pk_bf16_f32 v14, v14, v15
	v_cvt_pk_bf16_f32 v15, v16, v17
	v_cvt_pk_bf16_f32 v16, v10, v11
	v_cvt_pk_bf16_f32 v17, v12, v13
	v_cvt_pk_bf16_f32 v6, v6, v7
	v_cvt_pk_bf16_f32 v7, v8, v9
	v_cvt_pk_bf16_f32 v2, v2, v3
	v_cvt_pk_bf16_f32 v3, v4, v5
	s_mov_b64 s[4:5], 0xb0000
	v_lshl_add_u64 v[26:27], v[26:27], 0, v[140:141]
	global_store_dwordx4 v[28:29], v[22:25], off
	global_store_dwordx4 v[26:27], v[18:21], off
	v_lshl_add_u64 v[10:11], v[146:147], 0, s[4:5]
	v_mov_b32_dpp v8, v14 row_ror:8 row_mask:0xf bank_mask:0xf bound_ctrl:1
	v_mov_b32_dpp v9, v15 row_ror:8 row_mask:0xf bank_mask:0xf bound_ctrl:1
	v_mov_b32_dpp v4, v16 row_ror:8 row_mask:0xf bank_mask:0xf bound_ctrl:1
	v_mov_b32_dpp v5, v17 row_ror:8 row_mask:0xf bank_mask:0xf bound_ctrl:1
	v_mov_b32_dpp v18, v6 row_ror:8 row_mask:0xf bank_mask:0xf bound_ctrl:1
	v_mov_b32_dpp v19, v7 row_ror:8 row_mask:0xf bank_mask:0xf bound_ctrl:1
	v_mov_b32_dpp v20, v2 row_ror:8 row_mask:0xf bank_mask:0xf bound_ctrl:1
	v_mov_b32_dpp v21, v3 row_ror:8 row_mask:0xf bank_mask:0xf bound_ctrl:1
	v_lshl_add_u64 v[12:13], v[10:11], 0, v[138:139]
	v_cndmask_b32_e64 v5, v5, v3, s[6:7]
	v_cndmask_b32_e64 v4, v4, v2, s[6:7]
	v_cndmask_b32_e64 v3, v9, v7, s[6:7]
	v_cndmask_b32_e64 v2, v8, v6, s[6:7]
	v_cndmask_b32_e64 v9, v17, v21, s[6:7]
	v_cndmask_b32_e64 v8, v16, v20, s[6:7]
	v_cndmask_b32_e64 v7, v15, v19, s[6:7]
	v_cndmask_b32_e64 v6, v14, v18, s[6:7]
	s_and_b64 vcc, exec, s[10:11]
	s_cbranch_vccz .LBB0_1041
	s_barrier
; #define PG8_BAR __builtin_amdgcn_s_barrier()
; template <class Epi, class Sched, bool ABLK = false, bool ALIGN_EPI = true, bool SP2 = true, bool BBLK = true>
; __device__ __forceinline__ void gemm_phase(LAS unsigned char* lds, const Gemm g, const Sched& S, const Epi& E) {
;     ...
;         if constexpr (ALIGN_EPI) { if (wr == 0) PG8_BAR; }
;         E(acc, cur, wr, wc, fr, fq); S.done(cur);
;         if (!has_next) break;
; #pragma unroll
;         for (int a = 0; a < 2; ++a)
; #pragma unroll
;             for (int b = 0; b < 2; ++b)
; #pragma unroll
;                 for (int m = 0; m < 4; ++m)
; #pragma unroll
;                     for (int n = 0; n < 2; ++n) acc[a][b][m][n] = (f32x4){0.f, 0.f, 0.f, 0.f};
;         cur = nxt; uA = nuA; tbA = ntbA; cB = nB; ++ui;
;         if constexpr (ALIGN_EPI) { if (wr == 1) PG8_BAR; }
.LBB0_1041:
	s_and_b64 vcc, exec, s[8:9]
	s_mov_b64 s[8:9], -1
	v_lshl_add_u64 v[10:11], v[10:11], 0, v[140:141]
	global_store_dwordx4 v[12:13], v[6:9], off
	global_store_dwordx4 v[10:11], v[2:5], off
	s_cbranch_vccnz .LBB0_1036
	s_andn2_b64 vcc, exec, s[2:3]
	s_cbranch_vccnz .LBB0_1035
	s_barrier
	s_branch .LBB0_1035

; #define PG8_STAGE(bufoff, gbase, voff) do { _Pragma("unroll") for (int _i = 0; _i < 2; ++_i) \
;         __builtin_amdgcn_global_load_lds((const unsigned*)((const char*)(gbase) + (voff)[_i]), (LAS unsigned*)(lds + (bufoff) + ldsw + _i * 8192), 16, 0, 0); } while (0)
; #define PG8_LDA(dst, b, h) do { _Pragma("unroll") for (int m = 0; m < 4; ++m) _Pragma("unroll") for (int k = 0; k < 2; ++k) dst[m][k] = *(const LAS bf16x8*)(lds + PG8_SA(b, h) + aoff + m * 2048 + k * 1024); } while (0)
; #define PG8_LDB(dst, b, h) do { _Pragma("unroll") for (int n = 0; n < 2; ++n) _Pragma("unroll") for (int k = 0; k < 2; ++k) dst[n][k] = *(const LAS bf16x8*)(lds + PG8_SB(b, h) + boff + n * 2048 + k * 1024); } while (0)
; #define PG8_MMA(ai, bj, At, Bt) do { __builtin_amdgcn_s_setprio(1); _Pragma("unroll") for (int m = 0; m < 4; ++m) _Pragma("unroll") for (int n = 0; n < 2; ++n) _Pragma("unroll") for (int k = 0; k < 2; ++k) \
;         acc[ai][bj][m][n] = __builtin_amdgcn_mfma_f32_16x16x32_bf16(Bt[n][k], At[m][k], acc[ai][bj][m][n], 0, 0, 0); __builtin_amdgcn_s_setprio(0); } while (0)
; #define PG8_WAIT_V(n) asm volatile("s_waitcnt vmcnt(" #n ")" ::: "memory")
; #define PG8_WAIT_L(n) asm volatile("s_waitcnt lgkmcnt(" #n ")" ::: "memory")
; #define PG8_BAR __builtin_amdgcn_s_barrier()
; #define PG8_SCHED __builtin_amdgcn_sched_barrier(0)
; template <class Epi, class Sched, bool ABLK = false, bool ALIGN_EPI = true, bool SP2 = true, bool BBLK = true>
; __device__ __forceinline__ void gemm_phase(LAS unsigned char* lds, const Gemm g, const Sched& S, const Epi& E) {
;     ...
;             if constexpr (SP2) {
;             PG8_LDB(B0, 0, 0); PG8_LDB(B1, 0, 1); PG8_SCHED; PG8_LDA(At, 0, 0); PG8_STAGE(PG8_SA(1, 1), a1 + hstepA, voffA);
;             PG8_WAIT_V(8); PG8_WAIT_L(0); PG8_BAR; PG8_MMA(0, 0, At, B0); PG8_MMA(0, 1, At, B1); PG8_BAR; PG8_SCHED;
;             PG8_LDA(At, 0, 1); PG8_STAGE(PG8_SB(0, 0), b2, voffB); PG8_STAGE(PG8_SB(0, 1), b2 + hstepB, voffB); PG8_STAGE(PG8_SA(0, 0), a2, voffA);
;             PG8_WAIT_V(8); PG8_WAIT_L(0); PG8_BAR; PG8_MMA(1, 0, At, B0); PG8_MMA(1, 1, At, B1); PG8_BAR; PG8_SCHED;
.LBB0_1164:
	ds_read_b128 v[172:175], v169
	ds_read_b128 v[176:179], v169 offset:1024
	ds_read_b128 v[180:183], v169 offset:2048
	ds_read_b128 v[184:187], v169 offset:3072
	ds_read_b128 v[188:191], v170
	ds_read_b128 v[192:195], v170 offset:1024
	ds_read_b128 v[196:199], v170 offset:2048
	ds_read_b128 v[200:203], v170 offset:3072
	s_add_u32 s30, s26, s28
	s_addc_u32 s31, s27, s29
	s_add_u32 s36, s30, 0x100
	s_addc_u32 s37, s31, 0
	s_add_u32 s30, s30, 0x180
	s_addc_u32 s31, s31, 0
	s_cmpk_eq_i32 s28, 0xf00
	s_cselect_b32 s31, s57, s31
	s_cselect_b32 s30, s23, s30
	s_cselect_b32 s35, s11, s65
	s_cselect_b32 s34, s15, s64
	s_cselect_b32 s37, s4, s37
	s_cselect_b32 s36, s5, s36
	s_mov_b32 m0, s50
	v_lshl_add_u64 v[236:237], v[164:165], 0, s[28:29]
	ds_read_b128 v[204:207], v171
	ds_read_b128 v[208:211], v171 offset:1024
	ds_read_b128 v[212:215], v171 offset:2048
	ds_read_b128 v[216:219], v171 offset:3072
	ds_read_b128 v[220:223], v171 offset:4096
	ds_read_b128 v[224:227], v171 offset:5120
	ds_read_b128 v[228:231], v171 offset:6144
	ds_read_b128 v[232:235], v171 offset:7168
	global_load_lds_dwordx4 v[236:237], off
	v_lshl_add_u64 v[236:237], v[166:167], 0, s[28:29]
	s_mov_b32 m0, s51
	s_nop 0
	global_load_lds_dwordx4 v[236:237], off
	s_waitcnt vmcnt(8) lgkmcnt(0)
	s_barrier
	v_mfma_f32_16x16x32_bf16 v[126:129], v[172:175], v[204:207], v[126:129]
	v_mfma_f32_16x16x32_bf16 v[122:125], v[180:183], v[204:207], v[122:125]
	v_mfma_f32_16x16x32_bf16 v[110:113], v[172:175], v[212:215], v[110:113]
	v_mfma_f32_16x16x32_bf16 v[106:109], v[180:183], v[212:215], v[106:109]
	v_mfma_f32_16x16x32_bf16 v[94:97], v[172:175], v[220:223], v[94:97]
	v_mfma_f32_16x16x32_bf16 v[90:93], v[180:183], v[220:223], v[90:93]
	v_mfma_f32_16x16x32_bf16 v[78:81], v[172:175], v[228:231], v[78:81]
	v_mfma_f32_16x16x32_bf16 v[74:77], v[180:183], v[228:231], v[74:77]
	v_mfma_f32_16x16x32_bf16 v[126:129], v[176:179], v[208:211], v[126:129]
	v_mfma_f32_16x16x32_bf16 v[122:125], v[184:187], v[208:211], v[122:125]
	v_mfma_f32_16x16x32_bf16 v[110:113], v[176:179], v[216:219], v[110:113]
	v_mfma_f32_16x16x32_bf16 v[106:109], v[184:187], v[216:219], v[106:109]
	v_mfma_f32_16x16x32_bf16 v[94:97], v[176:179], v[224:227], v[94:97]
	v_mfma_f32_16x16x32_bf16 v[90:93], v[184:187], v[224:227], v[90:93]
	v_mfma_f32_16x16x32_bf16 v[78:81], v[176:179], v[232:235], v[78:81]
	v_mfma_f32_16x16x32_bf16 v[74:77], v[184:187], v[232:235], v[74:77]
	v_mfma_f32_16x16x32_bf16 v[118:121], v[188:191], v[204:207], v[118:121]
	v_mfma_f32_16x16x32_bf16 v[114:117], v[196:199], v[204:207], v[114:117]
	v_mfma_f32_16x16x32_bf16 v[102:105], v[188:191], v[212:215], v[102:105]
	v_mfma_f32_16x16x32_bf16 v[98:101], v[196:199], v[212:215], v[98:101]
	v_mfma_f32_16x16x32_bf16 v[86:89], v[188:191], v[220:223], v[86:89]
	v_mfma_f32_16x16x32_bf16 v[82:85], v[196:199], v[220:223], v[82:85]
	v_mfma_f32_16x16x32_bf16 v[70:73], v[188:191], v[228:231], v[70:73]
	v_mfma_f32_16x16x32_bf16 v[66:69], v[196:199], v[228:231], v[66:69]
	v_mfma_f32_16x16x32_bf16 v[118:121], v[192:195], v[208:211], v[118:121]
	v_mfma_f32_16x16x32_bf16 v[114:117], v[200:203], v[208:211], v[114:117]
	v_mfma_f32_16x16x32_bf16 v[102:105], v[192:195], v[216:219], v[102:105]
	v_mfma_f32_16x16x32_bf16 v[98:101], v[200:203], v[216:219], v[98:101]
	v_mfma_f32_16x16x32_bf16 v[86:89], v[192:195], v[224:227], v[86:89]
	v_mfma_f32_16x16x32_bf16 v[82:85], v[200:203], v[224:227], v[82:85]
	v_mfma_f32_16x16x32_bf16 v[70:73], v[192:195], v[232:235], v[70:73]
	v_mfma_f32_16x16x32_bf16 v[66:69], v[200:203], v[232:235], v[66:69]
	s_barrier
	s_mov_b32 m0, s55
	s_add_u32 s76, s34, 0x4000
	ds_read_b128 v[204:207], v171 offset:16384
	ds_read_b128 v[208:211], v171 offset:17408
	ds_read_b128 v[212:215], v171 offset:18432
	ds_read_b128 v[216:219], v171 offset:19456
	ds_read_b128 v[220:223], v171 offset:20480
	ds_read_b128 v[224:227], v171 offset:21504
	ds_read_b128 v[228:231], v171 offset:22528
	ds_read_b128 v[232:235], v171 offset:23552
	global_load_lds_dwordx4 v134, s[34:35]
	s_mov_b32 m0, s56
	s_addc_u32 s77, s35, 0
	s_add_i32 s67, s73, s42
	global_load_lds_dwordx4 v130, s[34:35]
	s_mov_b32 m0, s67
	s_nop 0
	global_load_lds_dwordx4 v134, s[76:77]
	s_add_i32 m0, s67, 0x2000
	s_nop 0
	global_load_lds_dwordx4 v130, s[76:77]
	s_mov_b32 m0, s25
	s_nop 0
	global_load_lds_dwordx4 v136, s[36:37]
	s_mov_b32 m0, s43
	s_nop 0
	global_load_lds_dwordx4 v132, s[36:37]
	s_waitcnt vmcnt(8) lgkmcnt(0)
	s_barrier
	v_mfma_f32_16x16x32_bf16 v[62:65], v[172:175], v[204:207], v[62:65]
	v_mfma_f32_16x16x32_bf16 v[58:61], v[180:183], v[204:207], v[58:61]
	v_mfma_f32_16x16x32_bf16 v[46:49], v[172:175], v[212:215], v[46:49]
	v_mfma_f32_16x16x32_bf16 v[42:45], v[180:183], v[212:215], v[42:45]
	v_mfma_f32_16x16x32_bf16 v[30:33], v[172:175], v[220:223], v[30:33]
	v_mfma_f32_16x16x32_bf16 v[26:29], v[180:183], v[220:223], v[26:29]
	v_mfma_f32_16x16x32_bf16 v[14:17], v[172:175], v[228:231], v[14:17]
	v_mfma_f32_16x16x32_bf16 v[10:13], v[180:183], v[228:231], v[10:13]
	v_mfma_f32_16x16x32_bf16 v[62:65], v[176:179], v[208:211], v[62:65]
	v_mfma_f32_16x16x32_bf16 v[58:61], v[184:187], v[208:211], v[58:61]
	v_mfma_f32_16x16x32_bf16 v[46:49], v[176:179], v[216:219], v[46:49]
	v_mfma_f32_16x16x32_bf16 v[42:45], v[184:187], v[216:219], v[42:45]
	v_mfma_f32_16x16x32_bf16 v[30:33], v[176:179], v[224:227], v[30:33]
	v_mfma_f32_16x16x32_bf16 v[26:29], v[184:187], v[224:227], v[26:29]
	v_mfma_f32_16x16x32_bf16 v[14:17], v[176:179], v[232:235], v[14:17]
	v_mfma_f32_16x16x32_bf16 v[10:13], v[184:187], v[232:235], v[10:13]
	v_mfma_f32_16x16x32_bf16 v[54:57], v[188:191], v[204:207], v[54:57]
	v_mfma_f32_16x16x32_bf16 v[50:53], v[196:199], v[204:207], v[50:53]
	v_mfma_f32_16x16x32_bf16 v[38:41], v[188:191], v[212:215], v[38:41]
	v_mfma_f32_16x16x32_bf16 v[34:37], v[196:199], v[212:215], v[34:37]
	v_mfma_f32_16x16x32_bf16 v[22:25], v[188:191], v[220:223], v[22:25]
	v_mfma_f32_16x16x32_bf16 v[18:21], v[196:199], v[220:223], v[18:21]
	v_mfma_f32_16x16x32_bf16 v[6:9], v[188:191], v[228:231], v[6:9]
	v_mfma_f32_16x16x32_bf16 v[2:5], v[196:199], v[228:231], v[2:5]
	v_mfma_f32_16x16x32_bf16 v[54:57], v[192:195], v[208:211], v[54:57]
	v_mfma_f32_16x16x32_bf16 v[50:53], v[200:203], v[208:211], v[50:53]
	v_mfma_f32_16x16x32_bf16 v[38:41], v[192:195], v[216:219], v[38:41]
	v_mfma_f32_16x16x32_bf16 v[34:37], v[200:203], v[216:219], v[34:37]
	v_mfma_f32_16x16x32_bf16 v[22:25], v[192:195], v[224:227], v[22:25]
	v_mfma_f32_16x16x32_bf16 v[18:21], v[200:203], v[224:227], v[18:21]
	v_mfma_f32_16x16x32_bf16 v[6:9], v[192:195], v[232:235], v[6:9]
	v_mfma_f32_16x16x32_bf16 v[2:5], v[200:203], v[232:235], v[2:5]
	s_barrier
; #define PG8_STAGE(bufoff, gbase, voff) do { _Pragma("unroll") for (int _i = 0; _i < 2; ++_i) \
;         __builtin_amdgcn_global_load_lds((const unsigned*)((const char*)(gbase) + (voff)[_i]), (LAS unsigned*)(lds + (bufoff) + ldsw + _i * 8192), 16, 0, 0); } while (0)
; #define PG8_LDA(dst, b, h) do { _Pragma("unroll") for (int m = 0; m < 4; ++m) _Pragma("unroll") for (int k = 0; k < 2; ++k) dst[m][k] = *(const LAS bf16x8*)(lds + PG8_SA(b, h) + aoff + m * 2048 + k * 1024); } while (0)
; #define PG8_LDB(dst, b, h) do { _Pragma("unroll") for (int n = 0; n < 2; ++n) _Pragma("unroll") for (int k = 0; k < 2; ++k) dst[n][k] = *(const LAS bf16x8*)(lds + PG8_SB(b, h) + boff + n * 2048 + k * 1024); } while (0)
; #define PG8_MMA(ai, bj, At, Bt) do { __builtin_amdgcn_s_setprio(1); _Pragma("unroll") for (int m = 0; m < 4; ++m) _Pragma("unroll") for (int n = 0; n < 2; ++n) _Pragma("unroll") for (int k = 0; k < 2; ++k) \
;         acc[ai][bj][m][n] = __builtin_amdgcn_mfma_f32_16x16x32_bf16(Bt[n][k], At[m][k], acc[ai][bj][m][n], 0, 0, 0); __builtin_amdgcn_s_setprio(0); } while (0)
; #define PG8_WAIT_V(n) asm volatile("s_waitcnt vmcnt(" #n ")" ::: "memory")
; #define PG8_WAIT_L(n) asm volatile("s_waitcnt lgkmcnt(" #n ")" ::: "memory")
; #define PG8_BAR __builtin_amdgcn_s_barrier()
; #define PG8_SCHED __builtin_amdgcn_sched_barrier(0)
; template <class Epi, class Sched, bool ABLK = false, bool ALIGN_EPI = true, bool SP2 = true, bool BBLK = true>
; __device__ __forceinline__ void gemm_phase(LAS unsigned char* lds, const Gemm g, const Sched& S, const Epi& E) {
;     ...
;             PG8_LDB(B0, 1, 0); PG8_LDB(B1, 1, 1); PG8_SCHED; PG8_LDA(At, 1, 0); PG8_STAGE(PG8_SA(0, 1), a2 + hstepA, voffA);
;             PG8_WAIT_V(8); PG8_WAIT_L(0); PG8_BAR; PG8_MMA(0, 0, At, B0); PG8_MMA(0, 1, At, B1); PG8_BAR; PG8_SCHED;
;             PG8_LDA(At, 1, 1); PG8_STAGE(PG8_SB(1, 0), b3, voffB); PG8_STAGE(PG8_SB(1, 1), b3 + hstepB, voffB); PG8_STAGE(PG8_SA(1, 0), a3, voffA);
;             PG8_WAIT_V(8); PG8_WAIT_L(0); PG8_BAR; PG8_MMA(1, 0, At, B0); PG8_MMA(1, 1, At, B1); PG8_BAR; PG8_SCHED;
	v_add_u32_e32 v184, s60, v168
	v_add_u32_e32 v200, s61, v168
	ds_read_b128 v[172:175], v184
	ds_read_b128 v[176:179], v184 offset:1024
	ds_read_b128 v[180:183], v184 offset:2048
	ds_read_b128 v[184:187], v184 offset:3072
	ds_read_b128 v[188:191], v200
	ds_read_b128 v[192:195], v200 offset:1024
	ds_read_b128 v[196:199], v200 offset:2048
	ds_read_b128 v[200:203], v200 offset:3072
	s_add_u32 s36, s36, 0x80000
	s_addc_u32 s37, s37, 0
	s_mov_b32 m0, s44
	ds_read_b128 v[204:207], v171 offset:32768
	ds_read_b128 v[208:211], v171 offset:33792
	ds_read_b128 v[212:215], v171 offset:34816
	ds_read_b128 v[216:219], v171 offset:35840
	ds_read_b128 v[220:223], v171 offset:36864
	ds_read_b128 v[224:227], v171 offset:37888
	ds_read_b128 v[228:231], v171 offset:38912
	ds_read_b128 v[232:235], v171 offset:39936
	global_load_lds_dwordx4 v136, s[36:37]
	s_mov_b32 m0, s45
	s_nop 0
	global_load_lds_dwordx4 v132, s[36:37]
	s_waitcnt vmcnt(8) lgkmcnt(0)
	s_barrier
	v_mfma_f32_16x16x32_bf16 v[126:129], v[172:175], v[204:207], v[126:129]
	v_mfma_f32_16x16x32_bf16 v[122:125], v[180:183], v[204:207], v[122:125]
	v_mfma_f32_16x16x32_bf16 v[110:113], v[172:175], v[212:215], v[110:113]
	v_mfma_f32_16x16x32_bf16 v[106:109], v[180:183], v[212:215], v[106:109]
	v_mfma_f32_16x16x32_bf16 v[94:97], v[172:175], v[220:223], v[94:97]
	v_mfma_f32_16x16x32_bf16 v[90:93], v[180:183], v[220:223], v[90:93]
	v_mfma_f32_16x16x32_bf16 v[78:81], v[172:175], v[228:231], v[78:81]
	v_mfma_f32_16x16x32_bf16 v[74:77], v[180:183], v[228:231], v[74:77]
	v_mfma_f32_16x16x32_bf16 v[126:129], v[176:179], v[208:211], v[126:129]
	v_mfma_f32_16x16x32_bf16 v[122:125], v[184:187], v[208:211], v[122:125]
	v_mfma_f32_16x16x32_bf16 v[110:113], v[176:179], v[216:219], v[110:113]
	v_mfma_f32_16x16x32_bf16 v[106:109], v[184:187], v[216:219], v[106:109]
	v_mfma_f32_16x16x32_bf16 v[94:97], v[176:179], v[224:227], v[94:97]
	v_mfma_f32_16x16x32_bf16 v[90:93], v[184:187], v[224:227], v[90:93]
	v_mfma_f32_16x16x32_bf16 v[78:81], v[176:179], v[232:235], v[78:81]
	v_mfma_f32_16x16x32_bf16 v[74:77], v[184:187], v[232:235], v[74:77]
	v_mfma_f32_16x16x32_bf16 v[118:121], v[188:191], v[204:207], v[118:121]
	v_mfma_f32_16x16x32_bf16 v[114:117], v[196:199], v[204:207], v[114:117]
	v_mfma_f32_16x16x32_bf16 v[102:105], v[188:191], v[212:215], v[102:105]
	v_mfma_f32_16x16x32_bf16 v[98:101], v[196:199], v[212:215], v[98:101]
	v_mfma_f32_16x16x32_bf16 v[86:89], v[188:191], v[220:223], v[86:89]
	v_mfma_f32_16x16x32_bf16 v[82:85], v[196:199], v[220:223], v[82:85]
	v_mfma_f32_16x16x32_bf16 v[70:73], v[188:191], v[228:231], v[70:73]
	v_mfma_f32_16x16x32_bf16 v[66:69], v[196:199], v[228:231], v[66:69]
	v_mfma_f32_16x16x32_bf16 v[118:121], v[192:195], v[208:211], v[118:121]
	v_mfma_f32_16x16x32_bf16 v[114:117], v[200:203], v[208:211], v[114:117]
	v_mfma_f32_16x16x32_bf16 v[102:105], v[192:195], v[216:219], v[102:105]
	v_mfma_f32_16x16x32_bf16 v[98:101], v[200:203], v[216:219], v[98:101]
	v_mfma_f32_16x16x32_bf16 v[86:89], v[192:195], v[224:227], v[86:89]
	v_mfma_f32_16x16x32_bf16 v[82:85], v[200:203], v[224:227], v[82:85]
	v_mfma_f32_16x16x32_bf16 v[70:73], v[192:195], v[232:235], v[70:73]
	v_mfma_f32_16x16x32_bf16 v[66:69], v[200:203], v[232:235], v[66:69]
	s_barrier
	s_add_u32 s36, s34, 0x8000
	s_addc_u32 s37, s35, 0
	s_add_i32 s67, s60, s42
	s_mov_b32 m0, s67
	ds_read_b128 v[204:207], v171 offset:49152
	ds_read_b128 v[208:211], v171 offset:50176
	ds_read_b128 v[212:215], v171 offset:51200
	ds_read_b128 v[216:219], v171 offset:52224
	ds_read_b128 v[220:223], v171 offset:53248
	ds_read_b128 v[224:227], v171 offset:54272
	ds_read_b128 v[228:231], v171 offset:55296
	ds_read_b128 v[232:235], v171 offset:56320
	global_load_lds_dwordx4 v134, s[36:37]
	s_add_i32 m0, s67, 0x2000
	s_add_u32 s34, s34, 0xc000
	v_lshl_add_u64 v[236:237], s[36:37], 0, v[130:131]
	s_addc_u32 s35, s35, 0
	s_add_i32 s36, s61, s42
	global_load_lds_dwordx4 v[236:237], off
	s_mov_b32 m0, s36
	s_nop 0
	global_load_lds_dwordx4 v134, s[34:35]
	s_add_i32 m0, s36, 0x2000
	s_nop 0
	global_load_lds_dwordx4 v130, s[34:35]
	s_mov_b32 m0, s48
	s_nop 0
	global_load_lds_dwordx4 v136, s[30:31]
	s_mov_b32 m0, s49
	s_nop 0
	global_load_lds_dwordx4 v132, s[30:31]
	s_waitcnt vmcnt(8) lgkmcnt(0)
	s_barrier
	v_mfma_f32_16x16x32_bf16 v[62:65], v[172:175], v[204:207], v[62:65]
	v_mfma_f32_16x16x32_bf16 v[58:61], v[180:183], v[204:207], v[58:61]
	v_mfma_f32_16x16x32_bf16 v[46:49], v[172:175], v[212:215], v[46:49]
	v_mfma_f32_16x16x32_bf16 v[42:45], v[180:183], v[212:215], v[42:45]
	v_mfma_f32_16x16x32_bf16 v[30:33], v[172:175], v[220:223], v[30:33]
	v_mfma_f32_16x16x32_bf16 v[26:29], v[180:183], v[220:223], v[26:29]
	v_mfma_f32_16x16x32_bf16 v[14:17], v[172:175], v[228:231], v[14:17]
	v_mfma_f32_16x16x32_bf16 v[10:13], v[180:183], v[228:231], v[10:13]
	v_mfma_f32_16x16x32_bf16 v[62:65], v[176:179], v[208:211], v[62:65]
	v_mfma_f32_16x16x32_bf16 v[58:61], v[184:187], v[208:211], v[58:61]
	v_mfma_f32_16x16x32_bf16 v[46:49], v[176:179], v[216:219], v[46:49]
	v_mfma_f32_16x16x32_bf16 v[42:45], v[184:187], v[216:219], v[42:45]
	v_mfma_f32_16x16x32_bf16 v[30:33], v[176:179], v[224:227], v[30:33]
	v_mfma_f32_16x16x32_bf16 v[26:29], v[184:187], v[224:227], v[26:29]
	v_mfma_f32_16x16x32_bf16 v[14:17], v[176:179], v[232:235], v[14:17]
	v_mfma_f32_16x16x32_bf16 v[10:13], v[184:187], v[232:235], v[10:13]
	v_mfma_f32_16x16x32_bf16 v[54:57], v[188:191], v[204:207], v[54:57]
	v_mfma_f32_16x16x32_bf16 v[50:53], v[196:199], v[204:207], v[50:53]
	v_mfma_f32_16x16x32_bf16 v[38:41], v[188:191], v[212:215], v[38:41]
	v_mfma_f32_16x16x32_bf16 v[34:37], v[196:199], v[212:215], v[34:37]
	v_mfma_f32_16x16x32_bf16 v[22:25], v[188:191], v[220:223], v[22:25]
	v_mfma_f32_16x16x32_bf16 v[18:21], v[196:199], v[220:223], v[18:21]
	v_mfma_f32_16x16x32_bf16 v[6:9], v[188:191], v[228:231], v[6:9]
	v_mfma_f32_16x16x32_bf16 v[2:5], v[196:199], v[228:231], v[2:5]
	v_mfma_f32_16x16x32_bf16 v[54:57], v[192:195], v[208:211], v[54:57]
	v_mfma_f32_16x16x32_bf16 v[50:53], v[200:203], v[208:211], v[50:53]
	v_mfma_f32_16x16x32_bf16 v[38:41], v[192:195], v[216:219], v[38:41]
	v_mfma_f32_16x16x32_bf16 v[34:37], v[200:203], v[216:219], v[34:37]
	v_mfma_f32_16x16x32_bf16 v[22:25], v[192:195], v[224:227], v[22:25]
	v_mfma_f32_16x16x32_bf16 v[18:21], v[200:203], v[224:227], v[18:21]
	v_mfma_f32_16x16x32_bf16 v[6:9], v[192:195], v[232:235], v[6:9]
	v_mfma_f32_16x16x32_bf16 v[2:5], v[200:203], v[232:235], v[2:5]
	s_barrier
; __device__ __forceinline__ unsigned pk2(float lo, float hi) { const f32x2 v = {lo, hi}; return __builtin_bit_cast(unsigned, __builtin_convertvector(v, bf16x2_t)); }
; #define PG8_BAR __builtin_amdgcn_s_barrier()
; template <class Epi, class Sched, bool ABLK = false, bool ALIGN_EPI = true, bool SP2 = true, bool BBLK = true>
; __device__ __forceinline__ void gemm_phase(LAS unsigned char* lds, const Gemm g, const Sched& S, const Epi& E) {
;     ...
;         if constexpr (ALIGN_EPI) { if (wr == 0) PG8_BAR; }
;     __device__ __forceinline__ void operator()(const f32x4 (&acc)[2][2][4][2], const Unit& u, int wr, int wc, int fr, int fq) const {
; #pragma unroll
;         for (int ai = 0; ai < 2; ++ai)
; #pragma unroll
;             for (int m = 0; m < 4; ++m) { unsigned char* rowp = (unsigned char*)(H + ((size_t)(u.pm * (FF / 64) + u.pn * 4 + wc) * 256 + (wr * 64 + fr + ai * 128 + m * 16)) * 64 + 8 * fq); u32x4 w[2];
; #pragma unroll
;                 for (int bj = 0; bj < 2; ++bj) { f32x4 v0 = acc[ai][bj][m][0], v1 = acc[ai][bj][m][1];
; #pragma unroll
;                     for (int j = 0; j < 4; ++j) { const float a = fmaxf(v0[j], 0.f), b = fmaxf(v1[j], 0.f); v0[j] = a * a; v1[j] = b * b; }
;                     w[bj].x = pk2(v0[0], v0[1]); w[bj].y = pk2(v0[2], v0[3]); w[bj].z = pk2(v1[0], v1[1]); w[bj].w = pk2(v1[2], v1[3]); }
;                 store_pair(rowp, (size_t)8 * 64 * 2, 64, w[0], w[1], fr >= 8); }
	s_add_i32 s66, s66, 2
	s_add_u32 s28, s28, 0x100
	s_addc_u32 s29, s29, 0
	s_add_u32 s64, s64, 0x10000
	s_addc_u32 s65, s65, 0
	s_cmp_gt_u32 s66, 29
	s_cbranch_scc0 .LBB0_1164
	s_lshl_b32 s4, s22, 7
	s_lshl_b32 s5, s24, 2
	s_add_i32 s5, s5, s4
	s_or_b32 s4, s5, s47
	s_ashr_i32 s5, s4, 31
	s_lshl_b64 s[4:5], s[4:5], 15
	s_add_u32 s22, s1, s4
	v_max_f32_e32 v126, 0, v126
	v_max_f32_e32 v122, 0, v122
	v_max_f32_e32 v127, 0, v127
	v_max_f32_e32 v123, 0, v123
	v_max_f32_e32 v128, 0, v128
	v_max_f32_e32 v124, 0, v124
	v_max_f32_e32 v129, 0, v129
	v_max_f32_e32 v125, 0, v125
	v_max_f32_e32 v118, 0, v118
	v_max_f32_e32 v114, 0, v114
	v_max_f32_e32 v119, 0, v119
	v_max_f32_e32 v115, 0, v115
	v_max_f32_e32 v120, 0, v120
	v_max_f32_e32 v116, 0, v116
	v_max_f32_e32 v121, 0, v121
	v_max_f32_e32 v117, 0, v117
	s_addc_u32 s23, s33, s5
	v_pk_mul_f32 v[126:127], v[126:127], v[126:127]
	v_pk_mul_f32 v[122:123], v[122:123], v[122:123]
	v_pk_mul_f32 v[128:129], v[128:129], v[128:129]
	v_pk_mul_f32 v[124:125], v[124:125], v[124:125]
	v_pk_mul_f32 v[118:119], v[118:119], v[118:119]
	v_pk_mul_f32 v[114:115], v[114:115], v[114:115]
	v_pk_mul_f32 v[120:121], v[120:121], v[120:121]
	v_pk_mul_f32 v[116:117], v[116:117], v[116:117]
	v_lshl_add_u64 v[164:165], s[22:23], 0, v[144:145]
	v_cvt_pk_bf16_f32 v126, v126, v127
	v_cvt_pk_bf16_f32 v127, v128, v129
	v_cvt_pk_bf16_f32 v128, v122, v123
	v_cvt_pk_bf16_f32 v129, v124, v125
	v_cvt_pk_bf16_f32 v118, v118, v119
	v_cvt_pk_bf16_f32 v119, v120, v121
	v_cvt_pk_bf16_f32 v114, v114, v115
	v_cvt_pk_bf16_f32 v115, v116, v117
	v_lshl_add_u64 v[122:123], v[164:165], 0, v[138:139]
	v_mov_b32_dpp v120, v126 row_ror:8 row_mask:0xf bank_mask:0xf bound_ctrl:1
	v_mov_b32_dpp v121, v127 row_ror:8 row_mask:0xf bank_mask:0xf bound_ctrl:1
	v_mov_b32_dpp v116, v128 row_ror:8 row_mask:0xf bank_mask:0xf bound_ctrl:1
	v_mov_b32_dpp v117, v129 row_ror:8 row_mask:0xf bank_mask:0xf bound_ctrl:1
	v_mov_b32_dpp v164, v118 row_ror:8 row_mask:0xf bank_mask:0xf bound_ctrl:1
	v_mov_b32_dpp v165, v119 row_ror:8 row_mask:0xf bank_mask:0xf bound_ctrl:1
	v_mov_b32_dpp v166, v114 row_ror:8 row_mask:0xf bank_mask:0xf bound_ctrl:1
	v_mov_b32_dpp v167, v115 row_ror:8 row_mask:0xf bank_mask:0xf bound_ctrl:1
	v_max_f32_e32 v110, 0, v110
	v_max_f32_e32 v106, 0, v106
	v_max_f32_e32 v111, 0, v111
	v_max_f32_e32 v107, 0, v107
	v_max_f32_e32 v112, 0, v112
	v_max_f32_e32 v108, 0, v108
	v_max_f32_e32 v113, 0, v113
	v_max_f32_e32 v109, 0, v109
	v_max_f32_e32 v102, 0, v102
	v_max_f32_e32 v98, 0, v98
	v_max_f32_e32 v103, 0, v103
	v_max_f32_e32 v99, 0, v99
	v_max_f32_e32 v104, 0, v104
	v_max_f32_e32 v100, 0, v100
	v_max_f32_e32 v105, 0, v105
	v_max_f32_e32 v101, 0, v101
	v_lshl_add_u64 v[124:125], v[122:123], 0, v[140:141]
	v_cndmask_b32_e64 v117, v117, v115, s[8:9]
	v_cndmask_b32_e64 v116, v116, v114, s[8:9]
	v_cndmask_b32_e64 v115, v121, v119, s[8:9]
	v_cndmask_b32_e64 v114, v120, v118, s[8:9]
	v_cndmask_b32_e64 v121, v129, v167, s[8:9]
	v_cndmask_b32_e64 v120, v128, v166, s[8:9]
	v_cndmask_b32_e64 v119, v127, v165, s[8:9]
	v_cndmask_b32_e64 v118, v126, v164, s[8:9]
	v_pk_mul_f32 v[110:111], v[110:111], v[110:111]
	v_pk_mul_f32 v[106:107], v[106:107], v[106:107]
	v_pk_mul_f32 v[112:113], v[112:113], v[112:113]
	v_pk_mul_f32 v[108:109], v[108:109], v[108:109]
	v_pk_mul_f32 v[102:103], v[102:103], v[102:103]
	v_pk_mul_f32 v[98:99], v[98:99], v[98:99]
	v_pk_mul_f32 v[104:105], v[104:105], v[104:105]
	v_pk_mul_f32 v[100:101], v[100:101], v[100:101]
	v_lshl_add_u64 v[122:123], v[122:123], 0, v[142:143]
	global_store_dwordx4 v[124:125], v[118:121], off
	global_store_dwordx4 v[122:123], v[114:117], off
	v_cvt_pk_bf16_f32 v110, v110, v111
	v_cvt_pk_bf16_f32 v111, v112, v113
	v_lshl_add_u64 v[114:115], s[22:23], 0, v[146:147]
	v_cvt_pk_bf16_f32 v112, v106, v107
	v_cvt_pk_bf16_f32 v113, v108, v109
	v_cvt_pk_bf16_f32 v102, v102, v103
	v_cvt_pk_bf16_f32 v103, v104, v105
	v_cvt_pk_bf16_f32 v98, v98, v99
	v_cvt_pk_bf16_f32 v99, v100, v101
	v_lshl_add_u64 v[106:107], v[114:115], 0, v[138:139]
	v_mov_b32_dpp v104, v110 row_ror:8 row_mask:0xf bank_mask:0xf bound_ctrl:1
	v_mov_b32_dpp v105, v111 row_ror:8 row_mask:0xf bank_mask:0xf bound_ctrl:1
	v_mov_b32_dpp v100, v112 row_ror:8 row_mask:0xf bank_mask:0xf bound_ctrl:1
	v_mov_b32_dpp v101, v113 row_ror:8 row_mask:0xf bank_mask:0xf bound_ctrl:1
	v_mov_b32_dpp v114, v102 row_ror:8 row_mask:0xf bank_mask:0xf bound_ctrl:1
	v_mov_b32_dpp v115, v103 row_ror:8 row_mask:0xf bank_mask:0xf bound_ctrl:1
	v_mov_b32_dpp v116, v98 row_ror:8 row_mask:0xf bank_mask:0xf bound_ctrl:1
	v_mov_b32_dpp v117, v99 row_ror:8 row_mask:0xf bank_mask:0xf bound_ctrl:1
	v_max_f32_e32 v94, 0, v94
	v_max_f32_e32 v90, 0, v90
	v_max_f32_e32 v95, 0, v95
	v_max_f32_e32 v91, 0, v91
	v_max_f32_e32 v96, 0, v96
	v_max_f32_e32 v92, 0, v92
	v_max_f32_e32 v97, 0, v97
	v_max_f32_e32 v93, 0, v93
	v_max_f32_e32 v86, 0, v86
	v_max_f32_e32 v82, 0, v82
	v_max_f32_e32 v87, 0, v87
	v_max_f32_e32 v83, 0, v83
	v_max_f32_e32 v88, 0, v88
	v_max_f32_e32 v84, 0, v84
	v_max_f32_e32 v89, 0, v89
	v_max_f32_e32 v85, 0, v85
	v_lshl_add_u64 v[108:109], v[106:107], 0, v[140:141]
	v_cndmask_b32_e64 v101, v101, v99, s[8:9]
	v_cndmask_b32_e64 v100, v100, v98, s[8:9]
	v_cndmask_b32_e64 v99, v105, v103, s[8:9]
	v_cndmask_b32_e64 v98, v104, v102, s[8:9]
	v_cndmask_b32_e64 v105, v113, v117, s[8:9]
	v_cndmask_b32_e64 v104, v112, v116, s[8:9]
	v_cndmask_b32_e64 v103, v111, v115, s[8:9]
	v_cndmask_b32_e64 v102, v110, v114, s[8:9]
	v_pk_mul_f32 v[94:95], v[94:95], v[94:95]
	v_pk_mul_f32 v[90:91], v[90:91], v[90:91]
	v_pk_mul_f32 v[96:97], v[96:97], v[96:97]
	v_pk_mul_f32 v[92:93], v[92:93], v[92:93]
; __device__ __forceinline__ unsigned pk2(float lo, float hi) { const f32x2 v = {lo, hi}; return __builtin_bit_cast(unsigned, __builtin_convertvector(v, bf16x2_t)); }
;     __device__ __forceinline__ void operator()(const f32x4 (&acc)[2][2][4][2], const Unit& u, int wr, int wc, int fr, int fq) const {
;     ...
;             for (int m = 0; m < 4; ++m) { unsigned char* rowp = (unsigned char*)(H + ((size_t)(u.pm * (FF / 64) + u.pn * 4 + wc) * 256 + (wr * 64 + fr + ai * 128 + m * 16)) * 64 + 8 * fq); u32x4 w[2];
; #pragma unroll
;                 for (int bj = 0; bj < 2; ++bj) { f32x4 v0 = acc[ai][bj][m][0], v1 = acc[ai][bj][m][1];
; #pragma unroll
;                     for (int j = 0; j < 4; ++j) { const float a = fmaxf(v0[j], 0.f), b = fmaxf(v1[j], 0.f); v0[j] = a * a; v1[j] = b * b; }
;                     w[bj].x = pk2(v0[0], v0[1]); w[bj].y = pk2(v0[2], v0[3]); w[bj].z = pk2(v1[0], v1[1]); w[bj].w = pk2(v1[2], v1[3]); }
;                 store_pair(rowp, (size_t)8 * 64 * 2, 64, w[0], w[1], fr >= 8); }
	v_pk_mul_f32 v[86:87], v[86:87], v[86:87]
	v_pk_mul_f32 v[82:83], v[82:83], v[82:83]
	v_pk_mul_f32 v[88:89], v[88:89], v[88:89]
	v_pk_mul_f32 v[84:85], v[84:85], v[84:85]
	v_lshl_add_u64 v[106:107], v[106:107], 0, v[142:143]
	global_store_dwordx4 v[108:109], v[102:105], off
	global_store_dwordx4 v[106:107], v[98:101], off
	v_cvt_pk_bf16_f32 v94, v94, v95
	v_cvt_pk_bf16_f32 v95, v96, v97
	v_lshl_add_u64 v[98:99], s[22:23], 0, v[148:149]
	v_cvt_pk_bf16_f32 v96, v90, v91
	v_cvt_pk_bf16_f32 v97, v92, v93
	v_cvt_pk_bf16_f32 v86, v86, v87
	v_cvt_pk_bf16_f32 v87, v88, v89
	v_cvt_pk_bf16_f32 v82, v82, v83
	v_cvt_pk_bf16_f32 v83, v84, v85
	v_lshl_add_u64 v[90:91], v[98:99], 0, v[138:139]
	v_mov_b32_dpp v88, v94 row_ror:8 row_mask:0xf bank_mask:0xf bound_ctrl:1
	v_mov_b32_dpp v89, v95 row_ror:8 row_mask:0xf bank_mask:0xf bound_ctrl:1
	v_mov_b32_dpp v84, v96 row_ror:8 row_mask:0xf bank_mask:0xf bound_ctrl:1
	v_mov_b32_dpp v85, v97 row_ror:8 row_mask:0xf bank_mask:0xf bound_ctrl:1
	v_mov_b32_dpp v98, v86 row_ror:8 row_mask:0xf bank_mask:0xf bound_ctrl:1
	v_mov_b32_dpp v99, v87 row_ror:8 row_mask:0xf bank_mask:0xf bound_ctrl:1
	v_mov_b32_dpp v100, v82 row_ror:8 row_mask:0xf bank_mask:0xf bound_ctrl:1
	v_mov_b32_dpp v101, v83 row_ror:8 row_mask:0xf bank_mask:0xf bound_ctrl:1
	v_max_f32_e32 v78, 0, v78
	v_max_f32_e32 v74, 0, v74
	v_max_f32_e32 v79, 0, v79
	v_max_f32_e32 v75, 0, v75
	v_max_f32_e32 v80, 0, v80
	v_max_f32_e32 v76, 0, v76
	v_max_f32_e32 v81, 0, v81
	v_max_f32_e32 v77, 0, v77
	v_max_f32_e32 v70, 0, v70
	v_max_f32_e32 v66, 0, v66
	v_max_f32_e32 v71, 0, v71
	v_max_f32_e32 v67, 0, v67
	v_max_f32_e32 v72, 0, v72
	v_max_f32_e32 v68, 0, v68
	v_max_f32_e32 v73, 0, v73
	v_max_f32_e32 v69, 0, v69
	v_lshl_add_u64 v[92:93], v[90:91], 0, v[140:141]
	v_cndmask_b32_e64 v85, v85, v83, s[8:9]
	v_cndmask_b32_e64 v84, v84, v82, s[8:9]
	v_cndmask_b32_e64 v83, v89, v87, s[8:9]
	v_cndmask_b32_e64 v82, v88, v86, s[8:9]
	v_cndmask_b32_e64 v89, v97, v101, s[8:9]
	v_cndmask_b32_e64 v88, v96, v100, s[8:9]
	v_cndmask_b32_e64 v87, v95, v99, s[8:9]
	v_cndmask_b32_e64 v86, v94, v98, s[8:9]
	v_pk_mul_f32 v[78:79], v[78:79], v[78:79]
	v_pk_mul_f32 v[74:75], v[74:75], v[74:75]
	v_pk_mul_f32 v[80:81], v[80:81], v[80:81]
	v_pk_mul_f32 v[76:77], v[76:77], v[76:77]
	v_pk_mul_f32 v[70:71], v[70:71], v[70:71]
	v_pk_mul_f32 v[66:67], v[66:67], v[66:67]
	v_pk_mul_f32 v[72:73], v[72:73], v[72:73]
	v_pk_mul_f32 v[68:69], v[68:69], v[68:69]
	v_lshl_add_u64 v[90:91], v[90:91], 0, v[142:143]
	global_store_dwordx4 v[92:93], v[86:89], off
	global_store_dwordx4 v[90:91], v[82:85], off
	v_cvt_pk_bf16_f32 v78, v78, v79
	v_cvt_pk_bf16_f32 v79, v80, v81
	v_lshl_add_u64 v[82:83], s[22:23], 0, v[150:151]
	v_cvt_pk_bf16_f32 v80, v74, v75
	v_cvt_pk_bf16_f32 v81, v76, v77
	v_cvt_pk_bf16_f32 v70, v70, v71
	v_cvt_pk_bf16_f32 v71, v72, v73
	v_cvt_pk_bf16_f32 v66, v66, v67
	v_cvt_pk_bf16_f32 v67, v68, v69
	v_lshl_add_u64 v[74:75], v[82:83], 0, v[138:139]
	v_mov_b32_dpp v72, v78 row_ror:8 row_mask:0xf bank_mask:0xf bound_ctrl:1
	v_mov_b32_dpp v73, v79 row_ror:8 row_mask:0xf bank_mask:0xf bound_ctrl:1
	v_mov_b32_dpp v68, v80 row_ror:8 row_mask:0xf bank_mask:0xf bound_ctrl:1
	v_mov_b32_dpp v69, v81 row_ror:8 row_mask:0xf bank_mask:0xf bound_ctrl:1
	v_mov_b32_dpp v82, v70 row_ror:8 row_mask:0xf bank_mask:0xf bound_ctrl:1
	v_mov_b32_dpp v83, v71 row_ror:8 row_mask:0xf bank_mask:0xf bound_ctrl:1
	v_mov_b32_dpp v84, v66 row_ror:8 row_mask:0xf bank_mask:0xf bound_ctrl:1
	v_mov_b32_dpp v85, v67 row_ror:8 row_mask:0xf bank_mask:0xf bound_ctrl:1
	v_max_f32_e32 v62, 0, v62
	v_max_f32_e32 v58, 0, v58
	v_max_f32_e32 v63, 0, v63
	v_max_f32_e32 v59, 0, v59
	v_max_f32_e32 v64, 0, v64
	v_max_f32_e32 v60, 0, v60
	v_max_f32_e32 v65, 0, v65
	v_max_f32_e32 v61, 0, v61
	v_max_f32_e32 v54, 0, v54
	v_max_f32_e32 v50, 0, v50
	v_max_f32_e32 v55, 0, v55
	v_max_f32_e32 v51, 0, v51
	v_max_f32_e32 v56, 0, v56
	v_max_f32_e32 v52, 0, v52
	v_max_f32_e32 v57, 0, v57
	v_max_f32_e32 v53, 0, v53
	v_lshl_add_u64 v[76:77], v[74:75], 0, v[140:141]
	v_cndmask_b32_e64 v69, v69, v67, s[8:9]
	v_cndmask_b32_e64 v68, v68, v66, s[8:9]
	v_cndmask_b32_e64 v67, v73, v71, s[8:9]
	v_cndmask_b32_e64 v66, v72, v70, s[8:9]
	v_cndmask_b32_e64 v73, v81, v85, s[8:9]
	v_cndmask_b32_e64 v72, v80, v84, s[8:9]
	v_cndmask_b32_e64 v71, v79, v83, s[8:9]
	v_cndmask_b32_e64 v70, v78, v82, s[8:9]
	v_pk_mul_f32 v[62:63], v[62:63], v[62:63]
	v_pk_mul_f32 v[58:59], v[58:59], v[58:59]
	v_pk_mul_f32 v[64:65], v[64:65], v[64:65]
	v_pk_mul_f32 v[60:61], v[60:61], v[60:61]
	v_pk_mul_f32 v[54:55], v[54:55], v[54:55]
	v_pk_mul_f32 v[50:51], v[50:51], v[50:51]
	v_pk_mul_f32 v[56:57], v[56:57], v[56:57]
	v_pk_mul_f32 v[52:53], v[52:53], v[52:53]
	v_lshl_add_u64 v[74:75], v[74:75], 0, v[142:143]
	global_store_dwordx4 v[76:77], v[70:73], off
	global_store_dwordx4 v[74:75], v[66:69], off
	v_cvt_pk_bf16_f32 v62, v62, v63
	v_cvt_pk_bf16_f32 v63, v64, v65
	v_lshl_add_u64 v[66:67], s[22:23], 0, v[152:153]
	v_cvt_pk_bf16_f32 v64, v58, v59
	v_cvt_pk_bf16_f32 v65, v60, v61
	v_cvt_pk_bf16_f32 v54, v54, v55
	v_cvt_pk_bf16_f32 v55, v56, v57
	v_cvt_pk_bf16_f32 v50, v50, v51
	v_cvt_pk_bf16_f32 v51, v52, v53
	v_lshl_add_u64 v[58:59], v[66:67], 0, v[138:139]
	v_mov_b32_dpp v56, v62 row_ror:8 row_mask:0xf bank_mask:0xf bound_ctrl:1
	v_mov_b32_dpp v57, v63 row_ror:8 row_mask:0xf bank_mask:0xf bound_ctrl:1
	v_mov_b32_dpp v52, v64 row_ror:8 row_mask:0xf bank_mask:0xf bound_ctrl:1
	v_mov_b32_dpp v53, v65 row_ror:8 row_mask:0xf bank_mask:0xf bound_ctrl:1
	v_mov_b32_dpp v66, v54 row_ror:8 row_mask:0xf bank_mask:0xf bound_ctrl:1
	v_mov_b32_dpp v67, v55 row_ror:8 row_mask:0xf bank_mask:0xf bound_ctrl:1
; __device__ __forceinline__ unsigned pk2(float lo, float hi) { const f32x2 v = {lo, hi}; return __builtin_bit_cast(unsigned, __builtin_convertvector(v, bf16x2_t)); }
;     __device__ __forceinline__ void operator()(const f32x4 (&acc)[2][2][4][2], const Unit& u, int wr, int wc, int fr, int fq) const {
;     ...
;             for (int m = 0; m < 4; ++m) { unsigned char* rowp = (unsigned char*)(H + ((size_t)(u.pm * (FF / 64) + u.pn * 4 + wc) * 256 + (wr * 64 + fr + ai * 128 + m * 16)) * 64 + 8 * fq); u32x4 w[2];
; #pragma unroll
;                 for (int bj = 0; bj < 2; ++bj) { f32x4 v0 = acc[ai][bj][m][0], v1 = acc[ai][bj][m][1];
; #pragma unroll
;                     for (int j = 0; j < 4; ++j) { const float a = fmaxf(v0[j], 0.f), b = fmaxf(v1[j], 0.f); v0[j] = a * a; v1[j] = b * b; }
;                     w[bj].x = pk2(v0[0], v0[1]); w[bj].y = pk2(v0[2], v0[3]); w[bj].z = pk2(v1[0], v1[1]); w[bj].w = pk2(v1[2], v1[3]); }
;                 store_pair(rowp, (size_t)8 * 64 * 2, 64, w[0], w[1], fr >= 8); }
	v_mov_b32_dpp v68, v50 row_ror:8 row_mask:0xf bank_mask:0xf bound_ctrl:1
	v_mov_b32_dpp v69, v51 row_ror:8 row_mask:0xf bank_mask:0xf bound_ctrl:1
	v_max_f32_e32 v46, 0, v46
	v_max_f32_e32 v42, 0, v42
	v_max_f32_e32 v47, 0, v47
	v_max_f32_e32 v43, 0, v43
	v_max_f32_e32 v48, 0, v48
	v_max_f32_e32 v44, 0, v44
	v_max_f32_e32 v49, 0, v49
	v_max_f32_e32 v45, 0, v45
	v_max_f32_e32 v38, 0, v38
	v_max_f32_e32 v34, 0, v34
	v_max_f32_e32 v39, 0, v39
	v_max_f32_e32 v35, 0, v35
	v_max_f32_e32 v40, 0, v40
	v_max_f32_e32 v36, 0, v36
	v_max_f32_e32 v41, 0, v41
	v_max_f32_e32 v37, 0, v37
	v_lshl_add_u64 v[60:61], v[58:59], 0, v[140:141]
	v_cndmask_b32_e64 v53, v53, v51, s[8:9]
	v_cndmask_b32_e64 v52, v52, v50, s[8:9]
	v_cndmask_b32_e64 v51, v57, v55, s[8:9]
	v_cndmask_b32_e64 v50, v56, v54, s[8:9]
	v_cndmask_b32_e64 v57, v65, v69, s[8:9]
	v_cndmask_b32_e64 v56, v64, v68, s[8:9]
	v_cndmask_b32_e64 v55, v63, v67, s[8:9]
	v_cndmask_b32_e64 v54, v62, v66, s[8:9]
	v_pk_mul_f32 v[46:47], v[46:47], v[46:47]
	v_pk_mul_f32 v[42:43], v[42:43], v[42:43]
	v_pk_mul_f32 v[48:49], v[48:49], v[48:49]
	v_pk_mul_f32 v[44:45], v[44:45], v[44:45]
	v_pk_mul_f32 v[38:39], v[38:39], v[38:39]
	v_pk_mul_f32 v[34:35], v[34:35], v[34:35]
	v_pk_mul_f32 v[40:41], v[40:41], v[40:41]
	v_pk_mul_f32 v[36:37], v[36:37], v[36:37]
	v_lshl_add_u64 v[58:59], v[58:59], 0, v[142:143]
	global_store_dwordx4 v[60:61], v[54:57], off
	global_store_dwordx4 v[58:59], v[50:53], off
	v_cvt_pk_bf16_f32 v46, v46, v47
	v_cvt_pk_bf16_f32 v47, v48, v49
	v_lshl_add_u64 v[50:51], s[22:23], 0, v[154:155]
	v_cvt_pk_bf16_f32 v48, v42, v43
	v_cvt_pk_bf16_f32 v49, v44, v45
	v_cvt_pk_bf16_f32 v38, v38, v39
	v_cvt_pk_bf16_f32 v39, v40, v41
	v_cvt_pk_bf16_f32 v34, v34, v35
	v_cvt_pk_bf16_f32 v35, v36, v37
	v_lshl_add_u64 v[42:43], v[50:51], 0, v[138:139]
	v_mov_b32_dpp v40, v46 row_ror:8 row_mask:0xf bank_mask:0xf bound_ctrl:1
	v_mov_b32_dpp v41, v47 row_ror:8 row_mask:0xf bank_mask:0xf bound_ctrl:1
	v_mov_b32_dpp v36, v48 row_ror:8 row_mask:0xf bank_mask:0xf bound_ctrl:1
	v_mov_b32_dpp v37, v49 row_ror:8 row_mask:0xf bank_mask:0xf bound_ctrl:1
	v_mov_b32_dpp v50, v38 row_ror:8 row_mask:0xf bank_mask:0xf bound_ctrl:1
	v_mov_b32_dpp v51, v39 row_ror:8 row_mask:0xf bank_mask:0xf bound_ctrl:1
	v_mov_b32_dpp v52, v34 row_ror:8 row_mask:0xf bank_mask:0xf bound_ctrl:1
	v_mov_b32_dpp v53, v35 row_ror:8 row_mask:0xf bank_mask:0xf bound_ctrl:1
	v_max_f32_e32 v30, 0, v30
	v_max_f32_e32 v26, 0, v26
	v_max_f32_e32 v31, 0, v31
	v_max_f32_e32 v27, 0, v27
	v_max_f32_e32 v32, 0, v32
	v_max_f32_e32 v28, 0, v28
	v_max_f32_e32 v33, 0, v33
	v_max_f32_e32 v29, 0, v29
	v_max_f32_e32 v22, 0, v22
	v_max_f32_e32 v18, 0, v18
	v_max_f32_e32 v23, 0, v23
	v_max_f32_e32 v19, 0, v19
	v_max_f32_e32 v24, 0, v24
	v_max_f32_e32 v20, 0, v20
	v_max_f32_e32 v25, 0, v25
	v_max_f32_e32 v21, 0, v21
	v_lshl_add_u64 v[44:45], v[42:43], 0, v[140:141]
	v_cndmask_b32_e64 v37, v37, v35, s[8:9]
	v_cndmask_b32_e64 v36, v36, v34, s[8:9]
	v_cndmask_b32_e64 v35, v41, v39, s[8:9]
	v_cndmask_b32_e64 v34, v40, v38, s[8:9]
	v_cndmask_b32_e64 v41, v49, v53, s[8:9]
	v_cndmask_b32_e64 v40, v48, v52, s[8:9]
	v_cndmask_b32_e64 v39, v47, v51, s[8:9]
	v_cndmask_b32_e64 v38, v46, v50, s[8:9]
	v_pk_mul_f32 v[30:31], v[30:31], v[30:31]
	v_pk_mul_f32 v[26:27], v[26:27], v[26:27]
	v_pk_mul_f32 v[32:33], v[32:33], v[32:33]
	v_pk_mul_f32 v[28:29], v[28:29], v[28:29]
	v_pk_mul_f32 v[22:23], v[22:23], v[22:23]
	v_pk_mul_f32 v[18:19], v[18:19], v[18:19]
	v_pk_mul_f32 v[24:25], v[24:25], v[24:25]
	v_pk_mul_f32 v[20:21], v[20:21], v[20:21]
	v_lshl_add_u64 v[42:43], v[42:43], 0, v[142:143]
	global_store_dwordx4 v[44:45], v[38:41], off
; __device__ __forceinline__ unsigned pk2(float lo, float hi) { const f32x2 v = {lo, hi}; return __builtin_bit_cast(unsigned, __builtin_convertvector(v, bf16x2_t)); }
; #define PG8_BAR __builtin_amdgcn_s_barrier()
; template <class Epi, class Sched, bool ABLK = false, bool ALIGN_EPI = true, bool SP2 = true, bool BBLK = true>
; __device__ __forceinline__ void gemm_phase(LAS unsigned char* lds, const Gemm g, const Sched& S, const Epi& E) {
;     ...
;         if constexpr (ALIGN_EPI) { if (wr == 0) PG8_BAR; }
;     __device__ __forceinline__ void operator()(const f32x4 (&acc)[2][2][4][2], const Unit& u, int wr, int wc, int fr, int fq) const {
;     ...
;             for (int m = 0; m < 4; ++m) { unsigned char* rowp = (unsigned char*)(H + ((size_t)(u.pm * (FF / 64) + u.pn * 4 + wc) * 256 + (wr * 64 + fr + ai * 128 + m * 16)) * 64 + 8 * fq); u32x4 w[2];
; #pragma unroll
;                 for (int bj = 0; bj < 2; ++bj) { f32x4 v0 = acc[ai][bj][m][0], v1 = acc[ai][bj][m][1];
; #pragma unroll
;                     for (int j = 0; j < 4; ++j) { const float a = fmaxf(v0[j], 0.f), b = fmaxf(v1[j], 0.f); v0[j] = a * a; v1[j] = b * b; }
;                     w[bj].x = pk2(v0[0], v0[1]); w[bj].y = pk2(v0[2], v0[3]); w[bj].z = pk2(v1[0], v1[1]); w[bj].w = pk2(v1[2], v1[3]); }
;                 store_pair(rowp, (size_t)8 * 64 * 2, 64, w[0], w[1], fr >= 8); }
	global_store_dwordx4 v[42:43], v[34:37], off
	v_cvt_pk_bf16_f32 v30, v30, v31
	v_cvt_pk_bf16_f32 v31, v32, v33
	v_lshl_add_u64 v[34:35], s[22:23], 0, v[156:157]
	v_cvt_pk_bf16_f32 v32, v26, v27
	v_cvt_pk_bf16_f32 v33, v28, v29
	v_cvt_pk_bf16_f32 v22, v22, v23
	v_cvt_pk_bf16_f32 v23, v24, v25
	v_cvt_pk_bf16_f32 v18, v18, v19
	v_cvt_pk_bf16_f32 v19, v20, v21
	v_lshl_add_u64 v[26:27], v[34:35], 0, v[138:139]
	v_mov_b32_dpp v24, v30 row_ror:8 row_mask:0xf bank_mask:0xf bound_ctrl:1
	v_mov_b32_dpp v25, v31 row_ror:8 row_mask:0xf bank_mask:0xf bound_ctrl:1
	v_mov_b32_dpp v20, v32 row_ror:8 row_mask:0xf bank_mask:0xf bound_ctrl:1
	v_mov_b32_dpp v21, v33 row_ror:8 row_mask:0xf bank_mask:0xf bound_ctrl:1
	v_mov_b32_dpp v34, v22 row_ror:8 row_mask:0xf bank_mask:0xf bound_ctrl:1
	v_mov_b32_dpp v35, v23 row_ror:8 row_mask:0xf bank_mask:0xf bound_ctrl:1
	v_mov_b32_dpp v36, v18 row_ror:8 row_mask:0xf bank_mask:0xf bound_ctrl:1
	v_mov_b32_dpp v37, v19 row_ror:8 row_mask:0xf bank_mask:0xf bound_ctrl:1
	v_max_f32_e32 v14, 0, v14
	v_max_f32_e32 v10, 0, v10
	v_max_f32_e32 v15, 0, v15
	v_max_f32_e32 v11, 0, v11
	v_max_f32_e32 v16, 0, v16
	v_max_f32_e32 v12, 0, v12
	v_max_f32_e32 v17, 0, v17
	v_max_f32_e32 v13, 0, v13
	v_max_f32_e32 v6, 0, v6
	v_max_f32_e32 v2, 0, v2
	v_max_f32_e32 v7, 0, v7
	v_max_f32_e32 v3, 0, v3
	v_max_f32_e32 v8, 0, v8
	v_max_f32_e32 v4, 0, v4
	v_max_f32_e32 v9, 0, v9
	v_max_f32_e32 v5, 0, v5
	v_lshl_add_u64 v[28:29], v[26:27], 0, v[140:141]
	v_cndmask_b32_e64 v21, v21, v19, s[8:9]
	v_cndmask_b32_e64 v20, v20, v18, s[8:9]
	v_cndmask_b32_e64 v19, v25, v23, s[8:9]
	v_cndmask_b32_e64 v18, v24, v22, s[8:9]
	v_cndmask_b32_e64 v25, v33, v37, s[8:9]
	v_cndmask_b32_e64 v24, v32, v36, s[8:9]
	v_cndmask_b32_e64 v23, v31, v35, s[8:9]
	v_cndmask_b32_e64 v22, v30, v34, s[8:9]
	v_pk_mul_f32 v[14:15], v[14:15], v[14:15]
	v_pk_mul_f32 v[10:11], v[10:11], v[10:11]
	v_pk_mul_f32 v[16:17], v[16:17], v[16:17]
	v_pk_mul_f32 v[12:13], v[12:13], v[12:13]
	v_pk_mul_f32 v[6:7], v[6:7], v[6:7]
	v_pk_mul_f32 v[2:3], v[2:3], v[2:3]
	v_pk_mul_f32 v[8:9], v[8:9], v[8:9]
	v_pk_mul_f32 v[4:5], v[4:5], v[4:5]
	v_lshl_add_u64 v[26:27], v[26:27], 0, v[142:143]
	global_store_dwordx4 v[28:29], v[22:25], off
	global_store_dwordx4 v[26:27], v[18:21], off
	v_cvt_pk_bf16_f32 v14, v14, v15
	v_cvt_pk_bf16_f32 v15, v16, v17
	v_lshl_add_u64 v[18:19], s[22:23], 0, v[158:159]
	v_cvt_pk_bf16_f32 v16, v10, v11
	v_cvt_pk_bf16_f32 v17, v12, v13
	v_cvt_pk_bf16_f32 v6, v6, v7
	v_cvt_pk_bf16_f32 v7, v8, v9
	v_cvt_pk_bf16_f32 v2, v2, v3
	v_cvt_pk_bf16_f32 v3, v4, v5
	v_lshl_add_u64 v[10:11], v[18:19], 0, v[138:139]
	v_mov_b32_dpp v8, v14 row_ror:8 row_mask:0xf bank_mask:0xf bound_ctrl:1
	v_mov_b32_dpp v9, v15 row_ror:8 row_mask:0xf bank_mask:0xf bound_ctrl:1
	v_mov_b32_dpp v4, v16 row_ror:8 row_mask:0xf bank_mask:0xf bound_ctrl:1
	v_mov_b32_dpp v5, v17 row_ror:8 row_mask:0xf bank_mask:0xf bound_ctrl:1
	v_mov_b32_dpp v18, v6 row_ror:8 row_mask:0xf bank_mask:0xf bound_ctrl:1
	v_mov_b32_dpp v19, v7 row_ror:8 row_mask:0xf bank_mask:0xf bound_ctrl:1
	v_mov_b32_dpp v20, v2 row_ror:8 row_mask:0xf bank_mask:0xf bound_ctrl:1
	v_mov_b32_dpp v21, v3 row_ror:8 row_mask:0xf bank_mask:0xf bound_ctrl:1
	v_lshl_add_u64 v[12:13], v[10:11], 0, v[140:141]
	v_cndmask_b32_e64 v5, v5, v3, s[8:9]
	v_cndmask_b32_e64 v4, v4, v2, s[8:9]
	v_cndmask_b32_e64 v3, v9, v7, s[8:9]
	v_cndmask_b32_e64 v2, v8, v6, s[8:9]
	v_cndmask_b32_e64 v9, v17, v21, s[8:9]
	v_cndmask_b32_e64 v8, v16, v20, s[8:9]
	v_cndmask_b32_e64 v7, v15, v19, s[8:9]
	v_cndmask_b32_e64 v6, v14, v18, s[8:9]
	s_and_b64 vcc, exec, s[6:7]
	s_cbranch_vccz .LBB0_1167
	s_barrier

; #define PG8_STAGE(bufoff, gbase, voff) do { _Pragma("unroll") for (int _i = 0; _i < 2; ++_i) \
;         __builtin_amdgcn_global_load_lds((const unsigned*)((const char*)(gbase) + (voff)[_i]), (LAS unsigned*)(lds + (bufoff) + ldsw + _i * 8192), 16, 0, 0); } while (0)
; #define PG8_LDA(dst, b, h) do { _Pragma("unroll") for (int m = 0; m < 4; ++m) _Pragma("unroll") for (int k = 0; k < 2; ++k) dst[m][k] = *(const LAS bf16x8*)(lds + PG8_SA(b, h) + aoff + m * 2048 + k * 1024); } while (0)
; #define PG8_LDB(dst, b, h) do { _Pragma("unroll") for (int n = 0; n < 2; ++n) _Pragma("unroll") for (int k = 0; k < 2; ++k) dst[n][k] = *(const LAS bf16x8*)(lds + PG8_SB(b, h) + boff + n * 2048 + k * 1024); } while (0)
; #define PG8_MMA(ai, bj, At, Bt) do { __builtin_amdgcn_s_setprio(1); _Pragma("unroll") for (int m = 0; m < 4; ++m) _Pragma("unroll") for (int n = 0; n < 2; ++n) _Pragma("unroll") for (int k = 0; k < 2; ++k) \
;         acc[ai][bj][m][n] = __builtin_amdgcn_mfma_f32_16x16x32_bf16(Bt[n][k], At[m][k], acc[ai][bj][m][n], 0, 0, 0); __builtin_amdgcn_s_setprio(0); } while (0)
; #define PG8_WAIT_V(n) asm volatile("s_waitcnt vmcnt(" #n ")" ::: "memory")
; #define PG8_WAIT_L(n) asm volatile("s_waitcnt lgkmcnt(" #n ")" ::: "memory")
; #define PG8_BAR __builtin_amdgcn_s_barrier()
; #define PG8_SCHED __builtin_amdgcn_sched_barrier(0)
; template <class Epi, class Sched, bool ABLK = false, bool ALIGN_EPI = true, bool SP2 = true, bool BBLK = true>
; __device__ __forceinline__ void gemm_phase(LAS unsigned char* lds, const Gemm g, const Sched& S, const Epi& E) {
;     ...
;             if constexpr (SP2) {
;             PG8_LDB(B0, 0, 0); PG8_LDB(B1, 0, 1); PG8_SCHED; PG8_LDA(At, 0, 0); PG8_STAGE(PG8_SA(1, 1), a1 + hstepA, voffA);
;             PG8_WAIT_V(8); PG8_WAIT_L(0); PG8_BAR; PG8_MMA(0, 0, At, B0); PG8_MMA(0, 1, At, B1); PG8_BAR; PG8_SCHED;
.LBB0_1229:
	ds_read_b128 v[152:155], v149
	ds_read_b128 v[156:159], v149 offset:1024
	ds_read_b128 v[160:163], v149 offset:2048
	ds_read_b128 v[164:167], v149 offset:3072
	ds_read_b128 v[168:171], v150
	ds_read_b128 v[172:175], v150 offset:1024
	ds_read_b128 v[176:179], v150 offset:2048
	ds_read_b128 v[180:183], v150 offset:3072
	s_add_u32 s24, s51, s22
	s_addc_u32 s25, s55, s23
	s_add_u32 s28, s24, 0x10000
	s_addc_u32 s29, s25, 0
	s_add_i32 s57, s57, 2
	s_add_u32 s26, s49, s22
	s_addc_u32 s27, s50, s23
	s_add_u32 s24, s24, 0x18000
	s_addc_u32 s25, s25, 0
	s_cmp_eq_u32 s56, s22
	s_cselect_b32 s25, s48, s25
	s_cselect_b32 s24, s47, s24
	s_cselect_b32 s27, s4, s27
	s_cselect_b32 s26, s5, s26
	s_cselect_b32 s29, s46, s29
	s_cselect_b32 s28, s19, s28
	v_lshl_add_u64 v[216:217], v[142:143], 0, s[22:23]
	s_add_i32 m0, s35, 0xc000
	ds_read_b128 v[184:187], v151
	ds_read_b128 v[188:191], v151 offset:1024
	ds_read_b128 v[192:195], v151 offset:2048
	ds_read_b128 v[196:199], v151 offset:3072
	ds_read_b128 v[200:203], v151 offset:4096
	ds_read_b128 v[204:207], v151 offset:5120
	ds_read_b128 v[208:211], v151 offset:6144
	ds_read_b128 v[212:215], v151 offset:7168
	global_load_lds_dwordx4 v[216:217], off
	v_lshl_add_u64 v[216:217], v[144:145], 0, s[22:23]
	s_add_i32 m0, s35, 0xe000
	s_nop 0
	global_load_lds_dwordx4 v[216:217], off
	s_waitcnt vmcnt(8) lgkmcnt(0)
	s_barrier
	v_mfma_f32_16x16x32_bf16 v[126:129], v[152:155], v[184:187], v[126:129]
	v_mfma_f32_16x16x32_bf16 v[122:125], v[160:163], v[184:187], v[122:125]
	v_mfma_f32_16x16x32_bf16 v[110:113], v[152:155], v[192:195], v[110:113]
	v_mfma_f32_16x16x32_bf16 v[106:109], v[160:163], v[192:195], v[106:109]
	v_mfma_f32_16x16x32_bf16 v[94:97], v[152:155], v[200:203], v[94:97]
	v_mfma_f32_16x16x32_bf16 v[90:93], v[160:163], v[200:203], v[90:93]
	v_mfma_f32_16x16x32_bf16 v[78:81], v[152:155], v[208:211], v[78:81]
	v_mfma_f32_16x16x32_bf16 v[74:77], v[160:163], v[208:211], v[74:77]
	v_mfma_f32_16x16x32_bf16 v[126:129], v[156:159], v[188:191], v[126:129]
	v_mfma_f32_16x16x32_bf16 v[122:125], v[164:167], v[188:191], v[122:125]
	v_mfma_f32_16x16x32_bf16 v[110:113], v[156:159], v[196:199], v[110:113]
	v_mfma_f32_16x16x32_bf16 v[106:109], v[164:167], v[196:199], v[106:109]
	v_mfma_f32_16x16x32_bf16 v[94:97], v[156:159], v[204:207], v[94:97]
	v_mfma_f32_16x16x32_bf16 v[90:93], v[164:167], v[204:207], v[90:93]
	v_mfma_f32_16x16x32_bf16 v[78:81], v[156:159], v[212:215], v[78:81]
	v_mfma_f32_16x16x32_bf16 v[74:77], v[164:167], v[212:215], v[74:77]
	v_mfma_f32_16x16x32_bf16 v[118:121], v[168:171], v[184:187], v[118:121]
	v_mfma_f32_16x16x32_bf16 v[114:117], v[176:179], v[184:187], v[114:117]
	v_mfma_f32_16x16x32_bf16 v[102:105], v[168:171], v[192:195], v[102:105]
	v_mfma_f32_16x16x32_bf16 v[98:101], v[176:179], v[192:195], v[98:101]
	v_mfma_f32_16x16x32_bf16 v[86:89], v[168:171], v[200:203], v[86:89]
	v_mfma_f32_16x16x32_bf16 v[82:85], v[176:179], v[200:203], v[82:85]
	v_mfma_f32_16x16x32_bf16 v[70:73], v[168:171], v[208:211], v[70:73]
	v_mfma_f32_16x16x32_bf16 v[66:69], v[176:179], v[208:211], v[66:69]
	v_mfma_f32_16x16x32_bf16 v[118:121], v[172:175], v[188:191], v[118:121]
	v_mfma_f32_16x16x32_bf16 v[114:117], v[180:183], v[188:191], v[114:117]
	v_mfma_f32_16x16x32_bf16 v[102:105], v[172:175], v[196:199], v[102:105]
	v_mfma_f32_16x16x32_bf16 v[98:101], v[180:183], v[196:199], v[98:101]
	v_mfma_f32_16x16x32_bf16 v[86:89], v[172:175], v[204:207], v[86:89]
	v_mfma_f32_16x16x32_bf16 v[82:85], v[180:183], v[204:207], v[82:85]
	v_mfma_f32_16x16x32_bf16 v[70:73], v[172:175], v[212:215], v[70:73]
	v_mfma_f32_16x16x32_bf16 v[66:69], v[180:183], v[212:215], v[66:69]
	s_barrier
	s_add_i32 s59, s72, s34
	s_mov_b32 m0, s59
	ds_read_b128 v[184:187], v151 offset:16384
	ds_read_b128 v[188:191], v151 offset:17408
	ds_read_b128 v[192:195], v151 offset:18432
	ds_read_b128 v[196:199], v151 offset:19456
	ds_read_b128 v[200:203], v151 offset:20480
	ds_read_b128 v[204:207], v151 offset:21504
	ds_read_b128 v[208:211], v151 offset:22528
	ds_read_b128 v[212:215], v151 offset:23552
	global_load_lds_dwordx4 v130, s[26:27]
	s_add_i32 m0, s59, 0x2000
	s_add_u32 s64, s26, 0x4000
	s_addc_u32 s65, s27, 0
	s_add_i32 s59, s73, s34
	global_load_lds_dwordx4 v132, s[26:27]
	s_mov_b32 m0, s59
	s_nop 0
	global_load_lds_dwordx4 v130, s[64:65]
	s_add_i32 m0, s59, 0x2000
	s_nop 0
	global_load_lds_dwordx4 v132, s[64:65]
	s_mov_b32 m0, s35
	s_nop 0
	global_load_lds_dwordx4 v130, s[28:29]
	s_mov_b32 m0, s36
	s_nop 0
	global_load_lds_dwordx4 v132, s[28:29]
	s_waitcnt vmcnt(8) lgkmcnt(0)
	s_barrier
; #define PG8_STAGE(bufoff, gbase, voff) do { _Pragma("unroll") for (int _i = 0; _i < 2; ++_i) \
;         __builtin_amdgcn_global_load_lds((const unsigned*)((const char*)(gbase) + (voff)[_i]), (LAS unsigned*)(lds + (bufoff) + ldsw + _i * 8192), 16, 0, 0); } while (0)
; #define PG8_LDA(dst, b, h) do { _Pragma("unroll") for (int m = 0; m < 4; ++m) _Pragma("unroll") for (int k = 0; k < 2; ++k) dst[m][k] = *(const LAS bf16x8*)(lds + PG8_SA(b, h) + aoff + m * 2048 + k * 1024); } while (0)
; #define PG8_LDB(dst, b, h) do { _Pragma("unroll") for (int n = 0; n < 2; ++n) _Pragma("unroll") for (int k = 0; k < 2; ++k) dst[n][k] = *(const LAS bf16x8*)(lds + PG8_SB(b, h) + boff + n * 2048 + k * 1024); } while (0)
; #define PG8_MMA(ai, bj, At, Bt) do { __builtin_amdgcn_s_setprio(1); _Pragma("unroll") for (int m = 0; m < 4; ++m) _Pragma("unroll") for (int n = 0; n < 2; ++n) _Pragma("unroll") for (int k = 0; k < 2; ++k) \
;         acc[ai][bj][m][n] = __builtin_amdgcn_mfma_f32_16x16x32_bf16(Bt[n][k], At[m][k], acc[ai][bj][m][n], 0, 0, 0); __builtin_amdgcn_s_setprio(0); } while (0)
; #define PG8_WAIT_V(n) asm volatile("s_waitcnt vmcnt(" #n ")" ::: "memory")
; #define PG8_WAIT_L(n) asm volatile("s_waitcnt lgkmcnt(" #n ")" ::: "memory")
; #define PG8_BAR __builtin_amdgcn_s_barrier()
; #define PG8_SCHED __builtin_amdgcn_sched_barrier(0)
; template <class Epi, class Sched, bool ABLK = false, bool ALIGN_EPI = true, bool SP2 = true, bool BBLK = true>
; __device__ __forceinline__ void gemm_phase(LAS unsigned char* lds, const Gemm g, const Sched& S, const Epi& E) {
;     ...
;             PG8_WAIT_V(8); PG8_WAIT_L(0); PG8_BAR; PG8_MMA(0, 0, At, B0); PG8_MMA(0, 1, At, B1); PG8_BAR; PG8_SCHED;
;             PG8_LDA(At, 0, 1); PG8_STAGE(PG8_SB(0, 0), b2, voffB); PG8_STAGE(PG8_SB(0, 1), b2 + hstepB, voffB); PG8_STAGE(PG8_SA(0, 0), a2, voffA);
;             PG8_WAIT_V(8); PG8_WAIT_L(0); PG8_BAR; PG8_MMA(1, 0, At, B0); PG8_MMA(1, 1, At, B1); PG8_BAR; PG8_SCHED;
;             PG8_LDB(B0, 1, 0); PG8_LDB(B1, 1, 1); PG8_SCHED; PG8_LDA(At, 1, 0); PG8_STAGE(PG8_SA(0, 1), a2 + hstepA, voffA);
;             PG8_WAIT_V(8); PG8_WAIT_L(0); PG8_BAR; PG8_MMA(0, 0, At, B0); PG8_MMA(0, 1, At, B1); PG8_BAR; PG8_SCHED;
	v_mfma_f32_16x16x32_bf16 v[62:65], v[152:155], v[184:187], v[62:65]
	v_mfma_f32_16x16x32_bf16 v[58:61], v[160:163], v[184:187], v[58:61]
	v_mfma_f32_16x16x32_bf16 v[46:49], v[152:155], v[192:195], v[46:49]
	v_mfma_f32_16x16x32_bf16 v[42:45], v[160:163], v[192:195], v[42:45]
	v_mfma_f32_16x16x32_bf16 v[30:33], v[152:155], v[200:203], v[30:33]
	v_mfma_f32_16x16x32_bf16 v[26:29], v[160:163], v[200:203], v[26:29]
	v_mfma_f32_16x16x32_bf16 v[14:17], v[152:155], v[208:211], v[14:17]
	v_mfma_f32_16x16x32_bf16 v[10:13], v[160:163], v[208:211], v[10:13]
	v_mfma_f32_16x16x32_bf16 v[62:65], v[156:159], v[188:191], v[62:65]
	v_mfma_f32_16x16x32_bf16 v[58:61], v[164:167], v[188:191], v[58:61]
	v_mfma_f32_16x16x32_bf16 v[46:49], v[156:159], v[196:199], v[46:49]
	v_mfma_f32_16x16x32_bf16 v[42:45], v[164:167], v[196:199], v[42:45]
	v_mfma_f32_16x16x32_bf16 v[30:33], v[156:159], v[204:207], v[30:33]
	v_mfma_f32_16x16x32_bf16 v[26:29], v[164:167], v[204:207], v[26:29]
	v_mfma_f32_16x16x32_bf16 v[14:17], v[156:159], v[212:215], v[14:17]
	v_mfma_f32_16x16x32_bf16 v[10:13], v[164:167], v[212:215], v[10:13]
	v_mfma_f32_16x16x32_bf16 v[54:57], v[168:171], v[184:187], v[54:57]
	v_mfma_f32_16x16x32_bf16 v[50:53], v[176:179], v[184:187], v[50:53]
	v_mfma_f32_16x16x32_bf16 v[38:41], v[168:171], v[192:195], v[38:41]
	v_mfma_f32_16x16x32_bf16 v[34:37], v[176:179], v[192:195], v[34:37]
	v_mfma_f32_16x16x32_bf16 v[22:25], v[168:171], v[200:203], v[22:25]
	v_mfma_f32_16x16x32_bf16 v[18:21], v[176:179], v[200:203], v[18:21]
	v_mfma_f32_16x16x32_bf16 v[6:9], v[168:171], v[208:211], v[6:9]
	v_mfma_f32_16x16x32_bf16 v[2:5], v[176:179], v[208:211], v[2:5]
	v_mfma_f32_16x16x32_bf16 v[54:57], v[172:175], v[188:191], v[54:57]
	v_mfma_f32_16x16x32_bf16 v[50:53], v[180:183], v[188:191], v[50:53]
	v_mfma_f32_16x16x32_bf16 v[38:41], v[172:175], v[196:199], v[38:41]
	v_mfma_f32_16x16x32_bf16 v[34:37], v[180:183], v[196:199], v[34:37]
	v_mfma_f32_16x16x32_bf16 v[22:25], v[172:175], v[204:207], v[22:25]
	v_mfma_f32_16x16x32_bf16 v[18:21], v[180:183], v[204:207], v[18:21]
	v_mfma_f32_16x16x32_bf16 v[6:9], v[172:175], v[212:215], v[6:9]
	v_mfma_f32_16x16x32_bf16 v[2:5], v[180:183], v[212:215], v[2:5]
	s_barrier
	v_add_u32_e32 v164, s60, v147
	v_add_u32_e32 v180, s61, v147
	ds_read_b128 v[152:155], v164
	ds_read_b128 v[156:159], v164 offset:1024
	ds_read_b128 v[160:163], v164 offset:2048
	ds_read_b128 v[164:167], v164 offset:3072
	ds_read_b128 v[168:171], v180
	ds_read_b128 v[172:175], v180 offset:1024
	ds_read_b128 v[176:179], v180 offset:2048
	ds_read_b128 v[180:183], v180 offset:3072
	s_add_u32 s28, s28, 0x4000
	s_addc_u32 s29, s29, 0
	s_mov_b32 m0, s37
	ds_read_b128 v[184:187], v151 offset:32768
	ds_read_b128 v[188:191], v151 offset:33792
	ds_read_b128 v[192:195], v151 offset:34816
	ds_read_b128 v[196:199], v151 offset:35840
	ds_read_b128 v[200:203], v151 offset:36864
	ds_read_b128 v[204:207], v151 offset:37888
	ds_read_b128 v[208:211], v151 offset:38912
	ds_read_b128 v[212:215], v151 offset:39936
	global_load_lds_dwordx4 v130, s[28:29]
	s_mov_b32 m0, s40
	s_nop 0
	global_load_lds_dwordx4 v132, s[28:29]
	s_waitcnt vmcnt(8) lgkmcnt(0)
	s_barrier
	v_mfma_f32_16x16x32_bf16 v[126:129], v[152:155], v[184:187], v[126:129]
	v_mfma_f32_16x16x32_bf16 v[122:125], v[160:163], v[184:187], v[122:125]
	v_mfma_f32_16x16x32_bf16 v[110:113], v[152:155], v[192:195], v[110:113]
	v_mfma_f32_16x16x32_bf16 v[106:109], v[160:163], v[192:195], v[106:109]
	v_mfma_f32_16x16x32_bf16 v[94:97], v[152:155], v[200:203], v[94:97]
	v_mfma_f32_16x16x32_bf16 v[90:93], v[160:163], v[200:203], v[90:93]
	v_mfma_f32_16x16x32_bf16 v[78:81], v[152:155], v[208:211], v[78:81]
	v_mfma_f32_16x16x32_bf16 v[74:77], v[160:163], v[208:211], v[74:77]
	v_mfma_f32_16x16x32_bf16 v[126:129], v[156:159], v[188:191], v[126:129]
	v_mfma_f32_16x16x32_bf16 v[122:125], v[164:167], v[188:191], v[122:125]
	v_mfma_f32_16x16x32_bf16 v[110:113], v[156:159], v[196:199], v[110:113]
	v_mfma_f32_16x16x32_bf16 v[106:109], v[164:167], v[196:199], v[106:109]
	v_mfma_f32_16x16x32_bf16 v[94:97], v[156:159], v[204:207], v[94:97]
	v_mfma_f32_16x16x32_bf16 v[90:93], v[164:167], v[204:207], v[90:93]
	v_mfma_f32_16x16x32_bf16 v[78:81], v[156:159], v[212:215], v[78:81]
	v_mfma_f32_16x16x32_bf16 v[74:77], v[164:167], v[212:215], v[74:77]
	v_mfma_f32_16x16x32_bf16 v[118:121], v[168:171], v[184:187], v[118:121]
	v_mfma_f32_16x16x32_bf16 v[114:117], v[176:179], v[184:187], v[114:117]
	v_mfma_f32_16x16x32_bf16 v[102:105], v[168:171], v[192:195], v[102:105]
	v_mfma_f32_16x16x32_bf16 v[98:101], v[176:179], v[192:195], v[98:101]
	v_mfma_f32_16x16x32_bf16 v[86:89], v[168:171], v[200:203], v[86:89]
	v_mfma_f32_16x16x32_bf16 v[82:85], v[176:179], v[200:203], v[82:85]
	v_mfma_f32_16x16x32_bf16 v[70:73], v[168:171], v[208:211], v[70:73]
	v_mfma_f32_16x16x32_bf16 v[66:69], v[176:179], v[208:211], v[66:69]
	v_mfma_f32_16x16x32_bf16 v[118:121], v[172:175], v[188:191], v[118:121]
	v_mfma_f32_16x16x32_bf16 v[114:117], v[180:183], v[188:191], v[114:117]
	v_mfma_f32_16x16x32_bf16 v[102:105], v[172:175], v[196:199], v[102:105]
	v_mfma_f32_16x16x32_bf16 v[98:101], v[180:183], v[196:199], v[98:101]
	v_mfma_f32_16x16x32_bf16 v[86:89], v[172:175], v[204:207], v[86:89]
	v_mfma_f32_16x16x32_bf16 v[82:85], v[180:183], v[204:207], v[82:85]
	v_mfma_f32_16x16x32_bf16 v[70:73], v[172:175], v[212:215], v[70:73]
	v_mfma_f32_16x16x32_bf16 v[66:69], v[180:183], v[212:215], v[66:69]
	s_barrier
; __device__ __forceinline__ unsigned pk2(float lo, float hi) { const f32x2 v = {lo, hi}; return __builtin_bit_cast(unsigned, __builtin_convertvector(v, bf16x2_t)); }
; #define PG8_STAGE(bufoff, gbase, voff) do { _Pragma("unroll") for (int _i = 0; _i < 2; ++_i) \
;         __builtin_amdgcn_global_load_lds((const unsigned*)((const char*)(gbase) + (voff)[_i]), (LAS unsigned*)(lds + (bufoff) + ldsw + _i * 8192), 16, 0, 0); } while (0)
; #define PG8_LDA(dst, b, h) do { _Pragma("unroll") for (int m = 0; m < 4; ++m) _Pragma("unroll") for (int k = 0; k < 2; ++k) dst[m][k] = *(const LAS bf16x8*)(lds + PG8_SA(b, h) + aoff + m * 2048 + k * 1024); } while (0)
; #define PG8_WAIT_V(n) asm volatile("s_waitcnt vmcnt(" #n ")" ::: "memory")
; #define PG8_WAIT_L(n) asm volatile("s_waitcnt lgkmcnt(" #n ")" ::: "memory")
; #define PG8_BAR __builtin_amdgcn_s_barrier()
; #define PG8_SCHED __builtin_amdgcn_sched_barrier(0)
; template <class Epi, class Sched, bool ABLK = false, bool ALIGN_EPI = true, bool SP2 = true, bool BBLK = true>
; __device__ __forceinline__ void gemm_phase(LAS unsigned char* lds, const Gemm g, const Sched& S, const Epi& E) {
;     ...
;             PG8_WAIT_V(8); PG8_WAIT_L(0); PG8_BAR; PG8_MMA(0, 0, At, B0); PG8_MMA(0, 1, At, B1); PG8_BAR; PG8_SCHED;
;             PG8_LDA(At, 1, 1); PG8_STAGE(PG8_SB(1, 0), b3, voffB); PG8_STAGE(PG8_SB(1, 1), b3 + hstepB, voffB); PG8_STAGE(PG8_SA(1, 0), a3, voffA);
;             PG8_WAIT_V(8); PG8_WAIT_L(0); PG8_BAR; PG8_MMA(1, 0, At, B0); PG8_MMA(1, 1, At, B1); PG8_BAR; PG8_SCHED;
;     __device__ __forceinline__ void operator()(const f32x4 (&acc)[2][2][4][2], const Unit& u, int wr, int wc, int fr, int fq) const {
;         const int row0 = u.pm * 256 + wr * 64 + fr, col0 = u.pn * 256 + wc * 64 + 8 * fq;
;         bf16_t* base = u.part == 0 ? Z + (size_t)row0 * D + col0 : P + ((size_t)(u.part - 1) * MS + (row0 - MP)) * D + col0;
; #pragma unroll
;         for (int ai = 0; ai < 2; ++ai)
; #pragma unroll
;             for (int m = 0; m < 4; ++m) { u32x4 w[2];
; #pragma unroll
;                 for (int bj = 0; bj < 2; ++bj) { const f32x4 v0 = acc[ai][bj][m][0], v1 = acc[ai][bj][m][1]; w[bj].x = pk2(v0[0], v0[1]); w[bj].y = pk2(v0[2], v0[3]); w[bj].z = pk2(v1[0], v1[1]); w[bj].w = pk2(v1[2], v1[3]); }
;                 store_pair((unsigned char*)(base + (size_t)(ai * 128 + m * 16) * D), (size_t)8 * D * 2, 64, w[0], w[1], fr >= 8); }
	s_add_u32 s28, s26, 0x8000
	s_addc_u32 s29, s27, 0
	s_add_i32 s59, s60, s34
	s_mov_b32 m0, s59
	ds_read_b128 v[184:187], v151 offset:49152
	ds_read_b128 v[188:191], v151 offset:50176
	ds_read_b128 v[192:195], v151 offset:51200
	ds_read_b128 v[196:199], v151 offset:52224
	ds_read_b128 v[200:203], v151 offset:53248
	ds_read_b128 v[204:207], v151 offset:54272
	ds_read_b128 v[208:211], v151 offset:55296
	ds_read_b128 v[212:215], v151 offset:56320
	global_load_lds_dwordx4 v130, s[28:29]
	s_add_i32 m0, s59, 0x2000
	s_add_u32 s26, s26, 0xc000
	v_lshl_add_u64 v[216:217], s[28:29], 0, v[132:133]
	s_addc_u32 s27, s27, 0
	s_add_i32 s28, s61, s34
	global_load_lds_dwordx4 v[216:217], off
	s_mov_b32 m0, s28
	s_nop 0
	global_load_lds_dwordx4 v130, s[26:27]
	s_add_i32 m0, s28, 0x2000
	s_nop 0
	global_load_lds_dwordx4 v132, s[26:27]
	s_mov_b32 m0, s41
	s_nop 0
	global_load_lds_dwordx4 v130, s[24:25]
	s_mov_b32 m0, s42
	s_nop 0
	global_load_lds_dwordx4 v132, s[24:25]
	s_waitcnt vmcnt(8) lgkmcnt(0)
	s_barrier
	v_mfma_f32_16x16x32_bf16 v[62:65], v[152:155], v[184:187], v[62:65]
	v_mfma_f32_16x16x32_bf16 v[58:61], v[160:163], v[184:187], v[58:61]
	v_mfma_f32_16x16x32_bf16 v[46:49], v[152:155], v[192:195], v[46:49]
	v_mfma_f32_16x16x32_bf16 v[42:45], v[160:163], v[192:195], v[42:45]
	v_mfma_f32_16x16x32_bf16 v[30:33], v[152:155], v[200:203], v[30:33]
	v_mfma_f32_16x16x32_bf16 v[26:29], v[160:163], v[200:203], v[26:29]
	v_mfma_f32_16x16x32_bf16 v[14:17], v[152:155], v[208:211], v[14:17]
	v_mfma_f32_16x16x32_bf16 v[10:13], v[160:163], v[208:211], v[10:13]
	v_mfma_f32_16x16x32_bf16 v[62:65], v[156:159], v[188:191], v[62:65]
	v_mfma_f32_16x16x32_bf16 v[58:61], v[164:167], v[188:191], v[58:61]
	v_mfma_f32_16x16x32_bf16 v[46:49], v[156:159], v[196:199], v[46:49]
	v_mfma_f32_16x16x32_bf16 v[42:45], v[164:167], v[196:199], v[42:45]
	v_mfma_f32_16x16x32_bf16 v[30:33], v[156:159], v[204:207], v[30:33]
	v_mfma_f32_16x16x32_bf16 v[26:29], v[164:167], v[204:207], v[26:29]
	v_mfma_f32_16x16x32_bf16 v[14:17], v[156:159], v[212:215], v[14:17]
	v_mfma_f32_16x16x32_bf16 v[10:13], v[164:167], v[212:215], v[10:13]
	v_mfma_f32_16x16x32_bf16 v[54:57], v[168:171], v[184:187], v[54:57]
	v_mfma_f32_16x16x32_bf16 v[50:53], v[176:179], v[184:187], v[50:53]
	v_mfma_f32_16x16x32_bf16 v[38:41], v[168:171], v[192:195], v[38:41]
	v_mfma_f32_16x16x32_bf16 v[34:37], v[176:179], v[192:195], v[34:37]
	v_mfma_f32_16x16x32_bf16 v[22:25], v[168:171], v[200:203], v[22:25]
	v_mfma_f32_16x16x32_bf16 v[18:21], v[176:179], v[200:203], v[18:21]
	v_mfma_f32_16x16x32_bf16 v[6:9], v[168:171], v[208:211], v[6:9]
	v_mfma_f32_16x16x32_bf16 v[2:5], v[176:179], v[208:211], v[2:5]
	v_mfma_f32_16x16x32_bf16 v[54:57], v[172:175], v[188:191], v[54:57]
	v_mfma_f32_16x16x32_bf16 v[50:53], v[180:183], v[188:191], v[50:53]
	v_mfma_f32_16x16x32_bf16 v[38:41], v[172:175], v[196:199], v[38:41]
	v_mfma_f32_16x16x32_bf16 v[34:37], v[180:183], v[196:199], v[34:37]
	v_mfma_f32_16x16x32_bf16 v[22:25], v[172:175], v[204:207], v[22:25]
	v_mfma_f32_16x16x32_bf16 v[18:21], v[180:183], v[204:207], v[18:21]
	v_mfma_f32_16x16x32_bf16 v[6:9], v[172:175], v[212:215], v[6:9]
	v_mfma_f32_16x16x32_bf16 v[2:5], v[180:183], v[212:215], v[2:5]
	s_barrier
	s_add_u32 s22, s22, 0x10000
	s_addc_u32 s23, s23, 0
	s_cmp_ge_u32 s57, s44
	s_cbranch_scc0 .LBB0_1229
	v_lshl_add_u32 v143, s45, 8, v146
	v_add_u32_e32 v144, 0xffffe000, v143
	v_sub_co_u32_e64 v142, vcc, s43, 1
	v_mov_b32_e32 v145, s54
	s_nop 0
	v_cndmask_b32_e32 v144, v144, v143, vcc
	v_ashrrev_i32_e32 v143, 31, v142
	v_lshlrev_b64 v[142:143], 23, v[142:143]
	v_lshl_add_u64 v[142:143], s[12:13], 0, v[142:143]
	v_cndmask_b32_e32 v143, v143, v145, vcc
	v_mov_b32_e32 v145, s52
	v_cndmask_b32_e32 v142, v142, v145, vcc
	v_ashrrev_i32_e32 v145, 31, v144
	v_lshl_or_b32 v152, s78, 8, v148
	v_lshlrev_b64 v[144:145], 12, v[144:145]
	v_lshl_add_u64 v[142:143], v[142:143], 0, v[144:145]
	v_ashrrev_i32_e32 v153, 31, v152
	v_cvt_pk_bf16_f32 v126, v126, v127
	v_cvt_pk_bf16_f32 v127, v128, v129
	v_cvt_pk_bf16_f32 v128, v122, v123
	v_cvt_pk_bf16_f32 v124, v124, v125
	v_cvt_pk_bf16_f32 v118, v118, v119
	v_cvt_pk_bf16_f32 v119, v120, v121
	v_cvt_pk_bf16_f32 v114, v114, v115
	v_cvt_pk_bf16_f32 v115, v116, v117
	v_lshl_add_u64 v[142:143], v[152:153], 1, v[142:143]
	v_mov_b32_dpp v120, v126 row_ror:8 row_mask:0xf bank_mask:0xf bound_ctrl:1
	v_mov_b32_dpp v121, v127 row_ror:8 row_mask:0xf bank_mask:0xf bound_ctrl:1
	v_mov_b32_dpp v116, v128 row_ror:8 row_mask:0xf bank_mask:0xf bound_ctrl:1
	v_mov_b32_dpp v117, v124 row_ror:8 row_mask:0xf bank_mask:0xf bound_ctrl:1
	v_mov_b32_dpp v125, v118 row_ror:8 row_mask:0xf bank_mask:0xf bound_ctrl:1
	v_mov_b32_dpp v129, v119 row_ror:8 row_mask:0xf bank_mask:0xf bound_ctrl:1
	v_mov_b32_dpp v144, v114 row_ror:8 row_mask:0xf bank_mask:0xf bound_ctrl:1
	v_mov_b32_dpp v145, v115 row_ror:8 row_mask:0xf bank_mask:0xf bound_ctrl:1
	v_lshl_add_u64 v[122:123], v[142:143], 0, v[134:135]
	v_cndmask_b32_e64 v117, v117, v115, s[8:9]
	v_cndmask_b32_e64 v116, v116, v114, s[8:9]
	v_cndmask_b32_e64 v115, v121, v119, s[8:9]
	v_cndmask_b32_e64 v114, v120, v118, s[8:9]
	v_cndmask_b32_e64 v121, v124, v145, s[8:9]
	v_cndmask_b32_e64 v120, v128, v144, s[8:9]
	v_cndmask_b32_e64 v119, v127, v129, s[8:9]
	v_cndmask_b32_e64 v118, v126, v125, s[8:9]
	v_cvt_pk_bf16_f32 v110, v110, v111
	v_cvt_pk_bf16_f32 v111, v112, v113
	v_cvt_pk_bf16_f32 v112, v106, v107
	v_cvt_pk_bf16_f32 v113, v108, v109
	v_cvt_pk_bf16_f32 v102, v102, v103
	v_cvt_pk_bf16_f32 v103, v104, v105
	v_cvt_pk_bf16_f32 v98, v98, v99
	v_cvt_pk_bf16_f32 v99, v100, v101
	s_mov_b64 s[4:5], 0x10000
	v_lshl_add_u64 v[124:125], v[142:143], 0, v[136:137]
; __device__ __forceinline__ unsigned pk2(float lo, float hi) { const f32x2 v = {lo, hi}; return __builtin_bit_cast(unsigned, __builtin_convertvector(v, bf16x2_t)); }
;     __device__ __forceinline__ void operator()(const f32x4 (&acc)[2][2][4][2], const Unit& u, int wr, int wc, int fr, int fq) const {
;     ...
;         for (int ai = 0; ai < 2; ++ai)
; #pragma unroll
;             for (int m = 0; m < 4; ++m) { u32x4 w[2];
; #pragma unroll
;                 for (int bj = 0; bj < 2; ++bj) { const f32x4 v0 = acc[ai][bj][m][0], v1 = acc[ai][bj][m][1]; w[bj].x = pk2(v0[0], v0[1]); w[bj].y = pk2(v0[2], v0[3]); w[bj].z = pk2(v1[0], v1[1]); w[bj].w = pk2(v1[2], v1[3]); }
;                 store_pair((unsigned char*)(base + (size_t)(ai * 128 + m * 16) * D), (size_t)8 * D * 2, 64, w[0], w[1], fr >= 8); }
	global_store_dwordx4 v[122:123], v[118:121], off
	global_store_dwordx4 v[124:125], v[114:117], off
	v_lshl_add_u64 v[106:107], v[142:143], 0, s[4:5]
	v_mov_b32_dpp v104, v110 row_ror:8 row_mask:0xf bank_mask:0xf bound_ctrl:1
	v_mov_b32_dpp v105, v111 row_ror:8 row_mask:0xf bank_mask:0xf bound_ctrl:1
	v_mov_b32_dpp v100, v112 row_ror:8 row_mask:0xf bank_mask:0xf bound_ctrl:1
	v_mov_b32_dpp v101, v113 row_ror:8 row_mask:0xf bank_mask:0xf bound_ctrl:1
	v_mov_b32_dpp v114, v102 row_ror:8 row_mask:0xf bank_mask:0xf bound_ctrl:1
	v_mov_b32_dpp v115, v103 row_ror:8 row_mask:0xf bank_mask:0xf bound_ctrl:1
	v_mov_b32_dpp v116, v98 row_ror:8 row_mask:0xf bank_mask:0xf bound_ctrl:1
	v_mov_b32_dpp v117, v99 row_ror:8 row_mask:0xf bank_mask:0xf bound_ctrl:1
	v_lshl_add_u64 v[108:109], v[106:107], 0, v[134:135]
	v_cndmask_b32_e64 v101, v101, v99, s[8:9]
	v_cndmask_b32_e64 v100, v100, v98, s[8:9]
	v_cndmask_b32_e64 v99, v105, v103, s[8:9]
	v_cndmask_b32_e64 v98, v104, v102, s[8:9]
	v_cndmask_b32_e64 v105, v113, v117, s[8:9]
	v_cndmask_b32_e64 v104, v112, v116, s[8:9]
	v_cndmask_b32_e64 v103, v111, v115, s[8:9]
	v_cndmask_b32_e64 v102, v110, v114, s[8:9]
	v_cvt_pk_bf16_f32 v94, v94, v95
	v_cvt_pk_bf16_f32 v95, v96, v97
	v_cvt_pk_bf16_f32 v96, v90, v91
	v_cvt_pk_bf16_f32 v97, v92, v93
	v_cvt_pk_bf16_f32 v86, v86, v87
	v_cvt_pk_bf16_f32 v87, v88, v89
	v_cvt_pk_bf16_f32 v82, v82, v83
	v_cvt_pk_bf16_f32 v83, v84, v85
	s_mov_b64 s[4:5], 0x20000
	v_lshl_add_u64 v[106:107], v[106:107], 0, v[136:137]
	global_store_dwordx4 v[108:109], v[102:105], off
	global_store_dwordx4 v[106:107], v[98:101], off
	v_lshl_add_u64 v[90:91], v[142:143], 0, s[4:5]
	v_mov_b32_dpp v88, v94 row_ror:8 row_mask:0xf bank_mask:0xf bound_ctrl:1
	v_mov_b32_dpp v89, v95 row_ror:8 row_mask:0xf bank_mask:0xf bound_ctrl:1
	v_mov_b32_dpp v84, v96 row_ror:8 row_mask:0xf bank_mask:0xf bound_ctrl:1
	v_mov_b32_dpp v85, v97 row_ror:8 row_mask:0xf bank_mask:0xf bound_ctrl:1
	v_mov_b32_dpp v98, v86 row_ror:8 row_mask:0xf bank_mask:0xf bound_ctrl:1
	v_mov_b32_dpp v99, v87 row_ror:8 row_mask:0xf bank_mask:0xf bound_ctrl:1
	v_mov_b32_dpp v100, v82 row_ror:8 row_mask:0xf bank_mask:0xf bound_ctrl:1
	v_mov_b32_dpp v101, v83 row_ror:8 row_mask:0xf bank_mask:0xf bound_ctrl:1
	v_lshl_add_u64 v[92:93], v[90:91], 0, v[134:135]
	v_cndmask_b32_e64 v85, v85, v83, s[8:9]
	v_cndmask_b32_e64 v84, v84, v82, s[8:9]
	v_cndmask_b32_e64 v83, v89, v87, s[8:9]
	v_cndmask_b32_e64 v82, v88, v86, s[8:9]
	v_cndmask_b32_e64 v89, v97, v101, s[8:9]
	v_cndmask_b32_e64 v88, v96, v100, s[8:9]
	v_cndmask_b32_e64 v87, v95, v99, s[8:9]
	v_cndmask_b32_e64 v86, v94, v98, s[8:9]
	v_cvt_pk_bf16_f32 v78, v78, v79
	v_cvt_pk_bf16_f32 v79, v80, v81
	v_cvt_pk_bf16_f32 v80, v74, v75
	v_cvt_pk_bf16_f32 v81, v76, v77
	v_cvt_pk_bf16_f32 v70, v70, v71
	v_cvt_pk_bf16_f32 v71, v72, v73
	v_cvt_pk_bf16_f32 v66, v66, v67
	v_cvt_pk_bf16_f32 v67, v68, v69
	s_mov_b64 s[4:5], 0x30000
	v_lshl_add_u64 v[90:91], v[90:91], 0, v[136:137]
	global_store_dwordx4 v[92:93], v[86:89], off
	global_store_dwordx4 v[90:91], v[82:85], off
	v_lshl_add_u64 v[74:75], v[142:143], 0, s[4:5]
	v_mov_b32_dpp v72, v78 row_ror:8 row_mask:0xf bank_mask:0xf bound_ctrl:1
	v_mov_b32_dpp v73, v79 row_ror:8 row_mask:0xf bank_mask:0xf bound_ctrl:1
	v_mov_b32_dpp v68, v80 row_ror:8 row_mask:0xf bank_mask:0xf bound_ctrl:1
	v_mov_b32_dpp v69, v81 row_ror:8 row_mask:0xf bank_mask:0xf bound_ctrl:1
	v_mov_b32_dpp v82, v70 row_ror:8 row_mask:0xf bank_mask:0xf bound_ctrl:1
	v_mov_b32_dpp v83, v71 row_ror:8 row_mask:0xf bank_mask:0xf bound_ctrl:1
	v_mov_b32_dpp v84, v66 row_ror:8 row_mask:0xf bank_mask:0xf bound_ctrl:1
	v_mov_b32_dpp v85, v67 row_ror:8 row_mask:0xf bank_mask:0xf bound_ctrl:1
	v_lshl_add_u64 v[76:77], v[74:75], 0, v[134:135]
	v_cndmask_b32_e64 v69, v69, v67, s[8:9]
	v_cndmask_b32_e64 v68, v68, v66, s[8:9]
	v_cndmask_b32_e64 v67, v73, v71, s[8:9]
	v_cndmask_b32_e64 v66, v72, v70, s[8:9]
	v_cndmask_b32_e64 v73, v81, v85, s[8:9]
	v_cndmask_b32_e64 v72, v80, v84, s[8:9]
	v_cndmask_b32_e64 v71, v79, v83, s[8:9]
	v_cndmask_b32_e64 v70, v78, v82, s[8:9]
	v_cvt_pk_bf16_f32 v62, v62, v63
	v_cvt_pk_bf16_f32 v63, v64, v65
	v_cvt_pk_bf16_f32 v64, v58, v59
	v_cvt_pk_bf16_f32 v65, v60, v61
	v_cvt_pk_bf16_f32 v54, v54, v55
	v_cvt_pk_bf16_f32 v55, v56, v57
	v_cvt_pk_bf16_f32 v50, v50, v51
	v_cvt_pk_bf16_f32 v51, v52, v53
	s_mov_b64 s[4:5], 0x80000
	v_lshl_add_u64 v[74:75], v[74:75], 0, v[136:137]
	global_store_dwordx4 v[76:77], v[70:73], off
	global_store_dwordx4 v[74:75], v[66:69], off
	v_lshl_add_u64 v[58:59], v[142:143], 0, s[4:5]
	v_mov_b32_dpp v56, v62 row_ror:8 row_mask:0xf bank_mask:0xf bound_ctrl:1
	v_mov_b32_dpp v57, v63 row_ror:8 row_mask:0xf bank_mask:0xf bound_ctrl:1
	v_mov_b32_dpp v52, v64 row_ror:8 row_mask:0xf bank_mask:0xf bound_ctrl:1
	v_mov_b32_dpp v53, v65 row_ror:8 row_mask:0xf bank_mask:0xf bound_ctrl:1
	v_mov_b32_dpp v66, v54 row_ror:8 row_mask:0xf bank_mask:0xf bound_ctrl:1
	v_mov_b32_dpp v67, v55 row_ror:8 row_mask:0xf bank_mask:0xf bound_ctrl:1
	v_mov_b32_dpp v68, v50 row_ror:8 row_mask:0xf bank_mask:0xf bound_ctrl:1
; __device__ __forceinline__ unsigned pk2(float lo, float hi) { const f32x2 v = {lo, hi}; return __builtin_bit_cast(unsigned, __builtin_convertvector(v, bf16x2_t)); }
; #define PG8_BAR __builtin_amdgcn_s_barrier()
; template <class Epi, class Sched, bool ABLK = false, bool ALIGN_EPI = true, bool SP2 = true, bool BBLK = true>
; __device__ __forceinline__ void gemm_phase(LAS unsigned char* lds, const Gemm g, const Sched& S, const Epi& E) {
;     ...
;         if constexpr (ALIGN_EPI) { if (wr == 0) PG8_BAR; }
;         E(acc, cur, wr, wc, fr, fq); S.done(cur);
;         if (!has_next) break;
; #pragma unroll
;         for (int a = 0; a < 2; ++a)
; #pragma unroll
;             for (int b = 0; b < 2; ++b)
; #pragma unroll
;                 for (int m = 0; m < 4; ++m)
; #pragma unroll
;                     for (int n = 0; n < 2; ++n) acc[a][b][m][n] = (f32x4){0.f, 0.f, 0.f, 0.f};
;         cur = nxt; uA = nuA; tbA = ntbA; cB = nB; ++ui;
;         if constexpr (ALIGN_EPI) { if (wr == 1) PG8_BAR; }
;     __device__ __forceinline__ void operator()(const f32x4 (&acc)[2][2][4][2], const Unit& u, int wr, int wc, int fr, int fq) const {
;     ...
;         for (int ai = 0; ai < 2; ++ai)
; #pragma unroll
;             for (int m = 0; m < 4; ++m) { u32x4 w[2];
; #pragma unroll
;                 for (int bj = 0; bj < 2; ++bj) { const f32x4 v0 = acc[ai][bj][m][0], v1 = acc[ai][bj][m][1]; w[bj].x = pk2(v0[0], v0[1]); w[bj].y = pk2(v0[2], v0[3]); w[bj].z = pk2(v1[0], v1[1]); w[bj].w = pk2(v1[2], v1[3]); }
;                 store_pair((unsigned char*)(base + (size_t)(ai * 128 + m * 16) * D), (size_t)8 * D * 2, 64, w[0], w[1], fr >= 8); }
	v_mov_b32_dpp v69, v51 row_ror:8 row_mask:0xf bank_mask:0xf bound_ctrl:1
	v_lshl_add_u64 v[60:61], v[58:59], 0, v[134:135]
	v_cndmask_b32_e64 v53, v53, v51, s[8:9]
	v_cndmask_b32_e64 v52, v52, v50, s[8:9]
	v_cndmask_b32_e64 v51, v57, v55, s[8:9]
	v_cndmask_b32_e64 v50, v56, v54, s[8:9]
	v_cndmask_b32_e64 v57, v65, v69, s[8:9]
	v_cndmask_b32_e64 v56, v64, v68, s[8:9]
	v_cndmask_b32_e64 v55, v63, v67, s[8:9]
	v_cndmask_b32_e64 v54, v62, v66, s[8:9]
	v_cvt_pk_bf16_f32 v46, v46, v47
	v_cvt_pk_bf16_f32 v47, v48, v49
	v_cvt_pk_bf16_f32 v48, v42, v43
	v_cvt_pk_bf16_f32 v49, v44, v45
	v_cvt_pk_bf16_f32 v38, v38, v39
	v_cvt_pk_bf16_f32 v39, v40, v41
	v_cvt_pk_bf16_f32 v34, v34, v35
	v_cvt_pk_bf16_f32 v35, v36, v37
	s_mov_b64 s[4:5], 0x90000
	v_lshl_add_u64 v[58:59], v[58:59], 0, v[136:137]
	global_store_dwordx4 v[60:61], v[54:57], off
	global_store_dwordx4 v[58:59], v[50:53], off
	v_lshl_add_u64 v[42:43], v[142:143], 0, s[4:5]
	v_mov_b32_dpp v40, v46 row_ror:8 row_mask:0xf bank_mask:0xf bound_ctrl:1
	v_mov_b32_dpp v41, v47 row_ror:8 row_mask:0xf bank_mask:0xf bound_ctrl:1
	v_mov_b32_dpp v36, v48 row_ror:8 row_mask:0xf bank_mask:0xf bound_ctrl:1
	v_mov_b32_dpp v37, v49 row_ror:8 row_mask:0xf bank_mask:0xf bound_ctrl:1
	v_mov_b32_dpp v50, v38 row_ror:8 row_mask:0xf bank_mask:0xf bound_ctrl:1
	v_mov_b32_dpp v51, v39 row_ror:8 row_mask:0xf bank_mask:0xf bound_ctrl:1
	v_mov_b32_dpp v52, v34 row_ror:8 row_mask:0xf bank_mask:0xf bound_ctrl:1
	v_mov_b32_dpp v53, v35 row_ror:8 row_mask:0xf bank_mask:0xf bound_ctrl:1
	v_lshl_add_u64 v[44:45], v[42:43], 0, v[134:135]
	v_cndmask_b32_e64 v37, v37, v35, s[8:9]
	v_cndmask_b32_e64 v36, v36, v34, s[8:9]
	v_cndmask_b32_e64 v35, v41, v39, s[8:9]
	v_cndmask_b32_e64 v34, v40, v38, s[8:9]
	v_cndmask_b32_e64 v41, v49, v53, s[8:9]
	v_cndmask_b32_e64 v40, v48, v52, s[8:9]
	v_cndmask_b32_e64 v39, v47, v51, s[8:9]
	v_cndmask_b32_e64 v38, v46, v50, s[8:9]
	v_cvt_pk_bf16_f32 v30, v30, v31
	v_cvt_pk_bf16_f32 v31, v32, v33
	v_cvt_pk_bf16_f32 v32, v26, v27
	v_cvt_pk_bf16_f32 v33, v28, v29
	v_cvt_pk_bf16_f32 v22, v22, v23
	v_cvt_pk_bf16_f32 v23, v24, v25
	v_cvt_pk_bf16_f32 v18, v18, v19
	v_cvt_pk_bf16_f32 v19, v20, v21
	s_mov_b64 s[4:5], 0xa0000
	v_lshl_add_u64 v[42:43], v[42:43], 0, v[136:137]
	global_store_dwordx4 v[44:45], v[38:41], off
	global_store_dwordx4 v[42:43], v[34:37], off
	v_lshl_add_u64 v[26:27], v[142:143], 0, s[4:5]
	v_mov_b32_dpp v24, v30 row_ror:8 row_mask:0xf bank_mask:0xf bound_ctrl:1
	v_mov_b32_dpp v25, v31 row_ror:8 row_mask:0xf bank_mask:0xf bound_ctrl:1
	v_mov_b32_dpp v20, v32 row_ror:8 row_mask:0xf bank_mask:0xf bound_ctrl:1
	v_mov_b32_dpp v21, v33 row_ror:8 row_mask:0xf bank_mask:0xf bound_ctrl:1
	v_mov_b32_dpp v34, v22 row_ror:8 row_mask:0xf bank_mask:0xf bound_ctrl:1
	v_mov_b32_dpp v35, v23 row_ror:8 row_mask:0xf bank_mask:0xf bound_ctrl:1
	v_mov_b32_dpp v36, v18 row_ror:8 row_mask:0xf bank_mask:0xf bound_ctrl:1
	v_mov_b32_dpp v37, v19 row_ror:8 row_mask:0xf bank_mask:0xf bound_ctrl:1
	v_lshl_add_u64 v[28:29], v[26:27], 0, v[134:135]
	v_cndmask_b32_e64 v21, v21, v19, s[8:9]
	v_cndmask_b32_e64 v20, v20, v18, s[8:9]
	v_cndmask_b32_e64 v19, v25, v23, s[8:9]
	v_cndmask_b32_e64 v18, v24, v22, s[8:9]
	v_cndmask_b32_e64 v25, v33, v37, s[8:9]
	v_cndmask_b32_e64 v24, v32, v36, s[8:9]
	v_cndmask_b32_e64 v23, v31, v35, s[8:9]
	v_cndmask_b32_e64 v22, v30, v34, s[8:9]
	v_cvt_pk_bf16_f32 v14, v14, v15
	v_cvt_pk_bf16_f32 v15, v16, v17
	v_cvt_pk_bf16_f32 v16, v10, v11
	v_cvt_pk_bf16_f32 v17, v12, v13
	v_cvt_pk_bf16_f32 v6, v6, v7
	v_cvt_pk_bf16_f32 v7, v8, v9
	v_cvt_pk_bf16_f32 v2, v2, v3
	v_cvt_pk_bf16_f32 v3, v4, v5
	v_lshl_add_u64 v[26:27], v[26:27], 0, v[136:137]
	global_store_dwordx4 v[28:29], v[22:25], off
	global_store_dwordx4 v[26:27], v[18:21], off
	v_lshl_add_u64 v[10:11], v[142:143], 0, s[14:15]
	v_mov_b32_dpp v8, v14 row_ror:8 row_mask:0xf bank_mask:0xf bound_ctrl:1
	v_mov_b32_dpp v9, v15 row_ror:8 row_mask:0xf bank_mask:0xf bound_ctrl:1
	v_mov_b32_dpp v4, v16 row_ror:8 row_mask:0xf bank_mask:0xf bound_ctrl:1
	v_mov_b32_dpp v5, v17 row_ror:8 row_mask:0xf bank_mask:0xf bound_ctrl:1
	v_mov_b32_dpp v18, v6 row_ror:8 row_mask:0xf bank_mask:0xf bound_ctrl:1
	v_mov_b32_dpp v19, v7 row_ror:8 row_mask:0xf bank_mask:0xf bound_ctrl:1
	v_mov_b32_dpp v20, v2 row_ror:8 row_mask:0xf bank_mask:0xf bound_ctrl:1
	v_mov_b32_dpp v21, v3 row_ror:8 row_mask:0xf bank_mask:0xf bound_ctrl:1
	v_lshl_add_u64 v[12:13], v[10:11], 0, v[134:135]
	v_cndmask_b32_e64 v5, v5, v3, s[8:9]
	v_cndmask_b32_e64 v4, v4, v2, s[8:9]
	v_cndmask_b32_e64 v3, v9, v7, s[8:9]
	v_cndmask_b32_e64 v2, v8, v6, s[8:9]
	v_cndmask_b32_e64 v9, v17, v21, s[8:9]
	v_cndmask_b32_e64 v8, v16, v20, s[8:9]
	v_cndmask_b32_e64 v7, v15, v19, s[8:9]
	v_cndmask_b32_e64 v6, v14, v18, s[8:9]
	s_and_b64 vcc, exec, s[6:7]
	s_cbranch_vccz .LBB0_1232
	s_barrier
.LBB0_1232:
	s_and_b64 vcc, exec, s[10:11]
	s_mov_b64 s[10:11], -1
	v_lshl_add_u64 v[10:11], v[10:11], 0, v[136:137]
	global_store_dwordx4 v[12:13], v[6:9], off
	global_store_dwordx4 v[10:11], v[2:5], off
	s_cbranch_vccnz .LBB0_1227
	s_andn2_b64 vcc, exec, s[2:3]
	s_cbranch_vccnz .LBB0_1226
	s_barrier
	s_branch .LBB0_1226

; #define PG8_STAGE(bufoff, gbase, voff) do { _Pragma("unroll") for (int _i = 0; _i < 2; ++_i) \
;         __builtin_amdgcn_global_load_lds((const unsigned*)((const char*)(gbase) + (voff)[_i]), (LAS unsigned*)(lds + (bufoff) + ldsw + _i * 8192), 16, 0, 0); } while (0)
; #define PG8_LDA(dst, b, h) do { _Pragma("unroll") for (int m = 0; m < 4; ++m) _Pragma("unroll") for (int k = 0; k < 2; ++k) dst[m][k] = *(const LAS bf16x8*)(lds + PG8_SA(b, h) + aoff + m * 2048 + k * 1024); } while (0)
; #define PG8_LDB(dst, b, h) do { _Pragma("unroll") for (int n = 0; n < 2; ++n) _Pragma("unroll") for (int k = 0; k < 2; ++k) dst[n][k] = *(const LAS bf16x8*)(lds + PG8_SB(b, h) + boff + n * 2048 + k * 1024); } while (0)
; #define PG8_MMA(ai, bj, At, Bt) do { __builtin_amdgcn_s_setprio(1); _Pragma("unroll") for (int m = 0; m < 4; ++m) _Pragma("unroll") for (int n = 0; n < 2; ++n) _Pragma("unroll") for (int k = 0; k < 2; ++k) \
;         acc[ai][bj][m][n] = __builtin_amdgcn_mfma_f32_16x16x32_bf16(Bt[n][k], At[m][k], acc[ai][bj][m][n], 0, 0, 0); __builtin_amdgcn_s_setprio(0); } while (0)
; #define PG8_WAIT_V(n) asm volatile("s_waitcnt vmcnt(" #n ")" ::: "memory")
; #define PG8_WAIT_L(n) asm volatile("s_waitcnt lgkmcnt(" #n ")" ::: "memory")
; #define PG8_BAR __builtin_amdgcn_s_barrier()
; #define PG8_SCHED __builtin_amdgcn_sched_barrier(0)
; template <class Epi, class Sched, bool ABLK = false, bool ALIGN_EPI = true, bool SP2 = true, bool BBLK = true>
; __device__ __forceinline__ void gemm_phase(LAS unsigned char* lds, const Gemm g, const Sched& S, const Epi& E) {
;     ...
;             if constexpr (SP2) {
;             PG8_LDB(B0, 0, 0); PG8_LDB(B1, 0, 1); PG8_SCHED; PG8_LDA(At, 0, 0); PG8_STAGE(PG8_SA(1, 1), a1 + hstepA, voffA);
;             PG8_WAIT_V(8); PG8_WAIT_L(0); PG8_BAR; PG8_MMA(0, 0, At, B0); PG8_MMA(0, 1, At, B1); PG8_BAR; PG8_SCHED;
;             PG8_LDA(At, 0, 1); PG8_STAGE(PG8_SB(0, 0), b2, voffB); PG8_STAGE(PG8_SB(0, 1), b2 + hstepB, voffB); PG8_STAGE(PG8_SA(0, 0), a2, voffA);
;             PG8_WAIT_V(8); PG8_WAIT_L(0); PG8_BAR; PG8_MMA(1, 0, At, B0); PG8_MMA(1, 1, At, B1); PG8_BAR; PG8_SCHED;
.LBB0_1716:
	ds_read_b128 v[156:159], v152
	ds_read_b128 v[160:163], v152 offset:1024
	ds_read_b128 v[164:167], v152 offset:2048
	ds_read_b128 v[168:171], v152 offset:3072
	ds_read_b128 v[172:175], v153
	ds_read_b128 v[176:179], v153 offset:1024
	ds_read_b128 v[180:183], v153 offset:2048
	ds_read_b128 v[184:187], v153 offset:3072
	s_add_u32 s28, s54, s26
	s_addc_u32 s29, s55, s27
	s_add_u32 s34, s28, 0x100
	s_addc_u32 s35, s29, 0
	s_add_i32 s57, s57, 2
	s_add_u32 s28, s28, 0x180
	s_addc_u32 s29, s29, 0
	s_cmp_eq_u32 s56, s26
	s_cselect_b32 s29, s51, s29
	s_cselect_b32 s28, s50, s28
	s_cselect_b32 s31, s4, s53
	s_cselect_b32 s30, s5, s52
	s_cselect_b32 s35, s49, s35
	s_cselect_b32 s34, s23, s34
	v_lshl_add_u64 v[220:221], v[146:147], 0, s[26:27]
	s_add_i32 m0, s40, 0xc000
	ds_read_b128 v[188:191], v154
	ds_read_b128 v[192:195], v154 offset:1024
	ds_read_b128 v[196:199], v154 offset:2048
	ds_read_b128 v[200:203], v154 offset:3072
	ds_read_b128 v[204:207], v154 offset:4096
	ds_read_b128 v[208:211], v154 offset:5120
	ds_read_b128 v[212:215], v154 offset:6144
	ds_read_b128 v[216:219], v154 offset:7168
	global_load_lds_dwordx4 v[220:221], off
	v_lshl_add_u64 v[220:221], v[148:149], 0, s[26:27]
	s_add_i32 m0, s40, 0xe000
	s_nop 0
	global_load_lds_dwordx4 v[220:221], off
	s_waitcnt vmcnt(8) lgkmcnt(0)
	s_barrier
	v_mfma_f32_16x16x32_bf16 v[126:129], v[156:159], v[188:191], v[126:129]
	v_mfma_f32_16x16x32_bf16 v[122:125], v[164:167], v[188:191], v[122:125]
	v_mfma_f32_16x16x32_bf16 v[110:113], v[156:159], v[196:199], v[110:113]
	v_mfma_f32_16x16x32_bf16 v[106:109], v[164:167], v[196:199], v[106:109]
	v_mfma_f32_16x16x32_bf16 v[94:97], v[156:159], v[204:207], v[94:97]
	v_mfma_f32_16x16x32_bf16 v[90:93], v[164:167], v[204:207], v[90:93]
	v_mfma_f32_16x16x32_bf16 v[78:81], v[156:159], v[212:215], v[78:81]
	v_mfma_f32_16x16x32_bf16 v[74:77], v[164:167], v[212:215], v[74:77]
	v_mfma_f32_16x16x32_bf16 v[126:129], v[160:163], v[192:195], v[126:129]
	v_mfma_f32_16x16x32_bf16 v[122:125], v[168:171], v[192:195], v[122:125]
	v_mfma_f32_16x16x32_bf16 v[110:113], v[160:163], v[200:203], v[110:113]
	v_mfma_f32_16x16x32_bf16 v[106:109], v[168:171], v[200:203], v[106:109]
	v_mfma_f32_16x16x32_bf16 v[94:97], v[160:163], v[208:211], v[94:97]
	v_mfma_f32_16x16x32_bf16 v[90:93], v[168:171], v[208:211], v[90:93]
	v_mfma_f32_16x16x32_bf16 v[78:81], v[160:163], v[216:219], v[78:81]
	v_mfma_f32_16x16x32_bf16 v[74:77], v[168:171], v[216:219], v[74:77]
	v_mfma_f32_16x16x32_bf16 v[118:121], v[172:175], v[188:191], v[118:121]
	v_mfma_f32_16x16x32_bf16 v[114:117], v[180:183], v[188:191], v[114:117]
	v_mfma_f32_16x16x32_bf16 v[102:105], v[172:175], v[196:199], v[102:105]
	v_mfma_f32_16x16x32_bf16 v[98:101], v[180:183], v[196:199], v[98:101]
	v_mfma_f32_16x16x32_bf16 v[86:89], v[172:175], v[204:207], v[86:89]
	v_mfma_f32_16x16x32_bf16 v[82:85], v[180:183], v[204:207], v[82:85]
	v_mfma_f32_16x16x32_bf16 v[70:73], v[172:175], v[212:215], v[70:73]
	v_mfma_f32_16x16x32_bf16 v[66:69], v[180:183], v[212:215], v[66:69]
	v_mfma_f32_16x16x32_bf16 v[118:121], v[176:179], v[192:195], v[118:121]
	v_mfma_f32_16x16x32_bf16 v[114:117], v[184:187], v[192:195], v[114:117]
	v_mfma_f32_16x16x32_bf16 v[102:105], v[176:179], v[200:203], v[102:105]
	v_mfma_f32_16x16x32_bf16 v[98:101], v[184:187], v[200:203], v[98:101]
	v_mfma_f32_16x16x32_bf16 v[86:89], v[176:179], v[208:211], v[86:89]
	v_mfma_f32_16x16x32_bf16 v[82:85], v[184:187], v[208:211], v[82:85]
	v_mfma_f32_16x16x32_bf16 v[70:73], v[176:179], v[216:219], v[70:73]
	v_mfma_f32_16x16x32_bf16 v[66:69], v[184:187], v[216:219], v[66:69]
	s_barrier
	s_add_i32 s58, s72, s39
	s_mov_b32 m0, s58
	ds_read_b128 v[188:191], v154 offset:16384
	ds_read_b128 v[192:195], v154 offset:17408
	ds_read_b128 v[196:199], v154 offset:18432
	ds_read_b128 v[200:203], v154 offset:19456
	ds_read_b128 v[204:207], v154 offset:20480
	ds_read_b128 v[208:211], v154 offset:21504
	ds_read_b128 v[212:215], v154 offset:22528
	ds_read_b128 v[216:219], v154 offset:23552
	global_load_lds_dwordx4 v132, s[30:31]
	s_add_i32 m0, s58, 0x2000
	s_add_u32 s58, s30, 0x4000
	s_addc_u32 s59, s31, 0
	s_add_i32 s64, s73, s39
	global_load_lds_dwordx4 v136, s[30:31]
	s_mov_b32 m0, s64
	s_nop 0
	global_load_lds_dwordx4 v132, s[58:59]
	s_add_i32 m0, s64, 0x2000
	s_nop 0
	global_load_lds_dwordx4 v136, s[58:59]
	s_mov_b32 m0, s40
	s_nop 0
	global_load_lds_dwordx4 v130, s[34:35]
	s_mov_b32 m0, s41
	s_nop 0
	global_load_lds_dwordx4 v134, s[34:35]
	s_waitcnt vmcnt(8) lgkmcnt(0)
	s_barrier
	v_mfma_f32_16x16x32_bf16 v[62:65], v[156:159], v[188:191], v[62:65]
	v_mfma_f32_16x16x32_bf16 v[58:61], v[164:167], v[188:191], v[58:61]
	v_mfma_f32_16x16x32_bf16 v[46:49], v[156:159], v[196:199], v[46:49]
	v_mfma_f32_16x16x32_bf16 v[42:45], v[164:167], v[196:199], v[42:45]
	v_mfma_f32_16x16x32_bf16 v[30:33], v[156:159], v[204:207], v[30:33]
	v_mfma_f32_16x16x32_bf16 v[26:29], v[164:167], v[204:207], v[26:29]
	v_mfma_f32_16x16x32_bf16 v[14:17], v[156:159], v[212:215], v[14:17]
	v_mfma_f32_16x16x32_bf16 v[10:13], v[164:167], v[212:215], v[10:13]
	v_mfma_f32_16x16x32_bf16 v[62:65], v[160:163], v[192:195], v[62:65]
	v_mfma_f32_16x16x32_bf16 v[58:61], v[168:171], v[192:195], v[58:61]
	v_mfma_f32_16x16x32_bf16 v[46:49], v[160:163], v[200:203], v[46:49]
	v_mfma_f32_16x16x32_bf16 v[42:45], v[168:171], v[200:203], v[42:45]
	v_mfma_f32_16x16x32_bf16 v[30:33], v[160:163], v[208:211], v[30:33]
	v_mfma_f32_16x16x32_bf16 v[26:29], v[168:171], v[208:211], v[26:29]
	v_mfma_f32_16x16x32_bf16 v[14:17], v[160:163], v[216:219], v[14:17]
	v_mfma_f32_16x16x32_bf16 v[10:13], v[168:171], v[216:219], v[10:13]
	v_mfma_f32_16x16x32_bf16 v[54:57], v[172:175], v[188:191], v[54:57]
	v_mfma_f32_16x16x32_bf16 v[50:53], v[180:183], v[188:191], v[50:53]
	v_mfma_f32_16x16x32_bf16 v[38:41], v[172:175], v[196:199], v[38:41]
	v_mfma_f32_16x16x32_bf16 v[34:37], v[180:183], v[196:199], v[34:37]
	v_mfma_f32_16x16x32_bf16 v[22:25], v[172:175], v[204:207], v[22:25]
	v_mfma_f32_16x16x32_bf16 v[18:21], v[180:183], v[204:207], v[18:21]
	v_mfma_f32_16x16x32_bf16 v[6:9], v[172:175], v[212:215], v[6:9]
	v_mfma_f32_16x16x32_bf16 v[2:5], v[180:183], v[212:215], v[2:5]
	v_mfma_f32_16x16x32_bf16 v[54:57], v[176:179], v[192:195], v[54:57]
	v_mfma_f32_16x16x32_bf16 v[50:53], v[184:187], v[192:195], v[50:53]
	v_mfma_f32_16x16x32_bf16 v[38:41], v[176:179], v[200:203], v[38:41]
	v_mfma_f32_16x16x32_bf16 v[34:37], v[184:187], v[200:203], v[34:37]
	v_mfma_f32_16x16x32_bf16 v[22:25], v[176:179], v[208:211], v[22:25]
	v_mfma_f32_16x16x32_bf16 v[18:21], v[184:187], v[208:211], v[18:21]
	v_mfma_f32_16x16x32_bf16 v[6:9], v[176:179], v[216:219], v[6:9]
	v_mfma_f32_16x16x32_bf16 v[2:5], v[184:187], v[216:219], v[2:5]
	s_barrier
; #define PG8_STAGE(bufoff, gbase, voff) do { _Pragma("unroll") for (int _i = 0; _i < 2; ++_i) \
;         __builtin_amdgcn_global_load_lds((const unsigned*)((const char*)(gbase) + (voff)[_i]), (LAS unsigned*)(lds + (bufoff) + ldsw + _i * 8192), 16, 0, 0); } while (0)
; #define PG8_LDA(dst, b, h) do { _Pragma("unroll") for (int m = 0; m < 4; ++m) _Pragma("unroll") for (int k = 0; k < 2; ++k) dst[m][k] = *(const LAS bf16x8*)(lds + PG8_SA(b, h) + aoff + m * 2048 + k * 1024); } while (0)
; #define PG8_LDB(dst, b, h) do { _Pragma("unroll") for (int n = 0; n < 2; ++n) _Pragma("unroll") for (int k = 0; k < 2; ++k) dst[n][k] = *(const LAS bf16x8*)(lds + PG8_SB(b, h) + boff + n * 2048 + k * 1024); } while (0)
; #define PG8_MMA(ai, bj, At, Bt) do { __builtin_amdgcn_s_setprio(1); _Pragma("unroll") for (int m = 0; m < 4; ++m) _Pragma("unroll") for (int n = 0; n < 2; ++n) _Pragma("unroll") for (int k = 0; k < 2; ++k) \
;         acc[ai][bj][m][n] = __builtin_amdgcn_mfma_f32_16x16x32_bf16(Bt[n][k], At[m][k], acc[ai][bj][m][n], 0, 0, 0); __builtin_amdgcn_s_setprio(0); } while (0)
; #define PG8_WAIT_V(n) asm volatile("s_waitcnt vmcnt(" #n ")" ::: "memory")
; #define PG8_WAIT_L(n) asm volatile("s_waitcnt lgkmcnt(" #n ")" ::: "memory")
; #define PG8_BAR __builtin_amdgcn_s_barrier()
; #define PG8_SCHED __builtin_amdgcn_sched_barrier(0)
; template <class Epi, class Sched, bool ABLK = false, bool ALIGN_EPI = true, bool SP2 = true, bool BBLK = true>
; __device__ __forceinline__ void gemm_phase(LAS unsigned char* lds, const Gemm g, const Sched& S, const Epi& E) {
;     ...
;             PG8_LDB(B0, 1, 0); PG8_LDB(B1, 1, 1); PG8_SCHED; PG8_LDA(At, 1, 0); PG8_STAGE(PG8_SA(0, 1), a2 + hstepA, voffA);
;             PG8_WAIT_V(8); PG8_WAIT_L(0); PG8_BAR; PG8_MMA(0, 0, At, B0); PG8_MMA(0, 1, At, B1); PG8_BAR; PG8_SCHED;
;             PG8_LDA(At, 1, 1); PG8_STAGE(PG8_SB(1, 0), b3, voffB); PG8_STAGE(PG8_SB(1, 1), b3 + hstepB, voffB); PG8_STAGE(PG8_SA(1, 0), a3, voffA);
;             PG8_WAIT_V(8); PG8_WAIT_L(0); PG8_BAR; PG8_MMA(1, 0, At, B0); PG8_MMA(1, 1, At, B1); PG8_BAR; PG8_SCHED;
	v_add_u32_e32 v155, s60, v150
	ds_read_b128 v[156:159], v155
	ds_read_b128 v[160:163], v155 offset:1024
	ds_read_b128 v[164:167], v155 offset:2048
	ds_read_b128 v[168:171], v155 offset:3072
	v_add_u32_e32 v155, s61, v150
	ds_read_b128 v[172:175], v155
	ds_read_b128 v[176:179], v155 offset:1024
	ds_read_b128 v[180:183], v155 offset:2048
	ds_read_b128 v[184:187], v155 offset:3072
	s_add_u32 s34, s34, 0x80000
	s_addc_u32 s35, s35, 0
	s_mov_b32 m0, s42
	ds_read_b128 v[188:191], v154 offset:32768
	ds_read_b128 v[192:195], v154 offset:33792
	ds_read_b128 v[196:199], v154 offset:34816
	ds_read_b128 v[200:203], v154 offset:35840
	ds_read_b128 v[204:207], v154 offset:36864
	ds_read_b128 v[208:211], v154 offset:37888
	ds_read_b128 v[212:215], v154 offset:38912
	ds_read_b128 v[216:219], v154 offset:39936
	global_load_lds_dwordx4 v130, s[34:35]
	s_mov_b32 m0, s43
	s_nop 0
	global_load_lds_dwordx4 v134, s[34:35]
	s_waitcnt vmcnt(8) lgkmcnt(0)
	s_barrier
	v_mfma_f32_16x16x32_bf16 v[126:129], v[156:159], v[188:191], v[126:129]
	v_mfma_f32_16x16x32_bf16 v[122:125], v[164:167], v[188:191], v[122:125]
	v_mfma_f32_16x16x32_bf16 v[110:113], v[156:159], v[196:199], v[110:113]
	v_mfma_f32_16x16x32_bf16 v[106:109], v[164:167], v[196:199], v[106:109]
	v_mfma_f32_16x16x32_bf16 v[94:97], v[156:159], v[204:207], v[94:97]
	v_mfma_f32_16x16x32_bf16 v[90:93], v[164:167], v[204:207], v[90:93]
	v_mfma_f32_16x16x32_bf16 v[78:81], v[156:159], v[212:215], v[78:81]
	v_mfma_f32_16x16x32_bf16 v[74:77], v[164:167], v[212:215], v[74:77]
	v_mfma_f32_16x16x32_bf16 v[126:129], v[160:163], v[192:195], v[126:129]
	v_mfma_f32_16x16x32_bf16 v[122:125], v[168:171], v[192:195], v[122:125]
	v_mfma_f32_16x16x32_bf16 v[110:113], v[160:163], v[200:203], v[110:113]
	v_mfma_f32_16x16x32_bf16 v[106:109], v[168:171], v[200:203], v[106:109]
	v_mfma_f32_16x16x32_bf16 v[94:97], v[160:163], v[208:211], v[94:97]
	v_mfma_f32_16x16x32_bf16 v[90:93], v[168:171], v[208:211], v[90:93]
	v_mfma_f32_16x16x32_bf16 v[78:81], v[160:163], v[216:219], v[78:81]
	v_mfma_f32_16x16x32_bf16 v[74:77], v[168:171], v[216:219], v[74:77]
	v_mfma_f32_16x16x32_bf16 v[118:121], v[172:175], v[188:191], v[118:121]
	v_mfma_f32_16x16x32_bf16 v[114:117], v[180:183], v[188:191], v[114:117]
	v_mfma_f32_16x16x32_bf16 v[102:105], v[172:175], v[196:199], v[102:105]
	v_mfma_f32_16x16x32_bf16 v[98:101], v[180:183], v[196:199], v[98:101]
	v_mfma_f32_16x16x32_bf16 v[86:89], v[172:175], v[204:207], v[86:89]
	v_mfma_f32_16x16x32_bf16 v[82:85], v[180:183], v[204:207], v[82:85]
	v_mfma_f32_16x16x32_bf16 v[70:73], v[172:175], v[212:215], v[70:73]
	v_mfma_f32_16x16x32_bf16 v[66:69], v[180:183], v[212:215], v[66:69]
	v_mfma_f32_16x16x32_bf16 v[118:121], v[176:179], v[192:195], v[118:121]
	v_mfma_f32_16x16x32_bf16 v[114:117], v[184:187], v[192:195], v[114:117]
	v_mfma_f32_16x16x32_bf16 v[102:105], v[176:179], v[200:203], v[102:105]
	v_mfma_f32_16x16x32_bf16 v[98:101], v[184:187], v[200:203], v[98:101]
	v_mfma_f32_16x16x32_bf16 v[86:89], v[176:179], v[208:211], v[86:89]
	v_mfma_f32_16x16x32_bf16 v[82:85], v[184:187], v[208:211], v[82:85]
	v_mfma_f32_16x16x32_bf16 v[70:73], v[176:179], v[216:219], v[70:73]
	v_mfma_f32_16x16x32_bf16 v[66:69], v[184:187], v[216:219], v[66:69]
	s_barrier
	s_add_u32 s34, s30, 0x8000
	s_addc_u32 s35, s31, 0
	s_add_i32 s58, s60, s39
	s_mov_b32 m0, s58
	ds_read_b128 v[188:191], v154 offset:49152
	ds_read_b128 v[192:195], v154 offset:50176
	ds_read_b128 v[196:199], v154 offset:51200
	ds_read_b128 v[200:203], v154 offset:52224
	ds_read_b128 v[204:207], v154 offset:53248
	ds_read_b128 v[208:211], v154 offset:54272
	ds_read_b128 v[212:215], v154 offset:55296
	ds_read_b128 v[216:219], v154 offset:56320
	global_load_lds_dwordx4 v132, s[34:35]
	s_add_i32 m0, s58, 0x2000
	s_add_u32 s30, s30, 0xc000
	v_lshl_add_u64 v[220:221], s[34:35], 0, v[136:137]
	s_addc_u32 s31, s31, 0
	s_add_i32 s34, s61, s39
	global_load_lds_dwordx4 v[220:221], off
	s_mov_b32 m0, s34
	s_nop 0
	global_load_lds_dwordx4 v132, s[30:31]
	s_add_i32 m0, s34, 0x2000
	s_nop 0
	global_load_lds_dwordx4 v136, s[30:31]
	s_mov_b32 m0, s44
	s_nop 0
	global_load_lds_dwordx4 v130, s[28:29]
	s_mov_b32 m0, s45
	s_nop 0
	global_load_lds_dwordx4 v134, s[28:29]
	s_waitcnt vmcnt(8) lgkmcnt(0)
	s_barrier
	v_mfma_f32_16x16x32_bf16 v[62:65], v[156:159], v[188:191], v[62:65]
	v_mfma_f32_16x16x32_bf16 v[58:61], v[164:167], v[188:191], v[58:61]
	v_mfma_f32_16x16x32_bf16 v[46:49], v[156:159], v[196:199], v[46:49]
	v_mfma_f32_16x16x32_bf16 v[42:45], v[164:167], v[196:199], v[42:45]
	v_mfma_f32_16x16x32_bf16 v[30:33], v[156:159], v[204:207], v[30:33]
	v_mfma_f32_16x16x32_bf16 v[26:29], v[164:167], v[204:207], v[26:29]
	v_mfma_f32_16x16x32_bf16 v[14:17], v[156:159], v[212:215], v[14:17]
	v_mfma_f32_16x16x32_bf16 v[10:13], v[164:167], v[212:215], v[10:13]
	v_mfma_f32_16x16x32_bf16 v[62:65], v[160:163], v[192:195], v[62:65]
	v_mfma_f32_16x16x32_bf16 v[58:61], v[168:171], v[192:195], v[58:61]
	v_mfma_f32_16x16x32_bf16 v[46:49], v[160:163], v[200:203], v[46:49]
	v_mfma_f32_16x16x32_bf16 v[42:45], v[168:171], v[200:203], v[42:45]
	v_mfma_f32_16x16x32_bf16 v[30:33], v[160:163], v[208:211], v[30:33]
	v_mfma_f32_16x16x32_bf16 v[26:29], v[168:171], v[208:211], v[26:29]
	v_mfma_f32_16x16x32_bf16 v[14:17], v[160:163], v[216:219], v[14:17]
	v_mfma_f32_16x16x32_bf16 v[10:13], v[168:171], v[216:219], v[10:13]
	v_mfma_f32_16x16x32_bf16 v[54:57], v[172:175], v[188:191], v[54:57]
	v_mfma_f32_16x16x32_bf16 v[50:53], v[180:183], v[188:191], v[50:53]
	v_mfma_f32_16x16x32_bf16 v[38:41], v[172:175], v[196:199], v[38:41]
	v_mfma_f32_16x16x32_bf16 v[34:37], v[180:183], v[196:199], v[34:37]
	v_mfma_f32_16x16x32_bf16 v[22:25], v[172:175], v[204:207], v[22:25]
	v_mfma_f32_16x16x32_bf16 v[18:21], v[180:183], v[204:207], v[18:21]
	v_mfma_f32_16x16x32_bf16 v[6:9], v[172:175], v[212:215], v[6:9]
	v_mfma_f32_16x16x32_bf16 v[2:5], v[180:183], v[212:215], v[2:5]
	v_mfma_f32_16x16x32_bf16 v[54:57], v[176:179], v[192:195], v[54:57]
	v_mfma_f32_16x16x32_bf16 v[50:53], v[184:187], v[192:195], v[50:53]
	v_mfma_f32_16x16x32_bf16 v[38:41], v[176:179], v[200:203], v[38:41]
	v_mfma_f32_16x16x32_bf16 v[34:37], v[184:187], v[200:203], v[34:37]
	v_mfma_f32_16x16x32_bf16 v[22:25], v[176:179], v[208:211], v[22:25]
	v_mfma_f32_16x16x32_bf16 v[18:21], v[184:187], v[208:211], v[18:21]
	v_mfma_f32_16x16x32_bf16 v[6:9], v[176:179], v[216:219], v[6:9]
	v_mfma_f32_16x16x32_bf16 v[2:5], v[184:187], v[216:219], v[2:5]
	s_barrier
; __device__ __forceinline__ unsigned pk2(float lo, float hi) { const f32x2 v = {lo, hi}; return __builtin_bit_cast(unsigned, __builtin_convertvector(v, bf16x2_t)); }
; #define PG8_BAR __builtin_amdgcn_s_barrier()
; template <class Epi, class Sched, bool ABLK = false, bool ALIGN_EPI = true, bool SP2 = true, bool BBLK = true>
; __device__ __forceinline__ void gemm_phase(LAS unsigned char* lds, const Gemm g, const Sched& S, const Epi& E) {
;     ...
;         if constexpr (ALIGN_EPI) { if (wr == 0) PG8_BAR; }
;     __device__ __forceinline__ void operator()(const f32x4 (&acc)[2][2][4][2], const Unit& u, int wr, int wc, int fr, int fq) const {
;         const int row0 = u.pm * 256 + wr * 64 + fr, col0 = u.pn * 256 + wc * 64 + 8 * fq;
;         bf16_t* base = u.part == 0 ? Z + (size_t)row0 * D + col0 : P + ((size_t)(u.part - 1) * MS + (row0 - MP)) * D + col0;
; #pragma unroll
;         for (int ai = 0; ai < 2; ++ai)
; #pragma unroll
;             for (int m = 0; m < 4; ++m) { u32x4 w[2];
; #pragma unroll
;                 for (int bj = 0; bj < 2; ++bj) { const f32x4 v0 = acc[ai][bj][m][0], v1 = acc[ai][bj][m][1]; w[bj].x = pk2(v0[0], v0[1]); w[bj].y = pk2(v0[2], v0[3]); w[bj].z = pk2(v1[0], v1[1]); w[bj].w = pk2(v1[2], v1[3]); }
;                 store_pair((unsigned char*)(base + (size_t)(ai * 128 + m * 16) * D), (size_t)8 * D * 2, 64, w[0], w[1], fr >= 8); }
	s_add_u32 s52, s52, 0x10000
	s_addc_u32 s53, s53, 0
	s_add_u32 s26, s26, 0x100
	s_addc_u32 s27, s27, 0
	s_cmp_ge_u32 s57, s47
	s_cbranch_scc0 .LBB0_1716
	v_lshl_add_u32 v147, s48, 8, v1
	v_add_u32_e32 v148, 0xffffe000, v147
	v_sub_co_u32_e64 v146, vcc, s46, 1
	v_mov_b32_e32 v149, s91
	s_nop 0
	v_cndmask_b32_e32 v148, v148, v147, vcc
	v_ashrrev_i32_e32 v147, 31, v146
	v_lshlrev_b64 v[146:147], 23, v[146:147]
	v_lshl_add_u64 v[146:147], s[12:13], 0, v[146:147]
	v_cndmask_b32_e32 v147, v147, v149, vcc
	v_mov_b32_e32 v149, s90
	v_cndmask_b32_e32 v146, v146, v149, vcc
	v_ashrrev_i32_e32 v149, 31, v148
	v_lshl_or_b32 v156, s78, 8, v151
	v_lshlrev_b64 v[148:149], 12, v[148:149]
	v_lshl_add_u64 v[146:147], v[146:147], 0, v[148:149]
	v_ashrrev_i32_e32 v157, 31, v156
	v_cvt_pk_bf16_f32 v126, v126, v127
	v_cvt_pk_bf16_f32 v127, v128, v129
	v_cvt_pk_bf16_f32 v128, v122, v123
	v_cvt_pk_bf16_f32 v124, v124, v125
	v_cvt_pk_bf16_f32 v118, v118, v119
	v_cvt_pk_bf16_f32 v119, v120, v121
	v_cvt_pk_bf16_f32 v114, v114, v115
	v_cvt_pk_bf16_f32 v115, v116, v117
	v_lshl_add_u64 v[146:147], v[156:157], 1, v[146:147]
	v_mov_b32_dpp v120, v126 row_ror:8 row_mask:0xf bank_mask:0xf bound_ctrl:1
	v_mov_b32_dpp v121, v127 row_ror:8 row_mask:0xf bank_mask:0xf bound_ctrl:1
	v_mov_b32_dpp v116, v128 row_ror:8 row_mask:0xf bank_mask:0xf bound_ctrl:1
	v_mov_b32_dpp v117, v124 row_ror:8 row_mask:0xf bank_mask:0xf bound_ctrl:1
	v_mov_b32_dpp v125, v118 row_ror:8 row_mask:0xf bank_mask:0xf bound_ctrl:1
	v_mov_b32_dpp v129, v119 row_ror:8 row_mask:0xf bank_mask:0xf bound_ctrl:1
	v_mov_b32_dpp v148, v114 row_ror:8 row_mask:0xf bank_mask:0xf bound_ctrl:1
	v_mov_b32_dpp v149, v115 row_ror:8 row_mask:0xf bank_mask:0xf bound_ctrl:1
	v_lshl_add_u64 v[122:123], v[146:147], 0, v[138:139]
	v_cndmask_b32_e64 v117, v117, v115, s[8:9]
	v_cndmask_b32_e64 v116, v116, v114, s[8:9]
	v_cndmask_b32_e64 v115, v121, v119, s[8:9]
	v_cndmask_b32_e64 v114, v120, v118, s[8:9]
	v_cndmask_b32_e64 v121, v124, v149, s[8:9]
	v_cndmask_b32_e64 v120, v128, v148, s[8:9]
	v_cndmask_b32_e64 v119, v127, v129, s[8:9]
	v_cndmask_b32_e64 v118, v126, v125, s[8:9]
	v_cvt_pk_bf16_f32 v110, v110, v111
	v_cvt_pk_bf16_f32 v111, v112, v113
	v_cvt_pk_bf16_f32 v112, v106, v107
	v_cvt_pk_bf16_f32 v113, v108, v109
	v_cvt_pk_bf16_f32 v102, v102, v103
	v_cvt_pk_bf16_f32 v103, v104, v105
	v_cvt_pk_bf16_f32 v98, v98, v99
	v_cvt_pk_bf16_f32 v99, v100, v101
	s_mov_b64 s[4:5], 0x10000
	v_lshl_add_u64 v[124:125], v[146:147], 0, v[140:141]
	global_store_dwordx4 v[122:123], v[118:121], off
	global_store_dwordx4 v[124:125], v[114:117], off
	v_lshl_add_u64 v[106:107], v[146:147], 0, s[4:5]
	v_mov_b32_dpp v104, v110 row_ror:8 row_mask:0xf bank_mask:0xf bound_ctrl:1
	v_mov_b32_dpp v105, v111 row_ror:8 row_mask:0xf bank_mask:0xf bound_ctrl:1
	v_mov_b32_dpp v100, v112 row_ror:8 row_mask:0xf bank_mask:0xf bound_ctrl:1
	v_mov_b32_dpp v101, v113 row_ror:8 row_mask:0xf bank_mask:0xf bound_ctrl:1
	v_mov_b32_dpp v114, v102 row_ror:8 row_mask:0xf bank_mask:0xf bound_ctrl:1
	v_mov_b32_dpp v115, v103 row_ror:8 row_mask:0xf bank_mask:0xf bound_ctrl:1
	v_mov_b32_dpp v116, v98 row_ror:8 row_mask:0xf bank_mask:0xf bound_ctrl:1
	v_mov_b32_dpp v117, v99 row_ror:8 row_mask:0xf bank_mask:0xf bound_ctrl:1
	v_lshl_add_u64 v[108:109], v[106:107], 0, v[138:139]
	v_cndmask_b32_e64 v101, v101, v99, s[8:9]
	v_cndmask_b32_e64 v100, v100, v98, s[8:9]
	v_cndmask_b32_e64 v99, v105, v103, s[8:9]
	v_cndmask_b32_e64 v98, v104, v102, s[8:9]
	v_cndmask_b32_e64 v105, v113, v117, s[8:9]
	v_cndmask_b32_e64 v104, v112, v116, s[8:9]
	v_cndmask_b32_e64 v103, v111, v115, s[8:9]
	v_cndmask_b32_e64 v102, v110, v114, s[8:9]
	v_cvt_pk_bf16_f32 v94, v94, v95
	v_cvt_pk_bf16_f32 v95, v96, v97
	v_cvt_pk_bf16_f32 v96, v90, v91
	v_cvt_pk_bf16_f32 v97, v92, v93
	v_cvt_pk_bf16_f32 v86, v86, v87
	v_cvt_pk_bf16_f32 v87, v88, v89
	v_cvt_pk_bf16_f32 v82, v82, v83
	v_cvt_pk_bf16_f32 v83, v84, v85
	s_mov_b64 s[4:5], 0x20000
	v_lshl_add_u64 v[106:107], v[106:107], 0, v[140:141]
	global_store_dwordx4 v[108:109], v[102:105], off
	global_store_dwordx4 v[106:107], v[98:101], off
	v_lshl_add_u64 v[90:91], v[146:147], 0, s[4:5]
	v_mov_b32_dpp v88, v94 row_ror:8 row_mask:0xf bank_mask:0xf bound_ctrl:1
	v_mov_b32_dpp v89, v95 row_ror:8 row_mask:0xf bank_mask:0xf bound_ctrl:1
	v_mov_b32_dpp v84, v96 row_ror:8 row_mask:0xf bank_mask:0xf bound_ctrl:1
	v_mov_b32_dpp v85, v97 row_ror:8 row_mask:0xf bank_mask:0xf bound_ctrl:1
	v_mov_b32_dpp v98, v86 row_ror:8 row_mask:0xf bank_mask:0xf bound_ctrl:1
	v_mov_b32_dpp v99, v87 row_ror:8 row_mask:0xf bank_mask:0xf bound_ctrl:1
	v_mov_b32_dpp v100, v82 row_ror:8 row_mask:0xf bank_mask:0xf bound_ctrl:1
	v_mov_b32_dpp v101, v83 row_ror:8 row_mask:0xf bank_mask:0xf bound_ctrl:1
	v_lshl_add_u64 v[92:93], v[90:91], 0, v[138:139]
	v_cndmask_b32_e64 v85, v85, v83, s[8:9]
	v_cndmask_b32_e64 v84, v84, v82, s[8:9]
	v_cndmask_b32_e64 v83, v89, v87, s[8:9]
	v_cndmask_b32_e64 v82, v88, v86, s[8:9]
	v_cndmask_b32_e64 v89, v97, v101, s[8:9]
	v_cndmask_b32_e64 v88, v96, v100, s[8:9]
	v_cndmask_b32_e64 v87, v95, v99, s[8:9]
	v_cndmask_b32_e64 v86, v94, v98, s[8:9]
	v_cvt_pk_bf16_f32 v78, v78, v79
	v_cvt_pk_bf16_f32 v79, v80, v81
	v_cvt_pk_bf16_f32 v80, v74, v75
	v_cvt_pk_bf16_f32 v81, v76, v77
	v_cvt_pk_bf16_f32 v70, v70, v71
	v_cvt_pk_bf16_f32 v71, v72, v73
	v_cvt_pk_bf16_f32 v66, v66, v67
	v_cvt_pk_bf16_f32 v67, v68, v69
	s_mov_b64 s[4:5], 0x30000
	v_lshl_add_u64 v[90:91], v[90:91], 0, v[140:141]
	global_store_dwordx4 v[92:93], v[86:89], off
	global_store_dwordx4 v[90:91], v[82:85], off
	v_lshl_add_u64 v[74:75], v[146:147], 0, s[4:5]
	v_mov_b32_dpp v72, v78 row_ror:8 row_mask:0xf bank_mask:0xf bound_ctrl:1
; __device__ __forceinline__ unsigned pk2(float lo, float hi) { const f32x2 v = {lo, hi}; return __builtin_bit_cast(unsigned, __builtin_convertvector(v, bf16x2_t)); }
; #define PG8_BAR __builtin_amdgcn_s_barrier()
; template <class Epi, class Sched, bool ABLK = false, bool ALIGN_EPI = true, bool SP2 = true, bool BBLK = true>
; __device__ __forceinline__ void gemm_phase(LAS unsigned char* lds, const Gemm g, const Sched& S, const Epi& E) {
;     ...
;         if constexpr (ALIGN_EPI) { if (wr == 0) PG8_BAR; }
;         E(acc, cur, wr, wc, fr, fq); S.done(cur);
;         if (!has_next) break;
; #pragma unroll
;         for (int a = 0; a < 2; ++a)
; #pragma unroll
;             for (int b = 0; b < 2; ++b)
; #pragma unroll
;                 for (int m = 0; m < 4; ++m)
; #pragma unroll
;                     for (int n = 0; n < 2; ++n) acc[a][b][m][n] = (f32x4){0.f, 0.f, 0.f, 0.f};
;         cur = nxt; uA = nuA; tbA = ntbA; cB = nB; ++ui;
;         if constexpr (ALIGN_EPI) { if (wr == 1) PG8_BAR; }
;     __device__ __forceinline__ void operator()(const f32x4 (&acc)[2][2][4][2], const Unit& u, int wr, int wc, int fr, int fq) const {
;     ...
;         for (int ai = 0; ai < 2; ++ai)
; #pragma unroll
;             for (int m = 0; m < 4; ++m) { u32x4 w[2];
; #pragma unroll
;                 for (int bj = 0; bj < 2; ++bj) { const f32x4 v0 = acc[ai][bj][m][0], v1 = acc[ai][bj][m][1]; w[bj].x = pk2(v0[0], v0[1]); w[bj].y = pk2(v0[2], v0[3]); w[bj].z = pk2(v1[0], v1[1]); w[bj].w = pk2(v1[2], v1[3]); }
;                 store_pair((unsigned char*)(base + (size_t)(ai * 128 + m * 16) * D), (size_t)8 * D * 2, 64, w[0], w[1], fr >= 8); }
	v_mov_b32_dpp v73, v79 row_ror:8 row_mask:0xf bank_mask:0xf bound_ctrl:1
	v_mov_b32_dpp v68, v80 row_ror:8 row_mask:0xf bank_mask:0xf bound_ctrl:1
	v_mov_b32_dpp v69, v81 row_ror:8 row_mask:0xf bank_mask:0xf bound_ctrl:1
	v_mov_b32_dpp v82, v70 row_ror:8 row_mask:0xf bank_mask:0xf bound_ctrl:1
	v_mov_b32_dpp v83, v71 row_ror:8 row_mask:0xf bank_mask:0xf bound_ctrl:1
	v_mov_b32_dpp v84, v66 row_ror:8 row_mask:0xf bank_mask:0xf bound_ctrl:1
	v_mov_b32_dpp v85, v67 row_ror:8 row_mask:0xf bank_mask:0xf bound_ctrl:1
	v_lshl_add_u64 v[76:77], v[74:75], 0, v[138:139]
	v_cndmask_b32_e64 v69, v69, v67, s[8:9]
	v_cndmask_b32_e64 v68, v68, v66, s[8:9]
	v_cndmask_b32_e64 v67, v73, v71, s[8:9]
	v_cndmask_b32_e64 v66, v72, v70, s[8:9]
	v_cndmask_b32_e64 v73, v81, v85, s[8:9]
	v_cndmask_b32_e64 v72, v80, v84, s[8:9]
	v_cndmask_b32_e64 v71, v79, v83, s[8:9]
	v_cndmask_b32_e64 v70, v78, v82, s[8:9]
	v_cvt_pk_bf16_f32 v62, v62, v63
	v_cvt_pk_bf16_f32 v63, v64, v65
	v_cvt_pk_bf16_f32 v64, v58, v59
	v_cvt_pk_bf16_f32 v65, v60, v61
	v_cvt_pk_bf16_f32 v54, v54, v55
	v_cvt_pk_bf16_f32 v55, v56, v57
	v_cvt_pk_bf16_f32 v50, v50, v51
	v_cvt_pk_bf16_f32 v51, v52, v53
	s_mov_b64 s[4:5], 0x80000
	v_lshl_add_u64 v[74:75], v[74:75], 0, v[140:141]
	global_store_dwordx4 v[76:77], v[70:73], off
	global_store_dwordx4 v[74:75], v[66:69], off
	v_lshl_add_u64 v[58:59], v[146:147], 0, s[4:5]
	v_mov_b32_dpp v56, v62 row_ror:8 row_mask:0xf bank_mask:0xf bound_ctrl:1
	v_mov_b32_dpp v57, v63 row_ror:8 row_mask:0xf bank_mask:0xf bound_ctrl:1
	v_mov_b32_dpp v52, v64 row_ror:8 row_mask:0xf bank_mask:0xf bound_ctrl:1
	v_mov_b32_dpp v53, v65 row_ror:8 row_mask:0xf bank_mask:0xf bound_ctrl:1
	v_mov_b32_dpp v66, v54 row_ror:8 row_mask:0xf bank_mask:0xf bound_ctrl:1
	v_mov_b32_dpp v67, v55 row_ror:8 row_mask:0xf bank_mask:0xf bound_ctrl:1
	v_mov_b32_dpp v68, v50 row_ror:8 row_mask:0xf bank_mask:0xf bound_ctrl:1
	v_mov_b32_dpp v69, v51 row_ror:8 row_mask:0xf bank_mask:0xf bound_ctrl:1
	v_lshl_add_u64 v[60:61], v[58:59], 0, v[138:139]
	v_cndmask_b32_e64 v53, v53, v51, s[8:9]
	v_cndmask_b32_e64 v52, v52, v50, s[8:9]
	v_cndmask_b32_e64 v51, v57, v55, s[8:9]
	v_cndmask_b32_e64 v50, v56, v54, s[8:9]
	v_cndmask_b32_e64 v57, v65, v69, s[8:9]
	v_cndmask_b32_e64 v56, v64, v68, s[8:9]
	v_cndmask_b32_e64 v55, v63, v67, s[8:9]
	v_cndmask_b32_e64 v54, v62, v66, s[8:9]
	v_cvt_pk_bf16_f32 v46, v46, v47
	v_cvt_pk_bf16_f32 v47, v48, v49
	v_cvt_pk_bf16_f32 v48, v42, v43
	v_cvt_pk_bf16_f32 v49, v44, v45
	v_cvt_pk_bf16_f32 v38, v38, v39
	v_cvt_pk_bf16_f32 v39, v40, v41
	v_cvt_pk_bf16_f32 v34, v34, v35
	v_cvt_pk_bf16_f32 v35, v36, v37
	v_lshl_add_u64 v[58:59], v[58:59], 0, v[140:141]
	global_store_dwordx4 v[60:61], v[54:57], off
	global_store_dwordx4 v[58:59], v[50:53], off
	v_lshl_add_u64 v[42:43], v[146:147], 0, s[14:15]
	v_mov_b32_dpp v40, v46 row_ror:8 row_mask:0xf bank_mask:0xf bound_ctrl:1
	v_mov_b32_dpp v41, v47 row_ror:8 row_mask:0xf bank_mask:0xf bound_ctrl:1
	v_mov_b32_dpp v36, v48 row_ror:8 row_mask:0xf bank_mask:0xf bound_ctrl:1
	v_mov_b32_dpp v37, v49 row_ror:8 row_mask:0xf bank_mask:0xf bound_ctrl:1
	v_mov_b32_dpp v50, v38 row_ror:8 row_mask:0xf bank_mask:0xf bound_ctrl:1
	v_mov_b32_dpp v51, v39 row_ror:8 row_mask:0xf bank_mask:0xf bound_ctrl:1
	v_mov_b32_dpp v52, v34 row_ror:8 row_mask:0xf bank_mask:0xf bound_ctrl:1
	v_mov_b32_dpp v53, v35 row_ror:8 row_mask:0xf bank_mask:0xf bound_ctrl:1
	v_lshl_add_u64 v[44:45], v[42:43], 0, v[138:139]
	v_cndmask_b32_e64 v37, v37, v35, s[8:9]
	v_cndmask_b32_e64 v36, v36, v34, s[8:9]
	v_cndmask_b32_e64 v35, v41, v39, s[8:9]
	v_cndmask_b32_e64 v34, v40, v38, s[8:9]
	v_cndmask_b32_e64 v41, v49, v53, s[8:9]
	v_cndmask_b32_e64 v40, v48, v52, s[8:9]
	v_cndmask_b32_e64 v39, v47, v51, s[8:9]
	v_cndmask_b32_e64 v38, v46, v50, s[8:9]
	v_cvt_pk_bf16_f32 v30, v30, v31
	v_cvt_pk_bf16_f32 v31, v32, v33
	v_cvt_pk_bf16_f32 v32, v26, v27
	v_cvt_pk_bf16_f32 v33, v28, v29
	v_cvt_pk_bf16_f32 v22, v22, v23
	v_cvt_pk_bf16_f32 v23, v24, v25
	v_cvt_pk_bf16_f32 v18, v18, v19
	v_cvt_pk_bf16_f32 v19, v20, v21
	v_lshl_add_u64 v[42:43], v[42:43], 0, v[140:141]
	global_store_dwordx4 v[44:45], v[38:41], off
	global_store_dwordx4 v[42:43], v[34:37], off
	v_lshl_add_u64 v[26:27], v[146:147], 0, s[16:17]
	v_mov_b32_dpp v24, v30 row_ror:8 row_mask:0xf bank_mask:0xf bound_ctrl:1
	v_mov_b32_dpp v25, v31 row_ror:8 row_mask:0xf bank_mask:0xf bound_ctrl:1
	v_mov_b32_dpp v20, v32 row_ror:8 row_mask:0xf bank_mask:0xf bound_ctrl:1
	v_mov_b32_dpp v21, v33 row_ror:8 row_mask:0xf bank_mask:0xf bound_ctrl:1
	v_mov_b32_dpp v34, v22 row_ror:8 row_mask:0xf bank_mask:0xf bound_ctrl:1
	v_mov_b32_dpp v35, v23 row_ror:8 row_mask:0xf bank_mask:0xf bound_ctrl:1
	v_mov_b32_dpp v36, v18 row_ror:8 row_mask:0xf bank_mask:0xf bound_ctrl:1
	v_mov_b32_dpp v37, v19 row_ror:8 row_mask:0xf bank_mask:0xf bound_ctrl:1
	v_lshl_add_u64 v[28:29], v[26:27], 0, v[138:139]
	v_cndmask_b32_e64 v21, v21, v19, s[8:9]
	v_cndmask_b32_e64 v20, v20, v18, s[8:9]
	v_cndmask_b32_e64 v19, v25, v23, s[8:9]
	v_cndmask_b32_e64 v18, v24, v22, s[8:9]
	v_cndmask_b32_e64 v25, v33, v37, s[8:9]
	v_cndmask_b32_e64 v24, v32, v36, s[8:9]
	v_cndmask_b32_e64 v23, v31, v35, s[8:9]
	v_cndmask_b32_e64 v22, v30, v34, s[8:9]
	v_cvt_pk_bf16_f32 v14, v14, v15
	v_cvt_pk_bf16_f32 v15, v16, v17
	v_cvt_pk_bf16_f32 v16, v10, v11
	v_cvt_pk_bf16_f32 v17, v12, v13
	v_cvt_pk_bf16_f32 v6, v6, v7
	v_cvt_pk_bf16_f32 v7, v8, v9
	v_cvt_pk_bf16_f32 v2, v2, v3
	v_cvt_pk_bf16_f32 v3, v4, v5
	v_lshl_add_u64 v[26:27], v[26:27], 0, v[140:141]
	global_store_dwordx4 v[28:29], v[22:25], off
	global_store_dwordx4 v[26:27], v[18:21], off
	v_lshl_add_u64 v[10:11], v[146:147], 0, s[18:19]
	v_mov_b32_dpp v8, v14 row_ror:8 row_mask:0xf bank_mask:0xf bound_ctrl:1
	v_mov_b32_dpp v9, v15 row_ror:8 row_mask:0xf bank_mask:0xf bound_ctrl:1
	v_mov_b32_dpp v4, v16 row_ror:8 row_mask:0xf bank_mask:0xf bound_ctrl:1
	v_mov_b32_dpp v5, v17 row_ror:8 row_mask:0xf bank_mask:0xf bound_ctrl:1
	v_mov_b32_dpp v18, v6 row_ror:8 row_mask:0xf bank_mask:0xf bound_ctrl:1
	v_mov_b32_dpp v19, v7 row_ror:8 row_mask:0xf bank_mask:0xf bound_ctrl:1
	v_mov_b32_dpp v20, v2 row_ror:8 row_mask:0xf bank_mask:0xf bound_ctrl:1
	v_mov_b32_dpp v21, v3 row_ror:8 row_mask:0xf bank_mask:0xf bound_ctrl:1
	v_lshl_add_u64 v[12:13], v[10:11], 0, v[138:139]
	v_cndmask_b32_e64 v5, v5, v3, s[8:9]
	v_cndmask_b32_e64 v4, v4, v2, s[8:9]
	v_cndmask_b32_e64 v3, v9, v7, s[8:9]
	v_cndmask_b32_e64 v2, v8, v6, s[8:9]
	v_cndmask_b32_e64 v9, v17, v21, s[8:9]
	v_cndmask_b32_e64 v8, v16, v20, s[8:9]
	v_cndmask_b32_e64 v7, v15, v19, s[8:9]
	v_cndmask_b32_e64 v6, v14, v18, s[8:9]
	s_and_b64 vcc, exec, s[6:7]
	s_cbranch_vccz .LBB0_1719
	s_barrier
.LBB0_1719:
	s_and_b64 vcc, exec, s[10:11]
	s_mov_b64 s[10:11], -1
	v_lshl_add_u64 v[10:11], v[10:11], 0, v[140:141]
	global_store_dwordx4 v[12:13], v[6:9], off
	global_store_dwordx4 v[10:11], v[2:5], off
	s_cbranch_vccnz .LBB0_1714
	s_andn2_b64 vcc, exec, s[2:3]
	s_cbranch_vccnz .LBB0_1713
	s_barrier
	s_branch .LBB0_1713

; #define PG8_STAGE(bufoff, gbase, voff) do { _Pragma("unroll") for (int _i = 0; _i < 2; ++_i) \
;         __builtin_amdgcn_global_load_lds((const unsigned*)((const char*)(gbase) + (voff)[_i]), (LAS unsigned*)(lds + (bufoff) + ldsw + _i * 8192), 16, 0, 0); } while (0)
; #define PG8_LDA(dst, b, h) do { _Pragma("unroll") for (int m = 0; m < 4; ++m) _Pragma("unroll") for (int k = 0; k < 2; ++k) dst[m][k] = *(const LAS bf16x8*)(lds + PG8_SA(b, h) + aoff + m * 2048 + k * 1024); } while (0)
; #define PG8_LDB(dst, b, h) do { _Pragma("unroll") for (int n = 0; n < 2; ++n) _Pragma("unroll") for (int k = 0; k < 2; ++k) dst[n][k] = *(const LAS bf16x8*)(lds + PG8_SB(b, h) + boff + n * 2048 + k * 1024); } while (0)
; #define PG8_MMA(ai, bj, At, Bt) do { __builtin_amdgcn_s_setprio(1); _Pragma("unroll") for (int m = 0; m < 4; ++m) _Pragma("unroll") for (int n = 0; n < 2; ++n) _Pragma("unroll") for (int k = 0; k < 2; ++k) \
;         acc[ai][bj][m][n] = __builtin_amdgcn_mfma_f32_16x16x32_bf16(Bt[n][k], At[m][k], acc[ai][bj][m][n], 0, 0, 0); __builtin_amdgcn_s_setprio(0); } while (0)
; #define PG8_WAIT_V(n) asm volatile("s_waitcnt vmcnt(" #n ")" ::: "memory")
; #define PG8_WAIT_L(n) asm volatile("s_waitcnt lgkmcnt(" #n ")" ::: "memory")
; #define PG8_BAR __builtin_amdgcn_s_barrier()
; #define PG8_SCHED __builtin_amdgcn_sched_barrier(0)
; template <class Epi, class Sched, bool ABLK = false, bool ALIGN_EPI = true, bool SP2 = true, bool BBLK = true>
; __device__ __forceinline__ void gemm_phase(LAS unsigned char* lds, const Gemm g, const Sched& S, const Epi& E) {
;     ...
;             if constexpr (SP2) {
;             PG8_LDB(B0, 0, 0); PG8_LDB(B1, 0, 1); PG8_SCHED; PG8_LDA(At, 0, 0); PG8_STAGE(PG8_SA(1, 1), a1 + hstepA, voffA);
;             PG8_WAIT_V(8); PG8_WAIT_L(0); PG8_BAR; PG8_MMA(0, 0, At, B0); PG8_MMA(0, 1, At, B1); PG8_BAR; PG8_SCHED;
;             PG8_LDA(At, 0, 1); PG8_STAGE(PG8_SB(0, 0), b2, voffB); PG8_STAGE(PG8_SB(0, 1), b2 + hstepB, voffB); PG8_STAGE(PG8_SA(0, 0), a2, voffA);
;             PG8_WAIT_V(8); PG8_WAIT_L(0); PG8_BAR; PG8_MMA(1, 0, At, B0); PG8_MMA(1, 1, At, B1); PG8_BAR; PG8_SCHED;
.LBB0_1842:
	ds_read_b128 v[172:175], v168
	ds_read_b128 v[176:179], v168 offset:1024
	ds_read_b128 v[180:183], v168 offset:2048
	ds_read_b128 v[184:187], v168 offset:3072
	ds_read_b128 v[188:191], v169
	ds_read_b128 v[192:195], v169 offset:1024
	ds_read_b128 v[196:199], v169 offset:2048
	ds_read_b128 v[200:203], v169 offset:3072
	s_add_u32 s30, s26, s28
	s_addc_u32 s31, s27, s29
	s_add_u32 s36, s30, 0x100
	s_addc_u32 s37, s31, 0
	s_add_u32 s30, s30, 0x180
	s_addc_u32 s31, s31, 0
	s_cmpk_eq_i32 s28, 0xf00
	s_cselect_b32 s31, s51, s31
	s_cselect_b32 s30, s23, s30
	s_cselect_b32 s35, s11, s53
	s_cselect_b32 s34, s15, s52
	s_cselect_b32 s37, s4, s37
	s_cselect_b32 s36, s5, s36
	s_mov_b32 m0, s47
	v_lshl_add_u64 v[236:237], v[164:165], 0, s[28:29]
	ds_read_b128 v[204:207], v170
	ds_read_b128 v[208:211], v170 offset:1024
	ds_read_b128 v[212:215], v170 offset:2048
	ds_read_b128 v[216:219], v170 offset:3072
	ds_read_b128 v[220:223], v170 offset:4096
	ds_read_b128 v[224:227], v170 offset:5120
	ds_read_b128 v[228:231], v170 offset:6144
	ds_read_b128 v[232:235], v170 offset:7168
	global_load_lds_dwordx4 v[236:237], off
	v_lshl_add_u64 v[236:237], v[166:167], 0, s[28:29]
	s_mov_b32 m0, s48
	s_nop 0
	global_load_lds_dwordx4 v[236:237], off
	s_waitcnt vmcnt(8) lgkmcnt(0)
	s_barrier
	v_mfma_f32_16x16x32_bf16 v[126:129], v[172:175], v[204:207], v[126:129]
	v_mfma_f32_16x16x32_bf16 v[122:125], v[180:183], v[204:207], v[122:125]
	v_mfma_f32_16x16x32_bf16 v[110:113], v[172:175], v[212:215], v[110:113]
	v_mfma_f32_16x16x32_bf16 v[106:109], v[180:183], v[212:215], v[106:109]
	v_mfma_f32_16x16x32_bf16 v[94:97], v[172:175], v[220:223], v[94:97]
	v_mfma_f32_16x16x32_bf16 v[90:93], v[180:183], v[220:223], v[90:93]
	v_mfma_f32_16x16x32_bf16 v[78:81], v[172:175], v[228:231], v[78:81]
	v_mfma_f32_16x16x32_bf16 v[74:77], v[180:183], v[228:231], v[74:77]
	v_mfma_f32_16x16x32_bf16 v[126:129], v[176:179], v[208:211], v[126:129]
	v_mfma_f32_16x16x32_bf16 v[122:125], v[184:187], v[208:211], v[122:125]
	v_mfma_f32_16x16x32_bf16 v[110:113], v[176:179], v[216:219], v[110:113]
	v_mfma_f32_16x16x32_bf16 v[106:109], v[184:187], v[216:219], v[106:109]
	v_mfma_f32_16x16x32_bf16 v[94:97], v[176:179], v[224:227], v[94:97]
	v_mfma_f32_16x16x32_bf16 v[90:93], v[184:187], v[224:227], v[90:93]
	v_mfma_f32_16x16x32_bf16 v[78:81], v[176:179], v[232:235], v[78:81]
	v_mfma_f32_16x16x32_bf16 v[74:77], v[184:187], v[232:235], v[74:77]
	v_mfma_f32_16x16x32_bf16 v[118:121], v[188:191], v[204:207], v[118:121]
	v_mfma_f32_16x16x32_bf16 v[114:117], v[196:199], v[204:207], v[114:117]
	v_mfma_f32_16x16x32_bf16 v[102:105], v[188:191], v[212:215], v[102:105]
	v_mfma_f32_16x16x32_bf16 v[98:101], v[196:199], v[212:215], v[98:101]
	v_mfma_f32_16x16x32_bf16 v[86:89], v[188:191], v[220:223], v[86:89]
	v_mfma_f32_16x16x32_bf16 v[82:85], v[196:199], v[220:223], v[82:85]
	v_mfma_f32_16x16x32_bf16 v[70:73], v[188:191], v[228:231], v[70:73]
	v_mfma_f32_16x16x32_bf16 v[66:69], v[196:199], v[228:231], v[66:69]
	v_mfma_f32_16x16x32_bf16 v[118:121], v[192:195], v[208:211], v[118:121]
	v_mfma_f32_16x16x32_bf16 v[114:117], v[200:203], v[208:211], v[114:117]
	v_mfma_f32_16x16x32_bf16 v[102:105], v[192:195], v[216:219], v[102:105]
	v_mfma_f32_16x16x32_bf16 v[98:101], v[200:203], v[216:219], v[98:101]
	v_mfma_f32_16x16x32_bf16 v[86:89], v[192:195], v[224:227], v[86:89]
	v_mfma_f32_16x16x32_bf16 v[82:85], v[200:203], v[224:227], v[82:85]
	v_mfma_f32_16x16x32_bf16 v[70:73], v[192:195], v[232:235], v[70:73]
	v_mfma_f32_16x16x32_bf16 v[66:69], v[200:203], v[232:235], v[66:69]
	s_barrier
	s_mov_b32 m0, s49
	s_add_u32 s56, s34, 0x4000
	ds_read_b128 v[204:207], v170 offset:16384
	ds_read_b128 v[208:211], v170 offset:17408
	ds_read_b128 v[212:215], v170 offset:18432
	ds_read_b128 v[216:219], v170 offset:19456
	ds_read_b128 v[220:223], v170 offset:20480
	ds_read_b128 v[224:227], v170 offset:21504
	ds_read_b128 v[228:231], v170 offset:22528
	ds_read_b128 v[232:235], v170 offset:23552
	global_load_lds_dwordx4 v134, s[34:35]
	s_mov_b32 m0, s50
	s_addc_u32 s57, s35, 0
	s_add_i32 s55, s73, s39
	global_load_lds_dwordx4 v130, s[34:35]
	s_mov_b32 m0, s55
	s_nop 0
	global_load_lds_dwordx4 v134, s[56:57]
	s_add_i32 m0, s55, 0x2000
	s_nop 0
	global_load_lds_dwordx4 v130, s[56:57]
	s_mov_b32 m0, s25
	s_nop 0
	global_load_lds_dwordx4 v136, s[36:37]
	s_mov_b32 m0, s40
	s_nop 0
	global_load_lds_dwordx4 v132, s[36:37]
	s_waitcnt vmcnt(8) lgkmcnt(0)
	s_barrier
	v_mfma_f32_16x16x32_bf16 v[62:65], v[172:175], v[204:207], v[62:65]
	v_mfma_f32_16x16x32_bf16 v[58:61], v[180:183], v[204:207], v[58:61]
	v_mfma_f32_16x16x32_bf16 v[46:49], v[172:175], v[212:215], v[46:49]
	v_mfma_f32_16x16x32_bf16 v[42:45], v[180:183], v[212:215], v[42:45]
	v_mfma_f32_16x16x32_bf16 v[30:33], v[172:175], v[220:223], v[30:33]
	v_mfma_f32_16x16x32_bf16 v[26:29], v[180:183], v[220:223], v[26:29]
	v_mfma_f32_16x16x32_bf16 v[14:17], v[172:175], v[228:231], v[14:17]
	v_mfma_f32_16x16x32_bf16 v[10:13], v[180:183], v[228:231], v[10:13]
	v_mfma_f32_16x16x32_bf16 v[62:65], v[176:179], v[208:211], v[62:65]
	v_mfma_f32_16x16x32_bf16 v[58:61], v[184:187], v[208:211], v[58:61]
	v_mfma_f32_16x16x32_bf16 v[46:49], v[176:179], v[216:219], v[46:49]
	v_mfma_f32_16x16x32_bf16 v[42:45], v[184:187], v[216:219], v[42:45]
	v_mfma_f32_16x16x32_bf16 v[30:33], v[176:179], v[224:227], v[30:33]
	v_mfma_f32_16x16x32_bf16 v[26:29], v[184:187], v[224:227], v[26:29]
	v_mfma_f32_16x16x32_bf16 v[14:17], v[176:179], v[232:235], v[14:17]
	v_mfma_f32_16x16x32_bf16 v[10:13], v[184:187], v[232:235], v[10:13]
	v_mfma_f32_16x16x32_bf16 v[54:57], v[188:191], v[204:207], v[54:57]
	v_mfma_f32_16x16x32_bf16 v[50:53], v[196:199], v[204:207], v[50:53]
	v_mfma_f32_16x16x32_bf16 v[38:41], v[188:191], v[212:215], v[38:41]
	v_mfma_f32_16x16x32_bf16 v[34:37], v[196:199], v[212:215], v[34:37]
	v_mfma_f32_16x16x32_bf16 v[22:25], v[188:191], v[220:223], v[22:25]
	v_mfma_f32_16x16x32_bf16 v[18:21], v[196:199], v[220:223], v[18:21]
	v_mfma_f32_16x16x32_bf16 v[6:9], v[188:191], v[228:231], v[6:9]
	v_mfma_f32_16x16x32_bf16 v[2:5], v[196:199], v[228:231], v[2:5]
	v_mfma_f32_16x16x32_bf16 v[54:57], v[192:195], v[208:211], v[54:57]
	v_mfma_f32_16x16x32_bf16 v[50:53], v[200:203], v[208:211], v[50:53]
	v_mfma_f32_16x16x32_bf16 v[38:41], v[192:195], v[216:219], v[38:41]
	v_mfma_f32_16x16x32_bf16 v[34:37], v[200:203], v[216:219], v[34:37]
	v_mfma_f32_16x16x32_bf16 v[22:25], v[192:195], v[224:227], v[22:25]
	v_mfma_f32_16x16x32_bf16 v[18:21], v[200:203], v[224:227], v[18:21]
	v_mfma_f32_16x16x32_bf16 v[6:9], v[192:195], v[232:235], v[6:9]
	v_mfma_f32_16x16x32_bf16 v[2:5], v[200:203], v[232:235], v[2:5]
	s_barrier
; #define PG8_STAGE(bufoff, gbase, voff) do { _Pragma("unroll") for (int _i = 0; _i < 2; ++_i) \
;         __builtin_amdgcn_global_load_lds((const unsigned*)((const char*)(gbase) + (voff)[_i]), (LAS unsigned*)(lds + (bufoff) + ldsw + _i * 8192), 16, 0, 0); } while (0)
; #define PG8_LDA(dst, b, h) do { _Pragma("unroll") for (int m = 0; m < 4; ++m) _Pragma("unroll") for (int k = 0; k < 2; ++k) dst[m][k] = *(const LAS bf16x8*)(lds + PG8_SA(b, h) + aoff + m * 2048 + k * 1024); } while (0)
; #define PG8_LDB(dst, b, h) do { _Pragma("unroll") for (int n = 0; n < 2; ++n) _Pragma("unroll") for (int k = 0; k < 2; ++k) dst[n][k] = *(const LAS bf16x8*)(lds + PG8_SB(b, h) + boff + n * 2048 + k * 1024); } while (0)
; #define PG8_MMA(ai, bj, At, Bt) do { __builtin_amdgcn_s_setprio(1); _Pragma("unroll") for (int m = 0; m < 4; ++m) _Pragma("unroll") for (int n = 0; n < 2; ++n) _Pragma("unroll") for (int k = 0; k < 2; ++k) \
;         acc[ai][bj][m][n] = __builtin_amdgcn_mfma_f32_16x16x32_bf16(Bt[n][k], At[m][k], acc[ai][bj][m][n], 0, 0, 0); __builtin_amdgcn_s_setprio(0); } while (0)
; #define PG8_WAIT_V(n) asm volatile("s_waitcnt vmcnt(" #n ")" ::: "memory")
; #define PG8_WAIT_L(n) asm volatile("s_waitcnt lgkmcnt(" #n ")" ::: "memory")
; #define PG8_BAR __builtin_amdgcn_s_barrier()
; #define PG8_SCHED __builtin_amdgcn_sched_barrier(0)
; template <class Epi, class Sched, bool ABLK = false, bool ALIGN_EPI = true, bool SP2 = true, bool BBLK = true>
; __device__ __forceinline__ void gemm_phase(LAS unsigned char* lds, const Gemm g, const Sched& S, const Epi& E) {
;     ...
;             PG8_LDB(B0, 1, 0); PG8_LDB(B1, 1, 1); PG8_SCHED; PG8_LDA(At, 1, 0); PG8_STAGE(PG8_SA(0, 1), a2 + hstepA, voffA);
;             PG8_WAIT_V(8); PG8_WAIT_L(0); PG8_BAR; PG8_MMA(0, 0, At, B0); PG8_MMA(0, 1, At, B1); PG8_BAR; PG8_SCHED;
;             PG8_LDA(At, 1, 1); PG8_STAGE(PG8_SB(1, 0), b3, voffB); PG8_STAGE(PG8_SB(1, 1), b3 + hstepB, voffB); PG8_STAGE(PG8_SA(1, 0), a3, voffA);
;             PG8_WAIT_V(8); PG8_WAIT_L(0); PG8_BAR; PG8_MMA(1, 0, At, B0); PG8_MMA(1, 1, At, B1); PG8_BAR; PG8_SCHED;
	v_add_u32_e32 v171, s60, v1
	ds_read_b128 v[172:175], v171
	ds_read_b128 v[176:179], v171 offset:1024
	ds_read_b128 v[180:183], v171 offset:2048
	ds_read_b128 v[184:187], v171 offset:3072
	v_add_u32_e32 v171, s61, v1
	ds_read_b128 v[188:191], v171
	ds_read_b128 v[192:195], v171 offset:1024
	ds_read_b128 v[196:199], v171 offset:2048
	ds_read_b128 v[200:203], v171 offset:3072
	s_add_u32 s36, s36, 0x80000
	s_addc_u32 s37, s37, 0
	s_mov_b32 m0, s41
	ds_read_b128 v[204:207], v170 offset:32768
	ds_read_b128 v[208:211], v170 offset:33792
	ds_read_b128 v[212:215], v170 offset:34816
	ds_read_b128 v[216:219], v170 offset:35840
	ds_read_b128 v[220:223], v170 offset:36864
	ds_read_b128 v[224:227], v170 offset:37888
	ds_read_b128 v[228:231], v170 offset:38912
	ds_read_b128 v[232:235], v170 offset:39936
	global_load_lds_dwordx4 v136, s[36:37]
	s_mov_b32 m0, s42
	s_nop 0
	global_load_lds_dwordx4 v132, s[36:37]
	s_waitcnt vmcnt(8) lgkmcnt(0)
	s_barrier
	v_mfma_f32_16x16x32_bf16 v[126:129], v[172:175], v[204:207], v[126:129]
	v_mfma_f32_16x16x32_bf16 v[122:125], v[180:183], v[204:207], v[122:125]
	v_mfma_f32_16x16x32_bf16 v[110:113], v[172:175], v[212:215], v[110:113]
	v_mfma_f32_16x16x32_bf16 v[106:109], v[180:183], v[212:215], v[106:109]
	v_mfma_f32_16x16x32_bf16 v[94:97], v[172:175], v[220:223], v[94:97]
	v_mfma_f32_16x16x32_bf16 v[90:93], v[180:183], v[220:223], v[90:93]
	v_mfma_f32_16x16x32_bf16 v[78:81], v[172:175], v[228:231], v[78:81]
	v_mfma_f32_16x16x32_bf16 v[74:77], v[180:183], v[228:231], v[74:77]
	v_mfma_f32_16x16x32_bf16 v[126:129], v[176:179], v[208:211], v[126:129]
	v_mfma_f32_16x16x32_bf16 v[122:125], v[184:187], v[208:211], v[122:125]
	v_mfma_f32_16x16x32_bf16 v[110:113], v[176:179], v[216:219], v[110:113]
	v_mfma_f32_16x16x32_bf16 v[106:109], v[184:187], v[216:219], v[106:109]
	v_mfma_f32_16x16x32_bf16 v[94:97], v[176:179], v[224:227], v[94:97]
	v_mfma_f32_16x16x32_bf16 v[90:93], v[184:187], v[224:227], v[90:93]
	v_mfma_f32_16x16x32_bf16 v[78:81], v[176:179], v[232:235], v[78:81]
	v_mfma_f32_16x16x32_bf16 v[74:77], v[184:187], v[232:235], v[74:77]
	v_mfma_f32_16x16x32_bf16 v[118:121], v[188:191], v[204:207], v[118:121]
	v_mfma_f32_16x16x32_bf16 v[114:117], v[196:199], v[204:207], v[114:117]
	v_mfma_f32_16x16x32_bf16 v[102:105], v[188:191], v[212:215], v[102:105]
	v_mfma_f32_16x16x32_bf16 v[98:101], v[196:199], v[212:215], v[98:101]
	v_mfma_f32_16x16x32_bf16 v[86:89], v[188:191], v[220:223], v[86:89]
	v_mfma_f32_16x16x32_bf16 v[82:85], v[196:199], v[220:223], v[82:85]
	v_mfma_f32_16x16x32_bf16 v[70:73], v[188:191], v[228:231], v[70:73]
	v_mfma_f32_16x16x32_bf16 v[66:69], v[196:199], v[228:231], v[66:69]
	v_mfma_f32_16x16x32_bf16 v[118:121], v[192:195], v[208:211], v[118:121]
	v_mfma_f32_16x16x32_bf16 v[114:117], v[200:203], v[208:211], v[114:117]
	v_mfma_f32_16x16x32_bf16 v[102:105], v[192:195], v[216:219], v[102:105]
	v_mfma_f32_16x16x32_bf16 v[98:101], v[200:203], v[216:219], v[98:101]
	v_mfma_f32_16x16x32_bf16 v[86:89], v[192:195], v[224:227], v[86:89]
	v_mfma_f32_16x16x32_bf16 v[82:85], v[200:203], v[224:227], v[82:85]
	v_mfma_f32_16x16x32_bf16 v[70:73], v[192:195], v[232:235], v[70:73]
	v_mfma_f32_16x16x32_bf16 v[66:69], v[200:203], v[232:235], v[66:69]
	s_barrier
	s_add_u32 s36, s34, 0x8000
	s_addc_u32 s37, s35, 0
	s_add_i32 s55, s60, s39
	s_mov_b32 m0, s55
	ds_read_b128 v[204:207], v170 offset:49152
	ds_read_b128 v[208:211], v170 offset:50176
	ds_read_b128 v[212:215], v170 offset:51200
	ds_read_b128 v[216:219], v170 offset:52224
	ds_read_b128 v[220:223], v170 offset:53248
	ds_read_b128 v[224:227], v170 offset:54272
	ds_read_b128 v[228:231], v170 offset:55296
	ds_read_b128 v[232:235], v170 offset:56320
	global_load_lds_dwordx4 v134, s[36:37]
	s_add_i32 m0, s55, 0x2000
	s_add_u32 s34, s34, 0xc000
	v_lshl_add_u64 v[236:237], s[36:37], 0, v[130:131]
	s_addc_u32 s35, s35, 0
	s_add_i32 s36, s61, s39
	global_load_lds_dwordx4 v[236:237], off
	s_mov_b32 m0, s36
	s_nop 0
	global_load_lds_dwordx4 v134, s[34:35]
	s_add_i32 m0, s36, 0x2000
	s_nop 0
	global_load_lds_dwordx4 v130, s[34:35]
	s_mov_b32 m0, s45
	s_nop 0
	global_load_lds_dwordx4 v136, s[30:31]
	s_mov_b32 m0, s46
	s_nop 0
	global_load_lds_dwordx4 v132, s[30:31]
	s_waitcnt vmcnt(8) lgkmcnt(0)
	s_barrier
	v_mfma_f32_16x16x32_bf16 v[62:65], v[172:175], v[204:207], v[62:65]
	v_mfma_f32_16x16x32_bf16 v[58:61], v[180:183], v[204:207], v[58:61]
	v_mfma_f32_16x16x32_bf16 v[46:49], v[172:175], v[212:215], v[46:49]
	v_mfma_f32_16x16x32_bf16 v[42:45], v[180:183], v[212:215], v[42:45]
	v_mfma_f32_16x16x32_bf16 v[30:33], v[172:175], v[220:223], v[30:33]
	v_mfma_f32_16x16x32_bf16 v[26:29], v[180:183], v[220:223], v[26:29]
	v_mfma_f32_16x16x32_bf16 v[14:17], v[172:175], v[228:231], v[14:17]
	v_mfma_f32_16x16x32_bf16 v[10:13], v[180:183], v[228:231], v[10:13]
	v_mfma_f32_16x16x32_bf16 v[62:65], v[176:179], v[208:211], v[62:65]
	v_mfma_f32_16x16x32_bf16 v[58:61], v[184:187], v[208:211], v[58:61]
	v_mfma_f32_16x16x32_bf16 v[46:49], v[176:179], v[216:219], v[46:49]
	v_mfma_f32_16x16x32_bf16 v[42:45], v[184:187], v[216:219], v[42:45]
	v_mfma_f32_16x16x32_bf16 v[30:33], v[176:179], v[224:227], v[30:33]
	v_mfma_f32_16x16x32_bf16 v[26:29], v[184:187], v[224:227], v[26:29]
	v_mfma_f32_16x16x32_bf16 v[14:17], v[176:179], v[232:235], v[14:17]
	v_mfma_f32_16x16x32_bf16 v[10:13], v[184:187], v[232:235], v[10:13]
	v_mfma_f32_16x16x32_bf16 v[54:57], v[188:191], v[204:207], v[54:57]
	v_mfma_f32_16x16x32_bf16 v[50:53], v[196:199], v[204:207], v[50:53]
	v_mfma_f32_16x16x32_bf16 v[38:41], v[188:191], v[212:215], v[38:41]
	v_mfma_f32_16x16x32_bf16 v[34:37], v[196:199], v[212:215], v[34:37]
	v_mfma_f32_16x16x32_bf16 v[22:25], v[188:191], v[220:223], v[22:25]
	v_mfma_f32_16x16x32_bf16 v[18:21], v[196:199], v[220:223], v[18:21]
	v_mfma_f32_16x16x32_bf16 v[6:9], v[188:191], v[228:231], v[6:9]
	v_mfma_f32_16x16x32_bf16 v[2:5], v[196:199], v[228:231], v[2:5]
	v_mfma_f32_16x16x32_bf16 v[54:57], v[192:195], v[208:211], v[54:57]
	v_mfma_f32_16x16x32_bf16 v[50:53], v[200:203], v[208:211], v[50:53]
	v_mfma_f32_16x16x32_bf16 v[38:41], v[192:195], v[216:219], v[38:41]
	v_mfma_f32_16x16x32_bf16 v[34:37], v[200:203], v[216:219], v[34:37]
	v_mfma_f32_16x16x32_bf16 v[22:25], v[192:195], v[224:227], v[22:25]
	v_mfma_f32_16x16x32_bf16 v[18:21], v[200:203], v[224:227], v[18:21]
	v_mfma_f32_16x16x32_bf16 v[6:9], v[192:195], v[232:235], v[6:9]
	v_mfma_f32_16x16x32_bf16 v[2:5], v[200:203], v[232:235], v[2:5]
	s_barrier
; __device__ __forceinline__ unsigned pk2(float lo, float hi) { const f32x2 v = {lo, hi}; return __builtin_bit_cast(unsigned, __builtin_convertvector(v, bf16x2_t)); }
; #define PG8_BAR __builtin_amdgcn_s_barrier()
; template <class Epi, class Sched, bool ABLK = false, bool ALIGN_EPI = true, bool SP2 = true, bool BBLK = true>
; __device__ __forceinline__ void gemm_phase(LAS unsigned char* lds, const Gemm g, const Sched& S, const Epi& E) {
;     ...
;         if constexpr (ALIGN_EPI) { if (wr == 0) PG8_BAR; }
;     __device__ __forceinline__ void operator()(const f32x4 (&acc)[2][2][4][2], const Unit& u, int wr, int wc, int fr, int fq) const {
; #pragma unroll
;         for (int ai = 0; ai < 2; ++ai)
; #pragma unroll
;             for (int m = 0; m < 4; ++m) { unsigned char* rowp = (unsigned char*)(H + ((size_t)(u.pm * (FF / 64) + u.pn * 4 + wc) * 256 + (wr * 64 + fr + ai * 128 + m * 16)) * 64 + 8 * fq); u32x4 w[2];
; #pragma unroll
;                 for (int bj = 0; bj < 2; ++bj) { f32x4 v0 = acc[ai][bj][m][0], v1 = acc[ai][bj][m][1];
; #pragma unroll
;                     for (int j = 0; j < 4; ++j) { const float a = fmaxf(v0[j], 0.f), b = fmaxf(v1[j], 0.f); v0[j] = a * a; v1[j] = b * b; }
;                     w[bj].x = pk2(v0[0], v0[1]); w[bj].y = pk2(v0[2], v0[3]); w[bj].z = pk2(v1[0], v1[1]); w[bj].w = pk2(v1[2], v1[3]); }
;                 store_pair(rowp, (size_t)8 * 64 * 2, 64, w[0], w[1], fr >= 8); }
;     }
	s_add_i32 s54, s54, 2
	s_add_u32 s28, s28, 0x100
	s_addc_u32 s29, s29, 0
	s_add_u32 s52, s52, 0x10000
	s_addc_u32 s53, s53, 0
	s_cmp_gt_u32 s54, 29
	s_cbranch_scc0 .LBB0_1842
	s_lshl_b32 s4, s22, 7
	s_lshl_b32 s5, s24, 2
	s_add_i32 s5, s5, s4
	s_or_b32 s4, s5, s44
	s_ashr_i32 s5, s4, 31
	s_lshl_b64 s[4:5], s[4:5], 15
	s_add_u32 s22, s62, s4
	v_max_f32_e32 v126, 0, v126
	v_max_f32_e32 v122, 0, v122
	v_max_f32_e32 v127, 0, v127
	v_max_f32_e32 v123, 0, v123
	v_max_f32_e32 v128, 0, v128
	v_max_f32_e32 v124, 0, v124
	v_max_f32_e32 v129, 0, v129
	v_max_f32_e32 v125, 0, v125
	v_max_f32_e32 v118, 0, v118
	v_max_f32_e32 v114, 0, v114
	v_max_f32_e32 v119, 0, v119
	v_max_f32_e32 v115, 0, v115
	v_max_f32_e32 v120, 0, v120
	v_max_f32_e32 v116, 0, v116
	v_max_f32_e32 v121, 0, v121
	v_max_f32_e32 v117, 0, v117
	s_addc_u32 s23, s83, s5
	v_pk_mul_f32 v[126:127], v[126:127], v[126:127]
	v_pk_mul_f32 v[122:123], v[122:123], v[122:123]
	v_pk_mul_f32 v[128:129], v[128:129], v[128:129]
	v_pk_mul_f32 v[124:125], v[124:125], v[124:125]
	v_pk_mul_f32 v[118:119], v[118:119], v[118:119]
	v_pk_mul_f32 v[114:115], v[114:115], v[114:115]
	v_pk_mul_f32 v[120:121], v[120:121], v[120:121]
	v_pk_mul_f32 v[116:117], v[116:117], v[116:117]
	v_lshl_add_u64 v[164:165], s[22:23], 0, v[144:145]
	v_cvt_pk_bf16_f32 v126, v126, v127
	v_cvt_pk_bf16_f32 v127, v128, v129
	v_cvt_pk_bf16_f32 v128, v122, v123
	v_cvt_pk_bf16_f32 v129, v124, v125
	v_cvt_pk_bf16_f32 v118, v118, v119
	v_cvt_pk_bf16_f32 v119, v120, v121
	v_cvt_pk_bf16_f32 v114, v114, v115
	v_cvt_pk_bf16_f32 v115, v116, v117
	v_lshl_add_u64 v[122:123], v[164:165], 0, v[138:139]
	v_mov_b32_dpp v120, v126 row_ror:8 row_mask:0xf bank_mask:0xf bound_ctrl:1
	v_mov_b32_dpp v121, v127 row_ror:8 row_mask:0xf bank_mask:0xf bound_ctrl:1
	v_mov_b32_dpp v116, v128 row_ror:8 row_mask:0xf bank_mask:0xf bound_ctrl:1
	v_mov_b32_dpp v117, v129 row_ror:8 row_mask:0xf bank_mask:0xf bound_ctrl:1
	v_mov_b32_dpp v164, v118 row_ror:8 row_mask:0xf bank_mask:0xf bound_ctrl:1
	v_mov_b32_dpp v165, v119 row_ror:8 row_mask:0xf bank_mask:0xf bound_ctrl:1
	v_mov_b32_dpp v166, v114 row_ror:8 row_mask:0xf bank_mask:0xf bound_ctrl:1
	v_mov_b32_dpp v167, v115 row_ror:8 row_mask:0xf bank_mask:0xf bound_ctrl:1
	v_max_f32_e32 v110, 0, v110
	v_max_f32_e32 v106, 0, v106
	v_max_f32_e32 v111, 0, v111
	v_max_f32_e32 v107, 0, v107
	v_max_f32_e32 v112, 0, v112
	v_max_f32_e32 v108, 0, v108
	v_max_f32_e32 v113, 0, v113
	v_max_f32_e32 v109, 0, v109
	v_max_f32_e32 v102, 0, v102
	v_max_f32_e32 v98, 0, v98
	v_max_f32_e32 v103, 0, v103
	v_max_f32_e32 v99, 0, v99
	v_max_f32_e32 v104, 0, v104
	v_max_f32_e32 v100, 0, v100
	v_max_f32_e32 v105, 0, v105
	v_max_f32_e32 v101, 0, v101
	v_lshl_add_u64 v[124:125], v[122:123], 0, v[140:141]
	v_cndmask_b32_e64 v117, v117, v115, s[8:9]
	v_cndmask_b32_e64 v116, v116, v114, s[8:9]
	v_cndmask_b32_e64 v115, v121, v119, s[8:9]
	v_cndmask_b32_e64 v114, v120, v118, s[8:9]
	v_cndmask_b32_e64 v121, v129, v167, s[8:9]
	v_cndmask_b32_e64 v120, v128, v166, s[8:9]
	v_cndmask_b32_e64 v119, v127, v165, s[8:9]
	v_cndmask_b32_e64 v118, v126, v164, s[8:9]
	v_pk_mul_f32 v[110:111], v[110:111], v[110:111]
	v_pk_mul_f32 v[106:107], v[106:107], v[106:107]
	v_pk_mul_f32 v[112:113], v[112:113], v[112:113]
	v_pk_mul_f32 v[108:109], v[108:109], v[108:109]
	v_pk_mul_f32 v[102:103], v[102:103], v[102:103]
	v_pk_mul_f32 v[98:99], v[98:99], v[98:99]
	v_pk_mul_f32 v[104:105], v[104:105], v[104:105]
	v_pk_mul_f32 v[100:101], v[100:101], v[100:101]
	v_lshl_add_u64 v[122:123], v[122:123], 0, v[142:143]
	global_store_dwordx4 v[124:125], v[118:121], off
	global_store_dwordx4 v[122:123], v[114:117], off
	v_cvt_pk_bf16_f32 v110, v110, v111
	v_cvt_pk_bf16_f32 v111, v112, v113
	v_lshl_add_u64 v[114:115], s[22:23], 0, v[146:147]
	v_cvt_pk_bf16_f32 v112, v106, v107
	v_cvt_pk_bf16_f32 v113, v108, v109
	v_cvt_pk_bf16_f32 v102, v102, v103
	v_cvt_pk_bf16_f32 v103, v104, v105
	v_cvt_pk_bf16_f32 v98, v98, v99
	v_cvt_pk_bf16_f32 v99, v100, v101
	v_lshl_add_u64 v[106:107], v[114:115], 0, v[138:139]
	v_mov_b32_dpp v104, v110 row_ror:8 row_mask:0xf bank_mask:0xf bound_ctrl:1
	v_mov_b32_dpp v105, v111 row_ror:8 row_mask:0xf bank_mask:0xf bound_ctrl:1
	v_mov_b32_dpp v100, v112 row_ror:8 row_mask:0xf bank_mask:0xf bound_ctrl:1
	v_mov_b32_dpp v101, v113 row_ror:8 row_mask:0xf bank_mask:0xf bound_ctrl:1
	v_mov_b32_dpp v114, v102 row_ror:8 row_mask:0xf bank_mask:0xf bound_ctrl:1
	v_mov_b32_dpp v115, v103 row_ror:8 row_mask:0xf bank_mask:0xf bound_ctrl:1
	v_mov_b32_dpp v116, v98 row_ror:8 row_mask:0xf bank_mask:0xf bound_ctrl:1
	v_mov_b32_dpp v117, v99 row_ror:8 row_mask:0xf bank_mask:0xf bound_ctrl:1
	v_max_f32_e32 v94, 0, v94
	v_max_f32_e32 v90, 0, v90
	v_max_f32_e32 v95, 0, v95
	v_max_f32_e32 v91, 0, v91
	v_max_f32_e32 v96, 0, v96
	v_max_f32_e32 v92, 0, v92
	v_max_f32_e32 v97, 0, v97
	v_max_f32_e32 v93, 0, v93
	v_max_f32_e32 v86, 0, v86
	v_max_f32_e32 v82, 0, v82
	v_max_f32_e32 v87, 0, v87
	v_max_f32_e32 v83, 0, v83
	v_max_f32_e32 v88, 0, v88
	v_max_f32_e32 v84, 0, v84
	v_max_f32_e32 v89, 0, v89
	v_max_f32_e32 v85, 0, v85
	v_lshl_add_u64 v[108:109], v[106:107], 0, v[140:141]
	v_cndmask_b32_e64 v101, v101, v99, s[8:9]
	v_cndmask_b32_e64 v100, v100, v98, s[8:9]
	v_cndmask_b32_e64 v99, v105, v103, s[8:9]
	v_cndmask_b32_e64 v98, v104, v102, s[8:9]
	v_cndmask_b32_e64 v105, v113, v117, s[8:9]
	v_cndmask_b32_e64 v104, v112, v116, s[8:9]
	v_cndmask_b32_e64 v103, v111, v115, s[8:9]
	v_cndmask_b32_e64 v102, v110, v114, s[8:9]
	v_pk_mul_f32 v[94:95], v[94:95], v[94:95]
	v_pk_mul_f32 v[90:91], v[90:91], v[90:91]
	v_pk_mul_f32 v[96:97], v[96:97], v[96:97]
	v_pk_mul_f32 v[92:93], v[92:93], v[92:93]
; __device__ __forceinline__ unsigned pk2(float lo, float hi) { const f32x2 v = {lo, hi}; return __builtin_bit_cast(unsigned, __builtin_convertvector(v, bf16x2_t)); }
;     __device__ __forceinline__ void operator()(const f32x4 (&acc)[2][2][4][2], const Unit& u, int wr, int wc, int fr, int fq) const {
;     ...
;         for (int ai = 0; ai < 2; ++ai)
; #pragma unroll
;             for (int m = 0; m < 4; ++m) { unsigned char* rowp = (unsigned char*)(H + ((size_t)(u.pm * (FF / 64) + u.pn * 4 + wc) * 256 + (wr * 64 + fr + ai * 128 + m * 16)) * 64 + 8 * fq); u32x4 w[2];
; #pragma unroll
;                 for (int bj = 0; bj < 2; ++bj) { f32x4 v0 = acc[ai][bj][m][0], v1 = acc[ai][bj][m][1];
; #pragma unroll
;                     for (int j = 0; j < 4; ++j) { const float a = fmaxf(v0[j], 0.f), b = fmaxf(v1[j], 0.f); v0[j] = a * a; v1[j] = b * b; }
;                     w[bj].x = pk2(v0[0], v0[1]); w[bj].y = pk2(v0[2], v0[3]); w[bj].z = pk2(v1[0], v1[1]); w[bj].w = pk2(v1[2], v1[3]); }
;                 store_pair(rowp, (size_t)8 * 64 * 2, 64, w[0], w[1], fr >= 8); }
	v_pk_mul_f32 v[86:87], v[86:87], v[86:87]
	v_pk_mul_f32 v[82:83], v[82:83], v[82:83]
	v_pk_mul_f32 v[88:89], v[88:89], v[88:89]
	v_pk_mul_f32 v[84:85], v[84:85], v[84:85]
	v_lshl_add_u64 v[106:107], v[106:107], 0, v[142:143]
	global_store_dwordx4 v[108:109], v[102:105], off
	global_store_dwordx4 v[106:107], v[98:101], off
	v_cvt_pk_bf16_f32 v94, v94, v95
	v_cvt_pk_bf16_f32 v95, v96, v97
	v_lshl_add_u64 v[98:99], s[22:23], 0, v[148:149]
	v_cvt_pk_bf16_f32 v96, v90, v91
	v_cvt_pk_bf16_f32 v97, v92, v93
	v_cvt_pk_bf16_f32 v86, v86, v87
	v_cvt_pk_bf16_f32 v87, v88, v89
	v_cvt_pk_bf16_f32 v82, v82, v83
	v_cvt_pk_bf16_f32 v83, v84, v85
	v_lshl_add_u64 v[90:91], v[98:99], 0, v[138:139]
	v_mov_b32_dpp v88, v94 row_ror:8 row_mask:0xf bank_mask:0xf bound_ctrl:1
	v_mov_b32_dpp v89, v95 row_ror:8 row_mask:0xf bank_mask:0xf bound_ctrl:1
	v_mov_b32_dpp v84, v96 row_ror:8 row_mask:0xf bank_mask:0xf bound_ctrl:1
	v_mov_b32_dpp v85, v97 row_ror:8 row_mask:0xf bank_mask:0xf bound_ctrl:1
	v_mov_b32_dpp v98, v86 row_ror:8 row_mask:0xf bank_mask:0xf bound_ctrl:1
	v_mov_b32_dpp v99, v87 row_ror:8 row_mask:0xf bank_mask:0xf bound_ctrl:1
	v_mov_b32_dpp v100, v82 row_ror:8 row_mask:0xf bank_mask:0xf bound_ctrl:1
	v_mov_b32_dpp v101, v83 row_ror:8 row_mask:0xf bank_mask:0xf bound_ctrl:1
	v_max_f32_e32 v78, 0, v78
	v_max_f32_e32 v74, 0, v74
	v_max_f32_e32 v79, 0, v79
	v_max_f32_e32 v75, 0, v75
	v_max_f32_e32 v80, 0, v80
	v_max_f32_e32 v76, 0, v76
	v_max_f32_e32 v81, 0, v81
	v_max_f32_e32 v77, 0, v77
	v_max_f32_e32 v70, 0, v70
	v_max_f32_e32 v66, 0, v66
	v_max_f32_e32 v71, 0, v71
	v_max_f32_e32 v67, 0, v67
	v_max_f32_e32 v72, 0, v72
	v_max_f32_e32 v68, 0, v68
	v_max_f32_e32 v73, 0, v73
	v_max_f32_e32 v69, 0, v69
	v_lshl_add_u64 v[92:93], v[90:91], 0, v[140:141]
	v_cndmask_b32_e64 v85, v85, v83, s[8:9]
	v_cndmask_b32_e64 v84, v84, v82, s[8:9]
	v_cndmask_b32_e64 v83, v89, v87, s[8:9]
	v_cndmask_b32_e64 v82, v88, v86, s[8:9]
	v_cndmask_b32_e64 v89, v97, v101, s[8:9]
	v_cndmask_b32_e64 v88, v96, v100, s[8:9]
	v_cndmask_b32_e64 v87, v95, v99, s[8:9]
	v_cndmask_b32_e64 v86, v94, v98, s[8:9]
	v_pk_mul_f32 v[78:79], v[78:79], v[78:79]
	v_pk_mul_f32 v[74:75], v[74:75], v[74:75]
	v_pk_mul_f32 v[80:81], v[80:81], v[80:81]
	v_pk_mul_f32 v[76:77], v[76:77], v[76:77]
	v_pk_mul_f32 v[70:71], v[70:71], v[70:71]
	v_pk_mul_f32 v[66:67], v[66:67], v[66:67]
	v_pk_mul_f32 v[72:73], v[72:73], v[72:73]
	v_pk_mul_f32 v[68:69], v[68:69], v[68:69]
	v_lshl_add_u64 v[90:91], v[90:91], 0, v[142:143]
	global_store_dwordx4 v[92:93], v[86:89], off
	global_store_dwordx4 v[90:91], v[82:85], off
	v_cvt_pk_bf16_f32 v78, v78, v79
	v_cvt_pk_bf16_f32 v79, v80, v81
	v_lshl_add_u64 v[82:83], s[22:23], 0, v[150:151]
	v_cvt_pk_bf16_f32 v80, v74, v75
	v_cvt_pk_bf16_f32 v81, v76, v77
	v_cvt_pk_bf16_f32 v70, v70, v71
	v_cvt_pk_bf16_f32 v71, v72, v73
	v_cvt_pk_bf16_f32 v66, v66, v67
	v_cvt_pk_bf16_f32 v67, v68, v69
	v_lshl_add_u64 v[74:75], v[82:83], 0, v[138:139]
	v_mov_b32_dpp v72, v78 row_ror:8 row_mask:0xf bank_mask:0xf bound_ctrl:1
	v_mov_b32_dpp v73, v79 row_ror:8 row_mask:0xf bank_mask:0xf bound_ctrl:1
	v_mov_b32_dpp v68, v80 row_ror:8 row_mask:0xf bank_mask:0xf bound_ctrl:1
	v_mov_b32_dpp v69, v81 row_ror:8 row_mask:0xf bank_mask:0xf bound_ctrl:1
	v_mov_b32_dpp v82, v70 row_ror:8 row_mask:0xf bank_mask:0xf bound_ctrl:1
	v_mov_b32_dpp v83, v71 row_ror:8 row_mask:0xf bank_mask:0xf bound_ctrl:1
	v_mov_b32_dpp v84, v66 row_ror:8 row_mask:0xf bank_mask:0xf bound_ctrl:1
	v_mov_b32_dpp v85, v67 row_ror:8 row_mask:0xf bank_mask:0xf bound_ctrl:1
	v_max_f32_e32 v62, 0, v62
	v_max_f32_e32 v58, 0, v58
	v_max_f32_e32 v63, 0, v63
	v_max_f32_e32 v59, 0, v59
	v_max_f32_e32 v64, 0, v64
	v_max_f32_e32 v60, 0, v60
	v_max_f32_e32 v65, 0, v65
	v_max_f32_e32 v61, 0, v61
	v_max_f32_e32 v54, 0, v54
	v_max_f32_e32 v50, 0, v50
	v_max_f32_e32 v55, 0, v55
	v_max_f32_e32 v51, 0, v51
	v_max_f32_e32 v56, 0, v56
	v_max_f32_e32 v52, 0, v52
	v_max_f32_e32 v57, 0, v57
	v_max_f32_e32 v53, 0, v53
	v_lshl_add_u64 v[76:77], v[74:75], 0, v[140:141]
	v_cndmask_b32_e64 v69, v69, v67, s[8:9]
	v_cndmask_b32_e64 v68, v68, v66, s[8:9]
	v_cndmask_b32_e64 v67, v73, v71, s[8:9]
	v_cndmask_b32_e64 v66, v72, v70, s[8:9]
	v_cndmask_b32_e64 v73, v81, v85, s[8:9]
	v_cndmask_b32_e64 v72, v80, v84, s[8:9]
	v_cndmask_b32_e64 v71, v79, v83, s[8:9]
	v_cndmask_b32_e64 v70, v78, v82, s[8:9]
	v_pk_mul_f32 v[62:63], v[62:63], v[62:63]
	v_pk_mul_f32 v[58:59], v[58:59], v[58:59]
	v_pk_mul_f32 v[64:65], v[64:65], v[64:65]
	v_pk_mul_f32 v[60:61], v[60:61], v[60:61]
	v_pk_mul_f32 v[54:55], v[54:55], v[54:55]
	v_pk_mul_f32 v[50:51], v[50:51], v[50:51]
	v_pk_mul_f32 v[56:57], v[56:57], v[56:57]
	v_pk_mul_f32 v[52:53], v[52:53], v[52:53]
	v_lshl_add_u64 v[74:75], v[74:75], 0, v[142:143]
	global_store_dwordx4 v[76:77], v[70:73], off
	global_store_dwordx4 v[74:75], v[66:69], off
	v_cvt_pk_bf16_f32 v62, v62, v63
	v_cvt_pk_bf16_f32 v63, v64, v65
	v_lshl_add_u64 v[66:67], s[22:23], 0, v[152:153]
	v_cvt_pk_bf16_f32 v64, v58, v59
	v_cvt_pk_bf16_f32 v65, v60, v61
	v_cvt_pk_bf16_f32 v54, v54, v55
	v_cvt_pk_bf16_f32 v55, v56, v57
	v_cvt_pk_bf16_f32 v50, v50, v51
	v_cvt_pk_bf16_f32 v51, v52, v53
	v_lshl_add_u64 v[58:59], v[66:67], 0, v[138:139]
	v_mov_b32_dpp v56, v62 row_ror:8 row_mask:0xf bank_mask:0xf bound_ctrl:1
	v_mov_b32_dpp v57, v63 row_ror:8 row_mask:0xf bank_mask:0xf bound_ctrl:1
	v_mov_b32_dpp v52, v64 row_ror:8 row_mask:0xf bank_mask:0xf bound_ctrl:1
	v_mov_b32_dpp v53, v65 row_ror:8 row_mask:0xf bank_mask:0xf bound_ctrl:1
	v_mov_b32_dpp v66, v54 row_ror:8 row_mask:0xf bank_mask:0xf bound_ctrl:1
	v_mov_b32_dpp v67, v55 row_ror:8 row_mask:0xf bank_mask:0xf bound_ctrl:1
; __device__ __forceinline__ unsigned pk2(float lo, float hi) { const f32x2 v = {lo, hi}; return __builtin_bit_cast(unsigned, __builtin_convertvector(v, bf16x2_t)); }
;     __device__ __forceinline__ void operator()(const f32x4 (&acc)[2][2][4][2], const Unit& u, int wr, int wc, int fr, int fq) const {
;     ...
;         for (int ai = 0; ai < 2; ++ai)
; #pragma unroll
;             for (int m = 0; m < 4; ++m) { unsigned char* rowp = (unsigned char*)(H + ((size_t)(u.pm * (FF / 64) + u.pn * 4 + wc) * 256 + (wr * 64 + fr + ai * 128 + m * 16)) * 64 + 8 * fq); u32x4 w[2];
; #pragma unroll
;                 for (int bj = 0; bj < 2; ++bj) { f32x4 v0 = acc[ai][bj][m][0], v1 = acc[ai][bj][m][1];
; #pragma unroll
;                     for (int j = 0; j < 4; ++j) { const float a = fmaxf(v0[j], 0.f), b = fmaxf(v1[j], 0.f); v0[j] = a * a; v1[j] = b * b; }
;                     w[bj].x = pk2(v0[0], v0[1]); w[bj].y = pk2(v0[2], v0[3]); w[bj].z = pk2(v1[0], v1[1]); w[bj].w = pk2(v1[2], v1[3]); }
;                 store_pair(rowp, (size_t)8 * 64 * 2, 64, w[0], w[1], fr >= 8); }
	v_mov_b32_dpp v68, v50 row_ror:8 row_mask:0xf bank_mask:0xf bound_ctrl:1
	v_mov_b32_dpp v69, v51 row_ror:8 row_mask:0xf bank_mask:0xf bound_ctrl:1
	v_max_f32_e32 v46, 0, v46
	v_max_f32_e32 v42, 0, v42
	v_max_f32_e32 v47, 0, v47
	v_max_f32_e32 v43, 0, v43
	v_max_f32_e32 v48, 0, v48
	v_max_f32_e32 v44, 0, v44
	v_max_f32_e32 v49, 0, v49
	v_max_f32_e32 v45, 0, v45
	v_max_f32_e32 v38, 0, v38
	v_max_f32_e32 v34, 0, v34
	v_max_f32_e32 v39, 0, v39
	v_max_f32_e32 v35, 0, v35
	v_max_f32_e32 v40, 0, v40
	v_max_f32_e32 v36, 0, v36
	v_max_f32_e32 v41, 0, v41
	v_max_f32_e32 v37, 0, v37
	v_lshl_add_u64 v[60:61], v[58:59], 0, v[140:141]
	v_cndmask_b32_e64 v53, v53, v51, s[8:9]
	v_cndmask_b32_e64 v52, v52, v50, s[8:9]
	v_cndmask_b32_e64 v51, v57, v55, s[8:9]
	v_cndmask_b32_e64 v50, v56, v54, s[8:9]
	v_cndmask_b32_e64 v57, v65, v69, s[8:9]
	v_cndmask_b32_e64 v56, v64, v68, s[8:9]
	v_cndmask_b32_e64 v55, v63, v67, s[8:9]
	v_cndmask_b32_e64 v54, v62, v66, s[8:9]
	v_pk_mul_f32 v[46:47], v[46:47], v[46:47]
	v_pk_mul_f32 v[42:43], v[42:43], v[42:43]
	v_pk_mul_f32 v[48:49], v[48:49], v[48:49]
	v_pk_mul_f32 v[44:45], v[44:45], v[44:45]
	v_pk_mul_f32 v[38:39], v[38:39], v[38:39]
	v_pk_mul_f32 v[34:35], v[34:35], v[34:35]
	v_pk_mul_f32 v[40:41], v[40:41], v[40:41]
	v_pk_mul_f32 v[36:37], v[36:37], v[36:37]
	v_lshl_add_u64 v[58:59], v[58:59], 0, v[142:143]
	global_store_dwordx4 v[60:61], v[54:57], off
	global_store_dwordx4 v[58:59], v[50:53], off
	v_cvt_pk_bf16_f32 v46, v46, v47
	v_cvt_pk_bf16_f32 v47, v48, v49
	v_lshl_add_u64 v[50:51], s[22:23], 0, v[154:155]
	v_cvt_pk_bf16_f32 v48, v42, v43
	v_cvt_pk_bf16_f32 v49, v44, v45
	v_cvt_pk_bf16_f32 v38, v38, v39
	v_cvt_pk_bf16_f32 v39, v40, v41
	v_cvt_pk_bf16_f32 v34, v34, v35
	v_cvt_pk_bf16_f32 v35, v36, v37
	v_lshl_add_u64 v[42:43], v[50:51], 0, v[138:139]
	v_mov_b32_dpp v40, v46 row_ror:8 row_mask:0xf bank_mask:0xf bound_ctrl:1
	v_mov_b32_dpp v41, v47 row_ror:8 row_mask:0xf bank_mask:0xf bound_ctrl:1
	v_mov_b32_dpp v36, v48 row_ror:8 row_mask:0xf bank_mask:0xf bound_ctrl:1
	v_mov_b32_dpp v37, v49 row_ror:8 row_mask:0xf bank_mask:0xf bound_ctrl:1
	v_mov_b32_dpp v50, v38 row_ror:8 row_mask:0xf bank_mask:0xf bound_ctrl:1
	v_mov_b32_dpp v51, v39 row_ror:8 row_mask:0xf bank_mask:0xf bound_ctrl:1
	v_mov_b32_dpp v52, v34 row_ror:8 row_mask:0xf bank_mask:0xf bound_ctrl:1
	v_mov_b32_dpp v53, v35 row_ror:8 row_mask:0xf bank_mask:0xf bound_ctrl:1
	v_max_f32_e32 v30, 0, v30
	v_max_f32_e32 v26, 0, v26
	v_max_f32_e32 v31, 0, v31
	v_max_f32_e32 v27, 0, v27
	v_max_f32_e32 v32, 0, v32
	v_max_f32_e32 v28, 0, v28
	v_max_f32_e32 v33, 0, v33
	v_max_f32_e32 v29, 0, v29
	v_max_f32_e32 v22, 0, v22
	v_max_f32_e32 v18, 0, v18
	v_max_f32_e32 v23, 0, v23
	v_max_f32_e32 v19, 0, v19
	v_max_f32_e32 v24, 0, v24
	v_max_f32_e32 v20, 0, v20
	v_max_f32_e32 v25, 0, v25
	v_max_f32_e32 v21, 0, v21
	v_lshl_add_u64 v[44:45], v[42:43], 0, v[140:141]
	v_cndmask_b32_e64 v37, v37, v35, s[8:9]
	v_cndmask_b32_e64 v36, v36, v34, s[8:9]
	v_cndmask_b32_e64 v35, v41, v39, s[8:9]
	v_cndmask_b32_e64 v34, v40, v38, s[8:9]
	v_cndmask_b32_e64 v41, v49, v53, s[8:9]
	v_cndmask_b32_e64 v40, v48, v52, s[8:9]
	v_cndmask_b32_e64 v39, v47, v51, s[8:9]
	v_cndmask_b32_e64 v38, v46, v50, s[8:9]
	v_pk_mul_f32 v[30:31], v[30:31], v[30:31]
	v_pk_mul_f32 v[26:27], v[26:27], v[26:27]
	v_pk_mul_f32 v[32:33], v[32:33], v[32:33]
	v_pk_mul_f32 v[28:29], v[28:29], v[28:29]
	v_pk_mul_f32 v[22:23], v[22:23], v[22:23]
	v_pk_mul_f32 v[18:19], v[18:19], v[18:19]
	v_pk_mul_f32 v[24:25], v[24:25], v[24:25]
	v_pk_mul_f32 v[20:21], v[20:21], v[20:21]
	v_lshl_add_u64 v[42:43], v[42:43], 0, v[142:143]
	global_store_dwordx4 v[44:45], v[38:41], off
; __device__ __forceinline__ unsigned pk2(float lo, float hi) { const f32x2 v = {lo, hi}; return __builtin_bit_cast(unsigned, __builtin_convertvector(v, bf16x2_t)); }
; #define PG8_BAR __builtin_amdgcn_s_barrier()
; template <class Epi, class Sched, bool ABLK = false, bool ALIGN_EPI = true, bool SP2 = true, bool BBLK = true>
; __device__ __forceinline__ void gemm_phase(LAS unsigned char* lds, const Gemm g, const Sched& S, const Epi& E) {
;     ...
;         if constexpr (ALIGN_EPI) { if (wr == 0) PG8_BAR; }
;     __device__ __forceinline__ void operator()(const f32x4 (&acc)[2][2][4][2], const Unit& u, int wr, int wc, int fr, int fq) const {
;     ...
;         for (int ai = 0; ai < 2; ++ai)
; #pragma unroll
;             for (int m = 0; m < 4; ++m) { unsigned char* rowp = (unsigned char*)(H + ((size_t)(u.pm * (FF / 64) + u.pn * 4 + wc) * 256 + (wr * 64 + fr + ai * 128 + m * 16)) * 64 + 8 * fq); u32x4 w[2];
; #pragma unroll
;                 for (int bj = 0; bj < 2; ++bj) { f32x4 v0 = acc[ai][bj][m][0], v1 = acc[ai][bj][m][1];
; #pragma unroll
;                     for (int j = 0; j < 4; ++j) { const float a = fmaxf(v0[j], 0.f), b = fmaxf(v1[j], 0.f); v0[j] = a * a; v1[j] = b * b; }
;                     w[bj].x = pk2(v0[0], v0[1]); w[bj].y = pk2(v0[2], v0[3]); w[bj].z = pk2(v1[0], v1[1]); w[bj].w = pk2(v1[2], v1[3]); }
;                 store_pair(rowp, (size_t)8 * 64 * 2, 64, w[0], w[1], fr >= 8); }
	global_store_dwordx4 v[42:43], v[34:37], off
	v_cvt_pk_bf16_f32 v30, v30, v31
	v_cvt_pk_bf16_f32 v31, v32, v33
	v_lshl_add_u64 v[34:35], s[22:23], 0, v[156:157]
	v_cvt_pk_bf16_f32 v32, v26, v27
	v_cvt_pk_bf16_f32 v33, v28, v29
	v_cvt_pk_bf16_f32 v22, v22, v23
	v_cvt_pk_bf16_f32 v23, v24, v25
	v_cvt_pk_bf16_f32 v18, v18, v19
	v_cvt_pk_bf16_f32 v19, v20, v21
	v_lshl_add_u64 v[26:27], v[34:35], 0, v[138:139]
	v_mov_b32_dpp v24, v30 row_ror:8 row_mask:0xf bank_mask:0xf bound_ctrl:1
	v_mov_b32_dpp v25, v31 row_ror:8 row_mask:0xf bank_mask:0xf bound_ctrl:1
	v_mov_b32_dpp v20, v32 row_ror:8 row_mask:0xf bank_mask:0xf bound_ctrl:1
	v_mov_b32_dpp v21, v33 row_ror:8 row_mask:0xf bank_mask:0xf bound_ctrl:1
	v_mov_b32_dpp v34, v22 row_ror:8 row_mask:0xf bank_mask:0xf bound_ctrl:1
	v_mov_b32_dpp v35, v23 row_ror:8 row_mask:0xf bank_mask:0xf bound_ctrl:1
	v_mov_b32_dpp v36, v18 row_ror:8 row_mask:0xf bank_mask:0xf bound_ctrl:1
	v_mov_b32_dpp v37, v19 row_ror:8 row_mask:0xf bank_mask:0xf bound_ctrl:1
	v_max_f32_e32 v14, 0, v14
	v_max_f32_e32 v10, 0, v10
	v_max_f32_e32 v15, 0, v15
	v_max_f32_e32 v11, 0, v11
	v_max_f32_e32 v16, 0, v16
	v_max_f32_e32 v12, 0, v12
	v_max_f32_e32 v17, 0, v17
	v_max_f32_e32 v13, 0, v13
	v_max_f32_e32 v6, 0, v6
	v_max_f32_e32 v2, 0, v2
	v_max_f32_e32 v7, 0, v7
	v_max_f32_e32 v3, 0, v3
	v_max_f32_e32 v8, 0, v8
	v_max_f32_e32 v4, 0, v4
	v_max_f32_e32 v9, 0, v9
	v_max_f32_e32 v5, 0, v5
	v_lshl_add_u64 v[28:29], v[26:27], 0, v[140:141]
	v_cndmask_b32_e64 v21, v21, v19, s[8:9]
	v_cndmask_b32_e64 v20, v20, v18, s[8:9]
	v_cndmask_b32_e64 v19, v25, v23, s[8:9]
	v_cndmask_b32_e64 v18, v24, v22, s[8:9]
	v_cndmask_b32_e64 v25, v33, v37, s[8:9]
	v_cndmask_b32_e64 v24, v32, v36, s[8:9]
	v_cndmask_b32_e64 v23, v31, v35, s[8:9]
	v_cndmask_b32_e64 v22, v30, v34, s[8:9]
	v_pk_mul_f32 v[14:15], v[14:15], v[14:15]
	v_pk_mul_f32 v[10:11], v[10:11], v[10:11]
	v_pk_mul_f32 v[16:17], v[16:17], v[16:17]
	v_pk_mul_f32 v[12:13], v[12:13], v[12:13]
	v_pk_mul_f32 v[6:7], v[6:7], v[6:7]
	v_pk_mul_f32 v[2:3], v[2:3], v[2:3]
	v_pk_mul_f32 v[8:9], v[8:9], v[8:9]
	v_pk_mul_f32 v[4:5], v[4:5], v[4:5]
	v_lshl_add_u64 v[26:27], v[26:27], 0, v[142:143]
	global_store_dwordx4 v[28:29], v[22:25], off
	global_store_dwordx4 v[26:27], v[18:21], off
	v_cvt_pk_bf16_f32 v14, v14, v15
	v_cvt_pk_bf16_f32 v15, v16, v17
	v_lshl_add_u64 v[18:19], s[22:23], 0, v[158:159]
	v_cvt_pk_bf16_f32 v16, v10, v11
	v_cvt_pk_bf16_f32 v17, v12, v13
	v_cvt_pk_bf16_f32 v6, v6, v7
	v_cvt_pk_bf16_f32 v7, v8, v9
	v_cvt_pk_bf16_f32 v2, v2, v3
	v_cvt_pk_bf16_f32 v3, v4, v5
	v_lshl_add_u64 v[10:11], v[18:19], 0, v[138:139]
	v_mov_b32_dpp v8, v14 row_ror:8 row_mask:0xf bank_mask:0xf bound_ctrl:1
	v_mov_b32_dpp v9, v15 row_ror:8 row_mask:0xf bank_mask:0xf bound_ctrl:1
	v_mov_b32_dpp v4, v16 row_ror:8 row_mask:0xf bank_mask:0xf bound_ctrl:1
	v_mov_b32_dpp v5, v17 row_ror:8 row_mask:0xf bank_mask:0xf bound_ctrl:1
	v_mov_b32_dpp v18, v6 row_ror:8 row_mask:0xf bank_mask:0xf bound_ctrl:1
	v_mov_b32_dpp v19, v7 row_ror:8 row_mask:0xf bank_mask:0xf bound_ctrl:1
	v_mov_b32_dpp v20, v2 row_ror:8 row_mask:0xf bank_mask:0xf bound_ctrl:1
	v_mov_b32_dpp v21, v3 row_ror:8 row_mask:0xf bank_mask:0xf bound_ctrl:1
	v_lshl_add_u64 v[12:13], v[10:11], 0, v[140:141]
	v_cndmask_b32_e64 v5, v5, v3, s[8:9]
	v_cndmask_b32_e64 v4, v4, v2, s[8:9]
	v_cndmask_b32_e64 v3, v9, v7, s[8:9]
	v_cndmask_b32_e64 v2, v8, v6, s[8:9]
	v_cndmask_b32_e64 v9, v17, v21, s[8:9]
	v_cndmask_b32_e64 v8, v16, v20, s[8:9]
	v_cndmask_b32_e64 v7, v15, v19, s[8:9]
	v_cndmask_b32_e64 v6, v14, v18, s[8:9]
	s_and_b64 vcc, exec, s[6:7]
	s_cbranch_vccz .LBB0_1845
	s_barrier

; #define PG8_STAGE(bufoff, gbase, voff) do { _Pragma("unroll") for (int _i = 0; _i < 2; ++_i) \
;         __builtin_amdgcn_global_load_lds((const unsigned*)((const char*)(gbase) + (voff)[_i]), (LAS unsigned*)(lds + (bufoff) + ldsw + _i * 8192), 16, 0, 0); } while (0)
; #define PG8_LDA(dst, b, h) do { _Pragma("unroll") for (int m = 0; m < 4; ++m) _Pragma("unroll") for (int k = 0; k < 2; ++k) dst[m][k] = *(const LAS bf16x8*)(lds + PG8_SA(b, h) + aoff + m * 2048 + k * 1024); } while (0)
; #define PG8_LDB(dst, b, h) do { _Pragma("unroll") for (int n = 0; n < 2; ++n) _Pragma("unroll") for (int k = 0; k < 2; ++k) dst[n][k] = *(const LAS bf16x8*)(lds + PG8_SB(b, h) + boff + n * 2048 + k * 1024); } while (0)
; #define PG8_MMA(ai, bj, At, Bt) do { __builtin_amdgcn_s_setprio(1); _Pragma("unroll") for (int m = 0; m < 4; ++m) _Pragma("unroll") for (int n = 0; n < 2; ++n) _Pragma("unroll") for (int k = 0; k < 2; ++k) \
;         acc[ai][bj][m][n] = __builtin_amdgcn_mfma_f32_16x16x32_bf16(Bt[n][k], At[m][k], acc[ai][bj][m][n], 0, 0, 0); __builtin_amdgcn_s_setprio(0); } while (0)
; #define PG8_WAIT_V(n) asm volatile("s_waitcnt vmcnt(" #n ")" ::: "memory")
; #define PG8_WAIT_L(n) asm volatile("s_waitcnt lgkmcnt(" #n ")" ::: "memory")
; template <class Epi, class Sched, bool ABLK = false, bool ALIGN_EPI = true, bool SP2 = true, bool BBLK = true>
; __device__ __forceinline__ void gemm_phase(LAS unsigned char* lds, const Gemm g, const Sched& S, const Epi& E) {
;     ...
;             const char* a1 = a_tile(uA, tbA + t + 1);
;             const char* a2 = last ? a_tile(nuA, ntbA) : a_tile(uA, tbA + t + 2); const char* b2 = last ? nB : cB + (size_t)(t + 2) * kstepB;
;             const char* a3 = last ? a_tile(nuA, ntbA + 1) : a_tile(uA, tbA + t + 3); const char* b3 = b2 + kstepB;
;             if (last && has_next) S.a_ready(nxt);
;             if constexpr (SP2) {
;             PG8_LDB(B0, 0, 0); PG8_LDB(B1, 0, 1); PG8_SCHED; PG8_LDA(At, 0, 0); PG8_STAGE(PG8_SA(1, 1), a1 + hstepA, voffA);
;             PG8_WAIT_V(8); PG8_WAIT_L(0); PG8_BAR; PG8_MMA(0, 0, At, B0); PG8_MMA(0, 1, At, B1); PG8_BAR; PG8_SCHED;
;             PG8_LDA(At, 0, 1); PG8_STAGE(PG8_SB(0, 0), b2, voffB); PG8_STAGE(PG8_SB(0, 1), b2 + hstepB, voffB); PG8_STAGE(PG8_SA(0, 0), a2, voffA);
;             PG8_WAIT_V(8); PG8_WAIT_L(0); PG8_BAR; PG8_MMA(1, 0, At, B0); PG8_MMA(1, 1, At, B1); PG8_BAR; PG8_SCHED;
.LBB0_1907:
	ds_read_b128 v[152:155], v148
	ds_read_b128 v[156:159], v148 offset:1024
	ds_read_b128 v[160:163], v148 offset:2048
	ds_read_b128 v[164:167], v148 offset:3072
	ds_read_b128 v[168:171], v149
	ds_read_b128 v[172:175], v149 offset:1024
	ds_read_b128 v[176:179], v149 offset:2048
	ds_read_b128 v[180:183], v149 offset:3072
	s_add_u32 s34, s55, s30
	s_addc_u32 s35, s56, s31
	s_add_u32 s38, s34, 0x10000
	s_addc_u32 s39, s35, 0
	s_add_i32 s58, s58, 2
	s_add_u32 s36, s53, s30
	s_addc_u32 s37, s54, s31
	s_add_u32 s34, s34, 0x18000
	s_addc_u32 s35, s35, 0
	s_cmp_eq_u32 s57, s30
	s_cselect_b32 s35, s52, s35
	s_cselect_b32 s34, s51, s34
	s_cselect_b32 s37, s4, s37
	s_cselect_b32 s36, s5, s36
	s_cselect_b32 s39, s50, s39
	s_cselect_b32 s38, s27, s38
	v_lshl_add_u64 v[216:217], v[142:143], 0, s[30:31]
	s_add_i32 m0, s41, 0xc000
	ds_read_b128 v[184:187], v150
	ds_read_b128 v[188:191], v150 offset:1024
	ds_read_b128 v[192:195], v150 offset:2048
	ds_read_b128 v[196:199], v150 offset:3072
	ds_read_b128 v[200:203], v150 offset:4096
	ds_read_b128 v[204:207], v150 offset:5120
	ds_read_b128 v[208:211], v150 offset:6144
	ds_read_b128 v[212:215], v150 offset:7168
	global_load_lds_dwordx4 v[216:217], off
	v_lshl_add_u64 v[216:217], v[144:145], 0, s[30:31]
	s_add_i32 m0, s41, 0xe000
	s_nop 0
	global_load_lds_dwordx4 v[216:217], off
	s_waitcnt vmcnt(8) lgkmcnt(0)
	s_barrier
	v_mfma_f32_16x16x32_bf16 v[126:129], v[152:155], v[184:187], v[126:129]
	v_mfma_f32_16x16x32_bf16 v[122:125], v[160:163], v[184:187], v[122:125]
	v_mfma_f32_16x16x32_bf16 v[110:113], v[152:155], v[192:195], v[110:113]
	v_mfma_f32_16x16x32_bf16 v[106:109], v[160:163], v[192:195], v[106:109]
	v_mfma_f32_16x16x32_bf16 v[94:97], v[152:155], v[200:203], v[94:97]
	v_mfma_f32_16x16x32_bf16 v[90:93], v[160:163], v[200:203], v[90:93]
	v_mfma_f32_16x16x32_bf16 v[78:81], v[152:155], v[208:211], v[78:81]
	v_mfma_f32_16x16x32_bf16 v[74:77], v[160:163], v[208:211], v[74:77]
	v_mfma_f32_16x16x32_bf16 v[126:129], v[156:159], v[188:191], v[126:129]
	v_mfma_f32_16x16x32_bf16 v[122:125], v[164:167], v[188:191], v[122:125]
	v_mfma_f32_16x16x32_bf16 v[110:113], v[156:159], v[196:199], v[110:113]
	v_mfma_f32_16x16x32_bf16 v[106:109], v[164:167], v[196:199], v[106:109]
	v_mfma_f32_16x16x32_bf16 v[94:97], v[156:159], v[204:207], v[94:97]
	v_mfma_f32_16x16x32_bf16 v[90:93], v[164:167], v[204:207], v[90:93]
	v_mfma_f32_16x16x32_bf16 v[78:81], v[156:159], v[212:215], v[78:81]
	v_mfma_f32_16x16x32_bf16 v[74:77], v[164:167], v[212:215], v[74:77]
	v_mfma_f32_16x16x32_bf16 v[118:121], v[168:171], v[184:187], v[118:121]
	v_mfma_f32_16x16x32_bf16 v[114:117], v[176:179], v[184:187], v[114:117]
	v_mfma_f32_16x16x32_bf16 v[102:105], v[168:171], v[192:195], v[102:105]
	v_mfma_f32_16x16x32_bf16 v[98:101], v[176:179], v[192:195], v[98:101]
	v_mfma_f32_16x16x32_bf16 v[86:89], v[168:171], v[200:203], v[86:89]
	v_mfma_f32_16x16x32_bf16 v[82:85], v[176:179], v[200:203], v[82:85]
	v_mfma_f32_16x16x32_bf16 v[70:73], v[168:171], v[208:211], v[70:73]
	v_mfma_f32_16x16x32_bf16 v[66:69], v[176:179], v[208:211], v[66:69]
	v_mfma_f32_16x16x32_bf16 v[118:121], v[172:175], v[188:191], v[118:121]
	v_mfma_f32_16x16x32_bf16 v[114:117], v[180:183], v[188:191], v[114:117]
	v_mfma_f32_16x16x32_bf16 v[102:105], v[172:175], v[196:199], v[102:105]
	v_mfma_f32_16x16x32_bf16 v[98:101], v[180:183], v[196:199], v[98:101]
	v_mfma_f32_16x16x32_bf16 v[86:89], v[172:175], v[204:207], v[86:89]
	v_mfma_f32_16x16x32_bf16 v[82:85], v[180:183], v[204:207], v[82:85]
	v_mfma_f32_16x16x32_bf16 v[70:73], v[172:175], v[212:215], v[70:73]
	v_mfma_f32_16x16x32_bf16 v[66:69], v[180:183], v[212:215], v[66:69]
	s_barrier
	s_add_i32 s59, s72, s40
	s_mov_b32 m0, s59
	ds_read_b128 v[184:187], v150 offset:16384
	ds_read_b128 v[188:191], v150 offset:17408
	ds_read_b128 v[192:195], v150 offset:18432
	ds_read_b128 v[196:199], v150 offset:19456
	ds_read_b128 v[200:203], v150 offset:20480
	ds_read_b128 v[204:207], v150 offset:21504
	ds_read_b128 v[208:211], v150 offset:22528
	ds_read_b128 v[212:215], v150 offset:23552
	global_load_lds_dwordx4 v130, s[36:37]
	s_add_i32 m0, s59, 0x2000
	s_add_u32 s64, s36, 0x4000
	s_addc_u32 s65, s37, 0
	s_add_i32 s59, s73, s40
	global_load_lds_dwordx4 v132, s[36:37]
	s_mov_b32 m0, s59
	s_nop 0
	global_load_lds_dwordx4 v130, s[64:65]
	s_add_i32 m0, s59, 0x2000
	s_nop 0
	global_load_lds_dwordx4 v132, s[64:65]
	s_mov_b32 m0, s41
	s_nop 0
	global_load_lds_dwordx4 v130, s[38:39]
	s_mov_b32 m0, s42
	s_nop 0
	global_load_lds_dwordx4 v132, s[38:39]
	s_waitcnt vmcnt(8) lgkmcnt(0)
	s_barrier
; #define PG8_STAGE(bufoff, gbase, voff) do { _Pragma("unroll") for (int _i = 0; _i < 2; ++_i) \
;         __builtin_amdgcn_global_load_lds((const unsigned*)((const char*)(gbase) + (voff)[_i]), (LAS unsigned*)(lds + (bufoff) + ldsw + _i * 8192), 16, 0, 0); } while (0)
; #define PG8_LDA(dst, b, h) do { _Pragma("unroll") for (int m = 0; m < 4; ++m) _Pragma("unroll") for (int k = 0; k < 2; ++k) dst[m][k] = *(const LAS bf16x8*)(lds + PG8_SA(b, h) + aoff + m * 2048 + k * 1024); } while (0)
; #define PG8_LDB(dst, b, h) do { _Pragma("unroll") for (int n = 0; n < 2; ++n) _Pragma("unroll") for (int k = 0; k < 2; ++k) dst[n][k] = *(const LAS bf16x8*)(lds + PG8_SB(b, h) + boff + n * 2048 + k * 1024); } while (0)
; #define PG8_MMA(ai, bj, At, Bt) do { __builtin_amdgcn_s_setprio(1); _Pragma("unroll") for (int m = 0; m < 4; ++m) _Pragma("unroll") for (int n = 0; n < 2; ++n) _Pragma("unroll") for (int k = 0; k < 2; ++k) \
;         acc[ai][bj][m][n] = __builtin_amdgcn_mfma_f32_16x16x32_bf16(Bt[n][k], At[m][k], acc[ai][bj][m][n], 0, 0, 0); __builtin_amdgcn_s_setprio(0); } while (0)
; #define PG8_WAIT_V(n) asm volatile("s_waitcnt vmcnt(" #n ")" ::: "memory")
; #define PG8_WAIT_L(n) asm volatile("s_waitcnt lgkmcnt(" #n ")" ::: "memory")
; #define PG8_BAR __builtin_amdgcn_s_barrier()
; #define PG8_SCHED __builtin_amdgcn_sched_barrier(0)
; template <class Epi, class Sched, bool ABLK = false, bool ALIGN_EPI = true, bool SP2 = true, bool BBLK = true>
; __device__ __forceinline__ void gemm_phase(LAS unsigned char* lds, const Gemm g, const Sched& S, const Epi& E) {
;     ...
;             PG8_WAIT_V(8); PG8_WAIT_L(0); PG8_BAR; PG8_MMA(1, 0, At, B0); PG8_MMA(1, 1, At, B1); PG8_BAR; PG8_SCHED;
;             PG8_LDB(B0, 1, 0); PG8_LDB(B1, 1, 1); PG8_SCHED; PG8_LDA(At, 1, 0); PG8_STAGE(PG8_SA(0, 1), a2 + hstepA, voffA);
;             PG8_WAIT_V(8); PG8_WAIT_L(0); PG8_BAR; PG8_MMA(0, 0, At, B0); PG8_MMA(0, 1, At, B1); PG8_BAR; PG8_SCHED;
	v_mfma_f32_16x16x32_bf16 v[62:65], v[152:155], v[184:187], v[62:65]
	v_mfma_f32_16x16x32_bf16 v[58:61], v[160:163], v[184:187], v[58:61]
	v_mfma_f32_16x16x32_bf16 v[46:49], v[152:155], v[192:195], v[46:49]
	v_mfma_f32_16x16x32_bf16 v[42:45], v[160:163], v[192:195], v[42:45]
	v_mfma_f32_16x16x32_bf16 v[30:33], v[152:155], v[200:203], v[30:33]
	v_mfma_f32_16x16x32_bf16 v[26:29], v[160:163], v[200:203], v[26:29]
	v_mfma_f32_16x16x32_bf16 v[14:17], v[152:155], v[208:211], v[14:17]
	v_mfma_f32_16x16x32_bf16 v[10:13], v[160:163], v[208:211], v[10:13]
	v_mfma_f32_16x16x32_bf16 v[62:65], v[156:159], v[188:191], v[62:65]
	v_mfma_f32_16x16x32_bf16 v[58:61], v[164:167], v[188:191], v[58:61]
	v_mfma_f32_16x16x32_bf16 v[46:49], v[156:159], v[196:199], v[46:49]
	v_mfma_f32_16x16x32_bf16 v[42:45], v[164:167], v[196:199], v[42:45]
	v_mfma_f32_16x16x32_bf16 v[30:33], v[156:159], v[204:207], v[30:33]
	v_mfma_f32_16x16x32_bf16 v[26:29], v[164:167], v[204:207], v[26:29]
	v_mfma_f32_16x16x32_bf16 v[14:17], v[156:159], v[212:215], v[14:17]
	v_mfma_f32_16x16x32_bf16 v[10:13], v[164:167], v[212:215], v[10:13]
	v_mfma_f32_16x16x32_bf16 v[54:57], v[168:171], v[184:187], v[54:57]
	v_mfma_f32_16x16x32_bf16 v[50:53], v[176:179], v[184:187], v[50:53]
	v_mfma_f32_16x16x32_bf16 v[38:41], v[168:171], v[192:195], v[38:41]
	v_mfma_f32_16x16x32_bf16 v[34:37], v[176:179], v[192:195], v[34:37]
	v_mfma_f32_16x16x32_bf16 v[22:25], v[168:171], v[200:203], v[22:25]
	v_mfma_f32_16x16x32_bf16 v[18:21], v[176:179], v[200:203], v[18:21]
	v_mfma_f32_16x16x32_bf16 v[6:9], v[168:171], v[208:211], v[6:9]
	v_mfma_f32_16x16x32_bf16 v[2:5], v[176:179], v[208:211], v[2:5]
	v_mfma_f32_16x16x32_bf16 v[54:57], v[172:175], v[188:191], v[54:57]
	v_mfma_f32_16x16x32_bf16 v[50:53], v[180:183], v[188:191], v[50:53]
	v_mfma_f32_16x16x32_bf16 v[38:41], v[172:175], v[196:199], v[38:41]
	v_mfma_f32_16x16x32_bf16 v[34:37], v[180:183], v[196:199], v[34:37]
	v_mfma_f32_16x16x32_bf16 v[22:25], v[172:175], v[204:207], v[22:25]
	v_mfma_f32_16x16x32_bf16 v[18:21], v[180:183], v[204:207], v[18:21]
	v_mfma_f32_16x16x32_bf16 v[6:9], v[172:175], v[212:215], v[6:9]
	v_mfma_f32_16x16x32_bf16 v[2:5], v[180:183], v[212:215], v[2:5]
	s_barrier
	v_add_u32_e32 v151, s60, v146
	ds_read_b128 v[152:155], v151
	ds_read_b128 v[156:159], v151 offset:1024
	ds_read_b128 v[160:163], v151 offset:2048
	ds_read_b128 v[164:167], v151 offset:3072
	v_add_u32_e32 v151, s61, v146
	ds_read_b128 v[168:171], v151
	ds_read_b128 v[172:175], v151 offset:1024
	ds_read_b128 v[176:179], v151 offset:2048
	ds_read_b128 v[180:183], v151 offset:3072
	s_add_u32 s38, s38, 0x4000
	s_addc_u32 s39, s39, 0
	s_mov_b32 m0, s43
	ds_read_b128 v[184:187], v150 offset:32768
	ds_read_b128 v[188:191], v150 offset:33792
	ds_read_b128 v[192:195], v150 offset:34816
	ds_read_b128 v[196:199], v150 offset:35840
	ds_read_b128 v[200:203], v150 offset:36864
	ds_read_b128 v[204:207], v150 offset:37888
	ds_read_b128 v[208:211], v150 offset:38912
	ds_read_b128 v[212:215], v150 offset:39936
	global_load_lds_dwordx4 v130, s[38:39]
	s_mov_b32 m0, s44
	s_nop 0
	global_load_lds_dwordx4 v132, s[38:39]
	s_waitcnt vmcnt(8) lgkmcnt(0)
	s_barrier
	v_mfma_f32_16x16x32_bf16 v[126:129], v[152:155], v[184:187], v[126:129]
	v_mfma_f32_16x16x32_bf16 v[122:125], v[160:163], v[184:187], v[122:125]
	v_mfma_f32_16x16x32_bf16 v[110:113], v[152:155], v[192:195], v[110:113]
	v_mfma_f32_16x16x32_bf16 v[106:109], v[160:163], v[192:195], v[106:109]
	v_mfma_f32_16x16x32_bf16 v[94:97], v[152:155], v[200:203], v[94:97]
	v_mfma_f32_16x16x32_bf16 v[90:93], v[160:163], v[200:203], v[90:93]
	v_mfma_f32_16x16x32_bf16 v[78:81], v[152:155], v[208:211], v[78:81]
	v_mfma_f32_16x16x32_bf16 v[74:77], v[160:163], v[208:211], v[74:77]
	v_mfma_f32_16x16x32_bf16 v[126:129], v[156:159], v[188:191], v[126:129]
	v_mfma_f32_16x16x32_bf16 v[122:125], v[164:167], v[188:191], v[122:125]
	v_mfma_f32_16x16x32_bf16 v[110:113], v[156:159], v[196:199], v[110:113]
	v_mfma_f32_16x16x32_bf16 v[106:109], v[164:167], v[196:199], v[106:109]
	v_mfma_f32_16x16x32_bf16 v[94:97], v[156:159], v[204:207], v[94:97]
	v_mfma_f32_16x16x32_bf16 v[90:93], v[164:167], v[204:207], v[90:93]
	v_mfma_f32_16x16x32_bf16 v[78:81], v[156:159], v[212:215], v[78:81]
	v_mfma_f32_16x16x32_bf16 v[74:77], v[164:167], v[212:215], v[74:77]
	v_mfma_f32_16x16x32_bf16 v[118:121], v[168:171], v[184:187], v[118:121]
	v_mfma_f32_16x16x32_bf16 v[114:117], v[176:179], v[184:187], v[114:117]
	v_mfma_f32_16x16x32_bf16 v[102:105], v[168:171], v[192:195], v[102:105]
	v_mfma_f32_16x16x32_bf16 v[98:101], v[176:179], v[192:195], v[98:101]
	v_mfma_f32_16x16x32_bf16 v[86:89], v[168:171], v[200:203], v[86:89]
	v_mfma_f32_16x16x32_bf16 v[82:85], v[176:179], v[200:203], v[82:85]
	v_mfma_f32_16x16x32_bf16 v[70:73], v[168:171], v[208:211], v[70:73]
	v_mfma_f32_16x16x32_bf16 v[66:69], v[176:179], v[208:211], v[66:69]
	v_mfma_f32_16x16x32_bf16 v[118:121], v[172:175], v[188:191], v[118:121]
	v_mfma_f32_16x16x32_bf16 v[114:117], v[180:183], v[188:191], v[114:117]
	v_mfma_f32_16x16x32_bf16 v[102:105], v[172:175], v[196:199], v[102:105]
	v_mfma_f32_16x16x32_bf16 v[98:101], v[180:183], v[196:199], v[98:101]
	v_mfma_f32_16x16x32_bf16 v[86:89], v[172:175], v[204:207], v[86:89]
	v_mfma_f32_16x16x32_bf16 v[82:85], v[180:183], v[204:207], v[82:85]
	v_mfma_f32_16x16x32_bf16 v[70:73], v[172:175], v[212:215], v[70:73]
	v_mfma_f32_16x16x32_bf16 v[66:69], v[180:183], v[212:215], v[66:69]
	s_barrier
; __device__ __forceinline__ unsigned pk2(float lo, float hi) { const f32x2 v = {lo, hi}; return __builtin_bit_cast(unsigned, __builtin_convertvector(v, bf16x2_t)); }
; #define PG8_STAGE(bufoff, gbase, voff) do { _Pragma("unroll") for (int _i = 0; _i < 2; ++_i) \
;         __builtin_amdgcn_global_load_lds((const unsigned*)((const char*)(gbase) + (voff)[_i]), (LAS unsigned*)(lds + (bufoff) + ldsw + _i * 8192), 16, 0, 0); } while (0)
; #define PG8_LDA(dst, b, h) do { _Pragma("unroll") for (int m = 0; m < 4; ++m) _Pragma("unroll") for (int k = 0; k < 2; ++k) dst[m][k] = *(const LAS bf16x8*)(lds + PG8_SA(b, h) + aoff + m * 2048 + k * 1024); } while (0)
; #define PG8_MMA(ai, bj, At, Bt) do { __builtin_amdgcn_s_setprio(1); _Pragma("unroll") for (int m = 0; m < 4; ++m) _Pragma("unroll") for (int n = 0; n < 2; ++n) _Pragma("unroll") for (int k = 0; k < 2; ++k) \
;         acc[ai][bj][m][n] = __builtin_amdgcn_mfma_f32_16x16x32_bf16(Bt[n][k], At[m][k], acc[ai][bj][m][n], 0, 0, 0); __builtin_amdgcn_s_setprio(0); } while (0)
; template <class Epi, class Sched, bool ABLK = false, bool ALIGN_EPI = true, bool SP2 = true, bool BBLK = true>
; __device__ __forceinline__ void gemm_phase(LAS unsigned char* lds, const Gemm g, const Sched& S, const Epi& E) {
;     ...
;             PG8_LDA(At, 1, 1); PG8_STAGE(PG8_SB(1, 0), b3, voffB); PG8_STAGE(PG8_SB(1, 1), b3 + hstepB, voffB); PG8_STAGE(PG8_SA(1, 0), a3, voffA);
;             PG8_WAIT_V(8); PG8_WAIT_L(0); PG8_BAR; PG8_MMA(1, 0, At, B0); PG8_MMA(1, 1, At, B1); PG8_BAR; PG8_SCHED;
;     __device__ __forceinline__ void operator()(const f32x4 (&acc)[2][2][4][2], const Unit& u, int wr, int wc, int fr, int fq) const {
;         const int row0 = u.pm * 256 + wr * 64 + fr, col0 = u.pn * 256 + wc * 64 + 8 * fq;
;         bf16_t* base = u.part == 0 ? Z + (size_t)row0 * D + col0 : P + ((size_t)(u.part - 1) * MS + (row0 - MP)) * D + col0;
; #pragma unroll
;         for (int ai = 0; ai < 2; ++ai)
; #pragma unroll
;             for (int m = 0; m < 4; ++m) { u32x4 w[2];
; #pragma unroll
;                 for (int bj = 0; bj < 2; ++bj) { const f32x4 v0 = acc[ai][bj][m][0], v1 = acc[ai][bj][m][1]; w[bj].x = pk2(v0[0], v0[1]); w[bj].y = pk2(v0[2], v0[3]); w[bj].z = pk2(v1[0], v1[1]); w[bj].w = pk2(v1[2], v1[3]); }
;                 store_pair((unsigned char*)(base + (size_t)(ai * 128 + m * 16) * D), (size_t)8 * D * 2, 64, w[0], w[1], fr >= 8); }
	s_add_u32 s38, s36, 0x8000
	s_addc_u32 s39, s37, 0
	s_add_i32 s59, s60, s40
	s_mov_b32 m0, s59
	ds_read_b128 v[184:187], v150 offset:49152
	ds_read_b128 v[188:191], v150 offset:50176
	ds_read_b128 v[192:195], v150 offset:51200
	ds_read_b128 v[196:199], v150 offset:52224
	ds_read_b128 v[200:203], v150 offset:53248
	ds_read_b128 v[204:207], v150 offset:54272
	ds_read_b128 v[208:211], v150 offset:55296
	ds_read_b128 v[212:215], v150 offset:56320
	global_load_lds_dwordx4 v130, s[38:39]
	s_add_i32 m0, s59, 0x2000
	s_add_u32 s36, s36, 0xc000
	v_lshl_add_u64 v[216:217], s[38:39], 0, v[132:133]
	s_addc_u32 s37, s37, 0
	s_add_i32 s38, s61, s40
	global_load_lds_dwordx4 v[216:217], off
	s_mov_b32 m0, s38
	s_nop 0
	global_load_lds_dwordx4 v130, s[36:37]
	s_add_i32 m0, s38, 0x2000
	s_nop 0
	global_load_lds_dwordx4 v132, s[36:37]
	s_mov_b32 m0, s45
	s_nop 0
	global_load_lds_dwordx4 v130, s[34:35]
	s_mov_b32 m0, s46
	s_nop 0
	global_load_lds_dwordx4 v132, s[34:35]
	s_waitcnt vmcnt(8) lgkmcnt(0)
	s_barrier
	v_mfma_f32_16x16x32_bf16 v[62:65], v[152:155], v[184:187], v[62:65]
	v_mfma_f32_16x16x32_bf16 v[58:61], v[160:163], v[184:187], v[58:61]
	v_mfma_f32_16x16x32_bf16 v[46:49], v[152:155], v[192:195], v[46:49]
	v_mfma_f32_16x16x32_bf16 v[42:45], v[160:163], v[192:195], v[42:45]
	v_mfma_f32_16x16x32_bf16 v[30:33], v[152:155], v[200:203], v[30:33]
	v_mfma_f32_16x16x32_bf16 v[26:29], v[160:163], v[200:203], v[26:29]
	v_mfma_f32_16x16x32_bf16 v[14:17], v[152:155], v[208:211], v[14:17]
	v_mfma_f32_16x16x32_bf16 v[10:13], v[160:163], v[208:211], v[10:13]
	v_mfma_f32_16x16x32_bf16 v[62:65], v[156:159], v[188:191], v[62:65]
	v_mfma_f32_16x16x32_bf16 v[58:61], v[164:167], v[188:191], v[58:61]
	v_mfma_f32_16x16x32_bf16 v[46:49], v[156:159], v[196:199], v[46:49]
	v_mfma_f32_16x16x32_bf16 v[42:45], v[164:167], v[196:199], v[42:45]
	v_mfma_f32_16x16x32_bf16 v[30:33], v[156:159], v[204:207], v[30:33]
	v_mfma_f32_16x16x32_bf16 v[26:29], v[164:167], v[204:207], v[26:29]
	v_mfma_f32_16x16x32_bf16 v[14:17], v[156:159], v[212:215], v[14:17]
	v_mfma_f32_16x16x32_bf16 v[10:13], v[164:167], v[212:215], v[10:13]
	v_mfma_f32_16x16x32_bf16 v[54:57], v[168:171], v[184:187], v[54:57]
	v_mfma_f32_16x16x32_bf16 v[50:53], v[176:179], v[184:187], v[50:53]
	v_mfma_f32_16x16x32_bf16 v[38:41], v[168:171], v[192:195], v[38:41]
	v_mfma_f32_16x16x32_bf16 v[34:37], v[176:179], v[192:195], v[34:37]
	v_mfma_f32_16x16x32_bf16 v[22:25], v[168:171], v[200:203], v[22:25]
	v_mfma_f32_16x16x32_bf16 v[18:21], v[176:179], v[200:203], v[18:21]
	v_mfma_f32_16x16x32_bf16 v[6:9], v[168:171], v[208:211], v[6:9]
	v_mfma_f32_16x16x32_bf16 v[2:5], v[176:179], v[208:211], v[2:5]
	v_mfma_f32_16x16x32_bf16 v[54:57], v[172:175], v[188:191], v[54:57]
	v_mfma_f32_16x16x32_bf16 v[50:53], v[180:183], v[188:191], v[50:53]
	v_mfma_f32_16x16x32_bf16 v[38:41], v[172:175], v[196:199], v[38:41]
	v_mfma_f32_16x16x32_bf16 v[34:37], v[180:183], v[196:199], v[34:37]
	v_mfma_f32_16x16x32_bf16 v[22:25], v[172:175], v[204:207], v[22:25]
	v_mfma_f32_16x16x32_bf16 v[18:21], v[180:183], v[204:207], v[18:21]
	v_mfma_f32_16x16x32_bf16 v[6:9], v[172:175], v[212:215], v[6:9]
	v_mfma_f32_16x16x32_bf16 v[2:5], v[180:183], v[212:215], v[2:5]
	s_barrier
	s_add_u32 s30, s30, 0x10000
	s_addc_u32 s31, s31, 0
	s_cmp_ge_u32 s58, s48
	s_cbranch_scc0 .LBB0_1907
	v_lshl_add_u32 v143, s49, 8, v1
	v_add_u32_e32 v144, 0xffffe000, v143
	v_sub_co_u32_e64 v142, vcc, s47, 1
	v_mov_b32_e32 v145, s91
	s_nop 0
	v_cndmask_b32_e32 v144, v144, v143, vcc
	v_ashrrev_i32_e32 v143, 31, v142
	v_lshlrev_b64 v[142:143], 23, v[142:143]
	v_lshl_add_u64 v[142:143], s[12:13], 0, v[142:143]
	v_cndmask_b32_e32 v143, v143, v145, vcc
	v_mov_b32_e32 v145, s90
	v_cndmask_b32_e32 v142, v142, v145, vcc
	v_ashrrev_i32_e32 v145, 31, v144
	v_lshl_or_b32 v152, s78, 8, v147
	v_lshlrev_b64 v[144:145], 12, v[144:145]
	v_lshl_add_u64 v[142:143], v[142:143], 0, v[144:145]
	v_ashrrev_i32_e32 v153, 31, v152
	v_cvt_pk_bf16_f32 v126, v126, v127
	v_cvt_pk_bf16_f32 v127, v128, v129
	v_cvt_pk_bf16_f32 v128, v122, v123
	v_cvt_pk_bf16_f32 v124, v124, v125
	v_cvt_pk_bf16_f32 v118, v118, v119
	v_cvt_pk_bf16_f32 v119, v120, v121
	v_cvt_pk_bf16_f32 v114, v114, v115
	v_cvt_pk_bf16_f32 v115, v116, v117
	v_lshl_add_u64 v[142:143], v[152:153], 1, v[142:143]
	v_mov_b32_dpp v120, v126 row_ror:8 row_mask:0xf bank_mask:0xf bound_ctrl:1
	v_mov_b32_dpp v121, v127 row_ror:8 row_mask:0xf bank_mask:0xf bound_ctrl:1
	v_mov_b32_dpp v116, v128 row_ror:8 row_mask:0xf bank_mask:0xf bound_ctrl:1
	v_mov_b32_dpp v117, v124 row_ror:8 row_mask:0xf bank_mask:0xf bound_ctrl:1
	v_mov_b32_dpp v125, v118 row_ror:8 row_mask:0xf bank_mask:0xf bound_ctrl:1
	v_mov_b32_dpp v129, v119 row_ror:8 row_mask:0xf bank_mask:0xf bound_ctrl:1
	v_mov_b32_dpp v144, v114 row_ror:8 row_mask:0xf bank_mask:0xf bound_ctrl:1
	v_mov_b32_dpp v145, v115 row_ror:8 row_mask:0xf bank_mask:0xf bound_ctrl:1
	v_lshl_add_u64 v[122:123], v[142:143], 0, v[134:135]
	v_cndmask_b32_e64 v117, v117, v115, s[8:9]
	v_cndmask_b32_e64 v116, v116, v114, s[8:9]
	v_cndmask_b32_e64 v115, v121, v119, s[8:9]
	v_cndmask_b32_e64 v114, v120, v118, s[8:9]
	v_cndmask_b32_e64 v121, v124, v145, s[8:9]
	v_cndmask_b32_e64 v120, v128, v144, s[8:9]
	v_cndmask_b32_e64 v119, v127, v129, s[8:9]
	v_cndmask_b32_e64 v118, v126, v125, s[8:9]
	v_cvt_pk_bf16_f32 v110, v110, v111
	v_cvt_pk_bf16_f32 v111, v112, v113
	v_cvt_pk_bf16_f32 v112, v106, v107
	v_cvt_pk_bf16_f32 v113, v108, v109
	v_cvt_pk_bf16_f32 v102, v102, v103
	v_cvt_pk_bf16_f32 v103, v104, v105
	v_cvt_pk_bf16_f32 v98, v98, v99
	v_cvt_pk_bf16_f32 v99, v100, v101
	s_mov_b64 s[4:5], 0x10000
	v_lshl_add_u64 v[124:125], v[142:143], 0, v[136:137]
; __device__ __forceinline__ unsigned pk2(float lo, float hi) { const f32x2 v = {lo, hi}; return __builtin_bit_cast(unsigned, __builtin_convertvector(v, bf16x2_t)); }
; #define PG8_BAR __builtin_amdgcn_s_barrier()
; template <class Epi, class Sched, bool ABLK = false, bool ALIGN_EPI = true, bool SP2 = true, bool BBLK = true>
; __device__ __forceinline__ void gemm_phase(LAS unsigned char* lds, const Gemm g, const Sched& S, const Epi& E) {
;     ...
;         if constexpr (ALIGN_EPI) { if (wr == 0) PG8_BAR; }
;     __device__ __forceinline__ void operator()(const f32x4 (&acc)[2][2][4][2], const Unit& u, int wr, int wc, int fr, int fq) const {
;     ...
;         for (int ai = 0; ai < 2; ++ai)
; #pragma unroll
;             for (int m = 0; m < 4; ++m) { u32x4 w[2];
; #pragma unroll
;                 for (int bj = 0; bj < 2; ++bj) { const f32x4 v0 = acc[ai][bj][m][0], v1 = acc[ai][bj][m][1]; w[bj].x = pk2(v0[0], v0[1]); w[bj].y = pk2(v0[2], v0[3]); w[bj].z = pk2(v1[0], v1[1]); w[bj].w = pk2(v1[2], v1[3]); }
;                 store_pair((unsigned char*)(base + (size_t)(ai * 128 + m * 16) * D), (size_t)8 * D * 2, 64, w[0], w[1], fr >= 8); }
	global_store_dwordx4 v[122:123], v[118:121], off
	global_store_dwordx4 v[124:125], v[114:117], off
	v_lshl_add_u64 v[106:107], v[142:143], 0, s[4:5]
	v_mov_b32_dpp v104, v110 row_ror:8 row_mask:0xf bank_mask:0xf bound_ctrl:1
	v_mov_b32_dpp v105, v111 row_ror:8 row_mask:0xf bank_mask:0xf bound_ctrl:1
	v_mov_b32_dpp v100, v112 row_ror:8 row_mask:0xf bank_mask:0xf bound_ctrl:1
	v_mov_b32_dpp v101, v113 row_ror:8 row_mask:0xf bank_mask:0xf bound_ctrl:1
	v_mov_b32_dpp v114, v102 row_ror:8 row_mask:0xf bank_mask:0xf bound_ctrl:1
	v_mov_b32_dpp v115, v103 row_ror:8 row_mask:0xf bank_mask:0xf bound_ctrl:1
	v_mov_b32_dpp v116, v98 row_ror:8 row_mask:0xf bank_mask:0xf bound_ctrl:1
	v_mov_b32_dpp v117, v99 row_ror:8 row_mask:0xf bank_mask:0xf bound_ctrl:1
	v_lshl_add_u64 v[108:109], v[106:107], 0, v[134:135]
	v_cndmask_b32_e64 v101, v101, v99, s[8:9]
	v_cndmask_b32_e64 v100, v100, v98, s[8:9]
	v_cndmask_b32_e64 v99, v105, v103, s[8:9]
	v_cndmask_b32_e64 v98, v104, v102, s[8:9]
	v_cndmask_b32_e64 v105, v113, v117, s[8:9]
	v_cndmask_b32_e64 v104, v112, v116, s[8:9]
	v_cndmask_b32_e64 v103, v111, v115, s[8:9]
	v_cndmask_b32_e64 v102, v110, v114, s[8:9]
	v_cvt_pk_bf16_f32 v94, v94, v95
	v_cvt_pk_bf16_f32 v95, v96, v97
	v_cvt_pk_bf16_f32 v96, v90, v91
	v_cvt_pk_bf16_f32 v97, v92, v93
	v_cvt_pk_bf16_f32 v86, v86, v87
	v_cvt_pk_bf16_f32 v87, v88, v89
	v_cvt_pk_bf16_f32 v82, v82, v83
	v_cvt_pk_bf16_f32 v83, v84, v85
	s_mov_b64 s[4:5], 0x20000
	v_lshl_add_u64 v[106:107], v[106:107], 0, v[136:137]
	global_store_dwordx4 v[108:109], v[102:105], off
	global_store_dwordx4 v[106:107], v[98:101], off
	v_lshl_add_u64 v[90:91], v[142:143], 0, s[4:5]
	v_mov_b32_dpp v88, v94 row_ror:8 row_mask:0xf bank_mask:0xf bound_ctrl:1
	v_mov_b32_dpp v89, v95 row_ror:8 row_mask:0xf bank_mask:0xf bound_ctrl:1
	v_mov_b32_dpp v84, v96 row_ror:8 row_mask:0xf bank_mask:0xf bound_ctrl:1
	v_mov_b32_dpp v85, v97 row_ror:8 row_mask:0xf bank_mask:0xf bound_ctrl:1
	v_mov_b32_dpp v98, v86 row_ror:8 row_mask:0xf bank_mask:0xf bound_ctrl:1
	v_mov_b32_dpp v99, v87 row_ror:8 row_mask:0xf bank_mask:0xf bound_ctrl:1
	v_mov_b32_dpp v100, v82 row_ror:8 row_mask:0xf bank_mask:0xf bound_ctrl:1
	v_mov_b32_dpp v101, v83 row_ror:8 row_mask:0xf bank_mask:0xf bound_ctrl:1
	v_lshl_add_u64 v[92:93], v[90:91], 0, v[134:135]
	v_cndmask_b32_e64 v85, v85, v83, s[8:9]
	v_cndmask_b32_e64 v84, v84, v82, s[8:9]
	v_cndmask_b32_e64 v83, v89, v87, s[8:9]
	v_cndmask_b32_e64 v82, v88, v86, s[8:9]
	v_cndmask_b32_e64 v89, v97, v101, s[8:9]
	v_cndmask_b32_e64 v88, v96, v100, s[8:9]
	v_cndmask_b32_e64 v87, v95, v99, s[8:9]
	v_cndmask_b32_e64 v86, v94, v98, s[8:9]
	v_cvt_pk_bf16_f32 v78, v78, v79
	v_cvt_pk_bf16_f32 v79, v80, v81
	v_cvt_pk_bf16_f32 v80, v74, v75
	v_cvt_pk_bf16_f32 v81, v76, v77
	v_cvt_pk_bf16_f32 v70, v70, v71
	v_cvt_pk_bf16_f32 v71, v72, v73
	v_cvt_pk_bf16_f32 v66, v66, v67
	v_cvt_pk_bf16_f32 v67, v68, v69
	v_lshl_add_u64 v[90:91], v[90:91], 0, v[136:137]
	global_store_dwordx4 v[92:93], v[86:89], off
	global_store_dwordx4 v[90:91], v[82:85], off
	v_lshl_add_u64 v[74:75], v[142:143], 0, s[14:15]
	v_mov_b32_dpp v72, v78 row_ror:8 row_mask:0xf bank_mask:0xf bound_ctrl:1
	v_mov_b32_dpp v73, v79 row_ror:8 row_mask:0xf bank_mask:0xf bound_ctrl:1
	v_mov_b32_dpp v68, v80 row_ror:8 row_mask:0xf bank_mask:0xf bound_ctrl:1
	v_mov_b32_dpp v69, v81 row_ror:8 row_mask:0xf bank_mask:0xf bound_ctrl:1
	v_mov_b32_dpp v82, v70 row_ror:8 row_mask:0xf bank_mask:0xf bound_ctrl:1
	v_mov_b32_dpp v83, v71 row_ror:8 row_mask:0xf bank_mask:0xf bound_ctrl:1
	v_mov_b32_dpp v84, v66 row_ror:8 row_mask:0xf bank_mask:0xf bound_ctrl:1
	v_mov_b32_dpp v85, v67 row_ror:8 row_mask:0xf bank_mask:0xf bound_ctrl:1
	v_lshl_add_u64 v[76:77], v[74:75], 0, v[134:135]
	v_cndmask_b32_e64 v69, v69, v67, s[8:9]
	v_cndmask_b32_e64 v68, v68, v66, s[8:9]
	v_cndmask_b32_e64 v67, v73, v71, s[8:9]
	v_cndmask_b32_e64 v66, v72, v70, s[8:9]
	v_cndmask_b32_e64 v73, v81, v85, s[8:9]
	v_cndmask_b32_e64 v72, v80, v84, s[8:9]
	v_cndmask_b32_e64 v71, v79, v83, s[8:9]
	v_cndmask_b32_e64 v70, v78, v82, s[8:9]
	v_cvt_pk_bf16_f32 v62, v62, v63
	v_cvt_pk_bf16_f32 v63, v64, v65
	v_cvt_pk_bf16_f32 v64, v58, v59
	v_cvt_pk_bf16_f32 v65, v60, v61
	v_cvt_pk_bf16_f32 v54, v54, v55
	v_cvt_pk_bf16_f32 v55, v56, v57
	v_cvt_pk_bf16_f32 v50, v50, v51
	v_cvt_pk_bf16_f32 v51, v52, v53
	v_lshl_add_u64 v[74:75], v[74:75], 0, v[136:137]
	global_store_dwordx4 v[76:77], v[70:73], off
	global_store_dwordx4 v[74:75], v[66:69], off
	v_lshl_add_u64 v[58:59], v[142:143], 0, s[16:17]
	v_mov_b32_dpp v56, v62 row_ror:8 row_mask:0xf bank_mask:0xf bound_ctrl:1
	v_mov_b32_dpp v57, v63 row_ror:8 row_mask:0xf bank_mask:0xf bound_ctrl:1
	v_mov_b32_dpp v52, v64 row_ror:8 row_mask:0xf bank_mask:0xf bound_ctrl:1
	v_mov_b32_dpp v53, v65 row_ror:8 row_mask:0xf bank_mask:0xf bound_ctrl:1
	v_mov_b32_dpp v66, v54 row_ror:8 row_mask:0xf bank_mask:0xf bound_ctrl:1
; __device__ __forceinline__ unsigned pk2(float lo, float hi) { const f32x2 v = {lo, hi}; return __builtin_bit_cast(unsigned, __builtin_convertvector(v, bf16x2_t)); }
; #define PG8_BAR __builtin_amdgcn_s_barrier()
; template <class Epi, class Sched, bool ABLK = false, bool ALIGN_EPI = true, bool SP2 = true, bool BBLK = true>
; __device__ __forceinline__ void gemm_phase(LAS unsigned char* lds, const Gemm g, const Sched& S, const Epi& E) {
;     ...
;         if constexpr (ALIGN_EPI) { if (wr == 0) PG8_BAR; }
;     __device__ __forceinline__ void operator()(const f32x4 (&acc)[2][2][4][2], const Unit& u, int wr, int wc, int fr, int fq) const {
;     ...
;         for (int ai = 0; ai < 2; ++ai)
; #pragma unroll
;             for (int m = 0; m < 4; ++m) { u32x4 w[2];
; #pragma unroll
;                 for (int bj = 0; bj < 2; ++bj) { const f32x4 v0 = acc[ai][bj][m][0], v1 = acc[ai][bj][m][1]; w[bj].x = pk2(v0[0], v0[1]); w[bj].y = pk2(v0[2], v0[3]); w[bj].z = pk2(v1[0], v1[1]); w[bj].w = pk2(v1[2], v1[3]); }
;                 store_pair((unsigned char*)(base + (size_t)(ai * 128 + m * 16) * D), (size_t)8 * D * 2, 64, w[0], w[1], fr >= 8); }
	v_mov_b32_dpp v67, v55 row_ror:8 row_mask:0xf bank_mask:0xf bound_ctrl:1
	v_mov_b32_dpp v68, v50 row_ror:8 row_mask:0xf bank_mask:0xf bound_ctrl:1
	v_mov_b32_dpp v69, v51 row_ror:8 row_mask:0xf bank_mask:0xf bound_ctrl:1
	v_lshl_add_u64 v[60:61], v[58:59], 0, v[134:135]
	v_cndmask_b32_e64 v53, v53, v51, s[8:9]
	v_cndmask_b32_e64 v52, v52, v50, s[8:9]
	v_cndmask_b32_e64 v51, v57, v55, s[8:9]
	v_cndmask_b32_e64 v50, v56, v54, s[8:9]
	v_cndmask_b32_e64 v57, v65, v69, s[8:9]
	v_cndmask_b32_e64 v56, v64, v68, s[8:9]
	v_cndmask_b32_e64 v55, v63, v67, s[8:9]
	v_cndmask_b32_e64 v54, v62, v66, s[8:9]
	v_cvt_pk_bf16_f32 v46, v46, v47
	v_cvt_pk_bf16_f32 v47, v48, v49
	v_cvt_pk_bf16_f32 v48, v42, v43
	v_cvt_pk_bf16_f32 v49, v44, v45
	v_cvt_pk_bf16_f32 v38, v38, v39
	v_cvt_pk_bf16_f32 v39, v40, v41
	v_cvt_pk_bf16_f32 v34, v34, v35
	v_cvt_pk_bf16_f32 v35, v36, v37
	v_lshl_add_u64 v[58:59], v[58:59], 0, v[136:137]
	global_store_dwordx4 v[60:61], v[54:57], off
	global_store_dwordx4 v[58:59], v[50:53], off
	v_lshl_add_u64 v[42:43], v[142:143], 0, s[18:19]
	v_mov_b32_dpp v40, v46 row_ror:8 row_mask:0xf bank_mask:0xf bound_ctrl:1
	v_mov_b32_dpp v41, v47 row_ror:8 row_mask:0xf bank_mask:0xf bound_ctrl:1
	v_mov_b32_dpp v36, v48 row_ror:8 row_mask:0xf bank_mask:0xf bound_ctrl:1
	v_mov_b32_dpp v37, v49 row_ror:8 row_mask:0xf bank_mask:0xf bound_ctrl:1
	v_mov_b32_dpp v50, v38 row_ror:8 row_mask:0xf bank_mask:0xf bound_ctrl:1
	v_mov_b32_dpp v51, v39 row_ror:8 row_mask:0xf bank_mask:0xf bound_ctrl:1
	v_mov_b32_dpp v52, v34 row_ror:8 row_mask:0xf bank_mask:0xf bound_ctrl:1
	v_mov_b32_dpp v53, v35 row_ror:8 row_mask:0xf bank_mask:0xf bound_ctrl:1
	v_lshl_add_u64 v[44:45], v[42:43], 0, v[134:135]
	v_cndmask_b32_e64 v37, v37, v35, s[8:9]
	v_cndmask_b32_e64 v36, v36, v34, s[8:9]
	v_cndmask_b32_e64 v35, v41, v39, s[8:9]
	v_cndmask_b32_e64 v34, v40, v38, s[8:9]
	v_cndmask_b32_e64 v41, v49, v53, s[8:9]
	v_cndmask_b32_e64 v40, v48, v52, s[8:9]
	v_cndmask_b32_e64 v39, v47, v51, s[8:9]
	v_cndmask_b32_e64 v38, v46, v50, s[8:9]
	v_cvt_pk_bf16_f32 v30, v30, v31
	v_cvt_pk_bf16_f32 v31, v32, v33
	v_cvt_pk_bf16_f32 v32, v26, v27
	v_cvt_pk_bf16_f32 v33, v28, v29
	v_cvt_pk_bf16_f32 v22, v22, v23
	v_cvt_pk_bf16_f32 v23, v24, v25
	v_cvt_pk_bf16_f32 v18, v18, v19
	v_cvt_pk_bf16_f32 v19, v20, v21
	v_lshl_add_u64 v[42:43], v[42:43], 0, v[136:137]
	global_store_dwordx4 v[44:45], v[38:41], off
	global_store_dwordx4 v[42:43], v[34:37], off
	v_lshl_add_u64 v[26:27], v[142:143], 0, s[20:21]
	v_mov_b32_dpp v24, v30 row_ror:8 row_mask:0xf bank_mask:0xf bound_ctrl:1
	v_mov_b32_dpp v25, v31 row_ror:8 row_mask:0xf bank_mask:0xf bound_ctrl:1
	v_mov_b32_dpp v20, v32 row_ror:8 row_mask:0xf bank_mask:0xf bound_ctrl:1
	v_mov_b32_dpp v21, v33 row_ror:8 row_mask:0xf bank_mask:0xf bound_ctrl:1
	v_mov_b32_dpp v34, v22 row_ror:8 row_mask:0xf bank_mask:0xf bound_ctrl:1
	v_mov_b32_dpp v35, v23 row_ror:8 row_mask:0xf bank_mask:0xf bound_ctrl:1
	v_mov_b32_dpp v36, v18 row_ror:8 row_mask:0xf bank_mask:0xf bound_ctrl:1
	v_mov_b32_dpp v37, v19 row_ror:8 row_mask:0xf bank_mask:0xf bound_ctrl:1
	v_lshl_add_u64 v[28:29], v[26:27], 0, v[134:135]
	v_cndmask_b32_e64 v21, v21, v19, s[8:9]
	v_cndmask_b32_e64 v20, v20, v18, s[8:9]
	v_cndmask_b32_e64 v19, v25, v23, s[8:9]
	v_cndmask_b32_e64 v18, v24, v22, s[8:9]
	v_cndmask_b32_e64 v25, v33, v37, s[8:9]
	v_cndmask_b32_e64 v24, v32, v36, s[8:9]
	v_cndmask_b32_e64 v23, v31, v35, s[8:9]
	v_cndmask_b32_e64 v22, v30, v34, s[8:9]
	v_cvt_pk_bf16_f32 v14, v14, v15
	v_cvt_pk_bf16_f32 v15, v16, v17
	v_cvt_pk_bf16_f32 v16, v10, v11
	v_cvt_pk_bf16_f32 v17, v12, v13
	v_cvt_pk_bf16_f32 v6, v6, v7
	v_cvt_pk_bf16_f32 v7, v8, v9
	v_cvt_pk_bf16_f32 v2, v2, v3
	v_cvt_pk_bf16_f32 v3, v4, v5
	v_lshl_add_u64 v[26:27], v[26:27], 0, v[136:137]
	global_store_dwordx4 v[28:29], v[22:25], off
	global_store_dwordx4 v[26:27], v[18:21], off
	v_lshl_add_u64 v[10:11], v[142:143], 0, s[22:23]
	v_mov_b32_dpp v8, v14 row_ror:8 row_mask:0xf bank_mask:0xf bound_ctrl:1
	v_mov_b32_dpp v9, v15 row_ror:8 row_mask:0xf bank_mask:0xf bound_ctrl:1
	v_mov_b32_dpp v4, v16 row_ror:8 row_mask:0xf bank_mask:0xf bound_ctrl:1
	v_mov_b32_dpp v5, v17 row_ror:8 row_mask:0xf bank_mask:0xf bound_ctrl:1
	v_mov_b32_dpp v18, v6 row_ror:8 row_mask:0xf bank_mask:0xf bound_ctrl:1
	v_mov_b32_dpp v19, v7 row_ror:8 row_mask:0xf bank_mask:0xf bound_ctrl:1
	v_mov_b32_dpp v20, v2 row_ror:8 row_mask:0xf bank_mask:0xf bound_ctrl:1
	v_mov_b32_dpp v21, v3 row_ror:8 row_mask:0xf bank_mask:0xf bound_ctrl:1
	v_lshl_add_u64 v[12:13], v[10:11], 0, v[134:135]
	v_cndmask_b32_e64 v5, v5, v3, s[8:9]
	v_cndmask_b32_e64 v4, v4, v2, s[8:9]
	v_cndmask_b32_e64 v3, v9, v7, s[8:9]
	v_cndmask_b32_e64 v2, v8, v6, s[8:9]
	v_cndmask_b32_e64 v9, v17, v21, s[8:9]
	v_cndmask_b32_e64 v8, v16, v20, s[8:9]
	v_cndmask_b32_e64 v7, v15, v19, s[8:9]
	v_cndmask_b32_e64 v6, v14, v18, s[8:9]
	s_and_b64 vcc, exec, s[6:7]
	s_cbranch_vccz .LBB0_1910
	s_barrier

; #define PG8_STAGE(bufoff, gbase, voff) do { _Pragma("unroll") for (int _i = 0; _i < 2; ++_i) \
;         __builtin_amdgcn_global_load_lds((const unsigned*)((const char*)(gbase) + (voff)[_i]), (LAS unsigned*)(lds + (bufoff) + ldsw + _i * 8192), 16, 0, 0); } while (0)
; #define PG8_LDA(dst, b, h) do { _Pragma("unroll") for (int m = 0; m < 4; ++m) _Pragma("unroll") for (int k = 0; k < 2; ++k) dst[m][k] = *(const LAS bf16x8*)(lds + PG8_SA(b, h) + aoff + m * 2048 + k * 1024); } while (0)
; #define PG8_LDB(dst, b, h) do { _Pragma("unroll") for (int n = 0; n < 2; ++n) _Pragma("unroll") for (int k = 0; k < 2; ++k) dst[n][k] = *(const LAS bf16x8*)(lds + PG8_SB(b, h) + boff + n * 2048 + k * 1024); } while (0)
; #define PG8_MMA(ai, bj, At, Bt) do { __builtin_amdgcn_s_setprio(1); _Pragma("unroll") for (int m = 0; m < 4; ++m) _Pragma("unroll") for (int n = 0; n < 2; ++n) _Pragma("unroll") for (int k = 0; k < 2; ++k) \
;         acc[ai][bj][m][n] = __builtin_amdgcn_mfma_f32_16x16x32_bf16(Bt[n][k], At[m][k], acc[ai][bj][m][n], 0, 0, 0); __builtin_amdgcn_s_setprio(0); } while (0)
; #define PG8_WAIT_V(n) asm volatile("s_waitcnt vmcnt(" #n ")" ::: "memory")
; #define PG8_WAIT_L(n) asm volatile("s_waitcnt lgkmcnt(" #n ")" ::: "memory")
; template <class Epi, class Sched, bool ABLK = false, bool ALIGN_EPI = true, bool SP2 = true, bool BBLK = true>
; __device__ __forceinline__ void gemm_phase(LAS unsigned char* lds, const Gemm g, const Sched& S, const Epi& E) {
;     ...
;             const char* a1 = a_tile(uA, tbA + t + 1);
;             const char* a2 = last ? a_tile(nuA, ntbA) : a_tile(uA, tbA + t + 2); const char* b2 = last ? nB : cB + (size_t)(t + 2) * kstepB;
;             const char* a3 = last ? a_tile(nuA, ntbA + 1) : a_tile(uA, tbA + t + 3); const char* b3 = b2 + kstepB;
;             if (last && has_next) S.a_ready(nxt);
;             if constexpr (SP2) {
;             PG8_LDB(B0, 0, 0); PG8_LDB(B1, 0, 1); PG8_SCHED; PG8_LDA(At, 0, 0); PG8_STAGE(PG8_SA(1, 1), a1 + hstepA, voffA);
;             PG8_WAIT_V(8); PG8_WAIT_L(0); PG8_BAR; PG8_MMA(0, 0, At, B0); PG8_MMA(0, 1, At, B1); PG8_BAR; PG8_SCHED;
;             PG8_LDA(At, 0, 1); PG8_STAGE(PG8_SB(0, 0), b2, voffB); PG8_STAGE(PG8_SB(0, 1), b2 + hstepB, voffB); PG8_STAGE(PG8_SA(0, 0), a2, voffA);
;             PG8_WAIT_V(8); PG8_WAIT_L(0); PG8_BAR; PG8_MMA(1, 0, At, B0); PG8_MMA(1, 1, At, B1); PG8_BAR; PG8_SCHED;
.LBB0_2138:
	ds_read_b128 v[152:155], v148
	ds_read_b128 v[156:159], v148 offset:1024
	ds_read_b128 v[160:163], v148 offset:2048
	ds_read_b128 v[164:167], v148 offset:3072
	ds_read_b128 v[168:171], v149
	ds_read_b128 v[172:175], v149 offset:1024
	ds_read_b128 v[176:179], v149 offset:2048
	ds_read_b128 v[180:183], v149 offset:3072
	s_add_u32 s28, s24, s26
	s_addc_u32 s29, s25, s27
	s_add_u32 s34, s28, 0x100
	s_addc_u32 s35, s29, 0
	s_add_u32 s28, s28, 0x180
	s_addc_u32 s29, s29, 0
	s_cmpk_eq_i32 s26, 0xf00
	s_cselect_b32 s29, s49, s29
	s_cselect_b32 s28, s48, s28
	s_cselect_b32 s31, s11, s51
	s_cselect_b32 s30, s13, s50
	s_cselect_b32 s35, s4, s35
	s_cselect_b32 s34, s5, s34
	s_mov_b32 m0, s47
	v_lshl_add_u64 v[216:217], v[142:143], 0, s[26:27]
	ds_read_b128 v[184:187], v150
	ds_read_b128 v[188:191], v150 offset:1024
	ds_read_b128 v[192:195], v150 offset:2048
	ds_read_b128 v[196:199], v150 offset:3072
	ds_read_b128 v[200:203], v150 offset:4096
	ds_read_b128 v[204:207], v150 offset:5120
	ds_read_b128 v[208:211], v150 offset:6144
	ds_read_b128 v[212:215], v150 offset:7168
	global_load_lds_dwordx4 v[216:217], off
	v_lshl_add_u64 v[216:217], v[144:145], 0, s[26:27]
	s_add_i32 m0, s21, 0xe000
	s_nop 0
	global_load_lds_dwordx4 v[216:217], off
	s_waitcnt vmcnt(8) lgkmcnt(0)
	s_barrier
	v_mfma_f32_16x16x32_bf16 v[122:125], v[152:155], v[184:187], v[122:125]
	v_mfma_f32_16x16x32_bf16 v[118:121], v[160:163], v[184:187], v[118:121]
	v_mfma_f32_16x16x32_bf16 v[106:109], v[152:155], v[192:195], v[106:109]
	v_mfma_f32_16x16x32_bf16 v[102:105], v[160:163], v[192:195], v[102:105]
	v_mfma_f32_16x16x32_bf16 v[90:93], v[152:155], v[200:203], v[90:93]
	v_mfma_f32_16x16x32_bf16 v[86:89], v[160:163], v[200:203], v[86:89]
	v_mfma_f32_16x16x32_bf16 v[74:77], v[152:155], v[208:211], v[74:77]
	v_mfma_f32_16x16x32_bf16 v[70:73], v[160:163], v[208:211], v[70:73]
	v_mfma_f32_16x16x32_bf16 v[122:125], v[156:159], v[188:191], v[122:125]
	v_mfma_f32_16x16x32_bf16 v[118:121], v[164:167], v[188:191], v[118:121]
	v_mfma_f32_16x16x32_bf16 v[106:109], v[156:159], v[196:199], v[106:109]
	v_mfma_f32_16x16x32_bf16 v[102:105], v[164:167], v[196:199], v[102:105]
	v_mfma_f32_16x16x32_bf16 v[90:93], v[156:159], v[204:207], v[90:93]
	v_mfma_f32_16x16x32_bf16 v[86:89], v[164:167], v[204:207], v[86:89]
	v_mfma_f32_16x16x32_bf16 v[74:77], v[156:159], v[212:215], v[74:77]
	v_mfma_f32_16x16x32_bf16 v[70:73], v[164:167], v[212:215], v[70:73]
	v_mfma_f32_16x16x32_bf16 v[126:129], v[168:171], v[184:187], v[126:129]
	v_mfma_f32_16x16x32_bf16 v[114:117], v[176:179], v[184:187], v[114:117]
	v_mfma_f32_16x16x32_bf16 v[110:113], v[168:171], v[192:195], v[110:113]
	v_mfma_f32_16x16x32_bf16 v[98:101], v[176:179], v[192:195], v[98:101]
	v_mfma_f32_16x16x32_bf16 v[94:97], v[168:171], v[200:203], v[94:97]
	v_mfma_f32_16x16x32_bf16 v[82:85], v[176:179], v[200:203], v[82:85]
	v_mfma_f32_16x16x32_bf16 v[78:81], v[168:171], v[208:211], v[78:81]
	v_mfma_f32_16x16x32_bf16 v[66:69], v[176:179], v[208:211], v[66:69]
	v_mfma_f32_16x16x32_bf16 v[126:129], v[172:175], v[188:191], v[126:129]
	v_mfma_f32_16x16x32_bf16 v[114:117], v[180:183], v[188:191], v[114:117]
	v_mfma_f32_16x16x32_bf16 v[110:113], v[172:175], v[196:199], v[110:113]
	v_mfma_f32_16x16x32_bf16 v[98:101], v[180:183], v[196:199], v[98:101]
	v_mfma_f32_16x16x32_bf16 v[94:97], v[172:175], v[204:207], v[94:97]
	v_mfma_f32_16x16x32_bf16 v[82:85], v[180:183], v[204:207], v[82:85]
	v_mfma_f32_16x16x32_bf16 v[78:81], v[172:175], v[212:215], v[78:81]
	v_mfma_f32_16x16x32_bf16 v[66:69], v[180:183], v[212:215], v[66:69]
	s_barrier
	s_add_i32 s53, s72, s36
	s_mov_b32 m0, s53
	ds_read_b128 v[184:187], v150 offset:16384
	ds_read_b128 v[188:191], v150 offset:17408
	ds_read_b128 v[192:195], v150 offset:18432
	ds_read_b128 v[196:199], v150 offset:19456
	ds_read_b128 v[200:203], v150 offset:20480
	ds_read_b128 v[204:207], v150 offset:21504
	ds_read_b128 v[208:211], v150 offset:22528
	ds_read_b128 v[212:215], v150 offset:23552
	global_load_lds_dwordx4 v134, s[30:31]
	s_add_i32 m0, s53, 0x2000
	s_add_u32 s54, s30, 0x4000
	s_addc_u32 s55, s31, 0
	s_add_i32 s53, s73, s36
	global_load_lds_dwordx4 v130, s[30:31]
	s_mov_b32 m0, s53
	s_nop 0
	global_load_lds_dwordx4 v134, s[54:55]
	s_add_i32 m0, s53, 0x2000
	s_nop 0
	global_load_lds_dwordx4 v130, s[54:55]
	s_mov_b32 m0, s21
	s_nop 0
	global_load_lds_dwordx4 v136, s[34:35]
	s_mov_b32 m0, s23
	s_nop 0
	global_load_lds_dwordx4 v132, s[34:35]
	s_waitcnt vmcnt(8) lgkmcnt(0)
	s_barrier
	v_mfma_f32_16x16x32_bf16 v[58:61], v[152:155], v[184:187], v[58:61]
	v_mfma_f32_16x16x32_bf16 v[54:57], v[160:163], v[184:187], v[54:57]
	v_mfma_f32_16x16x32_bf16 v[42:45], v[152:155], v[192:195], v[42:45]
	v_mfma_f32_16x16x32_bf16 v[38:41], v[160:163], v[192:195], v[38:41]
	v_mfma_f32_16x16x32_bf16 v[26:29], v[152:155], v[200:203], v[26:29]
	v_mfma_f32_16x16x32_bf16 v[22:25], v[160:163], v[200:203], v[22:25]
	v_mfma_f32_16x16x32_bf16 v[10:13], v[152:155], v[208:211], v[10:13]
	v_mfma_f32_16x16x32_bf16 v[6:9], v[160:163], v[208:211], v[6:9]
	v_mfma_f32_16x16x32_bf16 v[58:61], v[156:159], v[188:191], v[58:61]
	v_mfma_f32_16x16x32_bf16 v[54:57], v[164:167], v[188:191], v[54:57]
	v_mfma_f32_16x16x32_bf16 v[42:45], v[156:159], v[196:199], v[42:45]
	v_mfma_f32_16x16x32_bf16 v[38:41], v[164:167], v[196:199], v[38:41]
	v_mfma_f32_16x16x32_bf16 v[26:29], v[156:159], v[204:207], v[26:29]
	v_mfma_f32_16x16x32_bf16 v[22:25], v[164:167], v[204:207], v[22:25]
	v_mfma_f32_16x16x32_bf16 v[10:13], v[156:159], v[212:215], v[10:13]
	v_mfma_f32_16x16x32_bf16 v[6:9], v[164:167], v[212:215], v[6:9]
	v_mfma_f32_16x16x32_bf16 v[62:65], v[168:171], v[184:187], v[62:65]
	v_mfma_f32_16x16x32_bf16 v[50:53], v[176:179], v[184:187], v[50:53]
	v_mfma_f32_16x16x32_bf16 v[46:49], v[168:171], v[192:195], v[46:49]
	v_mfma_f32_16x16x32_bf16 v[34:37], v[176:179], v[192:195], v[34:37]
	v_mfma_f32_16x16x32_bf16 v[30:33], v[168:171], v[200:203], v[30:33]
	v_mfma_f32_16x16x32_bf16 v[18:21], v[176:179], v[200:203], v[18:21]
	v_mfma_f32_16x16x32_bf16 v[14:17], v[168:171], v[208:211], v[14:17]
	v_mfma_f32_16x16x32_bf16 v[2:5], v[176:179], v[208:211], v[2:5]
	v_mfma_f32_16x16x32_bf16 v[62:65], v[172:175], v[188:191], v[62:65]
	v_mfma_f32_16x16x32_bf16 v[50:53], v[180:183], v[188:191], v[50:53]
	v_mfma_f32_16x16x32_bf16 v[46:49], v[172:175], v[196:199], v[46:49]
	v_mfma_f32_16x16x32_bf16 v[34:37], v[180:183], v[196:199], v[34:37]
	v_mfma_f32_16x16x32_bf16 v[30:33], v[172:175], v[204:207], v[30:33]
	v_mfma_f32_16x16x32_bf16 v[18:21], v[180:183], v[204:207], v[18:21]
	v_mfma_f32_16x16x32_bf16 v[14:17], v[172:175], v[212:215], v[14:17]
	v_mfma_f32_16x16x32_bf16 v[2:5], v[180:183], v[212:215], v[2:5]
	s_barrier
; #define PG8_STAGE(bufoff, gbase, voff) do { _Pragma("unroll") for (int _i = 0; _i < 2; ++_i) \
;         __builtin_amdgcn_global_load_lds((const unsigned*)((const char*)(gbase) + (voff)[_i]), (LAS unsigned*)(lds + (bufoff) + ldsw + _i * 8192), 16, 0, 0); } while (0)
; #define PG8_LDA(dst, b, h) do { _Pragma("unroll") for (int m = 0; m < 4; ++m) _Pragma("unroll") for (int k = 0; k < 2; ++k) dst[m][k] = *(const LAS bf16x8*)(lds + PG8_SA(b, h) + aoff + m * 2048 + k * 1024); } while (0)
; #define PG8_LDB(dst, b, h) do { _Pragma("unroll") for (int n = 0; n < 2; ++n) _Pragma("unroll") for (int k = 0; k < 2; ++k) dst[n][k] = *(const LAS bf16x8*)(lds + PG8_SB(b, h) + boff + n * 2048 + k * 1024); } while (0)
; #define PG8_MMA(ai, bj, At, Bt) do { __builtin_amdgcn_s_setprio(1); _Pragma("unroll") for (int m = 0; m < 4; ++m) _Pragma("unroll") for (int n = 0; n < 2; ++n) _Pragma("unroll") for (int k = 0; k < 2; ++k) \
;         acc[ai][bj][m][n] = __builtin_amdgcn_mfma_f32_16x16x32_bf16(Bt[n][k], At[m][k], acc[ai][bj][m][n], 0, 0, 0); __builtin_amdgcn_s_setprio(0); } while (0)
; #define PG8_WAIT_V(n) asm volatile("s_waitcnt vmcnt(" #n ")" ::: "memory")
; #define PG8_WAIT_L(n) asm volatile("s_waitcnt lgkmcnt(" #n ")" ::: "memory")
; #define PG8_BAR __builtin_amdgcn_s_barrier()
; #define PG8_SCHED __builtin_amdgcn_sched_barrier(0)
; template <class Epi, class Sched, bool ABLK = false, bool ALIGN_EPI = true, bool SP2 = true, bool BBLK = true>
; __device__ __forceinline__ void gemm_phase(LAS unsigned char* lds, const Gemm g, const Sched& S, const Epi& E) {
;     ...
;             PG8_LDB(B0, 1, 0); PG8_LDB(B1, 1, 1); PG8_SCHED; PG8_LDA(At, 1, 0); PG8_STAGE(PG8_SA(0, 1), a2 + hstepA, voffA);
;             PG8_WAIT_V(8); PG8_WAIT_L(0); PG8_BAR; PG8_MMA(0, 0, At, B0); PG8_MMA(0, 1, At, B1); PG8_BAR; PG8_SCHED;
;             PG8_LDA(At, 1, 1); PG8_STAGE(PG8_SB(1, 0), b3, voffB); PG8_STAGE(PG8_SB(1, 1), b3 + hstepB, voffB); PG8_STAGE(PG8_SA(1, 0), a3, voffA);
;             PG8_WAIT_V(8); PG8_WAIT_L(0); PG8_BAR; PG8_MMA(1, 0, At, B0); PG8_MMA(1, 1, At, B1); PG8_BAR; PG8_SCHED;
	v_add_u32_e32 v151, s60, v146
	ds_read_b128 v[152:155], v151
	ds_read_b128 v[156:159], v151 offset:1024
	ds_read_b128 v[160:163], v151 offset:2048
	ds_read_b128 v[164:167], v151 offset:3072
	v_add_u32_e32 v151, s61, v146
	ds_read_b128 v[168:171], v151
	ds_read_b128 v[172:175], v151 offset:1024
	ds_read_b128 v[176:179], v151 offset:2048
	ds_read_b128 v[180:183], v151 offset:3072
	s_add_u32 s34, s34, 0x80000
	s_addc_u32 s35, s35, 0
	s_mov_b32 m0, s39
	ds_read_b128 v[184:187], v150 offset:32768
	ds_read_b128 v[188:191], v150 offset:33792
	ds_read_b128 v[192:195], v150 offset:34816
	ds_read_b128 v[196:199], v150 offset:35840
	ds_read_b128 v[200:203], v150 offset:36864
	ds_read_b128 v[204:207], v150 offset:37888
	ds_read_b128 v[208:211], v150 offset:38912
	ds_read_b128 v[212:215], v150 offset:39936
	global_load_lds_dwordx4 v136, s[34:35]
	s_mov_b32 m0, s40
	s_nop 0
	global_load_lds_dwordx4 v132, s[34:35]
	s_waitcnt vmcnt(8) lgkmcnt(0)
	s_barrier
	v_mfma_f32_16x16x32_bf16 v[122:125], v[152:155], v[184:187], v[122:125]
	v_mfma_f32_16x16x32_bf16 v[118:121], v[160:163], v[184:187], v[118:121]
	v_mfma_f32_16x16x32_bf16 v[106:109], v[152:155], v[192:195], v[106:109]
	v_mfma_f32_16x16x32_bf16 v[102:105], v[160:163], v[192:195], v[102:105]
	v_mfma_f32_16x16x32_bf16 v[90:93], v[152:155], v[200:203], v[90:93]
	v_mfma_f32_16x16x32_bf16 v[86:89], v[160:163], v[200:203], v[86:89]
	v_mfma_f32_16x16x32_bf16 v[74:77], v[152:155], v[208:211], v[74:77]
	v_mfma_f32_16x16x32_bf16 v[70:73], v[160:163], v[208:211], v[70:73]
	v_mfma_f32_16x16x32_bf16 v[122:125], v[156:159], v[188:191], v[122:125]
	v_mfma_f32_16x16x32_bf16 v[118:121], v[164:167], v[188:191], v[118:121]
	v_mfma_f32_16x16x32_bf16 v[106:109], v[156:159], v[196:199], v[106:109]
	v_mfma_f32_16x16x32_bf16 v[102:105], v[164:167], v[196:199], v[102:105]
	v_mfma_f32_16x16x32_bf16 v[90:93], v[156:159], v[204:207], v[90:93]
	v_mfma_f32_16x16x32_bf16 v[86:89], v[164:167], v[204:207], v[86:89]
	v_mfma_f32_16x16x32_bf16 v[74:77], v[156:159], v[212:215], v[74:77]
	v_mfma_f32_16x16x32_bf16 v[70:73], v[164:167], v[212:215], v[70:73]
	v_mfma_f32_16x16x32_bf16 v[126:129], v[168:171], v[184:187], v[126:129]
	v_mfma_f32_16x16x32_bf16 v[114:117], v[176:179], v[184:187], v[114:117]
	v_mfma_f32_16x16x32_bf16 v[110:113], v[168:171], v[192:195], v[110:113]
	v_mfma_f32_16x16x32_bf16 v[98:101], v[176:179], v[192:195], v[98:101]
	v_mfma_f32_16x16x32_bf16 v[94:97], v[168:171], v[200:203], v[94:97]
	v_mfma_f32_16x16x32_bf16 v[82:85], v[176:179], v[200:203], v[82:85]
	v_mfma_f32_16x16x32_bf16 v[78:81], v[168:171], v[208:211], v[78:81]
	v_mfma_f32_16x16x32_bf16 v[66:69], v[176:179], v[208:211], v[66:69]
	v_mfma_f32_16x16x32_bf16 v[126:129], v[172:175], v[188:191], v[126:129]
	v_mfma_f32_16x16x32_bf16 v[114:117], v[180:183], v[188:191], v[114:117]
	v_mfma_f32_16x16x32_bf16 v[110:113], v[172:175], v[196:199], v[110:113]
	v_mfma_f32_16x16x32_bf16 v[98:101], v[180:183], v[196:199], v[98:101]
	v_mfma_f32_16x16x32_bf16 v[94:97], v[172:175], v[204:207], v[94:97]
	v_mfma_f32_16x16x32_bf16 v[82:85], v[180:183], v[204:207], v[82:85]
	v_mfma_f32_16x16x32_bf16 v[78:81], v[172:175], v[212:215], v[78:81]
	v_mfma_f32_16x16x32_bf16 v[66:69], v[180:183], v[212:215], v[66:69]
	s_barrier
	s_add_u32 s34, s30, 0x8000
	s_addc_u32 s35, s31, 0
	s_add_i32 s53, s60, s36
	s_mov_b32 m0, s53
	ds_read_b128 v[184:187], v150 offset:49152
	ds_read_b128 v[188:191], v150 offset:50176
	ds_read_b128 v[192:195], v150 offset:51200
	ds_read_b128 v[196:199], v150 offset:52224
	ds_read_b128 v[200:203], v150 offset:53248
	ds_read_b128 v[204:207], v150 offset:54272
	ds_read_b128 v[208:211], v150 offset:55296
	ds_read_b128 v[212:215], v150 offset:56320
	global_load_lds_dwordx4 v134, s[34:35]
	s_add_i32 m0, s53, 0x2000
	s_add_u32 s30, s30, 0xc000
	v_lshl_add_u64 v[216:217], s[34:35], 0, v[130:131]
	s_addc_u32 s31, s31, 0
	s_add_i32 s34, s61, s36
	global_load_lds_dwordx4 v[216:217], off
	s_mov_b32 m0, s34
	s_nop 0
	global_load_lds_dwordx4 v134, s[30:31]
	s_add_i32 m0, s34, 0x2000
	s_nop 0
	global_load_lds_dwordx4 v130, s[30:31]
	s_mov_b32 m0, s42
	s_nop 0
	global_load_lds_dwordx4 v136, s[28:29]
	s_mov_b32 m0, s43
	s_nop 0
	global_load_lds_dwordx4 v132, s[28:29]
	s_waitcnt vmcnt(8) lgkmcnt(0)
	s_barrier
	v_mfma_f32_16x16x32_bf16 v[58:61], v[152:155], v[184:187], v[58:61]
	v_mfma_f32_16x16x32_bf16 v[54:57], v[160:163], v[184:187], v[54:57]
	v_mfma_f32_16x16x32_bf16 v[42:45], v[152:155], v[192:195], v[42:45]
	v_mfma_f32_16x16x32_bf16 v[38:41], v[160:163], v[192:195], v[38:41]
	v_mfma_f32_16x16x32_bf16 v[26:29], v[152:155], v[200:203], v[26:29]
	v_mfma_f32_16x16x32_bf16 v[22:25], v[160:163], v[200:203], v[22:25]
	v_mfma_f32_16x16x32_bf16 v[10:13], v[152:155], v[208:211], v[10:13]
	v_mfma_f32_16x16x32_bf16 v[6:9], v[160:163], v[208:211], v[6:9]
	v_mfma_f32_16x16x32_bf16 v[58:61], v[156:159], v[188:191], v[58:61]
	v_mfma_f32_16x16x32_bf16 v[54:57], v[164:167], v[188:191], v[54:57]
	v_mfma_f32_16x16x32_bf16 v[42:45], v[156:159], v[196:199], v[42:45]
	v_mfma_f32_16x16x32_bf16 v[38:41], v[164:167], v[196:199], v[38:41]
	v_mfma_f32_16x16x32_bf16 v[26:29], v[156:159], v[204:207], v[26:29]
	v_mfma_f32_16x16x32_bf16 v[22:25], v[164:167], v[204:207], v[22:25]
	v_mfma_f32_16x16x32_bf16 v[10:13], v[156:159], v[212:215], v[10:13]
	v_mfma_f32_16x16x32_bf16 v[6:9], v[164:167], v[212:215], v[6:9]
	v_mfma_f32_16x16x32_bf16 v[62:65], v[168:171], v[184:187], v[62:65]
	v_mfma_f32_16x16x32_bf16 v[50:53], v[176:179], v[184:187], v[50:53]
	v_mfma_f32_16x16x32_bf16 v[46:49], v[168:171], v[192:195], v[46:49]
	v_mfma_f32_16x16x32_bf16 v[34:37], v[176:179], v[192:195], v[34:37]
	v_mfma_f32_16x16x32_bf16 v[30:33], v[168:171], v[200:203], v[30:33]
	v_mfma_f32_16x16x32_bf16 v[18:21], v[176:179], v[200:203], v[18:21]
	v_mfma_f32_16x16x32_bf16 v[14:17], v[168:171], v[208:211], v[14:17]
	v_mfma_f32_16x16x32_bf16 v[2:5], v[176:179], v[208:211], v[2:5]
	v_mfma_f32_16x16x32_bf16 v[62:65], v[172:175], v[188:191], v[62:65]
	v_mfma_f32_16x16x32_bf16 v[50:53], v[180:183], v[188:191], v[50:53]
	v_mfma_f32_16x16x32_bf16 v[46:49], v[172:175], v[196:199], v[46:49]
	v_mfma_f32_16x16x32_bf16 v[34:37], v[180:183], v[196:199], v[34:37]
	v_mfma_f32_16x16x32_bf16 v[30:33], v[172:175], v[204:207], v[30:33]
	v_mfma_f32_16x16x32_bf16 v[18:21], v[180:183], v[204:207], v[18:21]
	v_mfma_f32_16x16x32_bf16 v[14:17], v[172:175], v[212:215], v[14:17]
	v_mfma_f32_16x16x32_bf16 v[2:5], v[180:183], v[212:215], v[2:5]
	s_barrier
; __device__ __forceinline__ unsigned pk2(float lo, float hi) { const f32x2 v = {lo, hi}; return __builtin_bit_cast(unsigned, __builtin_convertvector(v, bf16x2_t)); }
; #define PG8_BAR __builtin_amdgcn_s_barrier()
; __device__ __forceinline__ float sigmoidf_(float x) { return __builtin_amdgcn_rcpf(1.0f + __expf(-x)); }
; template <class Epi, class Sched, bool ABLK = false, bool ALIGN_EPI = true, bool SP2 = true, bool BBLK = true>
; __device__ __forceinline__ void gemm_phase(LAS unsigned char* lds, const Gemm g, const Sched& S, const Epi& E) {
;     ...
;         if constexpr (ALIGN_EPI) { if (wr == 0) PG8_BAR; }
;     __device__ __forceinline__ void operator()(const f32x4 (&acc)[2][2][4][2], const Unit& u, int wr, int wc, int fr, int fq) const {
;         const int row0 = u.pm * 256 + wr * 64 + fr, ch0 = u.pn * 128 + wc * 32 + 8 * fq;
; #pragma unroll
;         for (int ai = 0; ai < 2; ++ai)
; #pragma unroll
;             for (int m = 0; m < 4; ++m) { f32x4 z[2];
; #pragma unroll
;                 for (int n = 0; n < 2; ++n) { const f32x4 o = acc[ai][0][m][n], gt = acc[ai][1][m][n];
; #pragma unroll
;                     for (int j = 0; j < 4; ++j) z[n][j] = o[j] * sigmoidf_(gt[j]); }
;                 u32x4 w; w.x = pk2(z[0][0], z[0][1]); w.y = pk2(z[0][2], z[0][3]); w.z = pk2(z[1][0], z[1][1]); w.w = pk2(z[1][2], z[1][3]);
;                 *(u32x4*)(Z + (size_t)(row0 + ai * 128 + m * 16) * D + ch0) = w; }
	s_add_i32 s52, s52, 2
	s_add_u32 s26, s26, 0x100
	s_addc_u32 s27, s27, 0
	s_add_u32 s50, s50, 0x10000
	s_addc_u32 s51, s51, 0
	s_cmp_gt_u32 s52, 29
	s_cbranch_scc0 .LBB0_2138
	v_mul_f32_e32 v114, 0xbfb8aa3b, v114
	v_mul_f32_e32 v115, 0xbfb8aa3b, v115
	v_exp_f32_e32 v114, v114
	v_exp_f32_e32 v115, v115
	v_mul_f32_e32 v116, 0xbfb8aa3b, v116
	v_mul_f32_e32 v117, 0xbfb8aa3b, v117
	v_exp_f32_e32 v116, v116
	v_exp_f32_e32 v117, v117
	v_mul_f32_e32 v50, 0xbfb8aa3b, v50
	v_mul_f32_e32 v51, 0xbfb8aa3b, v51
	v_exp_f32_e32 v50, v50
	v_exp_f32_e32 v51, v51
	v_mul_f32_e32 v52, 0xbfb8aa3b, v52
	v_mul_f32_e32 v53, 0xbfb8aa3b, v53
	v_add_f32_e32 v114, 1.0, v114
	v_add_f32_e32 v115, 1.0, v115
	v_exp_f32_e32 v52, v52
	v_exp_f32_e32 v53, v53
	v_mul_f32_e32 v34, 0xbfb8aa3b, v34
	v_mul_f32_e32 v35, 0xbfb8aa3b, v35
	v_rcp_f32_e32 v114, v114
	v_rcp_f32_e32 v115, v115
	v_add_f32_e32 v116, 1.0, v116
	v_add_f32_e32 v117, 1.0, v117
	v_exp_f32_e32 v34, v34
	v_exp_f32_e32 v35, v35
	v_mul_f32_e32 v36, 0xbfb8aa3b, v36
	v_mul_f32_e32 v37, 0xbfb8aa3b, v37
	v_rcp_f32_e32 v116, v116
	v_rcp_f32_e32 v117, v117
	v_mul_f32_e32 v98, 0xbfb8aa3b, v98
	v_mul_f32_e32 v99, 0xbfb8aa3b, v99
	v_mul_f32_e32 v82, 0xbfb8aa3b, v82
	v_mul_f32_e32 v83, 0xbfb8aa3b, v83
	v_mul_f32_e32 v66, 0xbfb8aa3b, v66
	v_mul_f32_e32 v67, 0xbfb8aa3b, v67
	v_exp_f32_e32 v36, v36
	v_exp_f32_e32 v37, v37
	v_mul_f32_e32 v18, 0xbfb8aa3b, v18
	v_mul_f32_e32 v19, 0xbfb8aa3b, v19
	v_exp_f32_e32 v98, v98
	v_exp_f32_e32 v99, v99
	v_mul_f32_e32 v100, 0xbfb8aa3b, v100
	v_mul_f32_e32 v101, 0xbfb8aa3b, v101
	v_exp_f32_e32 v82, v82
	v_exp_f32_e32 v83, v83
	v_mul_f32_e32 v84, 0xbfb8aa3b, v84
	v_mul_f32_e32 v85, 0xbfb8aa3b, v85
	v_exp_f32_e32 v66, v66
	v_exp_f32_e32 v67, v67
	v_mul_f32_e32 v68, 0xbfb8aa3b, v68
	v_mul_f32_e32 v69, 0xbfb8aa3b, v69
	v_add_f32_e32 v50, 1.0, v50
	v_add_f32_e32 v51, 1.0, v51
	v_exp_f32_e32 v18, v18
	v_exp_f32_e32 v19, v19
	v_mul_f32_e32 v20, 0xbfb8aa3b, v20
	v_mul_f32_e32 v21, 0xbfb8aa3b, v21
	v_lshl_add_u32 v142, s20, 8, v1
	v_exp_f32_e32 v100, v100
	v_exp_f32_e32 v101, v101
	v_exp_f32_e32 v84, v84
	v_exp_f32_e32 v85, v85
	v_exp_f32_e32 v68, v68
	v_exp_f32_e32 v69, v69
	v_rcp_f32_e32 v50, v50
	v_rcp_f32_e32 v51, v51
	v_add_f32_e32 v52, 1.0, v52
	v_add_f32_e32 v53, 1.0, v53
	v_exp_f32_e32 v20, v20
	v_exp_f32_e32 v21, v21
	v_mul_f32_e32 v2, 0xbfb8aa3b, v2
	v_mul_f32_e32 v3, 0xbfb8aa3b, v3
	v_lshl_or_b32 v144, s22, 7, v147
	v_pk_mul_f32 v[114:115], v[118:119], v[114:115]
	v_ashrrev_i32_e32 v143, 31, v142
	v_rcp_f32_e32 v52, v52
	v_rcp_f32_e32 v53, v53
	v_add_f32_e32 v34, 1.0, v34
	v_add_f32_e32 v35, 1.0, v35
	v_exp_f32_e32 v2, v2
	v_exp_f32_e32 v3, v3
	v_mul_f32_e32 v4, 0xbfb8aa3b, v4
	v_mul_f32_e32 v5, 0xbfb8aa3b, v5
	v_mul_f32_e32 v126, 0xbfb8aa3b, v126
	v_mul_f32_e32 v127, 0xbfb8aa3b, v127
	v_ashrrev_i32_e32 v145, 31, v144
	v_mul_f32_e32 v128, 0xbfb8aa3b, v128
	v_mul_f32_e32 v129, 0xbfb8aa3b, v129
	v_pk_mul_f32 v[120:121], v[120:121], v[116:117]
	v_cvt_pk_bf16_f32 v118, v114, v115
	v_lshlrev_b64 v[114:115], 12, v[142:143]
	v_mul_f32_e32 v110, 0xbfb8aa3b, v110
	v_mul_f32_e32 v111, 0xbfb8aa3b, v111
	v_mul_f32_e32 v112, 0xbfb8aa3b, v112
	v_mul_f32_e32 v113, 0xbfb8aa3b, v113
	v_mul_f32_e32 v94, 0xbfb8aa3b, v94
	v_mul_f32_e32 v95, 0xbfb8aa3b, v95
	v_mul_f32_e32 v96, 0xbfb8aa3b, v96
	v_mul_f32_e32 v97, 0xbfb8aa3b, v97
	v_mul_f32_e32 v78, 0xbfb8aa3b, v78
	v_mul_f32_e32 v79, 0xbfb8aa3b, v79
	v_mul_f32_e32 v80, 0xbfb8aa3b, v80
	v_mul_f32_e32 v81, 0xbfb8aa3b, v81
	v_mul_f32_e32 v62, 0xbfb8aa3b, v62
	v_mul_f32_e32 v63, 0xbfb8aa3b, v63
	v_mul_f32_e32 v64, 0xbfb8aa3b, v64
	v_mul_f32_e32 v65, 0xbfb8aa3b, v65
	v_mul_f32_e32 v46, 0xbfb8aa3b, v46
	v_mul_f32_e32 v47, 0xbfb8aa3b, v47
	v_mul_f32_e32 v48, 0xbfb8aa3b, v48
	v_mul_f32_e32 v49, 0xbfb8aa3b, v49
	v_rcp_f32_e32 v34, v34
	v_rcp_f32_e32 v35, v35
	v_add_f32_e32 v36, 1.0, v36
	v_add_f32_e32 v37, 1.0, v37
	v_mul_f32_e32 v30, 0xbfb8aa3b, v30
	v_mul_f32_e32 v31, 0xbfb8aa3b, v31
	v_mul_f32_e32 v32, 0xbfb8aa3b, v32
	v_mul_f32_e32 v33, 0xbfb8aa3b, v33
	v_mul_f32_e32 v14, 0xbfb8aa3b, v14
	v_mul_f32_e32 v15, 0xbfb8aa3b, v15
	v_mul_f32_e32 v16, 0xbfb8aa3b, v16
	v_mul_f32_e32 v17, 0xbfb8aa3b, v17
	v_exp_f32_e32 v4, v4
	v_exp_f32_e32 v5, v5
	v_exp_f32_e32 v126, v126
	v_exp_f32_e32 v127, v127
	v_exp_f32_e32 v128, v128
	v_exp_f32_e32 v129, v129
	v_cvt_pk_bf16_f32 v119, v120, v121
	v_lshl_add_u64 v[114:115], s[8:9], 0, v[114:115]
	v_lshlrev_b64 v[120:121], 1, v[144:145]
	v_exp_f32_e32 v110, v110
	v_exp_f32_e32 v111, v111
	v_exp_f32_e32 v112, v112
	v_exp_f32_e32 v113, v113
	v_add_f32_e32 v98, 1.0, v98
	v_add_f32_e32 v99, 1.0, v99
	v_exp_f32_e32 v94, v94
	v_exp_f32_e32 v95, v95
	v_exp_f32_e32 v96, v96
	v_exp_f32_e32 v97, v97
	v_add_f32_e32 v82, 1.0, v82
	v_add_f32_e32 v83, 1.0, v83
	v_exp_f32_e32 v78, v78
	v_exp_f32_e32 v79, v79
	v_exp_f32_e32 v80, v80
	v_exp_f32_e32 v81, v81
	v_add_f32_e32 v66, 1.0, v66
	v_add_f32_e32 v67, 1.0, v67
	v_exp_f32_e32 v62, v62
	v_exp_f32_e32 v63, v63
	v_exp_f32_e32 v64, v64
	v_exp_f32_e32 v65, v65
	v_exp_f32_e32 v46, v46
	v_exp_f32_e32 v47, v47
	v_exp_f32_e32 v48, v48
	v_exp_f32_e32 v49, v49
	v_rcp_f32_e32 v36, v36
	v_rcp_f32_e32 v37, v37
	v_exp_f32_e32 v30, v30
	v_exp_f32_e32 v31, v31
	v_exp_f32_e32 v32, v32
	v_exp_f32_e32 v33, v33
	v_add_f32_e32 v18, 1.0, v18
	v_add_f32_e32 v19, 1.0, v19
	v_exp_f32_e32 v14, v14
	v_exp_f32_e32 v15, v15
	v_exp_f32_e32 v16, v16
	v_exp_f32_e32 v17, v17
	v_lshl_add_u64 v[114:115], v[114:115], 0, v[120:121]
	v_rcp_f32_e32 v98, v98
	v_rcp_f32_e32 v99, v99
	v_add_f32_e32 v100, 1.0, v100
	v_add_f32_e32 v101, 1.0, v101
	v_rcp_f32_e32 v82, v82
	v_rcp_f32_e32 v83, v83
	v_add_f32_e32 v84, 1.0, v84
	v_add_f32_e32 v85, 1.0, v85
; __device__ __forceinline__ unsigned pk2(float lo, float hi) { const f32x2 v = {lo, hi}; return __builtin_bit_cast(unsigned, __builtin_convertvector(v, bf16x2_t)); }
; __device__ __forceinline__ float sigmoidf_(float x) { return __builtin_amdgcn_rcpf(1.0f + __expf(-x)); }
; #define PG8_BAR __builtin_amdgcn_s_barrier()
; template <class Epi, class Sched, bool ABLK = false, bool ALIGN_EPI = true, bool SP2 = true, bool BBLK = true>
; __device__ __forceinline__ void gemm_phase(LAS unsigned char* lds, const Gemm g, const Sched& S, const Epi& E) {
;     ...
;         if constexpr (ALIGN_EPI) { if (wr == 0) PG8_BAR; }
;         E(acc, cur, wr, wc, fr, fq); S.done(cur);
;         if (!has_next) break;
; #pragma unroll
;         for (int a = 0; a < 2; ++a)
; #pragma unroll
;             for (int b = 0; b < 2; ++b)
; #pragma unroll
;                 for (int m = 0; m < 4; ++m)
; #pragma unroll
;                     for (int n = 0; n < 2; ++n) acc[a][b][m][n] = (f32x4){0.f, 0.f, 0.f, 0.f};
;         cur = nxt; uA = nuA; tbA = ntbA; cB = nB; ++ui;
;         if constexpr (ALIGN_EPI) { if (wr == 1) PG8_BAR; }
;     __device__ __forceinline__ void operator()(const f32x4 (&acc)[2][2][4][2], const Unit& u, int wr, int wc, int fr, int fq) const {
;     ...
;             for (int m = 0; m < 4; ++m) { f32x4 z[2];
; #pragma unroll
;                 for (int n = 0; n < 2; ++n) { const f32x4 o = acc[ai][0][m][n], gt = acc[ai][1][m][n];
; #pragma unroll
;                     for (int j = 0; j < 4; ++j) z[n][j] = o[j] * sigmoidf_(gt[j]); }
;                 u32x4 w; w.x = pk2(z[0][0], z[0][1]); w.y = pk2(z[0][2], z[0][3]); w.z = pk2(z[1][0], z[1][1]); w.w = pk2(z[1][2], z[1][3]);
;                 *(u32x4*)(Z + (size_t)(row0 + ai * 128 + m * 16) * D + ch0) = w; }
	v_rcp_f32_e32 v66, v66
	v_rcp_f32_e32 v67, v67
	v_add_f32_e32 v68, 1.0, v68
	v_add_f32_e32 v69, 1.0, v69
	v_pk_mul_f32 v[54:55], v[54:55], v[50:51]
	v_rcp_f32_e32 v18, v18
	v_rcp_f32_e32 v19, v19
	v_add_f32_e32 v20, 1.0, v20
	v_add_f32_e32 v21, 1.0, v21
	v_rcp_f32_e32 v100, v100
	v_rcp_f32_e32 v101, v101
	v_rcp_f32_e32 v84, v84
	v_rcp_f32_e32 v85, v85
	v_rcp_f32_e32 v68, v68
	v_rcp_f32_e32 v69, v69
	v_pk_mul_f32 v[56:57], v[56:57], v[52:53]
	v_cvt_pk_bf16_f32 v52, v54, v55
	v_add_co_u32_e32 v54, vcc, s44, v114
	v_rcp_f32_e32 v20, v20
	v_rcp_f32_e32 v21, v21
	v_add_f32_e32 v2, 1.0, v2
	v_add_f32_e32 v3, 1.0, v3
	v_addc_co_u32_e32 v55, vcc, 0, v115, vcc
	v_pk_mul_f32 v[38:39], v[38:39], v[34:35]
	v_rcp_f32_e32 v2, v2
	v_rcp_f32_e32 v3, v3
	v_add_f32_e32 v4, 1.0, v4
	v_add_f32_e32 v5, 1.0, v5
	v_add_f32_e32 v126, 1.0, v126
	v_add_f32_e32 v127, 1.0, v127
	v_add_f32_e32 v128, 1.0, v128
	v_add_f32_e32 v129, 1.0, v129
	v_add_f32_e32 v110, 1.0, v110
	v_add_f32_e32 v111, 1.0, v111
	v_add_f32_e32 v112, 1.0, v112
	v_add_f32_e32 v113, 1.0, v113
	v_add_f32_e32 v94, 1.0, v94
	v_add_f32_e32 v95, 1.0, v95
	v_add_f32_e32 v96, 1.0, v96
	v_add_f32_e32 v97, 1.0, v97
	v_add_f32_e32 v78, 1.0, v78
	v_add_f32_e32 v79, 1.0, v79
	v_add_f32_e32 v80, 1.0, v80
	v_add_f32_e32 v81, 1.0, v81
	v_add_f32_e32 v62, 1.0, v62
	v_add_f32_e32 v63, 1.0, v63
	v_add_f32_e32 v64, 1.0, v64
	v_add_f32_e32 v65, 1.0, v65
	v_add_f32_e32 v46, 1.0, v46
	v_add_f32_e32 v47, 1.0, v47
	v_add_f32_e32 v48, 1.0, v48
	v_add_f32_e32 v49, 1.0, v49
	v_pk_mul_f32 v[40:41], v[40:41], v[36:37]
	v_cvt_pk_bf16_f32 v36, v38, v39
	v_add_co_u32_e32 v38, vcc, s45, v114
	v_add_f32_e32 v30, 1.0, v30
	v_add_f32_e32 v31, 1.0, v31
	v_add_f32_e32 v32, 1.0, v32
	v_add_f32_e32 v33, 1.0, v33
	v_add_f32_e32 v14, 1.0, v14
	v_add_f32_e32 v15, 1.0, v15
	v_add_f32_e32 v16, 1.0, v16
	v_add_f32_e32 v17, 1.0, v17
	v_rcp_f32_e32 v4, v4
	v_rcp_f32_e32 v5, v5
	v_rcp_f32_e32 v126, v126
	v_rcp_f32_e32 v127, v127
	v_rcp_f32_e32 v128, v128
	v_rcp_f32_e32 v129, v129
	v_rcp_f32_e32 v110, v110
	v_rcp_f32_e32 v111, v111
	v_rcp_f32_e32 v112, v112
	v_rcp_f32_e32 v113, v113
	v_pk_mul_f32 v[102:103], v[102:103], v[98:99]
	v_rcp_f32_e32 v94, v94
	v_rcp_f32_e32 v95, v95
	v_rcp_f32_e32 v96, v96
	v_rcp_f32_e32 v97, v97
	v_pk_mul_f32 v[86:87], v[86:87], v[82:83]
	v_rcp_f32_e32 v78, v78
	v_rcp_f32_e32 v79, v79
	v_rcp_f32_e32 v80, v80
	v_rcp_f32_e32 v81, v81
	v_pk_mul_f32 v[70:71], v[70:71], v[66:67]
	v_rcp_f32_e32 v62, v62
	v_rcp_f32_e32 v63, v63
	v_rcp_f32_e32 v64, v64
	v_rcp_f32_e32 v65, v65
	v_rcp_f32_e32 v46, v46
	v_rcp_f32_e32 v47, v47
	v_rcp_f32_e32 v48, v48
	v_rcp_f32_e32 v49, v49
	v_addc_co_u32_e32 v39, vcc, 0, v115, vcc
	v_rcp_f32_e32 v30, v30
	v_rcp_f32_e32 v31, v31
	v_rcp_f32_e32 v32, v32
	v_rcp_f32_e32 v33, v33
	v_pk_mul_f32 v[22:23], v[22:23], v[18:19]
	v_rcp_f32_e32 v14, v14
	v_rcp_f32_e32 v15, v15
	v_rcp_f32_e32 v16, v16
	v_rcp_f32_e32 v17, v17
	v_pk_mul_f32 v[104:105], v[104:105], v[100:101]
	v_cvt_pk_bf16_f32 v100, v102, v103
	v_or_b32_e32 v102, 16, v142
	v_pk_mul_f32 v[88:89], v[88:89], v[84:85]
	v_cvt_pk_bf16_f32 v84, v86, v87
	v_or_b32_e32 v86, 32, v142
	v_pk_mul_f32 v[72:73], v[72:73], v[68:69]
	v_cvt_pk_bf16_f32 v68, v70, v71
	v_or_b32_e32 v70, 48, v142
	v_pk_mul_f32 v[24:25], v[24:25], v[20:21]
	v_cvt_pk_bf16_f32 v20, v22, v23
	v_add_co_u32_e32 v22, vcc, s46, v114
	v_ashrrev_i32_e32 v103, 31, v102
	v_ashrrev_i32_e32 v87, 31, v86
	v_ashrrev_i32_e32 v71, 31, v70
	v_addc_co_u32_e32 v23, vcc, 0, v115, vcc
	v_pk_mul_f32 v[6:7], v[6:7], v[2:3]
	v_lshlrev_b64 v[102:103], 12, v[102:103]
	v_lshlrev_b64 v[86:87], 12, v[86:87]
	v_lshlrev_b64 v[70:71], 12, v[70:71]
	v_pk_mul_f32 v[8:9], v[8:9], v[4:5]
	v_cvt_pk_bf16_f32 v4, v6, v7
	v_add_co_u32_e32 v6, vcc, 0xb0000, v114
	v_pk_mul_f32 v[122:123], v[122:123], v[126:127]
	v_pk_mul_f32 v[124:125], v[124:125], v[128:129]
	v_pk_mul_f32 v[106:107], v[106:107], v[110:111]
	v_pk_mul_f32 v[108:109], v[108:109], v[112:113]
	v_lshl_add_u64 v[102:103], s[8:9], 0, v[102:103]
	v_pk_mul_f32 v[90:91], v[90:91], v[94:95]
	v_pk_mul_f32 v[92:93], v[92:93], v[96:97]
	v_lshl_add_u64 v[86:87], s[8:9], 0, v[86:87]
	v_pk_mul_f32 v[74:75], v[74:75], v[78:79]
	v_pk_mul_f32 v[76:77], v[76:77], v[80:81]
	v_lshl_add_u64 v[70:71], s[8:9], 0, v[70:71]
	v_pk_mul_f32 v[58:59], v[58:59], v[62:63]
	v_pk_mul_f32 v[60:61], v[60:61], v[64:65]
	v_pk_mul_f32 v[42:43], v[42:43], v[46:47]
	v_pk_mul_f32 v[44:45], v[44:45], v[48:49]
	v_pk_mul_f32 v[26:27], v[26:27], v[30:31]
	v_pk_mul_f32 v[28:29], v[28:29], v[32:33]
	v_pk_mul_f32 v[10:11], v[10:11], v[14:15]
	v_pk_mul_f32 v[12:13], v[12:13], v[16:17]
	v_addc_co_u32_e32 v7, vcc, 0, v115, vcc
	v_cvt_pk_bf16_f32 v116, v122, v123
	v_cvt_pk_bf16_f32 v117, v124, v125
	v_cvt_pk_bf16_f32 v98, v106, v107
	v_cvt_pk_bf16_f32 v99, v108, v109
	v_cvt_pk_bf16_f32 v101, v104, v105
	v_lshl_add_u64 v[102:103], v[102:103], 0, v[120:121]
	v_cvt_pk_bf16_f32 v82, v90, v91
	v_cvt_pk_bf16_f32 v83, v92, v93
	v_cvt_pk_bf16_f32 v85, v88, v89
	v_lshl_add_u64 v[86:87], v[86:87], 0, v[120:121]
	v_cvt_pk_bf16_f32 v66, v74, v75
	v_cvt_pk_bf16_f32 v67, v76, v77
	v_cvt_pk_bf16_f32 v69, v72, v73
	v_lshl_add_u64 v[70:71], v[70:71], 0, v[120:121]
	v_cvt_pk_bf16_f32 v50, v58, v59
	v_cvt_pk_bf16_f32 v51, v60, v61
	v_cvt_pk_bf16_f32 v53, v56, v57
	v_cvt_pk_bf16_f32 v34, v42, v43
	v_cvt_pk_bf16_f32 v35, v44, v45
	v_cvt_pk_bf16_f32 v37, v40, v41
	v_cvt_pk_bf16_f32 v18, v26, v27
	v_cvt_pk_bf16_f32 v19, v28, v29
	v_cvt_pk_bf16_f32 v21, v24, v25
	v_cvt_pk_bf16_f32 v2, v10, v11
	v_cvt_pk_bf16_f32 v3, v12, v13
	v_cvt_pk_bf16_f32 v5, v8, v9
	s_and_b64 vcc, exec, s[6:7]
	s_cbranch_vccz .LBB0_2141
	s_barrier
.LBB0_2141:
	s_andn2_b64 vcc, exec, s[16:17]
	s_mov_b64 s[4:5], -1
	global_store_dwordx4 v[114:115], v[116:119], off
	global_store_dwordx4 v[102:103], v[98:101], off
	global_store_dwordx4 v[86:87], v[82:85], off
	global_store_dwordx4 v[70:71], v[66:69], off
	global_store_dwordx4 v[54:55], v[50:53], off
	global_store_dwordx4 v[38:39], v[34:37], off
	global_store_dwordx4 v[22:23], v[18:21], off
	global_store_dwordx4 v[6:7], v[2:5], off
	s_cbranch_vccnz .LBB0_2134
	s_andn2_b64 vcc, exec, s[2:3]
	s_cbranch_vccnz .LBB0_2133
	s_barrier
	s_branch .LBB0_2133

; #define PG8_STAGE(bufoff, gbase, voff) do { _Pragma("unroll") for (int _i = 0; _i < 2; ++_i) \
;         __builtin_amdgcn_global_load_lds((const unsigned*)((const char*)(gbase) + (voff)[_i]), (LAS unsigned*)(lds + (bufoff) + ldsw + _i * 8192), 16, 0, 0); } while (0)
; #define PG8_LDA(dst, b, h) do { _Pragma("unroll") for (int m = 0; m < 4; ++m) _Pragma("unroll") for (int k = 0; k < 2; ++k) dst[m][k] = *(const LAS bf16x8*)(lds + PG8_SA(b, h) + aoff + m * 2048 + k * 1024); } while (0)
; #define PG8_LDB(dst, b, h) do { _Pragma("unroll") for (int n = 0; n < 2; ++n) _Pragma("unroll") for (int k = 0; k < 2; ++k) dst[n][k] = *(const LAS bf16x8*)(lds + PG8_SB(b, h) + boff + n * 2048 + k * 1024); } while (0)
; #define PG8_MMA(ai, bj, At, Bt) do { __builtin_amdgcn_s_setprio(1); _Pragma("unroll") for (int m = 0; m < 4; ++m) _Pragma("unroll") for (int n = 0; n < 2; ++n) _Pragma("unroll") for (int k = 0; k < 2; ++k) \
;         acc[ai][bj][m][n] = __builtin_amdgcn_mfma_f32_16x16x32_bf16(Bt[n][k], At[m][k], acc[ai][bj][m][n], 0, 0, 0); __builtin_amdgcn_s_setprio(0); } while (0)
; #define PG8_WAIT_V(n) asm volatile("s_waitcnt vmcnt(" #n ")" ::: "memory")
; #define PG8_WAIT_L(n) asm volatile("s_waitcnt lgkmcnt(" #n ")" ::: "memory")
; template <class Epi, class Sched, bool ABLK = false, bool ALIGN_EPI = true, bool SP2 = true, bool BBLK = true>
; __device__ __forceinline__ void gemm_phase(LAS unsigned char* lds, const Gemm g, const Sched& S, const Epi& E) {
;     ...
;             const char* a1 = a_tile(uA, tbA + t + 1);
;             const char* a2 = last ? a_tile(nuA, ntbA) : a_tile(uA, tbA + t + 2); const char* b2 = last ? nB : cB + (size_t)(t + 2) * kstepB;
;             const char* a3 = last ? a_tile(nuA, ntbA + 1) : a_tile(uA, tbA + t + 3); const char* b3 = b2 + kstepB;
;             if (last && has_next) S.a_ready(nxt);
;             if constexpr (SP2) {
;             PG8_LDB(B0, 0, 0); PG8_LDB(B1, 0, 1); PG8_SCHED; PG8_LDA(At, 0, 0); PG8_STAGE(PG8_SA(1, 1), a1 + hstepA, voffA);
;             PG8_WAIT_V(8); PG8_WAIT_L(0); PG8_BAR; PG8_MMA(0, 0, At, B0); PG8_MMA(0, 1, At, B1); PG8_BAR; PG8_SCHED;
;             PG8_LDA(At, 0, 1); PG8_STAGE(PG8_SB(0, 0), b2, voffB); PG8_STAGE(PG8_SB(0, 1), b2 + hstepB, voffB); PG8_STAGE(PG8_SA(0, 0), a2, voffA);
;             PG8_WAIT_V(8); PG8_WAIT_L(0); PG8_BAR; PG8_MMA(1, 0, At, B0); PG8_MMA(1, 1, At, B1); PG8_BAR; PG8_SCHED;
.LBB0_2263:
	ds_read_b128 v[172:175], v168
	ds_read_b128 v[176:179], v168 offset:1024
	ds_read_b128 v[180:183], v168 offset:2048
	ds_read_b128 v[184:187], v168 offset:3072
	ds_read_b128 v[188:191], v169
	ds_read_b128 v[192:195], v169 offset:1024
	ds_read_b128 v[196:199], v169 offset:2048
	ds_read_b128 v[200:203], v169 offset:3072
	s_add_u32 s30, s26, s28
	s_addc_u32 s31, s27, s29
	s_add_u32 s36, s30, 0x100
	s_addc_u32 s37, s31, 0
	s_add_u32 s30, s30, 0x180
	s_addc_u32 s31, s31, 0
	s_cmpk_eq_i32 s28, 0xf00
	s_cselect_b32 s31, s54, s31
	s_cselect_b32 s30, s23, s30
	s_cselect_b32 s35, s13, s56
	s_cselect_b32 s34, s15, s55
	s_cselect_b32 s37, s4, s37
	s_cselect_b32 s36, s5, s36
	s_mov_b32 m0, s50
	v_lshl_add_u64 v[236:237], v[164:165], 0, s[28:29]
	ds_read_b128 v[204:207], v170
	ds_read_b128 v[208:211], v170 offset:1024
	ds_read_b128 v[212:215], v170 offset:2048
	ds_read_b128 v[216:219], v170 offset:3072
	ds_read_b128 v[220:223], v170 offset:4096
	ds_read_b128 v[224:227], v170 offset:5120
	ds_read_b128 v[228:231], v170 offset:6144
	ds_read_b128 v[232:235], v170 offset:7168
	global_load_lds_dwordx4 v[236:237], off
	v_lshl_add_u64 v[236:237], v[166:167], 0, s[28:29]
	s_mov_b32 m0, s51
	s_nop 0
	global_load_lds_dwordx4 v[236:237], off
	s_waitcnt vmcnt(8) lgkmcnt(0)
	s_barrier
	v_mfma_f32_16x16x32_bf16 v[126:129], v[172:175], v[204:207], v[126:129]
	v_mfma_f32_16x16x32_bf16 v[122:125], v[180:183], v[204:207], v[122:125]
	v_mfma_f32_16x16x32_bf16 v[110:113], v[172:175], v[212:215], v[110:113]
	v_mfma_f32_16x16x32_bf16 v[106:109], v[180:183], v[212:215], v[106:109]
	v_mfma_f32_16x16x32_bf16 v[94:97], v[172:175], v[220:223], v[94:97]
	v_mfma_f32_16x16x32_bf16 v[90:93], v[180:183], v[220:223], v[90:93]
	v_mfma_f32_16x16x32_bf16 v[78:81], v[172:175], v[228:231], v[78:81]
	v_mfma_f32_16x16x32_bf16 v[74:77], v[180:183], v[228:231], v[74:77]
	v_mfma_f32_16x16x32_bf16 v[126:129], v[176:179], v[208:211], v[126:129]
	v_mfma_f32_16x16x32_bf16 v[122:125], v[184:187], v[208:211], v[122:125]
	v_mfma_f32_16x16x32_bf16 v[110:113], v[176:179], v[216:219], v[110:113]
	v_mfma_f32_16x16x32_bf16 v[106:109], v[184:187], v[216:219], v[106:109]
	v_mfma_f32_16x16x32_bf16 v[94:97], v[176:179], v[224:227], v[94:97]
	v_mfma_f32_16x16x32_bf16 v[90:93], v[184:187], v[224:227], v[90:93]
	v_mfma_f32_16x16x32_bf16 v[78:81], v[176:179], v[232:235], v[78:81]
	v_mfma_f32_16x16x32_bf16 v[74:77], v[184:187], v[232:235], v[74:77]
	v_mfma_f32_16x16x32_bf16 v[118:121], v[188:191], v[204:207], v[118:121]
	v_mfma_f32_16x16x32_bf16 v[114:117], v[196:199], v[204:207], v[114:117]
	v_mfma_f32_16x16x32_bf16 v[102:105], v[188:191], v[212:215], v[102:105]
	v_mfma_f32_16x16x32_bf16 v[98:101], v[196:199], v[212:215], v[98:101]
	v_mfma_f32_16x16x32_bf16 v[86:89], v[188:191], v[220:223], v[86:89]
	v_mfma_f32_16x16x32_bf16 v[82:85], v[196:199], v[220:223], v[82:85]
	v_mfma_f32_16x16x32_bf16 v[70:73], v[188:191], v[228:231], v[70:73]
	v_mfma_f32_16x16x32_bf16 v[66:69], v[196:199], v[228:231], v[66:69]
	v_mfma_f32_16x16x32_bf16 v[118:121], v[192:195], v[208:211], v[118:121]
	v_mfma_f32_16x16x32_bf16 v[114:117], v[200:203], v[208:211], v[114:117]
	v_mfma_f32_16x16x32_bf16 v[102:105], v[192:195], v[216:219], v[102:105]
	v_mfma_f32_16x16x32_bf16 v[98:101], v[200:203], v[216:219], v[98:101]
	v_mfma_f32_16x16x32_bf16 v[86:89], v[192:195], v[224:227], v[86:89]
	v_mfma_f32_16x16x32_bf16 v[82:85], v[200:203], v[224:227], v[82:85]
	v_mfma_f32_16x16x32_bf16 v[70:73], v[192:195], v[232:235], v[70:73]
	v_mfma_f32_16x16x32_bf16 v[66:69], v[200:203], v[232:235], v[66:69]
	s_barrier
	s_mov_b32 m0, s52
	s_add_u32 s58, s34, 0x4000
	ds_read_b128 v[204:207], v170 offset:16384
	ds_read_b128 v[208:211], v170 offset:17408
	ds_read_b128 v[212:215], v170 offset:18432
	ds_read_b128 v[216:219], v170 offset:19456
	ds_read_b128 v[220:223], v170 offset:20480
	ds_read_b128 v[224:227], v170 offset:21504
	ds_read_b128 v[228:231], v170 offset:22528
	ds_read_b128 v[232:235], v170 offset:23552
	global_load_lds_dwordx4 v134, s[34:35]
	s_mov_b32 m0, s53
	s_addc_u32 s59, s35, 0
	s_add_i32 s62, s73, s40
	global_load_lds_dwordx4 v130, s[34:35]
	s_mov_b32 m0, s62
	s_nop 0
	global_load_lds_dwordx4 v134, s[58:59]
	s_add_i32 m0, s62, 0x2000
	s_nop 0
	global_load_lds_dwordx4 v130, s[58:59]
	s_mov_b32 m0, s25
	s_nop 0
	global_load_lds_dwordx4 v136, s[36:37]
	s_mov_b32 m0, s43
	s_nop 0
	global_load_lds_dwordx4 v132, s[36:37]
	s_waitcnt vmcnt(8) lgkmcnt(0)
	s_barrier
	v_mfma_f32_16x16x32_bf16 v[62:65], v[172:175], v[204:207], v[62:65]
	v_mfma_f32_16x16x32_bf16 v[58:61], v[180:183], v[204:207], v[58:61]
	v_mfma_f32_16x16x32_bf16 v[46:49], v[172:175], v[212:215], v[46:49]
	v_mfma_f32_16x16x32_bf16 v[42:45], v[180:183], v[212:215], v[42:45]
	v_mfma_f32_16x16x32_bf16 v[30:33], v[172:175], v[220:223], v[30:33]
	v_mfma_f32_16x16x32_bf16 v[26:29], v[180:183], v[220:223], v[26:29]
	v_mfma_f32_16x16x32_bf16 v[14:17], v[172:175], v[228:231], v[14:17]
	v_mfma_f32_16x16x32_bf16 v[10:13], v[180:183], v[228:231], v[10:13]
	v_mfma_f32_16x16x32_bf16 v[62:65], v[176:179], v[208:211], v[62:65]
	v_mfma_f32_16x16x32_bf16 v[58:61], v[184:187], v[208:211], v[58:61]
	v_mfma_f32_16x16x32_bf16 v[46:49], v[176:179], v[216:219], v[46:49]
	v_mfma_f32_16x16x32_bf16 v[42:45], v[184:187], v[216:219], v[42:45]
	v_mfma_f32_16x16x32_bf16 v[30:33], v[176:179], v[224:227], v[30:33]
	v_mfma_f32_16x16x32_bf16 v[26:29], v[184:187], v[224:227], v[26:29]
	v_mfma_f32_16x16x32_bf16 v[14:17], v[176:179], v[232:235], v[14:17]
	v_mfma_f32_16x16x32_bf16 v[10:13], v[184:187], v[232:235], v[10:13]
	v_mfma_f32_16x16x32_bf16 v[54:57], v[188:191], v[204:207], v[54:57]
	v_mfma_f32_16x16x32_bf16 v[50:53], v[196:199], v[204:207], v[50:53]
	v_mfma_f32_16x16x32_bf16 v[38:41], v[188:191], v[212:215], v[38:41]
	v_mfma_f32_16x16x32_bf16 v[34:37], v[196:199], v[212:215], v[34:37]
	v_mfma_f32_16x16x32_bf16 v[22:25], v[188:191], v[220:223], v[22:25]
	v_mfma_f32_16x16x32_bf16 v[18:21], v[196:199], v[220:223], v[18:21]
	v_mfma_f32_16x16x32_bf16 v[6:9], v[188:191], v[228:231], v[6:9]
	v_mfma_f32_16x16x32_bf16 v[2:5], v[196:199], v[228:231], v[2:5]
	v_mfma_f32_16x16x32_bf16 v[54:57], v[192:195], v[208:211], v[54:57]
	v_mfma_f32_16x16x32_bf16 v[50:53], v[200:203], v[208:211], v[50:53]
	v_mfma_f32_16x16x32_bf16 v[38:41], v[192:195], v[216:219], v[38:41]
	v_mfma_f32_16x16x32_bf16 v[34:37], v[200:203], v[216:219], v[34:37]
	v_mfma_f32_16x16x32_bf16 v[22:25], v[192:195], v[224:227], v[22:25]
	v_mfma_f32_16x16x32_bf16 v[18:21], v[200:203], v[224:227], v[18:21]
	v_mfma_f32_16x16x32_bf16 v[6:9], v[192:195], v[232:235], v[6:9]
	v_mfma_f32_16x16x32_bf16 v[2:5], v[200:203], v[232:235], v[2:5]
	s_barrier
; #define PG8_STAGE(bufoff, gbase, voff) do { _Pragma("unroll") for (int _i = 0; _i < 2; ++_i) \
;         __builtin_amdgcn_global_load_lds((const unsigned*)((const char*)(gbase) + (voff)[_i]), (LAS unsigned*)(lds + (bufoff) + ldsw + _i * 8192), 16, 0, 0); } while (0)
; #define PG8_LDA(dst, b, h) do { _Pragma("unroll") for (int m = 0; m < 4; ++m) _Pragma("unroll") for (int k = 0; k < 2; ++k) dst[m][k] = *(const LAS bf16x8*)(lds + PG8_SA(b, h) + aoff + m * 2048 + k * 1024); } while (0)
; #define PG8_LDB(dst, b, h) do { _Pragma("unroll") for (int n = 0; n < 2; ++n) _Pragma("unroll") for (int k = 0; k < 2; ++k) dst[n][k] = *(const LAS bf16x8*)(lds + PG8_SB(b, h) + boff + n * 2048 + k * 1024); } while (0)
; #define PG8_MMA(ai, bj, At, Bt) do { __builtin_amdgcn_s_setprio(1); _Pragma("unroll") for (int m = 0; m < 4; ++m) _Pragma("unroll") for (int n = 0; n < 2; ++n) _Pragma("unroll") for (int k = 0; k < 2; ++k) \
;         acc[ai][bj][m][n] = __builtin_amdgcn_mfma_f32_16x16x32_bf16(Bt[n][k], At[m][k], acc[ai][bj][m][n], 0, 0, 0); __builtin_amdgcn_s_setprio(0); } while (0)
; #define PG8_WAIT_V(n) asm volatile("s_waitcnt vmcnt(" #n ")" ::: "memory")
; #define PG8_WAIT_L(n) asm volatile("s_waitcnt lgkmcnt(" #n ")" ::: "memory")
; #define PG8_BAR __builtin_amdgcn_s_barrier()
; #define PG8_SCHED __builtin_amdgcn_sched_barrier(0)
; template <class Epi, class Sched, bool ABLK = false, bool ALIGN_EPI = true, bool SP2 = true, bool BBLK = true>
; __device__ __forceinline__ void gemm_phase(LAS unsigned char* lds, const Gemm g, const Sched& S, const Epi& E) {
;     ...
;             PG8_LDB(B0, 1, 0); PG8_LDB(B1, 1, 1); PG8_SCHED; PG8_LDA(At, 1, 0); PG8_STAGE(PG8_SA(0, 1), a2 + hstepA, voffA);
;             PG8_WAIT_V(8); PG8_WAIT_L(0); PG8_BAR; PG8_MMA(0, 0, At, B0); PG8_MMA(0, 1, At, B1); PG8_BAR; PG8_SCHED;
;             PG8_LDA(At, 1, 1); PG8_STAGE(PG8_SB(1, 0), b3, voffB); PG8_STAGE(PG8_SB(1, 1), b3 + hstepB, voffB); PG8_STAGE(PG8_SA(1, 0), a3, voffA);
;             PG8_WAIT_V(8); PG8_WAIT_L(0); PG8_BAR; PG8_MMA(1, 0, At, B0); PG8_MMA(1, 1, At, B1); PG8_BAR; PG8_SCHED;
	v_add_u32_e32 v171, s60, v1
	ds_read_b128 v[172:175], v171
	ds_read_b128 v[176:179], v171 offset:1024
	ds_read_b128 v[180:183], v171 offset:2048
	ds_read_b128 v[184:187], v171 offset:3072
	v_add_u32_e32 v171, s61, v1
	ds_read_b128 v[188:191], v171
	ds_read_b128 v[192:195], v171 offset:1024
	ds_read_b128 v[196:199], v171 offset:2048
	ds_read_b128 v[200:203], v171 offset:3072
	s_add_u32 s36, s36, 0x80000
	s_addc_u32 s37, s37, 0
	s_mov_b32 m0, s44
	ds_read_b128 v[204:207], v170 offset:32768
	ds_read_b128 v[208:211], v170 offset:33792
	ds_read_b128 v[212:215], v170 offset:34816
	ds_read_b128 v[216:219], v170 offset:35840
	ds_read_b128 v[220:223], v170 offset:36864
	ds_read_b128 v[224:227], v170 offset:37888
	ds_read_b128 v[228:231], v170 offset:38912
	ds_read_b128 v[232:235], v170 offset:39936
	global_load_lds_dwordx4 v136, s[36:37]
	s_mov_b32 m0, s45
	s_nop 0
	global_load_lds_dwordx4 v132, s[36:37]
	s_waitcnt vmcnt(8) lgkmcnt(0)
	s_barrier
	v_mfma_f32_16x16x32_bf16 v[126:129], v[172:175], v[204:207], v[126:129]
	v_mfma_f32_16x16x32_bf16 v[122:125], v[180:183], v[204:207], v[122:125]
	v_mfma_f32_16x16x32_bf16 v[110:113], v[172:175], v[212:215], v[110:113]
	v_mfma_f32_16x16x32_bf16 v[106:109], v[180:183], v[212:215], v[106:109]
	v_mfma_f32_16x16x32_bf16 v[94:97], v[172:175], v[220:223], v[94:97]
	v_mfma_f32_16x16x32_bf16 v[90:93], v[180:183], v[220:223], v[90:93]
	v_mfma_f32_16x16x32_bf16 v[78:81], v[172:175], v[228:231], v[78:81]
	v_mfma_f32_16x16x32_bf16 v[74:77], v[180:183], v[228:231], v[74:77]
	v_mfma_f32_16x16x32_bf16 v[126:129], v[176:179], v[208:211], v[126:129]
	v_mfma_f32_16x16x32_bf16 v[122:125], v[184:187], v[208:211], v[122:125]
	v_mfma_f32_16x16x32_bf16 v[110:113], v[176:179], v[216:219], v[110:113]
	v_mfma_f32_16x16x32_bf16 v[106:109], v[184:187], v[216:219], v[106:109]
	v_mfma_f32_16x16x32_bf16 v[94:97], v[176:179], v[224:227], v[94:97]
	v_mfma_f32_16x16x32_bf16 v[90:93], v[184:187], v[224:227], v[90:93]
	v_mfma_f32_16x16x32_bf16 v[78:81], v[176:179], v[232:235], v[78:81]
	v_mfma_f32_16x16x32_bf16 v[74:77], v[184:187], v[232:235], v[74:77]
	v_mfma_f32_16x16x32_bf16 v[118:121], v[188:191], v[204:207], v[118:121]
	v_mfma_f32_16x16x32_bf16 v[114:117], v[196:199], v[204:207], v[114:117]
	v_mfma_f32_16x16x32_bf16 v[102:105], v[188:191], v[212:215], v[102:105]
	v_mfma_f32_16x16x32_bf16 v[98:101], v[196:199], v[212:215], v[98:101]
	v_mfma_f32_16x16x32_bf16 v[86:89], v[188:191], v[220:223], v[86:89]
	v_mfma_f32_16x16x32_bf16 v[82:85], v[196:199], v[220:223], v[82:85]
	v_mfma_f32_16x16x32_bf16 v[70:73], v[188:191], v[228:231], v[70:73]
	v_mfma_f32_16x16x32_bf16 v[66:69], v[196:199], v[228:231], v[66:69]
	v_mfma_f32_16x16x32_bf16 v[118:121], v[192:195], v[208:211], v[118:121]
	v_mfma_f32_16x16x32_bf16 v[114:117], v[200:203], v[208:211], v[114:117]
	v_mfma_f32_16x16x32_bf16 v[102:105], v[192:195], v[216:219], v[102:105]
	v_mfma_f32_16x16x32_bf16 v[98:101], v[200:203], v[216:219], v[98:101]
	v_mfma_f32_16x16x32_bf16 v[86:89], v[192:195], v[224:227], v[86:89]
	v_mfma_f32_16x16x32_bf16 v[82:85], v[200:203], v[224:227], v[82:85]
	v_mfma_f32_16x16x32_bf16 v[70:73], v[192:195], v[232:235], v[70:73]
	v_mfma_f32_16x16x32_bf16 v[66:69], v[200:203], v[232:235], v[66:69]
	s_barrier
	s_add_u32 s36, s34, 0x8000
	s_addc_u32 s37, s35, 0
	s_add_i32 s58, s60, s40
	s_mov_b32 m0, s58
	ds_read_b128 v[204:207], v170 offset:49152
	ds_read_b128 v[208:211], v170 offset:50176
	ds_read_b128 v[212:215], v170 offset:51200
	ds_read_b128 v[216:219], v170 offset:52224
	ds_read_b128 v[220:223], v170 offset:53248
	ds_read_b128 v[224:227], v170 offset:54272
	ds_read_b128 v[228:231], v170 offset:55296
	ds_read_b128 v[232:235], v170 offset:56320
	global_load_lds_dwordx4 v134, s[36:37]
	s_add_i32 m0, s58, 0x2000
	s_add_u32 s34, s34, 0xc000
	v_lshl_add_u64 v[236:237], s[36:37], 0, v[130:131]
	s_addc_u32 s35, s35, 0
	s_add_i32 s36, s61, s40
	global_load_lds_dwordx4 v[236:237], off
	s_mov_b32 m0, s36
	s_nop 0
	global_load_lds_dwordx4 v134, s[34:35]
	s_add_i32 m0, s36, 0x2000
	s_nop 0
	global_load_lds_dwordx4 v130, s[34:35]
	s_mov_b32 m0, s48
	s_nop 0
	global_load_lds_dwordx4 v136, s[30:31]
	s_mov_b32 m0, s49
	s_nop 0
	global_load_lds_dwordx4 v132, s[30:31]
	s_waitcnt vmcnt(8) lgkmcnt(0)
	s_barrier
	v_mfma_f32_16x16x32_bf16 v[62:65], v[172:175], v[204:207], v[62:65]
	v_mfma_f32_16x16x32_bf16 v[58:61], v[180:183], v[204:207], v[58:61]
	v_mfma_f32_16x16x32_bf16 v[46:49], v[172:175], v[212:215], v[46:49]
	v_mfma_f32_16x16x32_bf16 v[42:45], v[180:183], v[212:215], v[42:45]
	v_mfma_f32_16x16x32_bf16 v[30:33], v[172:175], v[220:223], v[30:33]
	v_mfma_f32_16x16x32_bf16 v[26:29], v[180:183], v[220:223], v[26:29]
	v_mfma_f32_16x16x32_bf16 v[14:17], v[172:175], v[228:231], v[14:17]
	v_mfma_f32_16x16x32_bf16 v[10:13], v[180:183], v[228:231], v[10:13]
	v_mfma_f32_16x16x32_bf16 v[62:65], v[176:179], v[208:211], v[62:65]
	v_mfma_f32_16x16x32_bf16 v[58:61], v[184:187], v[208:211], v[58:61]
	v_mfma_f32_16x16x32_bf16 v[46:49], v[176:179], v[216:219], v[46:49]
	v_mfma_f32_16x16x32_bf16 v[42:45], v[184:187], v[216:219], v[42:45]
	v_mfma_f32_16x16x32_bf16 v[30:33], v[176:179], v[224:227], v[30:33]
	v_mfma_f32_16x16x32_bf16 v[26:29], v[184:187], v[224:227], v[26:29]
	v_mfma_f32_16x16x32_bf16 v[14:17], v[176:179], v[232:235], v[14:17]
	v_mfma_f32_16x16x32_bf16 v[10:13], v[184:187], v[232:235], v[10:13]
	v_mfma_f32_16x16x32_bf16 v[54:57], v[188:191], v[204:207], v[54:57]
	v_mfma_f32_16x16x32_bf16 v[50:53], v[196:199], v[204:207], v[50:53]
	v_mfma_f32_16x16x32_bf16 v[38:41], v[188:191], v[212:215], v[38:41]
	v_mfma_f32_16x16x32_bf16 v[34:37], v[196:199], v[212:215], v[34:37]
	v_mfma_f32_16x16x32_bf16 v[22:25], v[188:191], v[220:223], v[22:25]
	v_mfma_f32_16x16x32_bf16 v[18:21], v[196:199], v[220:223], v[18:21]
	v_mfma_f32_16x16x32_bf16 v[6:9], v[188:191], v[228:231], v[6:9]
	v_mfma_f32_16x16x32_bf16 v[2:5], v[196:199], v[228:231], v[2:5]
	v_mfma_f32_16x16x32_bf16 v[54:57], v[192:195], v[208:211], v[54:57]
	v_mfma_f32_16x16x32_bf16 v[50:53], v[200:203], v[208:211], v[50:53]
	v_mfma_f32_16x16x32_bf16 v[38:41], v[192:195], v[216:219], v[38:41]
	v_mfma_f32_16x16x32_bf16 v[34:37], v[200:203], v[216:219], v[34:37]
	v_mfma_f32_16x16x32_bf16 v[22:25], v[192:195], v[224:227], v[22:25]
	v_mfma_f32_16x16x32_bf16 v[18:21], v[200:203], v[224:227], v[18:21]
	v_mfma_f32_16x16x32_bf16 v[6:9], v[192:195], v[232:235], v[6:9]
	v_mfma_f32_16x16x32_bf16 v[2:5], v[200:203], v[232:235], v[2:5]
	s_barrier
; __device__ __forceinline__ unsigned pk2(float lo, float hi) { const f32x2 v = {lo, hi}; return __builtin_bit_cast(unsigned, __builtin_convertvector(v, bf16x2_t)); }
; #define PG8_BAR __builtin_amdgcn_s_barrier()
; template <class Epi, class Sched, bool ABLK = false, bool ALIGN_EPI = true, bool SP2 = true, bool BBLK = true>
; __device__ __forceinline__ void gemm_phase(LAS unsigned char* lds, const Gemm g, const Sched& S, const Epi& E) {
;     ...
;         if constexpr (ALIGN_EPI) { if (wr == 0) PG8_BAR; }
;     __device__ __forceinline__ void operator()(const f32x4 (&acc)[2][2][4][2], const Unit& u, int wr, int wc, int fr, int fq) const {
; #pragma unroll
;         for (int ai = 0; ai < 2; ++ai)
; #pragma unroll
;             for (int m = 0; m < 4; ++m) { unsigned char* rowp = (unsigned char*)(H + ((size_t)(u.pm * (FF / 64) + u.pn * 4 + wc) * 256 + (wr * 64 + fr + ai * 128 + m * 16)) * 64 + 8 * fq); u32x4 w[2];
; #pragma unroll
;                 for (int bj = 0; bj < 2; ++bj) { f32x4 v0 = acc[ai][bj][m][0], v1 = acc[ai][bj][m][1];
; #pragma unroll
;                     for (int j = 0; j < 4; ++j) { const float a = fmaxf(v0[j], 0.f), b = fmaxf(v1[j], 0.f); v0[j] = a * a; v1[j] = b * b; }
;                     w[bj].x = pk2(v0[0], v0[1]); w[bj].y = pk2(v0[2], v0[3]); w[bj].z = pk2(v1[0], v1[1]); w[bj].w = pk2(v1[2], v1[3]); }
;                 store_pair(rowp, (size_t)8 * 64 * 2, 64, w[0], w[1], fr >= 8); }
;     }
	s_add_i32 s57, s57, 2
	s_add_u32 s28, s28, 0x100
	s_addc_u32 s29, s29, 0
	s_add_u32 s55, s55, 0x10000
	s_addc_u32 s56, s56, 0
	s_cmp_gt_u32 s57, 29
	s_cbranch_scc0 .LBB0_2263
	s_lshl_b32 s4, s22, 7
	s_lshl_b32 s5, s24, 2
	s_add_i32 s5, s5, s4
	s_or_b32 s4, s5, s47
	s_ashr_i32 s5, s4, 31
	s_lshl_b64 s[4:5], s[4:5], 15
	s_add_u32 s22, s1, s4
	v_max_f32_e32 v126, 0, v126
	v_max_f32_e32 v122, 0, v122
	v_max_f32_e32 v127, 0, v127
	v_max_f32_e32 v123, 0, v123
	v_max_f32_e32 v128, 0, v128
	v_max_f32_e32 v124, 0, v124
	v_max_f32_e32 v129, 0, v129
	v_max_f32_e32 v125, 0, v125
	v_max_f32_e32 v118, 0, v118
	v_max_f32_e32 v114, 0, v114
	v_max_f32_e32 v119, 0, v119
	v_max_f32_e32 v115, 0, v115
	v_max_f32_e32 v120, 0, v120
	v_max_f32_e32 v116, 0, v116
	v_max_f32_e32 v121, 0, v121
	v_max_f32_e32 v117, 0, v117
	s_addc_u32 s23, s33, s5
	v_pk_mul_f32 v[126:127], v[126:127], v[126:127]
	v_pk_mul_f32 v[122:123], v[122:123], v[122:123]
	v_pk_mul_f32 v[128:129], v[128:129], v[128:129]
	v_pk_mul_f32 v[124:125], v[124:125], v[124:125]
	v_pk_mul_f32 v[118:119], v[118:119], v[118:119]
	v_pk_mul_f32 v[114:115], v[114:115], v[114:115]
	v_pk_mul_f32 v[120:121], v[120:121], v[120:121]
	v_pk_mul_f32 v[116:117], v[116:117], v[116:117]
	v_lshl_add_u64 v[164:165], s[22:23], 0, v[144:145]
	v_cvt_pk_bf16_f32 v126, v126, v127
	v_cvt_pk_bf16_f32 v127, v128, v129
	v_cvt_pk_bf16_f32 v128, v122, v123
	v_cvt_pk_bf16_f32 v129, v124, v125
	v_cvt_pk_bf16_f32 v118, v118, v119
	v_cvt_pk_bf16_f32 v119, v120, v121
	v_cvt_pk_bf16_f32 v114, v114, v115
	v_cvt_pk_bf16_f32 v115, v116, v117
	v_lshl_add_u64 v[122:123], v[164:165], 0, v[138:139]
	v_mov_b32_dpp v120, v126 row_ror:8 row_mask:0xf bank_mask:0xf bound_ctrl:1
	v_mov_b32_dpp v121, v127 row_ror:8 row_mask:0xf bank_mask:0xf bound_ctrl:1
	v_mov_b32_dpp v116, v128 row_ror:8 row_mask:0xf bank_mask:0xf bound_ctrl:1
	v_mov_b32_dpp v117, v129 row_ror:8 row_mask:0xf bank_mask:0xf bound_ctrl:1
	v_mov_b32_dpp v164, v118 row_ror:8 row_mask:0xf bank_mask:0xf bound_ctrl:1
	v_mov_b32_dpp v165, v119 row_ror:8 row_mask:0xf bank_mask:0xf bound_ctrl:1
	v_mov_b32_dpp v166, v114 row_ror:8 row_mask:0xf bank_mask:0xf bound_ctrl:1
	v_mov_b32_dpp v167, v115 row_ror:8 row_mask:0xf bank_mask:0xf bound_ctrl:1
	v_max_f32_e32 v110, 0, v110
	v_max_f32_e32 v106, 0, v106
	v_max_f32_e32 v111, 0, v111
	v_max_f32_e32 v107, 0, v107
	v_max_f32_e32 v112, 0, v112
	v_max_f32_e32 v108, 0, v108
	v_max_f32_e32 v113, 0, v113
	v_max_f32_e32 v109, 0, v109
	v_max_f32_e32 v102, 0, v102
	v_max_f32_e32 v98, 0, v98
	v_max_f32_e32 v103, 0, v103
	v_max_f32_e32 v99, 0, v99
	v_max_f32_e32 v104, 0, v104
	v_max_f32_e32 v100, 0, v100
	v_max_f32_e32 v105, 0, v105
	v_max_f32_e32 v101, 0, v101
	v_lshl_add_u64 v[124:125], v[122:123], 0, v[140:141]
	v_cndmask_b32_e64 v117, v117, v115, s[2:3]
	v_cndmask_b32_e64 v116, v116, v114, s[2:3]
	v_cndmask_b32_e64 v115, v121, v119, s[2:3]
	v_cndmask_b32_e64 v114, v120, v118, s[2:3]
	v_cndmask_b32_e64 v121, v129, v167, s[2:3]
	v_cndmask_b32_e64 v120, v128, v166, s[2:3]
	v_cndmask_b32_e64 v119, v127, v165, s[2:3]
	v_cndmask_b32_e64 v118, v126, v164, s[2:3]
	v_pk_mul_f32 v[110:111], v[110:111], v[110:111]
	v_pk_mul_f32 v[106:107], v[106:107], v[106:107]
	v_pk_mul_f32 v[112:113], v[112:113], v[112:113]
	v_pk_mul_f32 v[108:109], v[108:109], v[108:109]
	v_pk_mul_f32 v[102:103], v[102:103], v[102:103]
	v_pk_mul_f32 v[98:99], v[98:99], v[98:99]
	v_pk_mul_f32 v[104:105], v[104:105], v[104:105]
	v_pk_mul_f32 v[100:101], v[100:101], v[100:101]
	v_lshl_add_u64 v[122:123], v[122:123], 0, v[142:143]
	global_store_dwordx4 v[124:125], v[118:121], off
	global_store_dwordx4 v[122:123], v[114:117], off
	v_cvt_pk_bf16_f32 v110, v110, v111
	v_cvt_pk_bf16_f32 v111, v112, v113
	v_lshl_add_u64 v[114:115], s[22:23], 0, v[146:147]
	v_cvt_pk_bf16_f32 v112, v106, v107
	v_cvt_pk_bf16_f32 v113, v108, v109
	v_cvt_pk_bf16_f32 v102, v102, v103
	v_cvt_pk_bf16_f32 v103, v104, v105
	v_cvt_pk_bf16_f32 v98, v98, v99
	v_cvt_pk_bf16_f32 v99, v100, v101
	v_lshl_add_u64 v[106:107], v[114:115], 0, v[138:139]
	v_mov_b32_dpp v104, v110 row_ror:8 row_mask:0xf bank_mask:0xf bound_ctrl:1
	v_mov_b32_dpp v105, v111 row_ror:8 row_mask:0xf bank_mask:0xf bound_ctrl:1
	v_mov_b32_dpp v100, v112 row_ror:8 row_mask:0xf bank_mask:0xf bound_ctrl:1
	v_mov_b32_dpp v101, v113 row_ror:8 row_mask:0xf bank_mask:0xf bound_ctrl:1
	v_mov_b32_dpp v114, v102 row_ror:8 row_mask:0xf bank_mask:0xf bound_ctrl:1
	v_mov_b32_dpp v115, v103 row_ror:8 row_mask:0xf bank_mask:0xf bound_ctrl:1
	v_mov_b32_dpp v116, v98 row_ror:8 row_mask:0xf bank_mask:0xf bound_ctrl:1
	v_mov_b32_dpp v117, v99 row_ror:8 row_mask:0xf bank_mask:0xf bound_ctrl:1
	v_max_f32_e32 v94, 0, v94
	v_max_f32_e32 v90, 0, v90
	v_max_f32_e32 v95, 0, v95
	v_max_f32_e32 v91, 0, v91
	v_max_f32_e32 v96, 0, v96
	v_max_f32_e32 v92, 0, v92
	v_max_f32_e32 v97, 0, v97
	v_max_f32_e32 v93, 0, v93
	v_max_f32_e32 v86, 0, v86
	v_max_f32_e32 v82, 0, v82
	v_max_f32_e32 v87, 0, v87
	v_max_f32_e32 v83, 0, v83
	v_max_f32_e32 v88, 0, v88
	v_max_f32_e32 v84, 0, v84
	v_max_f32_e32 v89, 0, v89
	v_max_f32_e32 v85, 0, v85
	v_lshl_add_u64 v[108:109], v[106:107], 0, v[140:141]
	v_cndmask_b32_e64 v101, v101, v99, s[2:3]
	v_cndmask_b32_e64 v100, v100, v98, s[2:3]
	v_cndmask_b32_e64 v99, v105, v103, s[2:3]
	v_cndmask_b32_e64 v98, v104, v102, s[2:3]
	v_cndmask_b32_e64 v105, v113, v117, s[2:3]
	v_cndmask_b32_e64 v104, v112, v116, s[2:3]
	v_cndmask_b32_e64 v103, v111, v115, s[2:3]
	v_cndmask_b32_e64 v102, v110, v114, s[2:3]
	v_pk_mul_f32 v[94:95], v[94:95], v[94:95]
	v_pk_mul_f32 v[90:91], v[90:91], v[90:91]
	v_pk_mul_f32 v[96:97], v[96:97], v[96:97]
	v_pk_mul_f32 v[92:93], v[92:93], v[92:93]
; __device__ __forceinline__ unsigned pk2(float lo, float hi) { const f32x2 v = {lo, hi}; return __builtin_bit_cast(unsigned, __builtin_convertvector(v, bf16x2_t)); }
;     __device__ __forceinline__ void operator()(const f32x4 (&acc)[2][2][4][2], const Unit& u, int wr, int wc, int fr, int fq) const {
;     ...
;         for (int ai = 0; ai < 2; ++ai)
; #pragma unroll
;             for (int m = 0; m < 4; ++m) { unsigned char* rowp = (unsigned char*)(H + ((size_t)(u.pm * (FF / 64) + u.pn * 4 + wc) * 256 + (wr * 64 + fr + ai * 128 + m * 16)) * 64 + 8 * fq); u32x4 w[2];
; #pragma unroll
;                 for (int bj = 0; bj < 2; ++bj) { f32x4 v0 = acc[ai][bj][m][0], v1 = acc[ai][bj][m][1];
; #pragma unroll
;                     for (int j = 0; j < 4; ++j) { const float a = fmaxf(v0[j], 0.f), b = fmaxf(v1[j], 0.f); v0[j] = a * a; v1[j] = b * b; }
;                     w[bj].x = pk2(v0[0], v0[1]); w[bj].y = pk2(v0[2], v0[3]); w[bj].z = pk2(v1[0], v1[1]); w[bj].w = pk2(v1[2], v1[3]); }
;                 store_pair(rowp, (size_t)8 * 64 * 2, 64, w[0], w[1], fr >= 8); }
	v_pk_mul_f32 v[86:87], v[86:87], v[86:87]
	v_pk_mul_f32 v[82:83], v[82:83], v[82:83]
	v_pk_mul_f32 v[88:89], v[88:89], v[88:89]
	v_pk_mul_f32 v[84:85], v[84:85], v[84:85]
	v_lshl_add_u64 v[106:107], v[106:107], 0, v[142:143]
	global_store_dwordx4 v[108:109], v[102:105], off
	global_store_dwordx4 v[106:107], v[98:101], off
	v_cvt_pk_bf16_f32 v94, v94, v95
	v_cvt_pk_bf16_f32 v95, v96, v97
	v_lshl_add_u64 v[98:99], s[22:23], 0, v[148:149]
	v_cvt_pk_bf16_f32 v96, v90, v91
	v_cvt_pk_bf16_f32 v97, v92, v93
	v_cvt_pk_bf16_f32 v86, v86, v87
	v_cvt_pk_bf16_f32 v87, v88, v89
	v_cvt_pk_bf16_f32 v82, v82, v83
	v_cvt_pk_bf16_f32 v83, v84, v85
	v_lshl_add_u64 v[90:91], v[98:99], 0, v[138:139]
	v_mov_b32_dpp v88, v94 row_ror:8 row_mask:0xf bank_mask:0xf bound_ctrl:1
	v_mov_b32_dpp v89, v95 row_ror:8 row_mask:0xf bank_mask:0xf bound_ctrl:1
	v_mov_b32_dpp v84, v96 row_ror:8 row_mask:0xf bank_mask:0xf bound_ctrl:1
	v_mov_b32_dpp v85, v97 row_ror:8 row_mask:0xf bank_mask:0xf bound_ctrl:1
	v_mov_b32_dpp v98, v86 row_ror:8 row_mask:0xf bank_mask:0xf bound_ctrl:1
	v_mov_b32_dpp v99, v87 row_ror:8 row_mask:0xf bank_mask:0xf bound_ctrl:1
	v_mov_b32_dpp v100, v82 row_ror:8 row_mask:0xf bank_mask:0xf bound_ctrl:1
	v_mov_b32_dpp v101, v83 row_ror:8 row_mask:0xf bank_mask:0xf bound_ctrl:1
	v_max_f32_e32 v78, 0, v78
	v_max_f32_e32 v74, 0, v74
	v_max_f32_e32 v79, 0, v79
	v_max_f32_e32 v75, 0, v75
	v_max_f32_e32 v80, 0, v80
	v_max_f32_e32 v76, 0, v76
	v_max_f32_e32 v81, 0, v81
	v_max_f32_e32 v77, 0, v77
	v_max_f32_e32 v70, 0, v70
	v_max_f32_e32 v66, 0, v66
	v_max_f32_e32 v71, 0, v71
	v_max_f32_e32 v67, 0, v67
	v_max_f32_e32 v72, 0, v72
	v_max_f32_e32 v68, 0, v68
	v_max_f32_e32 v73, 0, v73
	v_max_f32_e32 v69, 0, v69
	v_lshl_add_u64 v[92:93], v[90:91], 0, v[140:141]
	v_cndmask_b32_e64 v85, v85, v83, s[2:3]
	v_cndmask_b32_e64 v84, v84, v82, s[2:3]
	v_cndmask_b32_e64 v83, v89, v87, s[2:3]
	v_cndmask_b32_e64 v82, v88, v86, s[2:3]
	v_cndmask_b32_e64 v89, v97, v101, s[2:3]
	v_cndmask_b32_e64 v88, v96, v100, s[2:3]
	v_cndmask_b32_e64 v87, v95, v99, s[2:3]
	v_cndmask_b32_e64 v86, v94, v98, s[2:3]
	v_pk_mul_f32 v[78:79], v[78:79], v[78:79]
	v_pk_mul_f32 v[74:75], v[74:75], v[74:75]
	v_pk_mul_f32 v[80:81], v[80:81], v[80:81]
	v_pk_mul_f32 v[76:77], v[76:77], v[76:77]
	v_pk_mul_f32 v[70:71], v[70:71], v[70:71]
	v_pk_mul_f32 v[66:67], v[66:67], v[66:67]
	v_pk_mul_f32 v[72:73], v[72:73], v[72:73]
	v_pk_mul_f32 v[68:69], v[68:69], v[68:69]
	v_lshl_add_u64 v[90:91], v[90:91], 0, v[142:143]
	global_store_dwordx4 v[92:93], v[86:89], off
	global_store_dwordx4 v[90:91], v[82:85], off
	v_cvt_pk_bf16_f32 v78, v78, v79
	v_cvt_pk_bf16_f32 v79, v80, v81
	v_lshl_add_u64 v[82:83], s[22:23], 0, v[150:151]
	v_cvt_pk_bf16_f32 v80, v74, v75
	v_cvt_pk_bf16_f32 v81, v76, v77
	v_cvt_pk_bf16_f32 v70, v70, v71
	v_cvt_pk_bf16_f32 v71, v72, v73
	v_cvt_pk_bf16_f32 v66, v66, v67
	v_cvt_pk_bf16_f32 v67, v68, v69
	v_lshl_add_u64 v[74:75], v[82:83], 0, v[138:139]
	v_mov_b32_dpp v72, v78 row_ror:8 row_mask:0xf bank_mask:0xf bound_ctrl:1
	v_mov_b32_dpp v73, v79 row_ror:8 row_mask:0xf bank_mask:0xf bound_ctrl:1
	v_mov_b32_dpp v68, v80 row_ror:8 row_mask:0xf bank_mask:0xf bound_ctrl:1
	v_mov_b32_dpp v69, v81 row_ror:8 row_mask:0xf bank_mask:0xf bound_ctrl:1
	v_mov_b32_dpp v82, v70 row_ror:8 row_mask:0xf bank_mask:0xf bound_ctrl:1
	v_mov_b32_dpp v83, v71 row_ror:8 row_mask:0xf bank_mask:0xf bound_ctrl:1
	v_mov_b32_dpp v84, v66 row_ror:8 row_mask:0xf bank_mask:0xf bound_ctrl:1
	v_mov_b32_dpp v85, v67 row_ror:8 row_mask:0xf bank_mask:0xf bound_ctrl:1
	v_max_f32_e32 v62, 0, v62
	v_max_f32_e32 v58, 0, v58
	v_max_f32_e32 v63, 0, v63
	v_max_f32_e32 v59, 0, v59
	v_max_f32_e32 v64, 0, v64
	v_max_f32_e32 v60, 0, v60
	v_max_f32_e32 v65, 0, v65
	v_max_f32_e32 v61, 0, v61
	v_max_f32_e32 v54, 0, v54
	v_max_f32_e32 v50, 0, v50
	v_max_f32_e32 v55, 0, v55
	v_max_f32_e32 v51, 0, v51
	v_max_f32_e32 v56, 0, v56
	v_max_f32_e32 v52, 0, v52
	v_max_f32_e32 v57, 0, v57
	v_max_f32_e32 v53, 0, v53
	v_lshl_add_u64 v[76:77], v[74:75], 0, v[140:141]
	v_cndmask_b32_e64 v69, v69, v67, s[2:3]
	v_cndmask_b32_e64 v68, v68, v66, s[2:3]
	v_cndmask_b32_e64 v67, v73, v71, s[2:3]
	v_cndmask_b32_e64 v66, v72, v70, s[2:3]
	v_cndmask_b32_e64 v73, v81, v85, s[2:3]
	v_cndmask_b32_e64 v72, v80, v84, s[2:3]
	v_cndmask_b32_e64 v71, v79, v83, s[2:3]
	v_cndmask_b32_e64 v70, v78, v82, s[2:3]
	v_pk_mul_f32 v[62:63], v[62:63], v[62:63]
	v_pk_mul_f32 v[58:59], v[58:59], v[58:59]
	v_pk_mul_f32 v[64:65], v[64:65], v[64:65]
	v_pk_mul_f32 v[60:61], v[60:61], v[60:61]
	v_pk_mul_f32 v[54:55], v[54:55], v[54:55]
	v_pk_mul_f32 v[50:51], v[50:51], v[50:51]
	v_pk_mul_f32 v[56:57], v[56:57], v[56:57]
	v_pk_mul_f32 v[52:53], v[52:53], v[52:53]
	v_lshl_add_u64 v[74:75], v[74:75], 0, v[142:143]
	global_store_dwordx4 v[76:77], v[70:73], off
	global_store_dwordx4 v[74:75], v[66:69], off
	v_cvt_pk_bf16_f32 v62, v62, v63
	v_cvt_pk_bf16_f32 v63, v64, v65
	v_lshl_add_u64 v[66:67], s[22:23], 0, v[152:153]
	v_cvt_pk_bf16_f32 v64, v58, v59
	v_cvt_pk_bf16_f32 v65, v60, v61
	v_cvt_pk_bf16_f32 v54, v54, v55
	v_cvt_pk_bf16_f32 v55, v56, v57
	v_cvt_pk_bf16_f32 v50, v50, v51
	v_cvt_pk_bf16_f32 v51, v52, v53
	v_lshl_add_u64 v[58:59], v[66:67], 0, v[138:139]
	v_mov_b32_dpp v56, v62 row_ror:8 row_mask:0xf bank_mask:0xf bound_ctrl:1
	v_mov_b32_dpp v57, v63 row_ror:8 row_mask:0xf bank_mask:0xf bound_ctrl:1
	v_mov_b32_dpp v52, v64 row_ror:8 row_mask:0xf bank_mask:0xf bound_ctrl:1
	v_mov_b32_dpp v53, v65 row_ror:8 row_mask:0xf bank_mask:0xf bound_ctrl:1
	v_mov_b32_dpp v66, v54 row_ror:8 row_mask:0xf bank_mask:0xf bound_ctrl:1
	v_mov_b32_dpp v67, v55 row_ror:8 row_mask:0xf bank_mask:0xf bound_ctrl:1
; __device__ __forceinline__ unsigned pk2(float lo, float hi) { const f32x2 v = {lo, hi}; return __builtin_bit_cast(unsigned, __builtin_convertvector(v, bf16x2_t)); }
;     __device__ __forceinline__ void operator()(const f32x4 (&acc)[2][2][4][2], const Unit& u, int wr, int wc, int fr, int fq) const {
;     ...
;         for (int ai = 0; ai < 2; ++ai)
; #pragma unroll
;             for (int m = 0; m < 4; ++m) { unsigned char* rowp = (unsigned char*)(H + ((size_t)(u.pm * (FF / 64) + u.pn * 4 + wc) * 256 + (wr * 64 + fr + ai * 128 + m * 16)) * 64 + 8 * fq); u32x4 w[2];
; #pragma unroll
;                 for (int bj = 0; bj < 2; ++bj) { f32x4 v0 = acc[ai][bj][m][0], v1 = acc[ai][bj][m][1];
; #pragma unroll
;                     for (int j = 0; j < 4; ++j) { const float a = fmaxf(v0[j], 0.f), b = fmaxf(v1[j], 0.f); v0[j] = a * a; v1[j] = b * b; }
;                     w[bj].x = pk2(v0[0], v0[1]); w[bj].y = pk2(v0[2], v0[3]); w[bj].z = pk2(v1[0], v1[1]); w[bj].w = pk2(v1[2], v1[3]); }
;                 store_pair(rowp, (size_t)8 * 64 * 2, 64, w[0], w[1], fr >= 8); }
	v_mov_b32_dpp v68, v50 row_ror:8 row_mask:0xf bank_mask:0xf bound_ctrl:1
	v_mov_b32_dpp v69, v51 row_ror:8 row_mask:0xf bank_mask:0xf bound_ctrl:1
	v_max_f32_e32 v46, 0, v46
	v_max_f32_e32 v42, 0, v42
	v_max_f32_e32 v47, 0, v47
	v_max_f32_e32 v43, 0, v43
	v_max_f32_e32 v48, 0, v48
	v_max_f32_e32 v44, 0, v44
	v_max_f32_e32 v49, 0, v49
	v_max_f32_e32 v45, 0, v45
	v_max_f32_e32 v38, 0, v38
	v_max_f32_e32 v34, 0, v34
	v_max_f32_e32 v39, 0, v39
	v_max_f32_e32 v35, 0, v35
	v_max_f32_e32 v40, 0, v40
	v_max_f32_e32 v36, 0, v36
	v_max_f32_e32 v41, 0, v41
	v_max_f32_e32 v37, 0, v37
	v_lshl_add_u64 v[60:61], v[58:59], 0, v[140:141]
	v_cndmask_b32_e64 v53, v53, v51, s[2:3]
	v_cndmask_b32_e64 v52, v52, v50, s[2:3]
	v_cndmask_b32_e64 v51, v57, v55, s[2:3]
	v_cndmask_b32_e64 v50, v56, v54, s[2:3]
	v_cndmask_b32_e64 v57, v65, v69, s[2:3]
	v_cndmask_b32_e64 v56, v64, v68, s[2:3]
	v_cndmask_b32_e64 v55, v63, v67, s[2:3]
	v_cndmask_b32_e64 v54, v62, v66, s[2:3]
	v_pk_mul_f32 v[46:47], v[46:47], v[46:47]
	v_pk_mul_f32 v[42:43], v[42:43], v[42:43]
	v_pk_mul_f32 v[48:49], v[48:49], v[48:49]
	v_pk_mul_f32 v[44:45], v[44:45], v[44:45]
	v_pk_mul_f32 v[38:39], v[38:39], v[38:39]
	v_pk_mul_f32 v[34:35], v[34:35], v[34:35]
	v_pk_mul_f32 v[40:41], v[40:41], v[40:41]
	v_pk_mul_f32 v[36:37], v[36:37], v[36:37]
	v_lshl_add_u64 v[58:59], v[58:59], 0, v[142:143]
	global_store_dwordx4 v[60:61], v[54:57], off
	global_store_dwordx4 v[58:59], v[50:53], off
	v_cvt_pk_bf16_f32 v46, v46, v47
	v_cvt_pk_bf16_f32 v47, v48, v49
	v_lshl_add_u64 v[50:51], s[22:23], 0, v[154:155]
	v_cvt_pk_bf16_f32 v48, v42, v43
	v_cvt_pk_bf16_f32 v49, v44, v45
	v_cvt_pk_bf16_f32 v38, v38, v39
	v_cvt_pk_bf16_f32 v39, v40, v41
	v_cvt_pk_bf16_f32 v34, v34, v35
	v_cvt_pk_bf16_f32 v35, v36, v37
	v_lshl_add_u64 v[42:43], v[50:51], 0, v[138:139]
	v_mov_b32_dpp v40, v46 row_ror:8 row_mask:0xf bank_mask:0xf bound_ctrl:1
	v_mov_b32_dpp v41, v47 row_ror:8 row_mask:0xf bank_mask:0xf bound_ctrl:1
	v_mov_b32_dpp v36, v48 row_ror:8 row_mask:0xf bank_mask:0xf bound_ctrl:1
	v_mov_b32_dpp v37, v49 row_ror:8 row_mask:0xf bank_mask:0xf bound_ctrl:1
	v_mov_b32_dpp v50, v38 row_ror:8 row_mask:0xf bank_mask:0xf bound_ctrl:1
	v_mov_b32_dpp v51, v39 row_ror:8 row_mask:0xf bank_mask:0xf bound_ctrl:1
	v_mov_b32_dpp v52, v34 row_ror:8 row_mask:0xf bank_mask:0xf bound_ctrl:1
	v_mov_b32_dpp v53, v35 row_ror:8 row_mask:0xf bank_mask:0xf bound_ctrl:1
	v_max_f32_e32 v30, 0, v30
	v_max_f32_e32 v26, 0, v26
	v_max_f32_e32 v31, 0, v31
	v_max_f32_e32 v27, 0, v27
	v_max_f32_e32 v32, 0, v32
	v_max_f32_e32 v28, 0, v28
	v_max_f32_e32 v33, 0, v33
	v_max_f32_e32 v29, 0, v29
	v_max_f32_e32 v22, 0, v22
	v_max_f32_e32 v18, 0, v18
	v_max_f32_e32 v23, 0, v23
	v_max_f32_e32 v19, 0, v19
	v_max_f32_e32 v24, 0, v24
	v_max_f32_e32 v20, 0, v20
	v_max_f32_e32 v25, 0, v25
	v_max_f32_e32 v21, 0, v21
	v_lshl_add_u64 v[44:45], v[42:43], 0, v[140:141]
	v_cndmask_b32_e64 v37, v37, v35, s[2:3]
	v_cndmask_b32_e64 v36, v36, v34, s[2:3]
	v_cndmask_b32_e64 v35, v41, v39, s[2:3]
	v_cndmask_b32_e64 v34, v40, v38, s[2:3]
	v_cndmask_b32_e64 v41, v49, v53, s[2:3]
	v_cndmask_b32_e64 v40, v48, v52, s[2:3]
	v_cndmask_b32_e64 v39, v47, v51, s[2:3]
	v_cndmask_b32_e64 v38, v46, v50, s[2:3]
	v_pk_mul_f32 v[30:31], v[30:31], v[30:31]
	v_pk_mul_f32 v[26:27], v[26:27], v[26:27]
	v_pk_mul_f32 v[32:33], v[32:33], v[32:33]
	v_pk_mul_f32 v[28:29], v[28:29], v[28:29]
	v_pk_mul_f32 v[22:23], v[22:23], v[22:23]
	v_pk_mul_f32 v[18:19], v[18:19], v[18:19]
	v_pk_mul_f32 v[24:25], v[24:25], v[24:25]
	v_pk_mul_f32 v[20:21], v[20:21], v[20:21]
	v_lshl_add_u64 v[42:43], v[42:43], 0, v[142:143]
	global_store_dwordx4 v[44:45], v[38:41], off
	global_store_dwordx4 v[42:43], v[34:37], off
	v_cvt_pk_bf16_f32 v30, v30, v31
	v_cvt_pk_bf16_f32 v31, v32, v33
	v_lshl_add_u64 v[34:35], s[22:23], 0, v[156:157]
; __device__ __forceinline__ unsigned pk2(float lo, float hi) { const f32x2 v = {lo, hi}; return __builtin_bit_cast(unsigned, __builtin_convertvector(v, bf16x2_t)); }
; #define PG8_BAR __builtin_amdgcn_s_barrier()
; template <class Epi, class Sched, bool ABLK = false, bool ALIGN_EPI = true, bool SP2 = true, bool BBLK = true>
; __device__ __forceinline__ void gemm_phase(LAS unsigned char* lds, const Gemm g, const Sched& S, const Epi& E) {
;     ...
;         if constexpr (ALIGN_EPI) { if (wr == 0) PG8_BAR; }
;         E(acc, cur, wr, wc, fr, fq); S.done(cur);
;         if (!has_next) break;
; #pragma unroll
;         for (int a = 0; a < 2; ++a)
; #pragma unroll
;             for (int b = 0; b < 2; ++b)
; #pragma unroll
;                 for (int m = 0; m < 4; ++m)
; #pragma unroll
;                     for (int n = 0; n < 2; ++n) acc[a][b][m][n] = (f32x4){0.f, 0.f, 0.f, 0.f};
;         cur = nxt; uA = nuA; tbA = ntbA; cB = nB; ++ui;
;         if constexpr (ALIGN_EPI) { if (wr == 1) PG8_BAR; }
;     __device__ __forceinline__ void operator()(const f32x4 (&acc)[2][2][4][2], const Unit& u, int wr, int wc, int fr, int fq) const {
;     ...
;         for (int ai = 0; ai < 2; ++ai)
; #pragma unroll
;             for (int m = 0; m < 4; ++m) { unsigned char* rowp = (unsigned char*)(H + ((size_t)(u.pm * (FF / 64) + u.pn * 4 + wc) * 256 + (wr * 64 + fr + ai * 128 + m * 16)) * 64 + 8 * fq); u32x4 w[2];
; #pragma unroll
;                 for (int bj = 0; bj < 2; ++bj) { f32x4 v0 = acc[ai][bj][m][0], v1 = acc[ai][bj][m][1];
; #pragma unroll
;                     for (int j = 0; j < 4; ++j) { const float a = fmaxf(v0[j], 0.f), b = fmaxf(v1[j], 0.f); v0[j] = a * a; v1[j] = b * b; }
;                     w[bj].x = pk2(v0[0], v0[1]); w[bj].y = pk2(v0[2], v0[3]); w[bj].z = pk2(v1[0], v1[1]); w[bj].w = pk2(v1[2], v1[3]); }
;                 store_pair(rowp, (size_t)8 * 64 * 2, 64, w[0], w[1], fr >= 8); }
	v_cvt_pk_bf16_f32 v32, v26, v27
	v_cvt_pk_bf16_f32 v33, v28, v29
	v_cvt_pk_bf16_f32 v22, v22, v23
	v_cvt_pk_bf16_f32 v23, v24, v25
	v_cvt_pk_bf16_f32 v18, v18, v19
	v_cvt_pk_bf16_f32 v19, v20, v21
	v_lshl_add_u64 v[26:27], v[34:35], 0, v[138:139]
	v_mov_b32_dpp v24, v30 row_ror:8 row_mask:0xf bank_mask:0xf bound_ctrl:1
	v_mov_b32_dpp v25, v31 row_ror:8 row_mask:0xf bank_mask:0xf bound_ctrl:1
	v_mov_b32_dpp v20, v32 row_ror:8 row_mask:0xf bank_mask:0xf bound_ctrl:1
	v_mov_b32_dpp v21, v33 row_ror:8 row_mask:0xf bank_mask:0xf bound_ctrl:1
	v_mov_b32_dpp v34, v22 row_ror:8 row_mask:0xf bank_mask:0xf bound_ctrl:1
	v_mov_b32_dpp v35, v23 row_ror:8 row_mask:0xf bank_mask:0xf bound_ctrl:1
	v_mov_b32_dpp v36, v18 row_ror:8 row_mask:0xf bank_mask:0xf bound_ctrl:1
	v_mov_b32_dpp v37, v19 row_ror:8 row_mask:0xf bank_mask:0xf bound_ctrl:1
	v_max_f32_e32 v14, 0, v14
	v_max_f32_e32 v10, 0, v10
	v_max_f32_e32 v15, 0, v15
	v_max_f32_e32 v11, 0, v11
	v_max_f32_e32 v16, 0, v16
	v_max_f32_e32 v12, 0, v12
	v_max_f32_e32 v17, 0, v17
	v_max_f32_e32 v13, 0, v13
	v_max_f32_e32 v6, 0, v6
	v_max_f32_e32 v2, 0, v2
	v_max_f32_e32 v7, 0, v7
	v_max_f32_e32 v3, 0, v3
	v_max_f32_e32 v8, 0, v8
	v_max_f32_e32 v4, 0, v4
	v_max_f32_e32 v9, 0, v9
	v_max_f32_e32 v5, 0, v5
	v_lshl_add_u64 v[28:29], v[26:27], 0, v[140:141]
	v_cndmask_b32_e64 v21, v21, v19, s[2:3]
	v_cndmask_b32_e64 v20, v20, v18, s[2:3]
	v_cndmask_b32_e64 v19, v25, v23, s[2:3]
	v_cndmask_b32_e64 v18, v24, v22, s[2:3]
	v_cndmask_b32_e64 v25, v33, v37, s[2:3]
	v_cndmask_b32_e64 v24, v32, v36, s[2:3]
	v_cndmask_b32_e64 v23, v31, v35, s[2:3]
	v_cndmask_b32_e64 v22, v30, v34, s[2:3]
	v_pk_mul_f32 v[14:15], v[14:15], v[14:15]
	v_pk_mul_f32 v[10:11], v[10:11], v[10:11]
	v_pk_mul_f32 v[16:17], v[16:17], v[16:17]
	v_pk_mul_f32 v[12:13], v[12:13], v[12:13]
	v_pk_mul_f32 v[6:7], v[6:7], v[6:7]
	v_pk_mul_f32 v[2:3], v[2:3], v[2:3]
	v_pk_mul_f32 v[8:9], v[8:9], v[8:9]
	v_pk_mul_f32 v[4:5], v[4:5], v[4:5]
	v_lshl_add_u64 v[26:27], v[26:27], 0, v[142:143]
	global_store_dwordx4 v[28:29], v[22:25], off
	global_store_dwordx4 v[26:27], v[18:21], off
	v_cvt_pk_bf16_f32 v14, v14, v15
	v_cvt_pk_bf16_f32 v15, v16, v17
	v_lshl_add_u64 v[18:19], s[22:23], 0, v[158:159]
	v_cvt_pk_bf16_f32 v16, v10, v11
	v_cvt_pk_bf16_f32 v17, v12, v13
	v_cvt_pk_bf16_f32 v6, v6, v7
	v_cvt_pk_bf16_f32 v7, v8, v9
	v_cvt_pk_bf16_f32 v2, v2, v3
	v_cvt_pk_bf16_f32 v3, v4, v5
	v_lshl_add_u64 v[10:11], v[18:19], 0, v[138:139]
	v_mov_b32_dpp v8, v14 row_ror:8 row_mask:0xf bank_mask:0xf bound_ctrl:1
	v_mov_b32_dpp v9, v15 row_ror:8 row_mask:0xf bank_mask:0xf bound_ctrl:1
	v_mov_b32_dpp v4, v16 row_ror:8 row_mask:0xf bank_mask:0xf bound_ctrl:1
	v_mov_b32_dpp v5, v17 row_ror:8 row_mask:0xf bank_mask:0xf bound_ctrl:1
	v_mov_b32_dpp v18, v6 row_ror:8 row_mask:0xf bank_mask:0xf bound_ctrl:1
	v_mov_b32_dpp v19, v7 row_ror:8 row_mask:0xf bank_mask:0xf bound_ctrl:1
	v_mov_b32_dpp v20, v2 row_ror:8 row_mask:0xf bank_mask:0xf bound_ctrl:1
	v_mov_b32_dpp v21, v3 row_ror:8 row_mask:0xf bank_mask:0xf bound_ctrl:1
	v_lshl_add_u64 v[12:13], v[10:11], 0, v[140:141]
	v_cndmask_b32_e64 v5, v5, v3, s[2:3]
	v_cndmask_b32_e64 v4, v4, v2, s[2:3]
	v_cndmask_b32_e64 v3, v9, v7, s[2:3]
	v_cndmask_b32_e64 v2, v8, v6, s[2:3]
	v_cndmask_b32_e64 v9, v17, v21, s[2:3]
	v_cndmask_b32_e64 v8, v16, v20, s[2:3]
	v_cndmask_b32_e64 v7, v15, v19, s[2:3]
	v_cndmask_b32_e64 v6, v14, v18, s[2:3]
	s_and_b64 vcc, exec, s[10:11]
	s_cbranch_vccz .LBB0_2266
	s_barrier
.LBB0_2266:
	s_andn2_b64 vcc, exec, s[18:19]
	s_mov_b64 s[4:5], -1
	v_lshl_add_u64 v[10:11], v[10:11], 0, v[142:143]
	global_store_dwordx4 v[12:13], v[6:9], off
	global_store_dwordx4 v[10:11], v[2:5], off
	s_cbranch_vccnz .LBB0_2259
	s_andn2_b64 vcc, exec, s[6:7]
	s_cbranch_vccnz .LBB0_2258
	s_barrier
	s_branch .LBB0_2258

; #define PG8_STAGE(bufoff, gbase, voff) do { _Pragma("unroll") for (int _i = 0; _i < 2; ++_i) \
;         __builtin_amdgcn_global_load_lds((const unsigned*)((const char*)(gbase) + (voff)[_i]), (LAS unsigned*)(lds + (bufoff) + ldsw + _i * 8192), 16, 0, 0); } while (0)
; #define PG8_LDA(dst, b, h) do { _Pragma("unroll") for (int m = 0; m < 4; ++m) _Pragma("unroll") for (int k = 0; k < 2; ++k) dst[m][k] = *(const LAS bf16x8*)(lds + PG8_SA(b, h) + aoff + m * 2048 + k * 1024); } while (0)
; #define PG8_LDB(dst, b, h) do { _Pragma("unroll") for (int n = 0; n < 2; ++n) _Pragma("unroll") for (int k = 0; k < 2; ++k) dst[n][k] = *(const LAS bf16x8*)(lds + PG8_SB(b, h) + boff + n * 2048 + k * 1024); } while (0)
; #define PG8_MMA(ai, bj, At, Bt) do { __builtin_amdgcn_s_setprio(1); _Pragma("unroll") for (int m = 0; m < 4; ++m) _Pragma("unroll") for (int n = 0; n < 2; ++n) _Pragma("unroll") for (int k = 0; k < 2; ++k) \
;         acc[ai][bj][m][n] = __builtin_amdgcn_mfma_f32_16x16x32_bf16(Bt[n][k], At[m][k], acc[ai][bj][m][n], 0, 0, 0); __builtin_amdgcn_s_setprio(0); } while (0)
; #define PG8_WAIT_V(n) asm volatile("s_waitcnt vmcnt(" #n ")" ::: "memory")
; #define PG8_WAIT_L(n) asm volatile("s_waitcnt lgkmcnt(" #n ")" ::: "memory")
; template <class Epi, class Sched, bool ABLK = false, bool ALIGN_EPI = true, bool SP2 = true, bool BBLK = true>
; __device__ __forceinline__ void gemm_phase(LAS unsigned char* lds, const Gemm g, const Sched& S, const Epi& E) {
;     ...
;             const char* a1 = a_tile(uA, tbA + t + 1);
;             const char* a2 = last ? a_tile(nuA, ntbA) : a_tile(uA, tbA + t + 2); const char* b2 = last ? nB : cB + (size_t)(t + 2) * kstepB;
;             const char* a3 = last ? a_tile(nuA, ntbA + 1) : a_tile(uA, tbA + t + 3); const char* b3 = b2 + kstepB;
;             if (last && has_next) S.a_ready(nxt);
;             if constexpr (SP2) {
;             PG8_LDB(B0, 0, 0); PG8_LDB(B1, 0, 1); PG8_SCHED; PG8_LDA(At, 0, 0); PG8_STAGE(PG8_SA(1, 1), a1 + hstepA, voffA);
;             PG8_WAIT_V(8); PG8_WAIT_L(0); PG8_BAR; PG8_MMA(0, 0, At, B0); PG8_MMA(0, 1, At, B1); PG8_BAR; PG8_SCHED;
;             PG8_LDA(At, 0, 1); PG8_STAGE(PG8_SB(0, 0), b2, voffB); PG8_STAGE(PG8_SB(0, 1), b2 + hstepB, voffB); PG8_STAGE(PG8_SA(0, 0), a2, voffA);
;             PG8_WAIT_V(8); PG8_WAIT_L(0); PG8_BAR; PG8_MMA(1, 0, At, B0); PG8_MMA(1, 1, At, B1); PG8_BAR; PG8_SCHED;
.LBB0_2328:
	ds_read_b128 v[152:155], v148
	ds_read_b128 v[156:159], v148 offset:1024
	ds_read_b128 v[160:163], v148 offset:2048
	ds_read_b128 v[164:167], v148 offset:3072
	ds_read_b128 v[168:171], v149
	ds_read_b128 v[172:175], v149 offset:1024
	ds_read_b128 v[176:179], v149 offset:2048
	ds_read_b128 v[180:183], v149 offset:3072
	s_add_u32 s40, s64, s38
	s_addc_u32 s41, s65, s39
	s_add_u32 s44, s40, 0x10000
	s_addc_u32 s45, s41, 0
	s_add_i32 s67, s67, 2
	s_add_u32 s42, s62, s38
	s_addc_u32 s43, s63, s39
	s_add_u32 s40, s40, 0x18000
	s_addc_u32 s41, s41, 0
	s_cmp_eq_u32 s66, s38
	s_cselect_b32 s41, s59, s41
	s_cselect_b32 s40, s58, s40
	s_cselect_b32 s43, s4, s43
	s_cselect_b32 s42, s5, s42
	s_cselect_b32 s45, s57, s45
	s_cselect_b32 s44, s35, s44
	v_lshl_add_u64 v[216:217], v[142:143], 0, s[38:39]
	s_add_i32 m0, s49, 0xc000
	ds_read_b128 v[184:187], v150
	ds_read_b128 v[188:191], v150 offset:1024
	ds_read_b128 v[192:195], v150 offset:2048
	ds_read_b128 v[196:199], v150 offset:3072
	ds_read_b128 v[200:203], v150 offset:4096
	ds_read_b128 v[204:207], v150 offset:5120
	ds_read_b128 v[208:211], v150 offset:6144
	ds_read_b128 v[212:215], v150 offset:7168
	global_load_lds_dwordx4 v[216:217], off
	v_lshl_add_u64 v[216:217], v[144:145], 0, s[38:39]
	s_add_i32 m0, s49, 0xe000
	s_nop 0
	global_load_lds_dwordx4 v[216:217], off
	s_waitcnt vmcnt(8) lgkmcnt(0)
	s_barrier
	v_mfma_f32_16x16x32_bf16 v[126:129], v[152:155], v[184:187], v[126:129]
	v_mfma_f32_16x16x32_bf16 v[122:125], v[160:163], v[184:187], v[122:125]
	v_mfma_f32_16x16x32_bf16 v[110:113], v[152:155], v[192:195], v[110:113]
	v_mfma_f32_16x16x32_bf16 v[106:109], v[160:163], v[192:195], v[106:109]
	v_mfma_f32_16x16x32_bf16 v[94:97], v[152:155], v[200:203], v[94:97]
	v_mfma_f32_16x16x32_bf16 v[90:93], v[160:163], v[200:203], v[90:93]
	v_mfma_f32_16x16x32_bf16 v[78:81], v[152:155], v[208:211], v[78:81]
	v_mfma_f32_16x16x32_bf16 v[74:77], v[160:163], v[208:211], v[74:77]
	v_mfma_f32_16x16x32_bf16 v[126:129], v[156:159], v[188:191], v[126:129]
	v_mfma_f32_16x16x32_bf16 v[122:125], v[164:167], v[188:191], v[122:125]
	v_mfma_f32_16x16x32_bf16 v[110:113], v[156:159], v[196:199], v[110:113]
	v_mfma_f32_16x16x32_bf16 v[106:109], v[164:167], v[196:199], v[106:109]
	v_mfma_f32_16x16x32_bf16 v[94:97], v[156:159], v[204:207], v[94:97]
	v_mfma_f32_16x16x32_bf16 v[90:93], v[164:167], v[204:207], v[90:93]
	v_mfma_f32_16x16x32_bf16 v[78:81], v[156:159], v[212:215], v[78:81]
	v_mfma_f32_16x16x32_bf16 v[74:77], v[164:167], v[212:215], v[74:77]
	v_mfma_f32_16x16x32_bf16 v[118:121], v[168:171], v[184:187], v[118:121]
	v_mfma_f32_16x16x32_bf16 v[114:117], v[176:179], v[184:187], v[114:117]
	v_mfma_f32_16x16x32_bf16 v[102:105], v[168:171], v[192:195], v[102:105]
	v_mfma_f32_16x16x32_bf16 v[98:101], v[176:179], v[192:195], v[98:101]
	v_mfma_f32_16x16x32_bf16 v[86:89], v[168:171], v[200:203], v[86:89]
	v_mfma_f32_16x16x32_bf16 v[82:85], v[176:179], v[200:203], v[82:85]
	v_mfma_f32_16x16x32_bf16 v[70:73], v[168:171], v[208:211], v[70:73]
	v_mfma_f32_16x16x32_bf16 v[66:69], v[176:179], v[208:211], v[66:69]
	v_mfma_f32_16x16x32_bf16 v[118:121], v[172:175], v[188:191], v[118:121]
	v_mfma_f32_16x16x32_bf16 v[114:117], v[180:183], v[188:191], v[114:117]
	v_mfma_f32_16x16x32_bf16 v[102:105], v[172:175], v[196:199], v[102:105]
	v_mfma_f32_16x16x32_bf16 v[98:101], v[180:183], v[196:199], v[98:101]
	v_mfma_f32_16x16x32_bf16 v[86:89], v[172:175], v[204:207], v[86:89]
	v_mfma_f32_16x16x32_bf16 v[82:85], v[180:183], v[204:207], v[82:85]
	v_mfma_f32_16x16x32_bf16 v[70:73], v[172:175], v[212:215], v[70:73]
	v_mfma_f32_16x16x32_bf16 v[66:69], v[180:183], v[212:215], v[66:69]
	s_barrier
	s_add_i32 s70, s72, s48
	s_mov_b32 m0, s70
	ds_read_b128 v[184:187], v150 offset:16384
	ds_read_b128 v[188:191], v150 offset:17408
	ds_read_b128 v[192:195], v150 offset:18432
	ds_read_b128 v[196:199], v150 offset:19456
	ds_read_b128 v[200:203], v150 offset:20480
	ds_read_b128 v[204:207], v150 offset:21504
	ds_read_b128 v[208:211], v150 offset:22528
	ds_read_b128 v[212:215], v150 offset:23552
	global_load_lds_dwordx4 v130, s[42:43]
	s_add_i32 m0, s70, 0x2000
	s_add_u32 s76, s42, 0x4000
	s_addc_u32 s77, s43, 0
	s_add_i32 s70, s73, s48
	global_load_lds_dwordx4 v132, s[42:43]
	s_mov_b32 m0, s70
	s_nop 0
	global_load_lds_dwordx4 v130, s[76:77]
	s_add_i32 m0, s70, 0x2000
	s_nop 0
	global_load_lds_dwordx4 v132, s[76:77]
	s_mov_b32 m0, s49
	s_nop 0
	global_load_lds_dwordx4 v130, s[44:45]
	s_mov_b32 m0, s50
	s_nop 0
	global_load_lds_dwordx4 v132, s[44:45]
	s_waitcnt vmcnt(8) lgkmcnt(0)
	s_barrier
; #define PG8_STAGE(bufoff, gbase, voff) do { _Pragma("unroll") for (int _i = 0; _i < 2; ++_i) \
;         __builtin_amdgcn_global_load_lds((const unsigned*)((const char*)(gbase) + (voff)[_i]), (LAS unsigned*)(lds + (bufoff) + ldsw + _i * 8192), 16, 0, 0); } while (0)
; #define PG8_LDA(dst, b, h) do { _Pragma("unroll") for (int m = 0; m < 4; ++m) _Pragma("unroll") for (int k = 0; k < 2; ++k) dst[m][k] = *(const LAS bf16x8*)(lds + PG8_SA(b, h) + aoff + m * 2048 + k * 1024); } while (0)
; #define PG8_LDB(dst, b, h) do { _Pragma("unroll") for (int n = 0; n < 2; ++n) _Pragma("unroll") for (int k = 0; k < 2; ++k) dst[n][k] = *(const LAS bf16x8*)(lds + PG8_SB(b, h) + boff + n * 2048 + k * 1024); } while (0)
; #define PG8_MMA(ai, bj, At, Bt) do { __builtin_amdgcn_s_setprio(1); _Pragma("unroll") for (int m = 0; m < 4; ++m) _Pragma("unroll") for (int n = 0; n < 2; ++n) _Pragma("unroll") for (int k = 0; k < 2; ++k) \
;         acc[ai][bj][m][n] = __builtin_amdgcn_mfma_f32_16x16x32_bf16(Bt[n][k], At[m][k], acc[ai][bj][m][n], 0, 0, 0); __builtin_amdgcn_s_setprio(0); } while (0)
; #define PG8_WAIT_V(n) asm volatile("s_waitcnt vmcnt(" #n ")" ::: "memory")
; #define PG8_WAIT_L(n) asm volatile("s_waitcnt lgkmcnt(" #n ")" ::: "memory")
; #define PG8_BAR __builtin_amdgcn_s_barrier()
; #define PG8_SCHED __builtin_amdgcn_sched_barrier(0)
; template <class Epi, class Sched, bool ABLK = false, bool ALIGN_EPI = true, bool SP2 = true, bool BBLK = true>
; __device__ __forceinline__ void gemm_phase(LAS unsigned char* lds, const Gemm g, const Sched& S, const Epi& E) {
;     ...
;             PG8_WAIT_V(8); PG8_WAIT_L(0); PG8_BAR; PG8_MMA(1, 0, At, B0); PG8_MMA(1, 1, At, B1); PG8_BAR; PG8_SCHED;
;             PG8_LDB(B0, 1, 0); PG8_LDB(B1, 1, 1); PG8_SCHED; PG8_LDA(At, 1, 0); PG8_STAGE(PG8_SA(0, 1), a2 + hstepA, voffA);
;             PG8_WAIT_V(8); PG8_WAIT_L(0); PG8_BAR; PG8_MMA(0, 0, At, B0); PG8_MMA(0, 1, At, B1); PG8_BAR; PG8_SCHED;
	v_mfma_f32_16x16x32_bf16 v[62:65], v[152:155], v[184:187], v[62:65]
	v_mfma_f32_16x16x32_bf16 v[58:61], v[160:163], v[184:187], v[58:61]
	v_mfma_f32_16x16x32_bf16 v[46:49], v[152:155], v[192:195], v[46:49]
	v_mfma_f32_16x16x32_bf16 v[42:45], v[160:163], v[192:195], v[42:45]
	v_mfma_f32_16x16x32_bf16 v[30:33], v[152:155], v[200:203], v[30:33]
	v_mfma_f32_16x16x32_bf16 v[26:29], v[160:163], v[200:203], v[26:29]
	v_mfma_f32_16x16x32_bf16 v[14:17], v[152:155], v[208:211], v[14:17]
	v_mfma_f32_16x16x32_bf16 v[10:13], v[160:163], v[208:211], v[10:13]
	v_mfma_f32_16x16x32_bf16 v[62:65], v[156:159], v[188:191], v[62:65]
	v_mfma_f32_16x16x32_bf16 v[58:61], v[164:167], v[188:191], v[58:61]
	v_mfma_f32_16x16x32_bf16 v[46:49], v[156:159], v[196:199], v[46:49]
	v_mfma_f32_16x16x32_bf16 v[42:45], v[164:167], v[196:199], v[42:45]
	v_mfma_f32_16x16x32_bf16 v[30:33], v[156:159], v[204:207], v[30:33]
	v_mfma_f32_16x16x32_bf16 v[26:29], v[164:167], v[204:207], v[26:29]
	v_mfma_f32_16x16x32_bf16 v[14:17], v[156:159], v[212:215], v[14:17]
	v_mfma_f32_16x16x32_bf16 v[10:13], v[164:167], v[212:215], v[10:13]
	v_mfma_f32_16x16x32_bf16 v[54:57], v[168:171], v[184:187], v[54:57]
	v_mfma_f32_16x16x32_bf16 v[50:53], v[176:179], v[184:187], v[50:53]
	v_mfma_f32_16x16x32_bf16 v[38:41], v[168:171], v[192:195], v[38:41]
	v_mfma_f32_16x16x32_bf16 v[34:37], v[176:179], v[192:195], v[34:37]
	v_mfma_f32_16x16x32_bf16 v[22:25], v[168:171], v[200:203], v[22:25]
	v_mfma_f32_16x16x32_bf16 v[18:21], v[176:179], v[200:203], v[18:21]
	v_mfma_f32_16x16x32_bf16 v[6:9], v[168:171], v[208:211], v[6:9]
	v_mfma_f32_16x16x32_bf16 v[2:5], v[176:179], v[208:211], v[2:5]
	v_mfma_f32_16x16x32_bf16 v[54:57], v[172:175], v[188:191], v[54:57]
	v_mfma_f32_16x16x32_bf16 v[50:53], v[180:183], v[188:191], v[50:53]
	v_mfma_f32_16x16x32_bf16 v[38:41], v[172:175], v[196:199], v[38:41]
	v_mfma_f32_16x16x32_bf16 v[34:37], v[180:183], v[196:199], v[34:37]
	v_mfma_f32_16x16x32_bf16 v[22:25], v[172:175], v[204:207], v[22:25]
	v_mfma_f32_16x16x32_bf16 v[18:21], v[180:183], v[204:207], v[18:21]
	v_mfma_f32_16x16x32_bf16 v[6:9], v[172:175], v[212:215], v[6:9]
	v_mfma_f32_16x16x32_bf16 v[2:5], v[180:183], v[212:215], v[2:5]
	s_barrier
	v_add_u32_e32 v151, s60, v146
	ds_read_b128 v[152:155], v151
	ds_read_b128 v[156:159], v151 offset:1024
	ds_read_b128 v[160:163], v151 offset:2048
	ds_read_b128 v[164:167], v151 offset:3072
	v_add_u32_e32 v151, s61, v146
	ds_read_b128 v[168:171], v151
	ds_read_b128 v[172:175], v151 offset:1024
	ds_read_b128 v[176:179], v151 offset:2048
	ds_read_b128 v[180:183], v151 offset:3072
	s_add_u32 s44, s44, 0x4000
	s_addc_u32 s45, s45, 0
	s_mov_b32 m0, s51
	ds_read_b128 v[184:187], v150 offset:32768
	ds_read_b128 v[188:191], v150 offset:33792
	ds_read_b128 v[192:195], v150 offset:34816
	ds_read_b128 v[196:199], v150 offset:35840
	ds_read_b128 v[200:203], v150 offset:36864
	ds_read_b128 v[204:207], v150 offset:37888
	ds_read_b128 v[208:211], v150 offset:38912
	ds_read_b128 v[212:215], v150 offset:39936
	global_load_lds_dwordx4 v130, s[44:45]
	s_mov_b32 m0, s52
	s_nop 0
	global_load_lds_dwordx4 v132, s[44:45]
	s_waitcnt vmcnt(8) lgkmcnt(0)
	s_barrier
	v_mfma_f32_16x16x32_bf16 v[126:129], v[152:155], v[184:187], v[126:129]
	v_mfma_f32_16x16x32_bf16 v[122:125], v[160:163], v[184:187], v[122:125]
	v_mfma_f32_16x16x32_bf16 v[110:113], v[152:155], v[192:195], v[110:113]
	v_mfma_f32_16x16x32_bf16 v[106:109], v[160:163], v[192:195], v[106:109]
	v_mfma_f32_16x16x32_bf16 v[94:97], v[152:155], v[200:203], v[94:97]
	v_mfma_f32_16x16x32_bf16 v[90:93], v[160:163], v[200:203], v[90:93]
	v_mfma_f32_16x16x32_bf16 v[78:81], v[152:155], v[208:211], v[78:81]
	v_mfma_f32_16x16x32_bf16 v[74:77], v[160:163], v[208:211], v[74:77]
	v_mfma_f32_16x16x32_bf16 v[126:129], v[156:159], v[188:191], v[126:129]
	v_mfma_f32_16x16x32_bf16 v[122:125], v[164:167], v[188:191], v[122:125]
	v_mfma_f32_16x16x32_bf16 v[110:113], v[156:159], v[196:199], v[110:113]
	v_mfma_f32_16x16x32_bf16 v[106:109], v[164:167], v[196:199], v[106:109]
	v_mfma_f32_16x16x32_bf16 v[94:97], v[156:159], v[204:207], v[94:97]
	v_mfma_f32_16x16x32_bf16 v[90:93], v[164:167], v[204:207], v[90:93]
	v_mfma_f32_16x16x32_bf16 v[78:81], v[156:159], v[212:215], v[78:81]
	v_mfma_f32_16x16x32_bf16 v[74:77], v[164:167], v[212:215], v[74:77]
	v_mfma_f32_16x16x32_bf16 v[118:121], v[168:171], v[184:187], v[118:121]
	v_mfma_f32_16x16x32_bf16 v[114:117], v[176:179], v[184:187], v[114:117]
	v_mfma_f32_16x16x32_bf16 v[102:105], v[168:171], v[192:195], v[102:105]
	v_mfma_f32_16x16x32_bf16 v[98:101], v[176:179], v[192:195], v[98:101]
	v_mfma_f32_16x16x32_bf16 v[86:89], v[168:171], v[200:203], v[86:89]
	v_mfma_f32_16x16x32_bf16 v[82:85], v[176:179], v[200:203], v[82:85]
	v_mfma_f32_16x16x32_bf16 v[70:73], v[168:171], v[208:211], v[70:73]
	v_mfma_f32_16x16x32_bf16 v[66:69], v[176:179], v[208:211], v[66:69]
	v_mfma_f32_16x16x32_bf16 v[118:121], v[172:175], v[188:191], v[118:121]
	v_mfma_f32_16x16x32_bf16 v[114:117], v[180:183], v[188:191], v[114:117]
	v_mfma_f32_16x16x32_bf16 v[102:105], v[172:175], v[196:199], v[102:105]
	v_mfma_f32_16x16x32_bf16 v[98:101], v[180:183], v[196:199], v[98:101]
	v_mfma_f32_16x16x32_bf16 v[86:89], v[172:175], v[204:207], v[86:89]
	v_mfma_f32_16x16x32_bf16 v[82:85], v[180:183], v[204:207], v[82:85]
	v_mfma_f32_16x16x32_bf16 v[70:73], v[172:175], v[212:215], v[70:73]
	v_mfma_f32_16x16x32_bf16 v[66:69], v[180:183], v[212:215], v[66:69]
	s_barrier
; __device__ __forceinline__ unsigned pk2(float lo, float hi) { const f32x2 v = {lo, hi}; return __builtin_bit_cast(unsigned, __builtin_convertvector(v, bf16x2_t)); }
; #define PG8_STAGE(bufoff, gbase, voff) do { _Pragma("unroll") for (int _i = 0; _i < 2; ++_i) \
;         __builtin_amdgcn_global_load_lds((const unsigned*)((const char*)(gbase) + (voff)[_i]), (LAS unsigned*)(lds + (bufoff) + ldsw + _i * 8192), 16, 0, 0); } while (0)
; #define PG8_LDA(dst, b, h) do { _Pragma("unroll") for (int m = 0; m < 4; ++m) _Pragma("unroll") for (int k = 0; k < 2; ++k) dst[m][k] = *(const LAS bf16x8*)(lds + PG8_SA(b, h) + aoff + m * 2048 + k * 1024); } while (0)
; #define PG8_MMA(ai, bj, At, Bt) do { __builtin_amdgcn_s_setprio(1); _Pragma("unroll") for (int m = 0; m < 4; ++m) _Pragma("unroll") for (int n = 0; n < 2; ++n) _Pragma("unroll") for (int k = 0; k < 2; ++k) \
;         acc[ai][bj][m][n] = __builtin_amdgcn_mfma_f32_16x16x32_bf16(Bt[n][k], At[m][k], acc[ai][bj][m][n], 0, 0, 0); __builtin_amdgcn_s_setprio(0); } while (0)
; template <class Epi, class Sched, bool ABLK = false, bool ALIGN_EPI = true, bool SP2 = true, bool BBLK = true>
; __device__ __forceinline__ void gemm_phase(LAS unsigned char* lds, const Gemm g, const Sched& S, const Epi& E) {
;     ...
;             PG8_LDA(At, 1, 1); PG8_STAGE(PG8_SB(1, 0), b3, voffB); PG8_STAGE(PG8_SB(1, 1), b3 + hstepB, voffB); PG8_STAGE(PG8_SA(1, 0), a3, voffA);
;             PG8_WAIT_V(8); PG8_WAIT_L(0); PG8_BAR; PG8_MMA(1, 0, At, B0); PG8_MMA(1, 1, At, B1); PG8_BAR; PG8_SCHED;
;     __device__ __forceinline__ void operator()(const f32x4 (&acc)[2][2][4][2], const Unit& u, int wr, int wc, int fr, int fq) const {
;         const int row0 = u.pm * 256 + wr * 64 + fr, col0 = u.pn * 256 + wc * 64 + 8 * fq;
;         bf16_t* base = u.part == 0 ? Z + (size_t)row0 * D + col0 : P + ((size_t)(u.part - 1) * MS + (row0 - MP)) * D + col0;
; #pragma unroll
;         for (int ai = 0; ai < 2; ++ai)
; #pragma unroll
;             for (int m = 0; m < 4; ++m) { u32x4 w[2];
; #pragma unroll
;                 for (int bj = 0; bj < 2; ++bj) { const f32x4 v0 = acc[ai][bj][m][0], v1 = acc[ai][bj][m][1]; w[bj].x = pk2(v0[0], v0[1]); w[bj].y = pk2(v0[2], v0[3]); w[bj].z = pk2(v1[0], v1[1]); w[bj].w = pk2(v1[2], v1[3]); }
;                 store_pair((unsigned char*)(base + (size_t)(ai * 128 + m * 16) * D), (size_t)8 * D * 2, 64, w[0], w[1], fr >= 8); }
	s_add_u32 s44, s42, 0x8000
	s_addc_u32 s45, s43, 0
	s_add_i32 s70, s60, s48
	s_mov_b32 m0, s70
	ds_read_b128 v[184:187], v150 offset:49152
	ds_read_b128 v[188:191], v150 offset:50176
	ds_read_b128 v[192:195], v150 offset:51200
	ds_read_b128 v[196:199], v150 offset:52224
	ds_read_b128 v[200:203], v150 offset:53248
	ds_read_b128 v[204:207], v150 offset:54272
	ds_read_b128 v[208:211], v150 offset:55296
	ds_read_b128 v[212:215], v150 offset:56320
	global_load_lds_dwordx4 v130, s[44:45]
	s_add_i32 m0, s70, 0x2000
	s_add_u32 s42, s42, 0xc000
	v_lshl_add_u64 v[216:217], s[44:45], 0, v[132:133]
	s_addc_u32 s43, s43, 0
	s_add_i32 s44, s61, s48
	global_load_lds_dwordx4 v[216:217], off
	s_mov_b32 m0, s44
	s_nop 0
	global_load_lds_dwordx4 v130, s[42:43]
	s_add_i32 m0, s44, 0x2000
	s_nop 0
	global_load_lds_dwordx4 v132, s[42:43]
	s_mov_b32 m0, s53
	s_nop 0
	global_load_lds_dwordx4 v130, s[40:41]
	s_mov_b32 m0, s54
	s_nop 0
	global_load_lds_dwordx4 v132, s[40:41]
	s_waitcnt vmcnt(8) lgkmcnt(0)
	s_barrier
	v_mfma_f32_16x16x32_bf16 v[62:65], v[152:155], v[184:187], v[62:65]
	v_mfma_f32_16x16x32_bf16 v[58:61], v[160:163], v[184:187], v[58:61]
	v_mfma_f32_16x16x32_bf16 v[46:49], v[152:155], v[192:195], v[46:49]
	v_mfma_f32_16x16x32_bf16 v[42:45], v[160:163], v[192:195], v[42:45]
	v_mfma_f32_16x16x32_bf16 v[30:33], v[152:155], v[200:203], v[30:33]
	v_mfma_f32_16x16x32_bf16 v[26:29], v[160:163], v[200:203], v[26:29]
	v_mfma_f32_16x16x32_bf16 v[14:17], v[152:155], v[208:211], v[14:17]
	v_mfma_f32_16x16x32_bf16 v[10:13], v[160:163], v[208:211], v[10:13]
	v_mfma_f32_16x16x32_bf16 v[62:65], v[156:159], v[188:191], v[62:65]
	v_mfma_f32_16x16x32_bf16 v[58:61], v[164:167], v[188:191], v[58:61]
	v_mfma_f32_16x16x32_bf16 v[46:49], v[156:159], v[196:199], v[46:49]
	v_mfma_f32_16x16x32_bf16 v[42:45], v[164:167], v[196:199], v[42:45]
	v_mfma_f32_16x16x32_bf16 v[30:33], v[156:159], v[204:207], v[30:33]
	v_mfma_f32_16x16x32_bf16 v[26:29], v[164:167], v[204:207], v[26:29]
	v_mfma_f32_16x16x32_bf16 v[14:17], v[156:159], v[212:215], v[14:17]
	v_mfma_f32_16x16x32_bf16 v[10:13], v[164:167], v[212:215], v[10:13]
	v_mfma_f32_16x16x32_bf16 v[54:57], v[168:171], v[184:187], v[54:57]
	v_mfma_f32_16x16x32_bf16 v[50:53], v[176:179], v[184:187], v[50:53]
	v_mfma_f32_16x16x32_bf16 v[38:41], v[168:171], v[192:195], v[38:41]
	v_mfma_f32_16x16x32_bf16 v[34:37], v[176:179], v[192:195], v[34:37]
	v_mfma_f32_16x16x32_bf16 v[22:25], v[168:171], v[200:203], v[22:25]
	v_mfma_f32_16x16x32_bf16 v[18:21], v[176:179], v[200:203], v[18:21]
	v_mfma_f32_16x16x32_bf16 v[6:9], v[168:171], v[208:211], v[6:9]
	v_mfma_f32_16x16x32_bf16 v[2:5], v[176:179], v[208:211], v[2:5]
	v_mfma_f32_16x16x32_bf16 v[54:57], v[172:175], v[188:191], v[54:57]
	v_mfma_f32_16x16x32_bf16 v[50:53], v[180:183], v[188:191], v[50:53]
	v_mfma_f32_16x16x32_bf16 v[38:41], v[172:175], v[196:199], v[38:41]
	v_mfma_f32_16x16x32_bf16 v[34:37], v[180:183], v[196:199], v[34:37]
	v_mfma_f32_16x16x32_bf16 v[22:25], v[172:175], v[204:207], v[22:25]
	v_mfma_f32_16x16x32_bf16 v[18:21], v[180:183], v[204:207], v[18:21]
	v_mfma_f32_16x16x32_bf16 v[6:9], v[172:175], v[212:215], v[6:9]
	v_mfma_f32_16x16x32_bf16 v[2:5], v[180:183], v[212:215], v[2:5]
	s_barrier
	s_add_u32 s38, s38, 0x10000
	s_addc_u32 s39, s39, 0
	s_cmp_ge_u32 s67, s56
	s_cbranch_scc0 .LBB0_2328
	v_lshl_add_u32 v143, s82, 8, v1
	v_add_u32_e32 v144, 0xffffe000, v143
	v_sub_co_u32_e64 v142, vcc, s55, 1
	v_mov_b32_e32 v145, s9
	s_nop 0
	v_cndmask_b32_e32 v144, v144, v143, vcc
	v_ashrrev_i32_e32 v143, 31, v142
	v_lshlrev_b64 v[142:143], 23, v[142:143]
	v_lshl_add_u64 v[142:143], s[12:13], 0, v[142:143]
	v_cndmask_b32_e32 v143, v143, v145, vcc
	v_mov_b32_e32 v145, s8
	v_cndmask_b32_e32 v142, v142, v145, vcc
	v_ashrrev_i32_e32 v145, 31, v144
	v_lshl_or_b32 v152, s78, 8, v147
	v_lshlrev_b64 v[144:145], 12, v[144:145]
	v_lshl_add_u64 v[142:143], v[142:143], 0, v[144:145]
	v_ashrrev_i32_e32 v153, 31, v152
	v_cvt_pk_bf16_f32 v126, v126, v127
	v_cvt_pk_bf16_f32 v127, v128, v129
	v_cvt_pk_bf16_f32 v128, v122, v123
	v_cvt_pk_bf16_f32 v124, v124, v125
	v_cvt_pk_bf16_f32 v118, v118, v119
	v_cvt_pk_bf16_f32 v119, v120, v121
	v_cvt_pk_bf16_f32 v114, v114, v115
	v_cvt_pk_bf16_f32 v115, v116, v117
	v_lshl_add_u64 v[142:143], v[152:153], 1, v[142:143]
	v_mov_b32_dpp v120, v126 row_ror:8 row_mask:0xf bank_mask:0xf bound_ctrl:1
	v_mov_b32_dpp v121, v127 row_ror:8 row_mask:0xf bank_mask:0xf bound_ctrl:1
	v_mov_b32_dpp v116, v128 row_ror:8 row_mask:0xf bank_mask:0xf bound_ctrl:1
	v_mov_b32_dpp v117, v124 row_ror:8 row_mask:0xf bank_mask:0xf bound_ctrl:1
	v_mov_b32_dpp v125, v118 row_ror:8 row_mask:0xf bank_mask:0xf bound_ctrl:1
	v_mov_b32_dpp v129, v119 row_ror:8 row_mask:0xf bank_mask:0xf bound_ctrl:1
	v_mov_b32_dpp v144, v114 row_ror:8 row_mask:0xf bank_mask:0xf bound_ctrl:1
	v_mov_b32_dpp v145, v115 row_ror:8 row_mask:0xf bank_mask:0xf bound_ctrl:1
	v_lshl_add_u64 v[122:123], v[142:143], 0, v[134:135]
	v_cndmask_b32_e64 v117, v117, v115, s[2:3]
	v_cndmask_b32_e64 v116, v116, v114, s[2:3]
	v_cndmask_b32_e64 v115, v121, v119, s[2:3]
	v_cndmask_b32_e64 v114, v120, v118, s[2:3]
	v_cndmask_b32_e64 v121, v124, v145, s[2:3]
	v_cndmask_b32_e64 v120, v128, v144, s[2:3]
	v_cndmask_b32_e64 v119, v127, v129, s[2:3]
	v_cndmask_b32_e64 v118, v126, v125, s[2:3]
	v_cvt_pk_bf16_f32 v110, v110, v111
	v_cvt_pk_bf16_f32 v111, v112, v113
	v_cvt_pk_bf16_f32 v112, v106, v107
	v_cvt_pk_bf16_f32 v113, v108, v109
	v_cvt_pk_bf16_f32 v102, v102, v103
	v_cvt_pk_bf16_f32 v103, v104, v105
	v_cvt_pk_bf16_f32 v98, v98, v99
	v_cvt_pk_bf16_f32 v99, v100, v101
	v_lshl_add_u64 v[124:125], v[142:143], 0, v[136:137]
; __device__ __forceinline__ unsigned pk2(float lo, float hi) { const f32x2 v = {lo, hi}; return __builtin_bit_cast(unsigned, __builtin_convertvector(v, bf16x2_t)); }
; __device__ __forceinline__ void store_pair(unsigned char* own, size_t stride8, int hi_off, u32x4 lo, u32x4 hi, bool upper) {
;     const u32x4 tlo = ror8(lo), thi = ror8(hi);
;     const u32x4 A = upper ? thi : lo, B = upper ? hi : tlo;
;     unsigned char* pa = upper ? own - stride8 + hi_off : own;
;     unsigned char* pb = upper ? own + hi_off : own + stride8;
;     *(u32x4*)pa = A; *(u32x4*)pb = B;
;     __device__ __forceinline__ void operator()(const f32x4 (&acc)[2][2][4][2], const Unit& u, int wr, int wc, int fr, int fq) const {
;     ...
;         for (int ai = 0; ai < 2; ++ai)
; #pragma unroll
;             for (int m = 0; m < 4; ++m) { u32x4 w[2];
; #pragma unroll
;                 for (int bj = 0; bj < 2; ++bj) { const f32x4 v0 = acc[ai][bj][m][0], v1 = acc[ai][bj][m][1]; w[bj].x = pk2(v0[0], v0[1]); w[bj].y = pk2(v0[2], v0[3]); w[bj].z = pk2(v1[0], v1[1]); w[bj].w = pk2(v1[2], v1[3]); }
;                 store_pair((unsigned char*)(base + (size_t)(ai * 128 + m * 16) * D), (size_t)8 * D * 2, 64, w[0], w[1], fr >= 8); }
	global_store_dwordx4 v[122:123], v[118:121], off
	global_store_dwordx4 v[124:125], v[114:117], off
	v_lshl_add_u64 v[106:107], v[142:143], 0, s[16:17]
	v_mov_b32_dpp v104, v110 row_ror:8 row_mask:0xf bank_mask:0xf bound_ctrl:1
	v_mov_b32_dpp v105, v111 row_ror:8 row_mask:0xf bank_mask:0xf bound_ctrl:1
	v_mov_b32_dpp v100, v112 row_ror:8 row_mask:0xf bank_mask:0xf bound_ctrl:1
	v_mov_b32_dpp v101, v113 row_ror:8 row_mask:0xf bank_mask:0xf bound_ctrl:1
	v_mov_b32_dpp v114, v102 row_ror:8 row_mask:0xf bank_mask:0xf bound_ctrl:1
	v_mov_b32_dpp v115, v103 row_ror:8 row_mask:0xf bank_mask:0xf bound_ctrl:1
	v_mov_b32_dpp v116, v98 row_ror:8 row_mask:0xf bank_mask:0xf bound_ctrl:1
	v_mov_b32_dpp v117, v99 row_ror:8 row_mask:0xf bank_mask:0xf bound_ctrl:1
	v_lshl_add_u64 v[108:109], v[106:107], 0, v[134:135]
	v_cndmask_b32_e64 v101, v101, v99, s[2:3]
	v_cndmask_b32_e64 v100, v100, v98, s[2:3]
	v_cndmask_b32_e64 v99, v105, v103, s[2:3]
	v_cndmask_b32_e64 v98, v104, v102, s[2:3]
	v_cndmask_b32_e64 v105, v113, v117, s[2:3]
	v_cndmask_b32_e64 v104, v112, v116, s[2:3]
	v_cndmask_b32_e64 v103, v111, v115, s[2:3]
	v_cndmask_b32_e64 v102, v110, v114, s[2:3]
	v_cvt_pk_bf16_f32 v94, v94, v95
	v_cvt_pk_bf16_f32 v95, v96, v97
	v_cvt_pk_bf16_f32 v96, v90, v91
	v_cvt_pk_bf16_f32 v97, v92, v93
	v_cvt_pk_bf16_f32 v86, v86, v87
	v_cvt_pk_bf16_f32 v87, v88, v89
	v_cvt_pk_bf16_f32 v82, v82, v83
	v_cvt_pk_bf16_f32 v83, v84, v85
	v_lshl_add_u64 v[106:107], v[106:107], 0, v[136:137]
	global_store_dwordx4 v[108:109], v[102:105], off
	global_store_dwordx4 v[106:107], v[98:101], off
	v_lshl_add_u64 v[90:91], v[142:143], 0, s[18:19]
	v_mov_b32_dpp v88, v94 row_ror:8 row_mask:0xf bank_mask:0xf bound_ctrl:1
	v_mov_b32_dpp v89, v95 row_ror:8 row_mask:0xf bank_mask:0xf bound_ctrl:1
	v_mov_b32_dpp v84, v96 row_ror:8 row_mask:0xf bank_mask:0xf bound_ctrl:1
	v_mov_b32_dpp v85, v97 row_ror:8 row_mask:0xf bank_mask:0xf bound_ctrl:1
	v_mov_b32_dpp v98, v86 row_ror:8 row_mask:0xf bank_mask:0xf bound_ctrl:1
	v_mov_b32_dpp v99, v87 row_ror:8 row_mask:0xf bank_mask:0xf bound_ctrl:1
	v_mov_b32_dpp v100, v82 row_ror:8 row_mask:0xf bank_mask:0xf bound_ctrl:1
	v_mov_b32_dpp v101, v83 row_ror:8 row_mask:0xf bank_mask:0xf bound_ctrl:1
	v_lshl_add_u64 v[92:93], v[90:91], 0, v[134:135]
	v_cndmask_b32_e64 v85, v85, v83, s[2:3]
	v_cndmask_b32_e64 v84, v84, v82, s[2:3]
	v_cndmask_b32_e64 v83, v89, v87, s[2:3]
	v_cndmask_b32_e64 v82, v88, v86, s[2:3]
	v_cndmask_b32_e64 v89, v97, v101, s[2:3]
	v_cndmask_b32_e64 v88, v96, v100, s[2:3]
	v_cndmask_b32_e64 v87, v95, v99, s[2:3]
	v_cndmask_b32_e64 v86, v94, v98, s[2:3]
	v_cvt_pk_bf16_f32 v78, v78, v79
	v_cvt_pk_bf16_f32 v79, v80, v81
	v_cvt_pk_bf16_f32 v80, v74, v75
	v_cvt_pk_bf16_f32 v81, v76, v77
	v_cvt_pk_bf16_f32 v70, v70, v71
	v_cvt_pk_bf16_f32 v71, v72, v73
	v_cvt_pk_bf16_f32 v66, v66, v67
	v_cvt_pk_bf16_f32 v67, v68, v69
	v_lshl_add_u64 v[90:91], v[90:91], 0, v[136:137]
	global_store_dwordx4 v[92:93], v[86:89], off
	global_store_dwordx4 v[90:91], v[82:85], off
	v_lshl_add_u64 v[74:75], v[142:143], 0, s[20:21]
	v_mov_b32_dpp v72, v78 row_ror:8 row_mask:0xf bank_mask:0xf bound_ctrl:1
	v_mov_b32_dpp v73, v79 row_ror:8 row_mask:0xf bank_mask:0xf bound_ctrl:1
	v_mov_b32_dpp v68, v80 row_ror:8 row_mask:0xf bank_mask:0xf bound_ctrl:1
	v_mov_b32_dpp v69, v81 row_ror:8 row_mask:0xf bank_mask:0xf bound_ctrl:1
	v_mov_b32_dpp v82, v70 row_ror:8 row_mask:0xf bank_mask:0xf bound_ctrl:1
	v_mov_b32_dpp v83, v71 row_ror:8 row_mask:0xf bank_mask:0xf bound_ctrl:1
	v_mov_b32_dpp v84, v66 row_ror:8 row_mask:0xf bank_mask:0xf bound_ctrl:1
	v_mov_b32_dpp v85, v67 row_ror:8 row_mask:0xf bank_mask:0xf bound_ctrl:1
	v_lshl_add_u64 v[76:77], v[74:75], 0, v[134:135]
	v_cndmask_b32_e64 v69, v69, v67, s[2:3]
	v_cndmask_b32_e64 v68, v68, v66, s[2:3]
	v_cndmask_b32_e64 v67, v73, v71, s[2:3]
	v_cndmask_b32_e64 v66, v72, v70, s[2:3]
	v_cndmask_b32_e64 v73, v81, v85, s[2:3]
	v_cndmask_b32_e64 v72, v80, v84, s[2:3]
	v_cndmask_b32_e64 v71, v79, v83, s[2:3]
	v_cndmask_b32_e64 v70, v78, v82, s[2:3]
	v_cvt_pk_bf16_f32 v62, v62, v63
	v_cvt_pk_bf16_f32 v63, v64, v65
	v_cvt_pk_bf16_f32 v64, v58, v59
	v_cvt_pk_bf16_f32 v65, v60, v61
	v_cvt_pk_bf16_f32 v54, v54, v55
	v_cvt_pk_bf16_f32 v55, v56, v57
	v_cvt_pk_bf16_f32 v50, v50, v51
	v_cvt_pk_bf16_f32 v51, v52, v53
	v_lshl_add_u64 v[74:75], v[74:75], 0, v[136:137]
	global_store_dwordx4 v[76:77], v[70:73], off
	global_store_dwordx4 v[74:75], v[66:69], off
	v_lshl_add_u64 v[58:59], v[142:143], 0, s[22:23]
	v_mov_b32_dpp v56, v62 row_ror:8 row_mask:0xf bank_mask:0xf bound_ctrl:1
	v_mov_b32_dpp v57, v63 row_ror:8 row_mask:0xf bank_mask:0xf bound_ctrl:1
	v_mov_b32_dpp v52, v64 row_ror:8 row_mask:0xf bank_mask:0xf bound_ctrl:1
	v_mov_b32_dpp v53, v65 row_ror:8 row_mask:0xf bank_mask:0xf bound_ctrl:1
	v_mov_b32_dpp v66, v54 row_ror:8 row_mask:0xf bank_mask:0xf bound_ctrl:1
	v_mov_b32_dpp v67, v55 row_ror:8 row_mask:0xf bank_mask:0xf bound_ctrl:1
	v_mov_b32_dpp v68, v50 row_ror:8 row_mask:0xf bank_mask:0xf bound_ctrl:1
	v_mov_b32_dpp v69, v51 row_ror:8 row_mask:0xf bank_mask:0xf bound_ctrl:1
; __device__ __forceinline__ unsigned pk2(float lo, float hi) { const f32x2 v = {lo, hi}; return __builtin_bit_cast(unsigned, __builtin_convertvector(v, bf16x2_t)); }
; #define PG8_BAR __builtin_amdgcn_s_barrier()
; template <class Epi, class Sched, bool ABLK = false, bool ALIGN_EPI = true, bool SP2 = true, bool BBLK = true>
; __device__ __forceinline__ void gemm_phase(LAS unsigned char* lds, const Gemm g, const Sched& S, const Epi& E) {
;     ...
;         if constexpr (ALIGN_EPI) { if (wr == 0) PG8_BAR; }
;         E(acc, cur, wr, wc, fr, fq); S.done(cur);
;         if (!has_next) break;
; #pragma unroll
;         for (int a = 0; a < 2; ++a)
; #pragma unroll
;             for (int b = 0; b < 2; ++b)
; #pragma unroll
;                 for (int m = 0; m < 4; ++m)
; #pragma unroll
;                     for (int n = 0; n < 2; ++n) acc[a][b][m][n] = (f32x4){0.f, 0.f, 0.f, 0.f};
;         cur = nxt; uA = nuA; tbA = ntbA; cB = nB; ++ui;
;         if constexpr (ALIGN_EPI) { if (wr == 1) PG8_BAR; }
;     __device__ __forceinline__ void operator()(const f32x4 (&acc)[2][2][4][2], const Unit& u, int wr, int wc, int fr, int fq) const {
;     ...
;         for (int ai = 0; ai < 2; ++ai)
; #pragma unroll
;             for (int m = 0; m < 4; ++m) { u32x4 w[2];
; #pragma unroll
;                 for (int bj = 0; bj < 2; ++bj) { const f32x4 v0 = acc[ai][bj][m][0], v1 = acc[ai][bj][m][1]; w[bj].x = pk2(v0[0], v0[1]); w[bj].y = pk2(v0[2], v0[3]); w[bj].z = pk2(v1[0], v1[1]); w[bj].w = pk2(v1[2], v1[3]); }
;                 store_pair((unsigned char*)(base + (size_t)(ai * 128 + m * 16) * D), (size_t)8 * D * 2, 64, w[0], w[1], fr >= 8); }
	v_lshl_add_u64 v[60:61], v[58:59], 0, v[134:135]
	v_cndmask_b32_e64 v53, v53, v51, s[2:3]
	v_cndmask_b32_e64 v52, v52, v50, s[2:3]
	v_cndmask_b32_e64 v51, v57, v55, s[2:3]
	v_cndmask_b32_e64 v50, v56, v54, s[2:3]
	v_cndmask_b32_e64 v57, v65, v69, s[2:3]
	v_cndmask_b32_e64 v56, v64, v68, s[2:3]
	v_cndmask_b32_e64 v55, v63, v67, s[2:3]
	v_cndmask_b32_e64 v54, v62, v66, s[2:3]
	v_cvt_pk_bf16_f32 v46, v46, v47
	v_cvt_pk_bf16_f32 v47, v48, v49
	v_cvt_pk_bf16_f32 v48, v42, v43
	v_cvt_pk_bf16_f32 v49, v44, v45
	v_cvt_pk_bf16_f32 v38, v38, v39
	v_cvt_pk_bf16_f32 v39, v40, v41
	v_cvt_pk_bf16_f32 v34, v34, v35
	v_cvt_pk_bf16_f32 v35, v36, v37
	v_lshl_add_u64 v[58:59], v[58:59], 0, v[136:137]
	global_store_dwordx4 v[60:61], v[54:57], off
	global_store_dwordx4 v[58:59], v[50:53], off
	v_lshl_add_u64 v[42:43], v[142:143], 0, s[24:25]
	v_mov_b32_dpp v40, v46 row_ror:8 row_mask:0xf bank_mask:0xf bound_ctrl:1
	v_mov_b32_dpp v41, v47 row_ror:8 row_mask:0xf bank_mask:0xf bound_ctrl:1
	v_mov_b32_dpp v36, v48 row_ror:8 row_mask:0xf bank_mask:0xf bound_ctrl:1
	v_mov_b32_dpp v37, v49 row_ror:8 row_mask:0xf bank_mask:0xf bound_ctrl:1
	v_mov_b32_dpp v50, v38 row_ror:8 row_mask:0xf bank_mask:0xf bound_ctrl:1
	v_mov_b32_dpp v51, v39 row_ror:8 row_mask:0xf bank_mask:0xf bound_ctrl:1
	v_mov_b32_dpp v52, v34 row_ror:8 row_mask:0xf bank_mask:0xf bound_ctrl:1
	v_mov_b32_dpp v53, v35 row_ror:8 row_mask:0xf bank_mask:0xf bound_ctrl:1
	v_lshl_add_u64 v[44:45], v[42:43], 0, v[134:135]
	v_cndmask_b32_e64 v37, v37, v35, s[2:3]
	v_cndmask_b32_e64 v36, v36, v34, s[2:3]
	v_cndmask_b32_e64 v35, v41, v39, s[2:3]
	v_cndmask_b32_e64 v34, v40, v38, s[2:3]
	v_cndmask_b32_e64 v41, v49, v53, s[2:3]
	v_cndmask_b32_e64 v40, v48, v52, s[2:3]
	v_cndmask_b32_e64 v39, v47, v51, s[2:3]
	v_cndmask_b32_e64 v38, v46, v50, s[2:3]
	v_cvt_pk_bf16_f32 v30, v30, v31
	v_cvt_pk_bf16_f32 v31, v32, v33
	v_cvt_pk_bf16_f32 v32, v26, v27
	v_cvt_pk_bf16_f32 v33, v28, v29
	v_cvt_pk_bf16_f32 v22, v22, v23
	v_cvt_pk_bf16_f32 v23, v24, v25
	v_cvt_pk_bf16_f32 v18, v18, v19
	v_cvt_pk_bf16_f32 v19, v20, v21
	v_lshl_add_u64 v[42:43], v[42:43], 0, v[136:137]
	global_store_dwordx4 v[44:45], v[38:41], off
	global_store_dwordx4 v[42:43], v[34:37], off
	v_lshl_add_u64 v[26:27], v[142:143], 0, s[26:27]
	v_mov_b32_dpp v24, v30 row_ror:8 row_mask:0xf bank_mask:0xf bound_ctrl:1
	v_mov_b32_dpp v25, v31 row_ror:8 row_mask:0xf bank_mask:0xf bound_ctrl:1
	v_mov_b32_dpp v20, v32 row_ror:8 row_mask:0xf bank_mask:0xf bound_ctrl:1
	v_mov_b32_dpp v21, v33 row_ror:8 row_mask:0xf bank_mask:0xf bound_ctrl:1
	v_mov_b32_dpp v34, v22 row_ror:8 row_mask:0xf bank_mask:0xf bound_ctrl:1
	v_mov_b32_dpp v35, v23 row_ror:8 row_mask:0xf bank_mask:0xf bound_ctrl:1
	v_mov_b32_dpp v36, v18 row_ror:8 row_mask:0xf bank_mask:0xf bound_ctrl:1
	v_mov_b32_dpp v37, v19 row_ror:8 row_mask:0xf bank_mask:0xf bound_ctrl:1
	v_lshl_add_u64 v[28:29], v[26:27], 0, v[134:135]
	v_cndmask_b32_e64 v21, v21, v19, s[2:3]
	v_cndmask_b32_e64 v20, v20, v18, s[2:3]
	v_cndmask_b32_e64 v19, v25, v23, s[2:3]
	v_cndmask_b32_e64 v18, v24, v22, s[2:3]
	v_cndmask_b32_e64 v25, v33, v37, s[2:3]
	v_cndmask_b32_e64 v24, v32, v36, s[2:3]
	v_cndmask_b32_e64 v23, v31, v35, s[2:3]
	v_cndmask_b32_e64 v22, v30, v34, s[2:3]
	v_cvt_pk_bf16_f32 v14, v14, v15
	v_cvt_pk_bf16_f32 v15, v16, v17
	v_cvt_pk_bf16_f32 v16, v10, v11
	v_cvt_pk_bf16_f32 v17, v12, v13
	v_cvt_pk_bf16_f32 v6, v6, v7
	v_cvt_pk_bf16_f32 v7, v8, v9
	v_cvt_pk_bf16_f32 v2, v2, v3
	v_cvt_pk_bf16_f32 v3, v4, v5
	v_lshl_add_u64 v[26:27], v[26:27], 0, v[136:137]
	global_store_dwordx4 v[28:29], v[22:25], off
	global_store_dwordx4 v[26:27], v[18:21], off
	v_lshl_add_u64 v[10:11], v[142:143], 0, s[28:29]
	v_mov_b32_dpp v8, v14 row_ror:8 row_mask:0xf bank_mask:0xf bound_ctrl:1
	v_mov_b32_dpp v9, v15 row_ror:8 row_mask:0xf bank_mask:0xf bound_ctrl:1
	v_mov_b32_dpp v4, v16 row_ror:8 row_mask:0xf bank_mask:0xf bound_ctrl:1
	v_mov_b32_dpp v5, v17 row_ror:8 row_mask:0xf bank_mask:0xf bound_ctrl:1
	v_mov_b32_dpp v18, v6 row_ror:8 row_mask:0xf bank_mask:0xf bound_ctrl:1
	v_mov_b32_dpp v19, v7 row_ror:8 row_mask:0xf bank_mask:0xf bound_ctrl:1
	v_mov_b32_dpp v20, v2 row_ror:8 row_mask:0xf bank_mask:0xf bound_ctrl:1
	v_mov_b32_dpp v21, v3 row_ror:8 row_mask:0xf bank_mask:0xf bound_ctrl:1
	v_lshl_add_u64 v[12:13], v[10:11], 0, v[134:135]
	v_cndmask_b32_e64 v5, v5, v3, s[2:3]
	v_cndmask_b32_e64 v4, v4, v2, s[2:3]
	v_cndmask_b32_e64 v3, v9, v7, s[2:3]
	v_cndmask_b32_e64 v2, v8, v6, s[2:3]
	v_cndmask_b32_e64 v9, v17, v21, s[2:3]
	v_cndmask_b32_e64 v8, v16, v20, s[2:3]
	v_cndmask_b32_e64 v7, v15, v19, s[2:3]
	v_cndmask_b32_e64 v6, v14, v18, s[2:3]
	s_and_b64 vcc, exec, s[14:15]
	s_cbranch_vccz .LBB0_2331
	s_barrier
.LBB0_2331:
	s_and_b64 vcc, exec, s[6:7]
	s_mov_b64 s[6:7], -1
	v_lshl_add_u64 v[10:11], v[10:11], 0, v[136:137]
	global_store_dwordx4 v[12:13], v[6:9], off
	global_store_dwordx4 v[10:11], v[2:5], off
	s_cbranch_vccnz .LBB0_2326
	s_andn2_b64 vcc, exec, s[10:11]
	s_cbranch_vccnz .LBB0_2325
	s_barrier
	s_branch .LBB0_2325
